# comb7 = comb5 + GEMM accumulator zeroing removed (first K iteration peeled, first MFMA per accumulator uses C=0)
# speedup vs baseline: 1.0207x; 1.0090x over previous
; #define PG8_STAGE(bufoff, gbase, voff) do { _Pragma("unroll") for (int _i = 0; _i < 2; ++_i) \
;         __builtin_amdgcn_global_load_lds((const unsigned*)((const char*)(gbase) + (voff)[_i]), (LAS unsigned*)(lds + (bufoff) + ldsw + _i * 8192), 16, 0, 0); } while (0)
; #define PG8_LDA(dst, b, h) do { _Pragma("unroll") for (int m = 0; m < 4; ++m) _Pragma("unroll") for (int k = 0; k < 2; ++k) dst[m][k] = *(const LAS bf16x8*)(lds + PG8_SA(b, h) + aoff + m * 2048 + k * 1024); } while (0)
; #define PG8_LDB(dst, b, h) do { _Pragma("unroll") for (int n = 0; n < 2; ++n) _Pragma("unroll") for (int k = 0; k < 2; ++k) dst[n][k] = *(const LAS bf16x8*)(lds + PG8_SB(b, h) + boff + n * 2048 + k * 1024); } while (0)
; #define PG8_MMA(ai, bj, At, Bt) do { __builtin_amdgcn_s_setprio(1); _Pragma("unroll") for (int m = 0; m < 4; ++m) _Pragma("unroll") for (int n = 0; n < 2; ++n) _Pragma("unroll") for (int k = 0; k < 2; ++k) \
;         acc[ai][bj][m][n] = __builtin_amdgcn_mfma_f32_16x16x32_bf16(Bt[n][k], At[m][k], acc[ai][bj][m][n], 0, 0, 0); __builtin_amdgcn_s_setprio(0); } while (0)
; #define PG8_WAIT_V(n) asm volatile("s_waitcnt vmcnt(" #n ")" ::: "memory")
; #define PG8_BAR __builtin_amdgcn_s_barrier()
; template <class Epi>
; __device__ __forceinline__ void gemm_phase(LAS unsigned char* lds, const Gemm g, int G, int c, const Epi& E) {
;     ...
;     f32x4 acc[2][2][4][2];
; #pragma unroll
;     for (int a = 0; a < 2; ++a)
; #pragma unroll
;         for (int b = 0; b < 2; ++b)
; #pragma unroll
;             for (int m = 0; m < 4; ++m)
; #pragma unroll
;                 for (int n = 0; n < 2; ++n) acc[a][b][m][n] = (f32x4){0.f, 0.f, 0.f, 0.f};
;     ...
;         for (int t = 0; t < nt; t += 2) {
;             const bool last = (t == nt - 2);
;             const char* a1 = cA + (size_t)(t + 1) * kstep;
;             const char* a2 = last ? nA : cA + (size_t)(t + 2) * kstep; const char* b2 = last ? nB : cB + (size_t)(t + 2) * kstep;
;             const char* a3 = a2 + kstep; const char* b3 = b2 + kstep;
;             PG8_LDB(B0, 0, 0); PG8_LDB(B1, 0, 1); PG8_SCHED; PG8_LDA(At, 0, 0); PG8_STAGE(PG8_SA(1, 1), a1 + hstepA, voffA);
;             PG8_WAIT_V(8); PG8_WAIT_L(0); PG8_BAR; PG8_MMA(0, 0, At, B0); PG8_MMA(0, 1, At, B1); PG8_BAR; PG8_SCHED;
;             PG8_LDA(At, 0, 1); PG8_STAGE(PG8_SB(0, 0), b2, voffB); PG8_STAGE(PG8_SB(0, 1), b2 + hstepB, voffB); PG8_STAGE(PG8_SA(0, 0), a2, voffA);
.LBB0_235:
	s_ashr_i32 s43, s42, 31
	s_lshl_b64 s[52:53], s[42:43], 19
	s_add_u32 s52, s30, s52
	s_addc_u32 s53, s31, s53
	s_and_b64 s[4:5], s[4:5], exec
	s_cselect_b32 s7, s53, s55
	s_cselect_b32 s43, s52, s54
	s_add_u32 s4, s56, 0x40080
	s_addc_u32 s5, s57, 0
	s_add_u32 s45, s54, 0x100
	s_addc_u32 s84, s55, 0
	s_mov_b32 s85, -2
	s_waitcnt lgkmcnt(0)
	ds_read_b128 v[146:149], v152
	ds_read_b128 v[158:161], v152 offset:1024
	ds_read_b128 v[162:165], v152 offset:2048
	ds_read_b128 v[166:169], v152 offset:3072
	ds_read_b128 v[170:173], v153
	ds_read_b128 v[174:177], v153 offset:1024
	ds_read_b128 v[178:181], v153 offset:2048
	ds_read_b128 v[182:185], v153 offset:3072
	s_add_u32 s33, s4, 0xfffc0080
	s_addc_u32 s54, s5, -1
	s_cmp_eq_u32 s85, 12
	s_cselect_b32 s57, s47, s54
	s_cselect_b32 s56, s46, s33
	s_cselect_b32 s55, s7, s84
	s_cselect_b32 s54, s43, s45
	v_lshl_add_u64 v[218:219], s[4:5], 0, v[138:139]
	s_add_i32 m0, s11, 0xc000
	ds_read_b128 v[186:189], v154
	ds_read_b128 v[190:193], v154 offset:1024
	ds_read_b128 v[194:197], v154 offset:2048
	ds_read_b128 v[198:201], v154 offset:3072
	ds_read_b128 v[202:205], v154 offset:4096
	ds_read_b128 v[206:209], v154 offset:5120
	ds_read_b128 v[210:213], v154 offset:6144
	ds_read_b128 v[214:217], v154 offset:7168
	global_load_lds_dwordx4 v[218:219], off
	v_lshl_add_u64 v[218:219], s[4:5], 0, v[140:141]
	s_add_i32 m0, s11, 0xe000
	s_nop 0
	global_load_lds_dwordx4 v[218:219], off
	s_waitcnt vmcnt(8)
	s_waitcnt lgkmcnt(0)
	s_barrier
	s_setprio 0
	s_waitcnt lgkmcnt(0)
	v_mfma_f32_16x16x32_bf16 v[126:129], v[146:149], v[186:189], 0
	v_mfma_f32_16x16x32_bf16 v[122:125], v[162:165], v[186:189], 0
	v_mfma_f32_16x16x32_bf16 v[110:113], v[146:149], v[194:197], 0
	v_mfma_f32_16x16x32_bf16 v[106:109], v[162:165], v[194:197], 0
	v_mfma_f32_16x16x32_bf16 v[94:97], v[146:149], v[202:205], 0
	v_mfma_f32_16x16x32_bf16 v[90:93], v[162:165], v[202:205], 0
	v_mfma_f32_16x16x32_bf16 v[78:81], v[146:149], v[210:213], 0
	v_mfma_f32_16x16x32_bf16 v[74:77], v[162:165], v[210:213], 0
	v_mfma_f32_16x16x32_bf16 v[126:129], v[158:161], v[190:193], v[126:129]
	v_mfma_f32_16x16x32_bf16 v[122:125], v[166:169], v[190:193], v[122:125]
	v_mfma_f32_16x16x32_bf16 v[110:113], v[158:161], v[198:201], v[110:113]
	v_mfma_f32_16x16x32_bf16 v[106:109], v[166:169], v[198:201], v[106:109]
	v_mfma_f32_16x16x32_bf16 v[94:97], v[158:161], v[206:209], v[94:97]
	v_mfma_f32_16x16x32_bf16 v[90:93], v[166:169], v[206:209], v[90:93]
	v_mfma_f32_16x16x32_bf16 v[78:81], v[158:161], v[214:217], v[78:81]
	v_mfma_f32_16x16x32_bf16 v[74:77], v[166:169], v[214:217], v[74:77]
	s_setprio 2
	s_setprio 0
	v_mfma_f32_16x16x32_bf16 v[118:121], v[170:173], v[186:189], 0
	v_mfma_f32_16x16x32_bf16 v[114:117], v[178:181], v[186:189], 0
	v_mfma_f32_16x16x32_bf16 v[102:105], v[170:173], v[194:197], 0
	v_mfma_f32_16x16x32_bf16 v[98:101], v[178:181], v[194:197], 0
	v_mfma_f32_16x16x32_bf16 v[86:89], v[170:173], v[202:205], 0
	v_mfma_f32_16x16x32_bf16 v[82:85], v[178:181], v[202:205], 0
	v_mfma_f32_16x16x32_bf16 v[70:73], v[170:173], v[210:213], 0
	v_mfma_f32_16x16x32_bf16 v[66:69], v[178:181], v[210:213], 0
	v_mfma_f32_16x16x32_bf16 v[118:121], v[174:177], v[190:193], v[118:121]
	v_mfma_f32_16x16x32_bf16 v[114:117], v[182:185], v[190:193], v[114:117]
	v_mfma_f32_16x16x32_bf16 v[102:105], v[174:177], v[198:201], v[102:105]
	v_mfma_f32_16x16x32_bf16 v[98:101], v[182:185], v[198:201], v[98:101]
	v_mfma_f32_16x16x32_bf16 v[86:89], v[174:177], v[206:209], v[86:89]
	v_mfma_f32_16x16x32_bf16 v[82:85], v[182:185], v[206:209], v[82:85]
	v_mfma_f32_16x16x32_bf16 v[70:73], v[174:177], v[214:217], v[70:73]
	v_mfma_f32_16x16x32_bf16 v[66:69], v[182:185], v[214:217], v[66:69]
	s_setprio 2
	s_barrier
	s_add_i32 s33, s79, s60
	v_lshl_add_u64 v[218:219], s[54:55], 0, v[132:133]
	s_mov_b32 m0, s33
	ds_read_b128 v[186:189], v154 offset:16384
	ds_read_b128 v[190:193], v154 offset:17408
	ds_read_b128 v[194:197], v154 offset:18432
	ds_read_b128 v[198:201], v154 offset:19456
	ds_read_b128 v[202:205], v154 offset:20480
	ds_read_b128 v[206:209], v154 offset:21504
	ds_read_b128 v[210:213], v154 offset:22528
	ds_read_b128 v[214:217], v154 offset:23552
	global_load_lds_dwordx4 v[218:219], off
	s_add_i32 m0, s33, 0x2000
	s_add_u32 s62, s54, 0x40000
	v_lshl_add_u64 v[220:221], s[54:55], 0, v[136:137]
	s_addc_u32 s63, s55, 0
	s_add_i32 s33, s80, s60
	global_load_lds_dwordx4 v[220:221], off
	v_lshl_add_u64 v[222:223], s[62:63], 0, v[132:133]
	s_mov_b32 m0, s33
	v_lshl_add_u64 v[224:225], s[56:57], 0, v[134:135]
	global_load_lds_dwordx4 v[222:223], off
	v_lshl_add_u64 v[222:223], s[62:63], 0, v[136:137]
	s_add_i32 m0, s33, 0x2000
	s_nop 0
	global_load_lds_dwordx4 v[222:223], off
	v_lshl_add_u64 v[222:223], s[56:57], 0, v[130:131]
	s_mov_b32 m0, s11
	s_nop 0
	global_load_lds_dwordx4 v[222:223], off
	s_mov_b32 m0, s61
	s_nop 0
	global_load_lds_dwordx4 v[224:225], off
	s_waitcnt vmcnt(8)
	s_waitcnt lgkmcnt(0)
	s_barrier
; #define PG8_STAGE(bufoff, gbase, voff) do { _Pragma("unroll") for (int _i = 0; _i < 2; ++_i) \
;         __builtin_amdgcn_global_load_lds((const unsigned*)((const char*)(gbase) + (voff)[_i]), (LAS unsigned*)(lds + (bufoff) + ldsw + _i * 8192), 16, 0, 0); } while (0)
; #define PG8_LDA(dst, b, h) do { _Pragma("unroll") for (int m = 0; m < 4; ++m) _Pragma("unroll") for (int k = 0; k < 2; ++k) dst[m][k] = *(const LAS bf16x8*)(lds + PG8_SA(b, h) + aoff + m * 2048 + k * 1024); } while (0)
; #define PG8_LDB(dst, b, h) do { _Pragma("unroll") for (int n = 0; n < 2; ++n) _Pragma("unroll") for (int k = 0; k < 2; ++k) dst[n][k] = *(const LAS bf16x8*)(lds + PG8_SB(b, h) + boff + n * 2048 + k * 1024); } while (0)
; #define PG8_MMA(ai, bj, At, Bt) do { __builtin_amdgcn_s_setprio(1); _Pragma("unroll") for (int m = 0; m < 4; ++m) _Pragma("unroll") for (int n = 0; n < 2; ++n) _Pragma("unroll") for (int k = 0; k < 2; ++k) \
;         acc[ai][bj][m][n] = __builtin_amdgcn_mfma_f32_16x16x32_bf16(Bt[n][k], At[m][k], acc[ai][bj][m][n], 0, 0, 0); __builtin_amdgcn_s_setprio(0); } while (0)
; #define PG8_WAIT_V(n) asm volatile("s_waitcnt vmcnt(" #n ")" ::: "memory")
; #define PG8_WAIT_L(n) asm volatile("s_waitcnt lgkmcnt(" #n ")" ::: "memory")
; #define PG8_BAR __builtin_amdgcn_s_barrier()
; #define PG8_SCHED __builtin_amdgcn_sched_barrier(0)
; template <class Epi>
; __device__ __forceinline__ void gemm_phase(LAS unsigned char* lds, const Gemm g, int G, int c, const Epi& E) {
;     ...
;             PG8_WAIT_V(8); PG8_WAIT_L(0); PG8_BAR; PG8_MMA(1, 0, At, B0); PG8_MMA(1, 1, At, B1); PG8_BAR; PG8_SCHED;
;             PG8_LDB(B0, 1, 0); PG8_LDB(B1, 1, 1); PG8_SCHED; PG8_LDA(At, 1, 0); PG8_STAGE(PG8_SA(0, 1), a2 + hstepA, voffA);
;             PG8_WAIT_V(8); PG8_WAIT_L(0); PG8_BAR; PG8_MMA(0, 0, At, B0); PG8_MMA(0, 1, At, B1); PG8_BAR; PG8_SCHED;
	s_setprio 0
	s_waitcnt lgkmcnt(0)
	v_mfma_f32_16x16x32_bf16 v[62:65], v[146:149], v[186:189], 0
	v_mfma_f32_16x16x32_bf16 v[58:61], v[162:165], v[186:189], 0
	v_mfma_f32_16x16x32_bf16 v[46:49], v[146:149], v[194:197], 0
	v_mfma_f32_16x16x32_bf16 v[42:45], v[162:165], v[194:197], 0
	v_mfma_f32_16x16x32_bf16 v[30:33], v[146:149], v[202:205], 0
	v_mfma_f32_16x16x32_bf16 v[26:29], v[162:165], v[202:205], 0
	v_mfma_f32_16x16x32_bf16 v[14:17], v[146:149], v[210:213], 0
	v_mfma_f32_16x16x32_bf16 v[10:13], v[162:165], v[210:213], 0
	v_mfma_f32_16x16x32_bf16 v[62:65], v[158:161], v[190:193], v[62:65]
	v_mfma_f32_16x16x32_bf16 v[58:61], v[166:169], v[190:193], v[58:61]
	v_mfma_f32_16x16x32_bf16 v[46:49], v[158:161], v[198:201], v[46:49]
	v_mfma_f32_16x16x32_bf16 v[42:45], v[166:169], v[198:201], v[42:45]
	v_mfma_f32_16x16x32_bf16 v[30:33], v[158:161], v[206:209], v[30:33]
	v_mfma_f32_16x16x32_bf16 v[26:29], v[166:169], v[206:209], v[26:29]
	v_mfma_f32_16x16x32_bf16 v[14:17], v[158:161], v[214:217], v[14:17]
	v_mfma_f32_16x16x32_bf16 v[10:13], v[166:169], v[214:217], v[10:13]
	s_setprio 2
	s_setprio 0
	v_mfma_f32_16x16x32_bf16 v[54:57], v[170:173], v[186:189], 0
	v_mfma_f32_16x16x32_bf16 v[50:53], v[178:181], v[186:189], 0
	v_mfma_f32_16x16x32_bf16 v[38:41], v[170:173], v[194:197], 0
	v_mfma_f32_16x16x32_bf16 v[34:37], v[178:181], v[194:197], 0
	v_mfma_f32_16x16x32_bf16 v[22:25], v[170:173], v[202:205], 0
	v_mfma_f32_16x16x32_bf16 v[18:21], v[178:181], v[202:205], 0
	v_mfma_f32_16x16x32_bf16 v[6:9], v[170:173], v[210:213], 0
	v_mfma_f32_16x16x32_bf16 v[2:5], v[178:181], v[210:213], 0
	v_mfma_f32_16x16x32_bf16 v[54:57], v[174:177], v[190:193], v[54:57]
	v_mfma_f32_16x16x32_bf16 v[50:53], v[182:185], v[190:193], v[50:53]
	v_mfma_f32_16x16x32_bf16 v[38:41], v[174:177], v[198:201], v[38:41]
	v_mfma_f32_16x16x32_bf16 v[34:37], v[182:185], v[198:201], v[34:37]
	v_mfma_f32_16x16x32_bf16 v[22:25], v[174:177], v[206:209], v[22:25]
	v_mfma_f32_16x16x32_bf16 v[18:21], v[182:185], v[206:209], v[18:21]
	v_mfma_f32_16x16x32_bf16 v[6:9], v[174:177], v[214:217], v[6:9]
	v_mfma_f32_16x16x32_bf16 v[2:5], v[182:185], v[214:217], v[2:5]
	s_setprio 2
	s_barrier
	s_add_i32 s33, 0, 0x18000
	v_add_u32_e32 v157, s33, v151
	s_add_i32 s62, 0, 0x1c000
	ds_read_b128 v[146:149], v157
	ds_read_b128 v[158:161], v157 offset:1024
	ds_read_b128 v[162:165], v157 offset:2048
	ds_read_b128 v[166:169], v157 offset:3072
	v_add_u32_e32 v157, s62, v151
	ds_read_b128 v[170:173], v157
	ds_read_b128 v[174:177], v157 offset:1024
	ds_read_b128 v[178:181], v157 offset:2048
	ds_read_b128 v[182:185], v157 offset:3072
	s_add_u32 s56, s56, 0x40000
	s_addc_u32 s57, s57, 0
	s_mov_b32 m0, s66
	v_lshl_add_u64 v[226:227], s[56:57], 0, v[130:131]
	ds_read_b128 v[186:189], v154 offset:32768
	ds_read_b128 v[190:193], v154 offset:33792
	ds_read_b128 v[194:197], v154 offset:34816
	ds_read_b128 v[198:201], v154 offset:35840
	ds_read_b128 v[202:205], v154 offset:36864
	ds_read_b128 v[206:209], v154 offset:37888
	ds_read_b128 v[210:213], v154 offset:38912
	ds_read_b128 v[214:217], v154 offset:39936
	global_load_lds_dwordx4 v[226:227], off
	v_lshl_add_u64 v[226:227], s[56:57], 0, v[134:135]
	s_mov_b32 m0, s67
	s_nop 0
	global_load_lds_dwordx4 v[226:227], off
	s_waitcnt vmcnt(8)
	s_waitcnt lgkmcnt(0)
	s_barrier
	s_setprio 0
	s_waitcnt lgkmcnt(0)
	v_mfma_f32_16x16x32_bf16 v[126:129], v[146:149], v[186:189], v[126:129]
	v_mfma_f32_16x16x32_bf16 v[122:125], v[162:165], v[186:189], v[122:125]
	v_mfma_f32_16x16x32_bf16 v[110:113], v[146:149], v[194:197], v[110:113]
	v_mfma_f32_16x16x32_bf16 v[106:109], v[162:165], v[194:197], v[106:109]
	v_mfma_f32_16x16x32_bf16 v[94:97], v[146:149], v[202:205], v[94:97]
	v_mfma_f32_16x16x32_bf16 v[90:93], v[162:165], v[202:205], v[90:93]
	v_mfma_f32_16x16x32_bf16 v[78:81], v[146:149], v[210:213], v[78:81]
	v_mfma_f32_16x16x32_bf16 v[74:77], v[162:165], v[210:213], v[74:77]
	v_mfma_f32_16x16x32_bf16 v[126:129], v[158:161], v[190:193], v[126:129]
	v_mfma_f32_16x16x32_bf16 v[122:125], v[166:169], v[190:193], v[122:125]
	v_mfma_f32_16x16x32_bf16 v[110:113], v[158:161], v[198:201], v[110:113]
	v_mfma_f32_16x16x32_bf16 v[106:109], v[166:169], v[198:201], v[106:109]
	v_mfma_f32_16x16x32_bf16 v[94:97], v[158:161], v[206:209], v[94:97]
	v_mfma_f32_16x16x32_bf16 v[90:93], v[166:169], v[206:209], v[90:93]
	v_mfma_f32_16x16x32_bf16 v[78:81], v[158:161], v[214:217], v[78:81]
	v_mfma_f32_16x16x32_bf16 v[74:77], v[166:169], v[214:217], v[74:77]
	s_setprio 2
	s_setprio 0
	v_mfma_f32_16x16x32_bf16 v[118:121], v[170:173], v[186:189], v[118:121]
	v_mfma_f32_16x16x32_bf16 v[114:117], v[178:181], v[186:189], v[114:117]
	v_mfma_f32_16x16x32_bf16 v[102:105], v[170:173], v[194:197], v[102:105]
	v_mfma_f32_16x16x32_bf16 v[98:101], v[178:181], v[194:197], v[98:101]
	v_mfma_f32_16x16x32_bf16 v[86:89], v[170:173], v[202:205], v[86:89]
	v_mfma_f32_16x16x32_bf16 v[82:85], v[178:181], v[202:205], v[82:85]
	v_mfma_f32_16x16x32_bf16 v[70:73], v[170:173], v[210:213], v[70:73]
	v_mfma_f32_16x16x32_bf16 v[66:69], v[178:181], v[210:213], v[66:69]
	v_mfma_f32_16x16x32_bf16 v[118:121], v[174:177], v[190:193], v[118:121]
	v_mfma_f32_16x16x32_bf16 v[114:117], v[182:185], v[190:193], v[114:117]
	v_mfma_f32_16x16x32_bf16 v[102:105], v[174:177], v[198:201], v[102:105]
	v_mfma_f32_16x16x32_bf16 v[98:101], v[182:185], v[198:201], v[98:101]
	v_mfma_f32_16x16x32_bf16 v[86:89], v[174:177], v[206:209], v[86:89]
	v_mfma_f32_16x16x32_bf16 v[82:85], v[182:185], v[206:209], v[82:85]
	v_mfma_f32_16x16x32_bf16 v[70:73], v[174:177], v[214:217], v[70:73]
	v_mfma_f32_16x16x32_bf16 v[66:69], v[182:185], v[214:217], v[66:69]
	s_setprio 2
	s_barrier
; #define PG8_STAGE(bufoff, gbase, voff) do { _Pragma("unroll") for (int _i = 0; _i < 2; ++_i) \
;         __builtin_amdgcn_global_load_lds((const unsigned*)((const char*)(gbase) + (voff)[_i]), (LAS unsigned*)(lds + (bufoff) + ldsw + _i * 8192), 16, 0, 0); } while (0)
; #define PG8_LDA(dst, b, h) do { _Pragma("unroll") for (int m = 0; m < 4; ++m) _Pragma("unroll") for (int k = 0; k < 2; ++k) dst[m][k] = *(const LAS bf16x8*)(lds + PG8_SA(b, h) + aoff + m * 2048 + k * 1024); } while (0)
; #define PG8_MMA(ai, bj, At, Bt) do { __builtin_amdgcn_s_setprio(1); _Pragma("unroll") for (int m = 0; m < 4; ++m) _Pragma("unroll") for (int n = 0; n < 2; ++n) _Pragma("unroll") for (int k = 0; k < 2; ++k) \
;         acc[ai][bj][m][n] = __builtin_amdgcn_mfma_f32_16x16x32_bf16(Bt[n][k], At[m][k], acc[ai][bj][m][n], 0, 0, 0); __builtin_amdgcn_s_setprio(0); } while (0)
; #define PG8_WAIT_V(n) asm volatile("s_waitcnt vmcnt(" #n ")" ::: "memory")
; #define PG8_WAIT_L(n) asm volatile("s_waitcnt lgkmcnt(" #n ")" ::: "memory")
; #define PG8_BAR __builtin_amdgcn_s_barrier()
; #define PG8_SCHED __builtin_amdgcn_sched_barrier(0)
; template <class Epi>
; __device__ __forceinline__ void gemm_phase(LAS unsigned char* lds, const Gemm g, int G, int c, const Epi& E) {
;     ...
;             PG8_LDA(At, 1, 1); PG8_STAGE(PG8_SB(1, 0), b3, voffB); PG8_STAGE(PG8_SB(1, 1), b3 + hstepB, voffB); PG8_STAGE(PG8_SA(1, 0), a3, voffA);
;             PG8_WAIT_V(8); PG8_WAIT_L(0); PG8_BAR; PG8_MMA(1, 0, At, B0); PG8_MMA(1, 1, At, B1); PG8_BAR; PG8_SCHED;
;         }
	s_add_i32 s33, s33, s60
	v_lshl_add_u64 v[218:219], v[218:219], 0, s[20:21]
	s_mov_b32 m0, s33
	ds_read_b128 v[186:189], v154 offset:49152
	ds_read_b128 v[190:193], v154 offset:50176
	ds_read_b128 v[194:197], v154 offset:51200
	ds_read_b128 v[198:201], v154 offset:52224
	ds_read_b128 v[202:205], v154 offset:53248
	ds_read_b128 v[206:209], v154 offset:54272
	ds_read_b128 v[210:213], v154 offset:55296
	ds_read_b128 v[214:217], v154 offset:56320
	global_load_lds_dwordx4 v[218:219], off
	s_add_i32 m0, s33, 0x2000
	s_add_u32 s54, s54, 0x40080
	v_lshl_add_u64 v[218:219], v[220:221], 0, s[20:21]
	s_addc_u32 s55, s55, 0
	s_add_i32 s33, s62, s60
	global_load_lds_dwordx4 v[218:219], off
	v_lshl_add_u64 v[218:219], s[54:55], 0, v[132:133]
	s_mov_b32 m0, s33
	s_nop 0
	global_load_lds_dwordx4 v[218:219], off
	v_lshl_add_u64 v[218:219], s[54:55], 0, v[136:137]
	s_add_i32 m0, s33, 0x2000
	s_nop 0
	global_load_lds_dwordx4 v[218:219], off
	v_lshl_add_u64 v[218:219], v[222:223], 0, s[20:21]
	s_mov_b32 m0, s71
	s_nop 0
	global_load_lds_dwordx4 v[218:219], off
	v_lshl_add_u64 v[218:219], v[224:225], 0, s[20:21]
	s_mov_b32 m0, s72
	s_nop 0
	global_load_lds_dwordx4 v[218:219], off
	s_waitcnt vmcnt(8)
	s_waitcnt lgkmcnt(0)
	s_barrier
	s_setprio 0
	s_waitcnt lgkmcnt(0)
	v_mfma_f32_16x16x32_bf16 v[62:65], v[146:149], v[186:189], v[62:65]
	v_mfma_f32_16x16x32_bf16 v[58:61], v[162:165], v[186:189], v[58:61]
	v_mfma_f32_16x16x32_bf16 v[46:49], v[146:149], v[194:197], v[46:49]
	v_mfma_f32_16x16x32_bf16 v[42:45], v[162:165], v[194:197], v[42:45]
	v_mfma_f32_16x16x32_bf16 v[30:33], v[146:149], v[202:205], v[30:33]
	v_mfma_f32_16x16x32_bf16 v[26:29], v[162:165], v[202:205], v[26:29]
	v_mfma_f32_16x16x32_bf16 v[14:17], v[146:149], v[210:213], v[14:17]
	v_mfma_f32_16x16x32_bf16 v[10:13], v[162:165], v[210:213], v[10:13]
	v_mfma_f32_16x16x32_bf16 v[62:65], v[158:161], v[190:193], v[62:65]
	v_mfma_f32_16x16x32_bf16 v[58:61], v[166:169], v[190:193], v[58:61]
	v_mfma_f32_16x16x32_bf16 v[46:49], v[158:161], v[198:201], v[46:49]
	v_mfma_f32_16x16x32_bf16 v[42:45], v[166:169], v[198:201], v[42:45]
	v_mfma_f32_16x16x32_bf16 v[30:33], v[158:161], v[206:209], v[30:33]
	v_mfma_f32_16x16x32_bf16 v[26:29], v[166:169], v[206:209], v[26:29]
	v_mfma_f32_16x16x32_bf16 v[14:17], v[158:161], v[214:217], v[14:17]
	v_mfma_f32_16x16x32_bf16 v[10:13], v[166:169], v[214:217], v[10:13]
	s_setprio 2
	s_setprio 0
	v_mfma_f32_16x16x32_bf16 v[54:57], v[170:173], v[186:189], v[54:57]
	v_mfma_f32_16x16x32_bf16 v[50:53], v[178:181], v[186:189], v[50:53]
	v_mfma_f32_16x16x32_bf16 v[38:41], v[170:173], v[194:197], v[38:41]
	v_mfma_f32_16x16x32_bf16 v[34:37], v[178:181], v[194:197], v[34:37]
	v_mfma_f32_16x16x32_bf16 v[22:25], v[170:173], v[202:205], v[22:25]
	v_mfma_f32_16x16x32_bf16 v[18:21], v[178:181], v[202:205], v[18:21]
	v_mfma_f32_16x16x32_bf16 v[6:9], v[170:173], v[210:213], v[6:9]
	v_mfma_f32_16x16x32_bf16 v[2:5], v[178:181], v[210:213], v[2:5]
	v_mfma_f32_16x16x32_bf16 v[54:57], v[174:177], v[190:193], v[54:57]
	v_mfma_f32_16x16x32_bf16 v[50:53], v[182:185], v[190:193], v[50:53]
	v_mfma_f32_16x16x32_bf16 v[38:41], v[174:177], v[198:201], v[38:41]
	v_mfma_f32_16x16x32_bf16 v[34:37], v[182:185], v[198:201], v[34:37]
	v_mfma_f32_16x16x32_bf16 v[22:25], v[174:177], v[206:209], v[22:25]
	v_mfma_f32_16x16x32_bf16 v[18:21], v[182:185], v[206:209], v[18:21]
	v_mfma_f32_16x16x32_bf16 v[6:9], v[174:177], v[214:217], v[6:9]
	v_mfma_f32_16x16x32_bf16 v[2:5], v[182:185], v[214:217], v[2:5]
	s_setprio 2
	s_barrier
	s_add_i32 s85, s85, 2
	s_add_u32 s4, s4, 0x100
	s_addc_u32 s5, s5, 0
	s_add_u32 s45, s45, 0x100
	s_addc_u32 s84, s84, 0
	s_cmp_gt_u32 s85, 13
	s_cbranch_scc0 .LBB0_236

; #define PG8_STAGE(bufoff, gbase, voff) do { _Pragma("unroll") for (int _i = 0; _i < 2; ++_i) \
;         __builtin_amdgcn_global_load_lds((const unsigned*)((const char*)(gbase) + (voff)[_i]), (LAS unsigned*)(lds + (bufoff) + ldsw + _i * 8192), 16, 0, 0); } while (0)
; #define PG8_LDA(dst, b, h) do { _Pragma("unroll") for (int m = 0; m < 4; ++m) _Pragma("unroll") for (int k = 0; k < 2; ++k) dst[m][k] = *(const LAS bf16x8*)(lds + PG8_SA(b, h) + aoff + m * 2048 + k * 1024); } while (0)
; #define PG8_LDB(dst, b, h) do { _Pragma("unroll") for (int n = 0; n < 2; ++n) _Pragma("unroll") for (int k = 0; k < 2; ++k) dst[n][k] = *(const LAS bf16x8*)(lds + PG8_SB(b, h) + boff + n * 2048 + k * 1024); } while (0)
; #define PG8_MMA(ai, bj, At, Bt) do { __builtin_amdgcn_s_setprio(1); _Pragma("unroll") for (int m = 0; m < 4; ++m) _Pragma("unroll") for (int n = 0; n < 2; ++n) _Pragma("unroll") for (int k = 0; k < 2; ++k) \
;         acc[ai][bj][m][n] = __builtin_amdgcn_mfma_f32_16x16x32_bf16(Bt[n][k], At[m][k], acc[ai][bj][m][n], 0, 0, 0); __builtin_amdgcn_s_setprio(0); } while (0)
; #define PG8_WAIT_V(n) asm volatile("s_waitcnt vmcnt(" #n ")" ::: "memory")
; #define PG8_WAIT_L(n) asm volatile("s_waitcnt lgkmcnt(" #n ")" ::: "memory")
; template <class Epi>
; __device__ __forceinline__ void gemm_phase(LAS unsigned char* lds, const Gemm g, int G, int c, const Epi& E) {
;     ...
; #pragma unroll
;     for (int a = 0; a < 2; ++a)
; #pragma unroll
;         for (int b = 0; b < 2; ++b)
; #pragma unroll
;             for (int m = 0; m < 4; ++m)
; #pragma unroll
;                 for (int n = 0; n < 2; ++n) acc[a][b][m][n] = (f32x4){0.f, 0.f, 0.f, 0.f};
;     ...
;             const bool last = (t == nt - 2);
;             const char* a1 = cA + (size_t)(t + 1) * kstep;
;             const char* a2 = last ? nA : cA + (size_t)(t + 2) * kstep; const char* b2 = last ? nB : cB + (size_t)(t + 2) * kstep;
;             const char* a3 = a2 + kstep; const char* b3 = b2 + kstep;
;             PG8_LDB(B0, 0, 0); PG8_LDB(B1, 0, 1); PG8_SCHED; PG8_LDA(At, 0, 0); PG8_STAGE(PG8_SA(1, 1), a1 + hstepA, voffA);
;             PG8_WAIT_V(8); PG8_WAIT_L(0); PG8_BAR; PG8_MMA(0, 0, At, B0); PG8_MMA(0, 1, At, B1); PG8_BAR; PG8_SCHED;
;             PG8_LDA(At, 0, 1); PG8_STAGE(PG8_SB(0, 0), b2, voffB); PG8_STAGE(PG8_SB(0, 1), b2 + hstepB, voffB); PG8_STAGE(PG8_SA(0, 0), a2, voffA);
.LBB0_367:
	s_mov_b32 s13, 0
	s_mov_b64 s[22:23], -1
	s_mov_b64 s[24:25], 0
	s_add_u32 s33, s20, s13
	s_addc_u32 s42, s21, 0
	s_add_u32 s43, s33, 0x100
	s_addc_u32 s44, s42, 0
	s_and_b64 s[38:39], s[24:25], exec
	s_cselect_b32 s45, s5, s44
	s_cselect_b32 s44, s4, s43
	s_add_u32 s13, s18, s13
	s_addc_u32 s38, s19, 0
	s_add_u32 s13, s13, 0x100
	s_addc_u32 s38, s38, 0
	s_and_b64 s[24:25], s[24:25], exec
	s_cselect_b32 s47, s17, s38
	s_cselect_b32 s46, s16, s13
	s_add_u32 s54, s33, 0xb0080
	s_addc_u32 s55, s42, 0
	s_add_i32 s65, s81, s56
	ds_read_b128 v[142:145], v148
	ds_read_b128 v[152:155], v148 offset:1024
	ds_read_b128 v[156:159], v148 offset:2048
	ds_read_b128 v[160:163], v148 offset:3072
	ds_read_b128 v[164:167], v149
	ds_read_b128 v[168:171], v149 offset:1024
	ds_read_b128 v[172:175], v149 offset:2048
	ds_read_b128 v[176:179], v149 offset:3072
	s_add_i32 m0, s57, 0xc000
	s_add_i32 s74, s57, 0xe000
	s_add_i32 s62, s65, 0x2000
	s_add_u32 s52, s46, 0xb0000
	s_addc_u32 s53, s47, 0
	s_add_i32 s64, s82, s56
	s_add_i32 s63, s64, 0x2000
	s_add_i32 s73, 0, 0x18000
	s_add_i32 s33, 0, 0x1c000
	s_add_u32 s42, s44, 0xb0000
	s_addc_u32 s43, s45, 0
	s_add_i32 s88, s73, s56
	s_add_i32 s38, s88, 0x2000
	s_add_u32 s24, s46, 0xb0080
	s_addc_u32 s25, s47, 0
	s_add_i32 s39, s33, s56
	s_add_i32 s13, s39, 0x2000
	v_lshl_add_u64 v[212:213], s[54:55], 0, v[136:137]
	ds_read_b128 v[180:183], v150
	ds_read_b128 v[184:187], v150 offset:1024
	ds_read_b128 v[188:191], v150 offset:2048
	ds_read_b128 v[192:195], v150 offset:3072
	ds_read_b128 v[196:199], v150 offset:4096
	ds_read_b128 v[200:203], v150 offset:5120
	ds_read_b128 v[204:207], v150 offset:6144
	ds_read_b128 v[208:211], v150 offset:7168
	global_load_lds_dwordx4 v[212:213], off
	v_lshl_add_u64 v[212:213], s[54:55], 0, v[132:133]
	s_mov_b32 m0, s74
	s_nop 0
	global_load_lds_dwordx4 v[212:213], off
	s_waitcnt vmcnt(8)
	s_waitcnt lgkmcnt(0)
	s_barrier
	s_setprio 0
	s_waitcnt lgkmcnt(0)
	v_mfma_f32_16x16x32_bf16 v[126:129], v[142:145], v[180:183], 0
	v_mfma_f32_16x16x32_bf16 v[122:125], v[156:159], v[180:183], 0
	v_mfma_f32_16x16x32_bf16 v[118:121], v[142:145], v[188:191], 0
	v_mfma_f32_16x16x32_bf16 v[110:113], v[156:159], v[188:191], 0
	v_mfma_f32_16x16x32_bf16 v[102:105], v[142:145], v[196:199], 0
	v_mfma_f32_16x16x32_bf16 v[94:97], v[156:159], v[196:199], 0
	v_mfma_f32_16x16x32_bf16 v[86:89], v[142:145], v[204:207], 0
	v_mfma_f32_16x16x32_bf16 v[78:81], v[156:159], v[204:207], 0
	v_mfma_f32_16x16x32_bf16 v[126:129], v[152:155], v[184:187], v[126:129]
	v_mfma_f32_16x16x32_bf16 v[122:125], v[160:163], v[184:187], v[122:125]
	v_mfma_f32_16x16x32_bf16 v[118:121], v[152:155], v[192:195], v[118:121]
	v_mfma_f32_16x16x32_bf16 v[110:113], v[160:163], v[192:195], v[110:113]
	v_mfma_f32_16x16x32_bf16 v[102:105], v[152:155], v[200:203], v[102:105]
	v_mfma_f32_16x16x32_bf16 v[94:97], v[160:163], v[200:203], v[94:97]
	v_mfma_f32_16x16x32_bf16 v[86:89], v[152:155], v[208:211], v[86:89]
	v_mfma_f32_16x16x32_bf16 v[78:81], v[160:163], v[208:211], v[78:81]
	s_setprio 2
	s_setprio 0
	v_mfma_f32_16x16x32_bf16 v[114:117], v[164:167], v[180:183], 0
	v_mfma_f32_16x16x32_bf16 v[106:109], v[172:175], v[180:183], 0
	v_mfma_f32_16x16x32_bf16 v[98:101], v[164:167], v[188:191], 0
	v_mfma_f32_16x16x32_bf16 v[90:93], v[172:175], v[188:191], 0
	v_mfma_f32_16x16x32_bf16 v[82:85], v[164:167], v[196:199], 0
	v_mfma_f32_16x16x32_bf16 v[74:77], v[172:175], v[196:199], 0
	v_mfma_f32_16x16x32_bf16 v[70:73], v[164:167], v[204:207], 0
	v_mfma_f32_16x16x32_bf16 v[66:69], v[172:175], v[204:207], 0
	v_mfma_f32_16x16x32_bf16 v[114:117], v[168:171], v[184:187], v[114:117]
	v_mfma_f32_16x16x32_bf16 v[106:109], v[176:179], v[184:187], v[106:109]
	v_mfma_f32_16x16x32_bf16 v[98:101], v[168:171], v[192:195], v[98:101]
	v_mfma_f32_16x16x32_bf16 v[90:93], v[176:179], v[192:195], v[90:93]
	v_mfma_f32_16x16x32_bf16 v[82:85], v[168:171], v[200:203], v[82:85]
	v_mfma_f32_16x16x32_bf16 v[74:77], v[176:179], v[200:203], v[74:77]
	v_mfma_f32_16x16x32_bf16 v[70:73], v[168:171], v[208:211], v[70:73]
	v_mfma_f32_16x16x32_bf16 v[66:69], v[176:179], v[208:211], v[66:69]
	s_setprio 2
	s_barrier
	s_mov_b32 m0, s65
	v_lshl_add_u64 v[212:213], s[46:47], 0, v[134:135]
	ds_read_b128 v[180:183], v150 offset:16384
	ds_read_b128 v[184:187], v150 offset:17408
	ds_read_b128 v[188:191], v150 offset:18432
	ds_read_b128 v[192:195], v150 offset:19456
	ds_read_b128 v[196:199], v150 offset:20480
	ds_read_b128 v[200:203], v150 offset:21504
	ds_read_b128 v[204:207], v150 offset:22528
	ds_read_b128 v[208:211], v150 offset:23552
	global_load_lds_dwordx4 v[212:213], off
	v_lshl_add_u64 v[214:215], s[46:47], 0, v[130:131]
	s_mov_b32 m0, s62
	v_lshl_add_u64 v[216:217], s[52:53], 0, v[134:135]
	global_load_lds_dwordx4 v[214:215], off
	s_mov_b32 m0, s64
	v_lshl_add_u64 v[218:219], s[44:45], 0, v[132:133]
	global_load_lds_dwordx4 v[216:217], off
	v_lshl_add_u64 v[216:217], s[52:53], 0, v[130:131]
	s_mov_b32 m0, s63
	s_nop 0
	global_load_lds_dwordx4 v[216:217], off
	v_lshl_add_u64 v[216:217], s[44:45], 0, v[136:137]
	s_mov_b32 m0, s57
	s_nop 0
	global_load_lds_dwordx4 v[216:217], off
	s_mov_b32 m0, s58
	s_nop 0
	global_load_lds_dwordx4 v[218:219], off
	s_waitcnt vmcnt(8)
	s_waitcnt lgkmcnt(0)
	s_barrier
; #define PG8_STAGE(bufoff, gbase, voff) do { _Pragma("unroll") for (int _i = 0; _i < 2; ++_i) \
;         __builtin_amdgcn_global_load_lds((const unsigned*)((const char*)(gbase) + (voff)[_i]), (LAS unsigned*)(lds + (bufoff) + ldsw + _i * 8192), 16, 0, 0); } while (0)
; #define PG8_LDA(dst, b, h) do { _Pragma("unroll") for (int m = 0; m < 4; ++m) _Pragma("unroll") for (int k = 0; k < 2; ++k) dst[m][k] = *(const LAS bf16x8*)(lds + PG8_SA(b, h) + aoff + m * 2048 + k * 1024); } while (0)
; #define PG8_LDB(dst, b, h) do { _Pragma("unroll") for (int n = 0; n < 2; ++n) _Pragma("unroll") for (int k = 0; k < 2; ++k) dst[n][k] = *(const LAS bf16x8*)(lds + PG8_SB(b, h) + boff + n * 2048 + k * 1024); } while (0)
; #define PG8_MMA(ai, bj, At, Bt) do { __builtin_amdgcn_s_setprio(1); _Pragma("unroll") for (int m = 0; m < 4; ++m) _Pragma("unroll") for (int n = 0; n < 2; ++n) _Pragma("unroll") for (int k = 0; k < 2; ++k) \
;         acc[ai][bj][m][n] = __builtin_amdgcn_mfma_f32_16x16x32_bf16(Bt[n][k], At[m][k], acc[ai][bj][m][n], 0, 0, 0); __builtin_amdgcn_s_setprio(0); } while (0)
; #define PG8_WAIT_V(n) asm volatile("s_waitcnt vmcnt(" #n ")" ::: "memory")
; #define PG8_WAIT_L(n) asm volatile("s_waitcnt lgkmcnt(" #n ")" ::: "memory")
; #define PG8_BAR __builtin_amdgcn_s_barrier()
; #define PG8_SCHED __builtin_amdgcn_sched_barrier(0)
; template <class Epi>
; __device__ __forceinline__ void gemm_phase(LAS unsigned char* lds, const Gemm g, int G, int c, const Epi& E) {
;     ...
;             PG8_WAIT_V(8); PG8_WAIT_L(0); PG8_BAR; PG8_MMA(1, 0, At, B0); PG8_MMA(1, 1, At, B1); PG8_BAR; PG8_SCHED;
;             PG8_LDB(B0, 1, 0); PG8_LDB(B1, 1, 1); PG8_SCHED; PG8_LDA(At, 1, 0); PG8_STAGE(PG8_SA(0, 1), a2 + hstepA, voffA);
;             PG8_WAIT_V(8); PG8_WAIT_L(0); PG8_BAR; PG8_MMA(0, 0, At, B0); PG8_MMA(0, 1, At, B1); PG8_BAR; PG8_SCHED;
	s_setprio 0
	s_waitcnt lgkmcnt(0)
	v_mfma_f32_16x16x32_bf16 v[62:65], v[142:145], v[180:183], 0
	v_mfma_f32_16x16x32_bf16 v[58:61], v[156:159], v[180:183], 0
	v_mfma_f32_16x16x32_bf16 v[54:57], v[142:145], v[188:191], 0
	v_mfma_f32_16x16x32_bf16 v[46:49], v[156:159], v[188:191], 0
	v_mfma_f32_16x16x32_bf16 v[38:41], v[142:145], v[196:199], 0
	v_mfma_f32_16x16x32_bf16 v[30:33], v[156:159], v[196:199], 0
	v_mfma_f32_16x16x32_bf16 v[22:25], v[142:145], v[204:207], 0
	v_mfma_f32_16x16x32_bf16 v[14:17], v[156:159], v[204:207], 0
	v_mfma_f32_16x16x32_bf16 v[62:65], v[152:155], v[184:187], v[62:65]
	v_mfma_f32_16x16x32_bf16 v[58:61], v[160:163], v[184:187], v[58:61]
	v_mfma_f32_16x16x32_bf16 v[54:57], v[152:155], v[192:195], v[54:57]
	v_mfma_f32_16x16x32_bf16 v[46:49], v[160:163], v[192:195], v[46:49]
	v_mfma_f32_16x16x32_bf16 v[38:41], v[152:155], v[200:203], v[38:41]
	v_mfma_f32_16x16x32_bf16 v[30:33], v[160:163], v[200:203], v[30:33]
	v_mfma_f32_16x16x32_bf16 v[22:25], v[152:155], v[208:211], v[22:25]
	v_mfma_f32_16x16x32_bf16 v[14:17], v[160:163], v[208:211], v[14:17]
	s_setprio 2
	s_setprio 0
	v_mfma_f32_16x16x32_bf16 v[50:53], v[164:167], v[180:183], 0
	v_mfma_f32_16x16x32_bf16 v[42:45], v[172:175], v[180:183], 0
	v_mfma_f32_16x16x32_bf16 v[34:37], v[164:167], v[188:191], 0
	v_mfma_f32_16x16x32_bf16 v[26:29], v[172:175], v[188:191], 0
	v_mfma_f32_16x16x32_bf16 v[18:21], v[164:167], v[196:199], 0
	v_mfma_f32_16x16x32_bf16 v[10:13], v[172:175], v[196:199], 0
	v_mfma_f32_16x16x32_bf16 v[6:9], v[164:167], v[204:207], 0
	v_mfma_f32_16x16x32_bf16 v[2:5], v[172:175], v[204:207], 0
	v_mfma_f32_16x16x32_bf16 v[50:53], v[168:171], v[184:187], v[50:53]
	v_mfma_f32_16x16x32_bf16 v[42:45], v[176:179], v[184:187], v[42:45]
	v_mfma_f32_16x16x32_bf16 v[34:37], v[168:171], v[192:195], v[34:37]
	v_mfma_f32_16x16x32_bf16 v[26:29], v[176:179], v[192:195], v[26:29]
	v_mfma_f32_16x16x32_bf16 v[18:21], v[168:171], v[200:203], v[18:21]
	v_mfma_f32_16x16x32_bf16 v[10:13], v[176:179], v[200:203], v[10:13]
	v_mfma_f32_16x16x32_bf16 v[6:9], v[168:171], v[208:211], v[6:9]
	v_mfma_f32_16x16x32_bf16 v[2:5], v[176:179], v[208:211], v[2:5]
	s_setprio 2
	s_barrier
	v_add_u32_e32 v151, s73, v147
	ds_read_b128 v[142:145], v151
	ds_read_b128 v[152:155], v151 offset:1024
	ds_read_b128 v[156:159], v151 offset:2048
	ds_read_b128 v[160:163], v151 offset:3072
	v_add_u32_e32 v151, s33, v147
	ds_read_b128 v[164:167], v151
	ds_read_b128 v[168:171], v151 offset:1024
	ds_read_b128 v[172:175], v151 offset:2048
	ds_read_b128 v[176:179], v151 offset:3072
	s_mov_b32 m0, s59
	v_lshl_add_u64 v[220:221], s[42:43], 0, v[136:137]
	ds_read_b128 v[180:183], v150 offset:32768
	ds_read_b128 v[184:187], v150 offset:33792
	ds_read_b128 v[188:191], v150 offset:34816
	ds_read_b128 v[192:195], v150 offset:35840
	ds_read_b128 v[196:199], v150 offset:36864
	ds_read_b128 v[200:203], v150 offset:37888
	ds_read_b128 v[204:207], v150 offset:38912
	ds_read_b128 v[208:211], v150 offset:39936
	global_load_lds_dwordx4 v[220:221], off
	v_lshl_add_u64 v[220:221], s[42:43], 0, v[132:133]
	s_mov_b32 m0, s60
	s_nop 0
	global_load_lds_dwordx4 v[220:221], off
	s_waitcnt vmcnt(8)
	s_waitcnt lgkmcnt(0)
	s_barrier
	s_setprio 0
	s_waitcnt lgkmcnt(0)
	v_mfma_f32_16x16x32_bf16 v[126:129], v[142:145], v[180:183], v[126:129]
	v_mfma_f32_16x16x32_bf16 v[122:125], v[156:159], v[180:183], v[122:125]
	v_mfma_f32_16x16x32_bf16 v[118:121], v[142:145], v[188:191], v[118:121]
	v_mfma_f32_16x16x32_bf16 v[110:113], v[156:159], v[188:191], v[110:113]
	v_mfma_f32_16x16x32_bf16 v[102:105], v[142:145], v[196:199], v[102:105]
	v_mfma_f32_16x16x32_bf16 v[94:97], v[156:159], v[196:199], v[94:97]
	v_mfma_f32_16x16x32_bf16 v[86:89], v[142:145], v[204:207], v[86:89]
	v_mfma_f32_16x16x32_bf16 v[78:81], v[156:159], v[204:207], v[78:81]
	v_mfma_f32_16x16x32_bf16 v[126:129], v[152:155], v[184:187], v[126:129]
	v_mfma_f32_16x16x32_bf16 v[122:125], v[160:163], v[184:187], v[122:125]
	v_mfma_f32_16x16x32_bf16 v[118:121], v[152:155], v[192:195], v[118:121]
	v_mfma_f32_16x16x32_bf16 v[110:113], v[160:163], v[192:195], v[110:113]
	v_mfma_f32_16x16x32_bf16 v[102:105], v[152:155], v[200:203], v[102:105]
	v_mfma_f32_16x16x32_bf16 v[94:97], v[160:163], v[200:203], v[94:97]
	v_mfma_f32_16x16x32_bf16 v[86:89], v[152:155], v[208:211], v[86:89]
	v_mfma_f32_16x16x32_bf16 v[78:81], v[160:163], v[208:211], v[78:81]
	s_setprio 2
	s_setprio 0
	v_mfma_f32_16x16x32_bf16 v[114:117], v[164:167], v[180:183], v[114:117]
	v_mfma_f32_16x16x32_bf16 v[106:109], v[172:175], v[180:183], v[106:109]
	v_mfma_f32_16x16x32_bf16 v[98:101], v[164:167], v[188:191], v[98:101]
	v_mfma_f32_16x16x32_bf16 v[90:93], v[172:175], v[188:191], v[90:93]
	v_mfma_f32_16x16x32_bf16 v[82:85], v[164:167], v[196:199], v[82:85]
	v_mfma_f32_16x16x32_bf16 v[74:77], v[172:175], v[196:199], v[74:77]
	v_mfma_f32_16x16x32_bf16 v[70:73], v[164:167], v[204:207], v[70:73]
	v_mfma_f32_16x16x32_bf16 v[66:69], v[172:175], v[204:207], v[66:69]
	v_mfma_f32_16x16x32_bf16 v[114:117], v[168:171], v[184:187], v[114:117]
	v_mfma_f32_16x16x32_bf16 v[106:109], v[176:179], v[184:187], v[106:109]
	v_mfma_f32_16x16x32_bf16 v[98:101], v[168:171], v[192:195], v[98:101]
	v_mfma_f32_16x16x32_bf16 v[90:93], v[176:179], v[192:195], v[90:93]
	v_mfma_f32_16x16x32_bf16 v[82:85], v[168:171], v[200:203], v[82:85]
	v_mfma_f32_16x16x32_bf16 v[74:77], v[176:179], v[200:203], v[74:77]
	v_mfma_f32_16x16x32_bf16 v[70:73], v[168:171], v[208:211], v[70:73]
	v_mfma_f32_16x16x32_bf16 v[66:69], v[176:179], v[208:211], v[66:69]
	s_setprio 2
	s_barrier
; #define PG8_STAGE(bufoff, gbase, voff) do { _Pragma("unroll") for (int _i = 0; _i < 2; ++_i) \
;         __builtin_amdgcn_global_load_lds((const unsigned*)((const char*)(gbase) + (voff)[_i]), (LAS unsigned*)(lds + (bufoff) + ldsw + _i * 8192), 16, 0, 0); } while (0)
; #define PG8_LDA(dst, b, h) do { _Pragma("unroll") for (int m = 0; m < 4; ++m) _Pragma("unroll") for (int k = 0; k < 2; ++k) dst[m][k] = *(const LAS bf16x8*)(lds + PG8_SA(b, h) + aoff + m * 2048 + k * 1024); } while (0)
; #define PG8_MMA(ai, bj, At, Bt) do { __builtin_amdgcn_s_setprio(1); _Pragma("unroll") for (int m = 0; m < 4; ++m) _Pragma("unroll") for (int n = 0; n < 2; ++n) _Pragma("unroll") for (int k = 0; k < 2; ++k) \
;         acc[ai][bj][m][n] = __builtin_amdgcn_mfma_f32_16x16x32_bf16(Bt[n][k], At[m][k], acc[ai][bj][m][n], 0, 0, 0); __builtin_amdgcn_s_setprio(0); } while (0)
; #define PG8_WAIT_V(n) asm volatile("s_waitcnt vmcnt(" #n ")" ::: "memory")
; #define PG8_WAIT_L(n) asm volatile("s_waitcnt lgkmcnt(" #n ")" ::: "memory")
; #define PG8_BAR __builtin_amdgcn_s_barrier()
; #define PG8_SCHED __builtin_amdgcn_sched_barrier(0)
; template <class Epi>
; __device__ __forceinline__ void gemm_phase(LAS unsigned char* lds, const Gemm g, int G, int c, const Epi& E) {
;     ...
;         for (int t = 0; t < nt; t += 2) {
;     ...
;             PG8_LDA(At, 1, 1); PG8_STAGE(PG8_SB(1, 0), b3, voffB); PG8_STAGE(PG8_SB(1, 1), b3 + hstepB, voffB); PG8_STAGE(PG8_SA(1, 0), a3, voffA);
;             PG8_WAIT_V(8); PG8_WAIT_L(0); PG8_BAR; PG8_MMA(1, 0, At, B0); PG8_MMA(1, 1, At, B1); PG8_BAR; PG8_SCHED;
	s_mov_b32 m0, s88
	v_lshl_add_u64 v[212:213], v[212:213], 0, s[8:9]
	ds_read_b128 v[180:183], v150 offset:49152
	ds_read_b128 v[184:187], v150 offset:50176
	ds_read_b128 v[188:191], v150 offset:51200
	ds_read_b128 v[192:195], v150 offset:52224
	ds_read_b128 v[196:199], v150 offset:53248
	ds_read_b128 v[200:203], v150 offset:54272
	ds_read_b128 v[204:207], v150 offset:55296
	ds_read_b128 v[208:211], v150 offset:56320
	global_load_lds_dwordx4 v[212:213], off
	v_lshl_add_u64 v[212:213], v[214:215], 0, s[8:9]
	s_mov_b32 m0, s38
	s_nop 0
	global_load_lds_dwordx4 v[212:213], off
	v_lshl_add_u64 v[212:213], s[24:25], 0, v[134:135]
	s_mov_b32 m0, s39
	s_nop 0
	global_load_lds_dwordx4 v[212:213], off
	v_lshl_add_u64 v[212:213], s[24:25], 0, v[130:131]
	s_mov_b32 m0, s13
	s_nop 0
	global_load_lds_dwordx4 v[212:213], off
	v_lshl_add_u64 v[212:213], v[216:217], 0, s[8:9]
	s_mov_b32 m0, s79
	s_nop 0
	global_load_lds_dwordx4 v[212:213], off
	v_lshl_add_u64 v[212:213], v[218:219], 0, s[8:9]
	s_mov_b32 m0, s80
	s_nop 0
	global_load_lds_dwordx4 v[212:213], off
	s_waitcnt vmcnt(8)
	s_waitcnt lgkmcnt(0)
	s_barrier
	s_setprio 0
	s_waitcnt lgkmcnt(0)
	v_mfma_f32_16x16x32_bf16 v[62:65], v[142:145], v[180:183], v[62:65]
	v_mfma_f32_16x16x32_bf16 v[58:61], v[156:159], v[180:183], v[58:61]
	v_mfma_f32_16x16x32_bf16 v[54:57], v[142:145], v[188:191], v[54:57]
	v_mfma_f32_16x16x32_bf16 v[46:49], v[156:159], v[188:191], v[46:49]
	v_mfma_f32_16x16x32_bf16 v[38:41], v[142:145], v[196:199], v[38:41]
	v_mfma_f32_16x16x32_bf16 v[30:33], v[156:159], v[196:199], v[30:33]
	v_mfma_f32_16x16x32_bf16 v[22:25], v[142:145], v[204:207], v[22:25]
	v_mfma_f32_16x16x32_bf16 v[14:17], v[156:159], v[204:207], v[14:17]
	v_mfma_f32_16x16x32_bf16 v[62:65], v[152:155], v[184:187], v[62:65]
	v_mfma_f32_16x16x32_bf16 v[58:61], v[160:163], v[184:187], v[58:61]
	v_mfma_f32_16x16x32_bf16 v[54:57], v[152:155], v[192:195], v[54:57]
	v_mfma_f32_16x16x32_bf16 v[46:49], v[160:163], v[192:195], v[46:49]
	v_mfma_f32_16x16x32_bf16 v[38:41], v[152:155], v[200:203], v[38:41]
	v_mfma_f32_16x16x32_bf16 v[30:33], v[160:163], v[200:203], v[30:33]
	v_mfma_f32_16x16x32_bf16 v[22:25], v[152:155], v[208:211], v[22:25]
	v_mfma_f32_16x16x32_bf16 v[14:17], v[160:163], v[208:211], v[14:17]
	s_setprio 2
	s_setprio 0
	v_mfma_f32_16x16x32_bf16 v[50:53], v[164:167], v[180:183], v[50:53]
	v_mfma_f32_16x16x32_bf16 v[42:45], v[172:175], v[180:183], v[42:45]
	v_mfma_f32_16x16x32_bf16 v[34:37], v[164:167], v[188:191], v[34:37]
	v_mfma_f32_16x16x32_bf16 v[26:29], v[172:175], v[188:191], v[26:29]
	v_mfma_f32_16x16x32_bf16 v[18:21], v[164:167], v[196:199], v[18:21]
	v_mfma_f32_16x16x32_bf16 v[10:13], v[172:175], v[196:199], v[10:13]
	v_mfma_f32_16x16x32_bf16 v[6:9], v[164:167], v[204:207], v[6:9]
	v_mfma_f32_16x16x32_bf16 v[2:5], v[172:175], v[204:207], v[2:5]
	v_mfma_f32_16x16x32_bf16 v[50:53], v[168:171], v[184:187], v[50:53]
	v_mfma_f32_16x16x32_bf16 v[42:45], v[176:179], v[184:187], v[42:45]
	v_mfma_f32_16x16x32_bf16 v[34:37], v[168:171], v[192:195], v[34:37]
	v_mfma_f32_16x16x32_bf16 v[26:29], v[176:179], v[192:195], v[26:29]
	v_mfma_f32_16x16x32_bf16 v[18:21], v[168:171], v[200:203], v[18:21]
	v_mfma_f32_16x16x32_bf16 v[10:13], v[176:179], v[200:203], v[10:13]
	v_mfma_f32_16x16x32_bf16 v[6:9], v[168:171], v[208:211], v[6:9]
	v_mfma_f32_16x16x32_bf16 v[2:5], v[176:179], v[208:211], v[2:5]
	s_setprio 2
	s_barrier
	s_movk_i32 s13, 0x100
	s_andn2_b64 vcc, exec, s[22:23]
	s_mov_b64 s[24:25], -1
	s_mov_b64 s[22:23], 0
	s_cbranch_vccz .LBB0_368

; #define PG8_STAGE(bufoff, gbase, voff) do { _Pragma("unroll") for (int _i = 0; _i < 2; ++_i) \
;         __builtin_amdgcn_global_load_lds((const unsigned*)((const char*)(gbase) + (voff)[_i]), (LAS unsigned*)(lds + (bufoff) + ldsw + _i * 8192), 16, 0, 0); } while (0)
; #define PG8_LDA(dst, b, h) do { _Pragma("unroll") for (int m = 0; m < 4; ++m) _Pragma("unroll") for (int k = 0; k < 2; ++k) dst[m][k] = *(const LAS bf16x8*)(lds + PG8_SA(b, h) + aoff + m * 2048 + k * 1024); } while (0)
; #define PG8_LDB(dst, b, h) do { _Pragma("unroll") for (int n = 0; n < 2; ++n) _Pragma("unroll") for (int k = 0; k < 2; ++k) dst[n][k] = *(const LAS bf16x8*)(lds + PG8_SB(b, h) + boff + n * 2048 + k * 1024); } while (0)
; #define PG8_MMA(ai, bj, At, Bt) do { __builtin_amdgcn_s_setprio(1); _Pragma("unroll") for (int m = 0; m < 4; ++m) _Pragma("unroll") for (int n = 0; n < 2; ++n) _Pragma("unroll") for (int k = 0; k < 2; ++k) \
;         acc[ai][bj][m][n] = __builtin_amdgcn_mfma_f32_16x16x32_bf16(Bt[n][k], At[m][k], acc[ai][bj][m][n], 0, 0, 0); __builtin_amdgcn_s_setprio(0); } while (0)
; #define PG8_WAIT_V(n) asm volatile("s_waitcnt vmcnt(" #n ")" ::: "memory")
; #define PG8_WAIT_L(n) asm volatile("s_waitcnt lgkmcnt(" #n ")" ::: "memory")
; template <class Epi>
; __device__ __forceinline__ void gemm_phase(LAS unsigned char* lds, const Gemm g, int G, int c, const Epi& E) {
;     ...
; #pragma unroll
;     for (int a = 0; a < 2; ++a)
; #pragma unroll
;         for (int b = 0; b < 2; ++b)
; #pragma unroll
;             for (int m = 0; m < 4; ++m)
; #pragma unroll
;                 for (int n = 0; n < 2; ++n) acc[a][b][m][n] = (f32x4){0.f, 0.f, 0.f, 0.f};
;     ...
;             const bool last = (t == nt - 2);
;             const char* a1 = cA + (size_t)(t + 1) * kstep;
;             const char* a2 = last ? nA : cA + (size_t)(t + 2) * kstep; const char* b2 = last ? nB : cB + (size_t)(t + 2) * kstep;
;             const char* a3 = a2 + kstep; const char* b3 = b2 + kstep;
;             PG8_LDB(B0, 0, 0); PG8_LDB(B1, 0, 1); PG8_SCHED; PG8_LDA(At, 0, 0); PG8_STAGE(PG8_SA(1, 1), a1 + hstepA, voffA);
;             PG8_WAIT_V(8); PG8_WAIT_L(0); PG8_BAR; PG8_MMA(0, 0, At, B0); PG8_MMA(0, 1, At, B1); PG8_BAR; PG8_SCHED;
;             PG8_LDA(At, 0, 1); PG8_STAGE(PG8_SB(0, 0), b2, voffB); PG8_STAGE(PG8_SB(0, 1), b2 + hstepB, voffB); PG8_STAGE(PG8_SA(0, 0), a2, voffA);
.LBB0_389:
	s_mov_b32 s38, 0
	s_mov_b64 s[4:5], -1
	s_mov_b64 s[10:11], 0
	s_add_u32 s33, s8, s38
	s_addc_u32 s39, s9, 0
	s_add_u32 s56, s33, 0x100
	s_addc_u32 s57, s39, 0
	s_and_b64 s[54:55], s[10:11], exec
	s_cselect_b32 s57, s47, s57
	s_cselect_b32 s56, s46, s56
	s_add_u32 s38, s6, s38
	s_addc_u32 s54, s7, 0
	s_add_u32 s38, s38, 0x100
	s_addc_u32 s54, s54, 0
	s_and_b64 s[10:11], s[10:11], exec
	s_cselect_b32 s59, s53, s54
	s_cselect_b32 s58, s52, s38
	s_add_u32 s66, s33, 0xb0080
	s_addc_u32 s67, s39, 0
	s_add_i32 s65, s87, s14
	ds_read_b128 v[142:145], v160
	ds_read_b128 v[146:149], v160 offset:1024
	ds_read_b128 v[150:153], v160 offset:2048
	ds_read_b128 v[154:157], v160 offset:3072
	ds_read_b128 v[166:169], v161
	ds_read_b128 v[170:173], v161 offset:1024
	ds_read_b128 v[174:177], v161 offset:2048
	ds_read_b128 v[178:181], v161 offset:3072
	s_add_i32 m0, s78, 0xc000
	s_add_i32 s74, s78, 0xe000
	s_add_i32 s62, s65, 0x2000
	s_add_u32 s60, s58, 0xb0000
	s_addc_u32 s61, s59, 0
	s_add_i32 s64, s88, s14
	s_add_i32 s63, s64, 0x2000
	s_add_i32 s73, 0, 0x18000
	s_add_i32 s33, 0, 0x1c000
	s_add_u32 s54, s56, 0xb0000
	s_addc_u32 s55, s57, 0
	s_add_i32 vcc_hi, s73, s14
	s_add_i32 s39, vcc_hi, 0x2000
	s_add_u32 s10, s58, 0xb0080
	s_addc_u32 s11, s59, 0
	s_add_i32 vcc_lo, s33, s14
	s_add_i32 s38, vcc_lo, 0x2000
	v_lshl_add_u64 v[214:215], s[66:67], 0, v[130:131]
	ds_read_b128 v[182:185], v162
	ds_read_b128 v[186:189], v162 offset:1024
	ds_read_b128 v[190:193], v162 offset:2048
	ds_read_b128 v[194:197], v162 offset:3072
	ds_read_b128 v[198:201], v162 offset:4096
	ds_read_b128 v[202:205], v162 offset:5120
	ds_read_b128 v[206:209], v162 offset:6144
	ds_read_b128 v[210:213], v162 offset:7168
	global_load_lds_dwordx4 v[214:215], off
	v_lshl_add_u64 v[214:215], s[66:67], 0, v[134:135]
	s_mov_b32 m0, s74
	s_nop 0
	global_load_lds_dwordx4 v[214:215], off
	s_waitcnt vmcnt(8)
	s_waitcnt lgkmcnt(0)
	s_barrier
	s_setprio 0
	s_waitcnt lgkmcnt(0)
	v_mfma_f32_16x16x32_bf16 v[126:129], v[142:145], v[182:185], 0
	v_mfma_f32_16x16x32_bf16 v[122:125], v[150:153], v[182:185], 0
	v_mfma_f32_16x16x32_bf16 v[110:113], v[142:145], v[190:193], 0
	v_mfma_f32_16x16x32_bf16 v[106:109], v[150:153], v[190:193], 0
	v_mfma_f32_16x16x32_bf16 v[94:97], v[142:145], v[198:201], 0
	v_mfma_f32_16x16x32_bf16 v[90:93], v[150:153], v[198:201], 0
	v_mfma_f32_16x16x32_bf16 v[78:81], v[142:145], v[206:209], 0
	v_mfma_f32_16x16x32_bf16 v[74:77], v[150:153], v[206:209], 0
	v_mfma_f32_16x16x32_bf16 v[126:129], v[146:149], v[186:189], v[126:129]
	v_mfma_f32_16x16x32_bf16 v[122:125], v[154:157], v[186:189], v[122:125]
	v_mfma_f32_16x16x32_bf16 v[110:113], v[146:149], v[194:197], v[110:113]
	v_mfma_f32_16x16x32_bf16 v[106:109], v[154:157], v[194:197], v[106:109]
	v_mfma_f32_16x16x32_bf16 v[94:97], v[146:149], v[202:205], v[94:97]
	v_mfma_f32_16x16x32_bf16 v[90:93], v[154:157], v[202:205], v[90:93]
	v_mfma_f32_16x16x32_bf16 v[78:81], v[146:149], v[210:213], v[78:81]
	v_mfma_f32_16x16x32_bf16 v[74:77], v[154:157], v[210:213], v[74:77]
	s_setprio 2
	s_setprio 0
	v_mfma_f32_16x16x32_bf16 v[118:121], v[166:169], v[182:185], 0
	v_mfma_f32_16x16x32_bf16 v[114:117], v[174:177], v[182:185], 0
	v_mfma_f32_16x16x32_bf16 v[102:105], v[166:169], v[190:193], 0
	v_mfma_f32_16x16x32_bf16 v[98:101], v[174:177], v[190:193], 0
	v_mfma_f32_16x16x32_bf16 v[86:89], v[166:169], v[198:201], 0
	v_mfma_f32_16x16x32_bf16 v[82:85], v[174:177], v[198:201], 0
	v_mfma_f32_16x16x32_bf16 v[70:73], v[166:169], v[206:209], 0
	v_mfma_f32_16x16x32_bf16 v[66:69], v[174:177], v[206:209], 0
	v_mfma_f32_16x16x32_bf16 v[118:121], v[170:173], v[186:189], v[118:121]
	v_mfma_f32_16x16x32_bf16 v[114:117], v[178:181], v[186:189], v[114:117]
	v_mfma_f32_16x16x32_bf16 v[102:105], v[170:173], v[194:197], v[102:105]
	v_mfma_f32_16x16x32_bf16 v[98:101], v[178:181], v[194:197], v[98:101]
	v_mfma_f32_16x16x32_bf16 v[86:89], v[170:173], v[202:205], v[86:89]
	v_mfma_f32_16x16x32_bf16 v[82:85], v[178:181], v[202:205], v[82:85]
	v_mfma_f32_16x16x32_bf16 v[70:73], v[170:173], v[210:213], v[70:73]
	v_mfma_f32_16x16x32_bf16 v[66:69], v[178:181], v[210:213], v[66:69]
	s_setprio 2
	s_barrier
	s_mov_b32 m0, s65
	v_lshl_add_u64 v[214:215], s[58:59], 0, v[132:133]
	ds_read_b128 v[182:185], v162 offset:16384
	ds_read_b128 v[186:189], v162 offset:17408
	ds_read_b128 v[190:193], v162 offset:18432
	ds_read_b128 v[194:197], v162 offset:19456
	ds_read_b128 v[198:201], v162 offset:20480
	ds_read_b128 v[202:205], v162 offset:21504
	ds_read_b128 v[206:209], v162 offset:22528
	ds_read_b128 v[210:213], v162 offset:23552
	global_load_lds_dwordx4 v[214:215], off
	v_lshl_add_u64 v[216:217], s[58:59], 0, v[136:137]
	s_mov_b32 m0, s62
	v_lshl_add_u64 v[218:219], s[60:61], 0, v[132:133]
	global_load_lds_dwordx4 v[216:217], off
	s_mov_b32 m0, s64
	v_lshl_add_u64 v[220:221], s[56:57], 0, v[134:135]
	global_load_lds_dwordx4 v[218:219], off
	v_lshl_add_u64 v[218:219], s[60:61], 0, v[136:137]
	s_mov_b32 m0, s63
	s_nop 0
	global_load_lds_dwordx4 v[218:219], off
	v_lshl_add_u64 v[218:219], s[56:57], 0, v[130:131]
	s_mov_b32 m0, s78
	s_nop 0
	global_load_lds_dwordx4 v[218:219], off
	s_mov_b32 m0, s79
	s_nop 0
	global_load_lds_dwordx4 v[220:221], off
	s_waitcnt vmcnt(8)
	s_waitcnt lgkmcnt(0)
	s_barrier
; #define PG8_STAGE(bufoff, gbase, voff) do { _Pragma("unroll") for (int _i = 0; _i < 2; ++_i) \
;         __builtin_amdgcn_global_load_lds((const unsigned*)((const char*)(gbase) + (voff)[_i]), (LAS unsigned*)(lds + (bufoff) + ldsw + _i * 8192), 16, 0, 0); } while (0)
; #define PG8_LDA(dst, b, h) do { _Pragma("unroll") for (int m = 0; m < 4; ++m) _Pragma("unroll") for (int k = 0; k < 2; ++k) dst[m][k] = *(const LAS bf16x8*)(lds + PG8_SA(b, h) + aoff + m * 2048 + k * 1024); } while (0)
; #define PG8_LDB(dst, b, h) do { _Pragma("unroll") for (int n = 0; n < 2; ++n) _Pragma("unroll") for (int k = 0; k < 2; ++k) dst[n][k] = *(const LAS bf16x8*)(lds + PG8_SB(b, h) + boff + n * 2048 + k * 1024); } while (0)
; #define PG8_MMA(ai, bj, At, Bt) do { __builtin_amdgcn_s_setprio(1); _Pragma("unroll") for (int m = 0; m < 4; ++m) _Pragma("unroll") for (int n = 0; n < 2; ++n) _Pragma("unroll") for (int k = 0; k < 2; ++k) \
;         acc[ai][bj][m][n] = __builtin_amdgcn_mfma_f32_16x16x32_bf16(Bt[n][k], At[m][k], acc[ai][bj][m][n], 0, 0, 0); __builtin_amdgcn_s_setprio(0); } while (0)
; #define PG8_WAIT_V(n) asm volatile("s_waitcnt vmcnt(" #n ")" ::: "memory")
; #define PG8_WAIT_L(n) asm volatile("s_waitcnt lgkmcnt(" #n ")" ::: "memory")
; #define PG8_BAR __builtin_amdgcn_s_barrier()
; #define PG8_SCHED __builtin_amdgcn_sched_barrier(0)
; template <class Epi>
; __device__ __forceinline__ void gemm_phase(LAS unsigned char* lds, const Gemm g, int G, int c, const Epi& E) {
;     ...
;             PG8_WAIT_V(8); PG8_WAIT_L(0); PG8_BAR; PG8_MMA(1, 0, At, B0); PG8_MMA(1, 1, At, B1); PG8_BAR; PG8_SCHED;
;             PG8_LDB(B0, 1, 0); PG8_LDB(B1, 1, 1); PG8_SCHED; PG8_LDA(At, 1, 0); PG8_STAGE(PG8_SA(0, 1), a2 + hstepA, voffA);
;             PG8_WAIT_V(8); PG8_WAIT_L(0); PG8_BAR; PG8_MMA(0, 0, At, B0); PG8_MMA(0, 1, At, B1); PG8_BAR; PG8_SCHED;
	s_setprio 0
	s_waitcnt lgkmcnt(0)
	v_mfma_f32_16x16x32_bf16 v[62:65], v[142:145], v[182:185], 0
	v_mfma_f32_16x16x32_bf16 v[58:61], v[150:153], v[182:185], 0
	v_mfma_f32_16x16x32_bf16 v[46:49], v[142:145], v[190:193], 0
	v_mfma_f32_16x16x32_bf16 v[42:45], v[150:153], v[190:193], 0
	v_mfma_f32_16x16x32_bf16 v[30:33], v[142:145], v[198:201], 0
	v_mfma_f32_16x16x32_bf16 v[26:29], v[150:153], v[198:201], 0
	v_mfma_f32_16x16x32_bf16 v[14:17], v[142:145], v[206:209], 0
	v_mfma_f32_16x16x32_bf16 v[10:13], v[150:153], v[206:209], 0
	v_mfma_f32_16x16x32_bf16 v[62:65], v[146:149], v[186:189], v[62:65]
	v_mfma_f32_16x16x32_bf16 v[58:61], v[154:157], v[186:189], v[58:61]
	v_mfma_f32_16x16x32_bf16 v[46:49], v[146:149], v[194:197], v[46:49]
	v_mfma_f32_16x16x32_bf16 v[42:45], v[154:157], v[194:197], v[42:45]
	v_mfma_f32_16x16x32_bf16 v[30:33], v[146:149], v[202:205], v[30:33]
	v_mfma_f32_16x16x32_bf16 v[26:29], v[154:157], v[202:205], v[26:29]
	v_mfma_f32_16x16x32_bf16 v[14:17], v[146:149], v[210:213], v[14:17]
	v_mfma_f32_16x16x32_bf16 v[10:13], v[154:157], v[210:213], v[10:13]
	s_setprio 2
	s_setprio 0
	v_mfma_f32_16x16x32_bf16 v[54:57], v[166:169], v[182:185], 0
	v_mfma_f32_16x16x32_bf16 v[50:53], v[174:177], v[182:185], 0
	v_mfma_f32_16x16x32_bf16 v[38:41], v[166:169], v[190:193], 0
	v_mfma_f32_16x16x32_bf16 v[34:37], v[174:177], v[190:193], 0
	v_mfma_f32_16x16x32_bf16 v[22:25], v[166:169], v[198:201], 0
	v_mfma_f32_16x16x32_bf16 v[18:21], v[174:177], v[198:201], 0
	v_mfma_f32_16x16x32_bf16 v[6:9], v[166:169], v[206:209], 0
	v_mfma_f32_16x16x32_bf16 v[2:5], v[174:177], v[206:209], 0
	v_mfma_f32_16x16x32_bf16 v[54:57], v[170:173], v[186:189], v[54:57]
	v_mfma_f32_16x16x32_bf16 v[50:53], v[178:181], v[186:189], v[50:53]
	v_mfma_f32_16x16x32_bf16 v[38:41], v[170:173], v[194:197], v[38:41]
	v_mfma_f32_16x16x32_bf16 v[34:37], v[178:181], v[194:197], v[34:37]
	v_mfma_f32_16x16x32_bf16 v[22:25], v[170:173], v[202:205], v[22:25]
	v_mfma_f32_16x16x32_bf16 v[18:21], v[178:181], v[202:205], v[18:21]
	v_mfma_f32_16x16x32_bf16 v[6:9], v[170:173], v[210:213], v[6:9]
	v_mfma_f32_16x16x32_bf16 v[2:5], v[178:181], v[210:213], v[2:5]
	s_setprio 2
	s_barrier
	v_add_u32_e32 v154, s73, v159
	v_add_u32_e32 v178, s33, v159
	ds_read_b128 v[142:145], v154
	ds_read_b128 v[146:149], v154 offset:1024
	ds_read_b128 v[150:153], v154 offset:2048
	ds_read_b128 v[154:157], v154 offset:3072
	ds_read_b128 v[166:169], v178
	ds_read_b128 v[170:173], v178 offset:1024
	ds_read_b128 v[174:177], v178 offset:2048
	ds_read_b128 v[178:181], v178 offset:3072
	s_mov_b32 m0, s80
	v_lshl_add_u64 v[222:223], s[54:55], 0, v[130:131]
	ds_read_b128 v[182:185], v162 offset:32768
	ds_read_b128 v[186:189], v162 offset:33792
	ds_read_b128 v[190:193], v162 offset:34816
	ds_read_b128 v[194:197], v162 offset:35840
	ds_read_b128 v[198:201], v162 offset:36864
	ds_read_b128 v[202:205], v162 offset:37888
	ds_read_b128 v[206:209], v162 offset:38912
	ds_read_b128 v[210:213], v162 offset:39936
	global_load_lds_dwordx4 v[222:223], off
	v_lshl_add_u64 v[222:223], s[54:55], 0, v[134:135]
	s_mov_b32 m0, s81
	s_nop 0
	global_load_lds_dwordx4 v[222:223], off
	s_waitcnt vmcnt(8)
	s_waitcnt lgkmcnt(0)
	s_barrier
	s_setprio 0
	s_waitcnt lgkmcnt(0)
	v_mfma_f32_16x16x32_bf16 v[126:129], v[142:145], v[182:185], v[126:129]
	v_mfma_f32_16x16x32_bf16 v[122:125], v[150:153], v[182:185], v[122:125]
	v_mfma_f32_16x16x32_bf16 v[110:113], v[142:145], v[190:193], v[110:113]
	v_mfma_f32_16x16x32_bf16 v[106:109], v[150:153], v[190:193], v[106:109]
	v_mfma_f32_16x16x32_bf16 v[94:97], v[142:145], v[198:201], v[94:97]
	v_mfma_f32_16x16x32_bf16 v[90:93], v[150:153], v[198:201], v[90:93]
	v_mfma_f32_16x16x32_bf16 v[78:81], v[142:145], v[206:209], v[78:81]
	v_mfma_f32_16x16x32_bf16 v[74:77], v[150:153], v[206:209], v[74:77]
	v_mfma_f32_16x16x32_bf16 v[126:129], v[146:149], v[186:189], v[126:129]
	v_mfma_f32_16x16x32_bf16 v[122:125], v[154:157], v[186:189], v[122:125]
	v_mfma_f32_16x16x32_bf16 v[110:113], v[146:149], v[194:197], v[110:113]
	v_mfma_f32_16x16x32_bf16 v[106:109], v[154:157], v[194:197], v[106:109]
	v_mfma_f32_16x16x32_bf16 v[94:97], v[146:149], v[202:205], v[94:97]
	v_mfma_f32_16x16x32_bf16 v[90:93], v[154:157], v[202:205], v[90:93]
	v_mfma_f32_16x16x32_bf16 v[78:81], v[146:149], v[210:213], v[78:81]
	v_mfma_f32_16x16x32_bf16 v[74:77], v[154:157], v[210:213], v[74:77]
	s_setprio 2
	s_setprio 0
	v_mfma_f32_16x16x32_bf16 v[118:121], v[166:169], v[182:185], v[118:121]
	v_mfma_f32_16x16x32_bf16 v[114:117], v[174:177], v[182:185], v[114:117]
	v_mfma_f32_16x16x32_bf16 v[102:105], v[166:169], v[190:193], v[102:105]
	v_mfma_f32_16x16x32_bf16 v[98:101], v[174:177], v[190:193], v[98:101]
	v_mfma_f32_16x16x32_bf16 v[86:89], v[166:169], v[198:201], v[86:89]
	v_mfma_f32_16x16x32_bf16 v[82:85], v[174:177], v[198:201], v[82:85]
	v_mfma_f32_16x16x32_bf16 v[70:73], v[166:169], v[206:209], v[70:73]
	v_mfma_f32_16x16x32_bf16 v[66:69], v[174:177], v[206:209], v[66:69]
	v_mfma_f32_16x16x32_bf16 v[118:121], v[170:173], v[186:189], v[118:121]
	v_mfma_f32_16x16x32_bf16 v[114:117], v[178:181], v[186:189], v[114:117]
	v_mfma_f32_16x16x32_bf16 v[102:105], v[170:173], v[194:197], v[102:105]
	v_mfma_f32_16x16x32_bf16 v[98:101], v[178:181], v[194:197], v[98:101]
	v_mfma_f32_16x16x32_bf16 v[86:89], v[170:173], v[202:205], v[86:89]
	v_mfma_f32_16x16x32_bf16 v[82:85], v[178:181], v[202:205], v[82:85]
	v_mfma_f32_16x16x32_bf16 v[70:73], v[170:173], v[210:213], v[70:73]
	v_mfma_f32_16x16x32_bf16 v[66:69], v[178:181], v[210:213], v[66:69]
	s_setprio 2
	s_barrier
; #define PG8_STAGE(bufoff, gbase, voff) do { _Pragma("unroll") for (int _i = 0; _i < 2; ++_i) \
;         __builtin_amdgcn_global_load_lds((const unsigned*)((const char*)(gbase) + (voff)[_i]), (LAS unsigned*)(lds + (bufoff) + ldsw + _i * 8192), 16, 0, 0); } while (0)
; #define PG8_LDA(dst, b, h) do { _Pragma("unroll") for (int m = 0; m < 4; ++m) _Pragma("unroll") for (int k = 0; k < 2; ++k) dst[m][k] = *(const LAS bf16x8*)(lds + PG8_SA(b, h) + aoff + m * 2048 + k * 1024); } while (0)
; #define PG8_MMA(ai, bj, At, Bt) do { __builtin_amdgcn_s_setprio(1); _Pragma("unroll") for (int m = 0; m < 4; ++m) _Pragma("unroll") for (int n = 0; n < 2; ++n) _Pragma("unroll") for (int k = 0; k < 2; ++k) \
;         acc[ai][bj][m][n] = __builtin_amdgcn_mfma_f32_16x16x32_bf16(Bt[n][k], At[m][k], acc[ai][bj][m][n], 0, 0, 0); __builtin_amdgcn_s_setprio(0); } while (0)
; #define PG8_WAIT_V(n) asm volatile("s_waitcnt vmcnt(" #n ")" ::: "memory")
; #define PG8_WAIT_L(n) asm volatile("s_waitcnt lgkmcnt(" #n ")" ::: "memory")
; #define PG8_BAR __builtin_amdgcn_s_barrier()
; #define PG8_SCHED __builtin_amdgcn_sched_barrier(0)
; template <class Epi>
; __device__ __forceinline__ void gemm_phase(LAS unsigned char* lds, const Gemm g, int G, int c, const Epi& E) {
;     ...
;         for (int t = 0; t < nt; t += 2) {
;     ...
;             PG8_LDA(At, 1, 1); PG8_STAGE(PG8_SB(1, 0), b3, voffB); PG8_STAGE(PG8_SB(1, 1), b3 + hstepB, voffB); PG8_STAGE(PG8_SA(1, 0), a3, voffA);
;             PG8_WAIT_V(8); PG8_WAIT_L(0); PG8_BAR; PG8_MMA(1, 0, At, B0); PG8_MMA(1, 1, At, B1); PG8_BAR; PG8_SCHED;
	s_mov_b32 m0, vcc_hi
	v_lshl_add_u64 v[214:215], v[214:215], 0, s[24:25]
	ds_read_b128 v[182:185], v162 offset:49152
	ds_read_b128 v[186:189], v162 offset:50176
	ds_read_b128 v[190:193], v162 offset:51200
	ds_read_b128 v[194:197], v162 offset:52224
	ds_read_b128 v[198:201], v162 offset:53248
	ds_read_b128 v[202:205], v162 offset:54272
	ds_read_b128 v[206:209], v162 offset:55296
	ds_read_b128 v[210:213], v162 offset:56320
	global_load_lds_dwordx4 v[214:215], off
	v_lshl_add_u64 v[214:215], v[216:217], 0, s[24:25]
	s_mov_b32 m0, s39
	s_nop 0
	global_load_lds_dwordx4 v[214:215], off
	v_lshl_add_u64 v[214:215], s[10:11], 0, v[132:133]
	s_mov_b32 m0, vcc_lo
	s_nop 0
	global_load_lds_dwordx4 v[214:215], off
	v_lshl_add_u64 v[214:215], s[10:11], 0, v[136:137]
	s_mov_b32 m0, s38
	s_nop 0
	global_load_lds_dwordx4 v[214:215], off
	v_lshl_add_u64 v[214:215], v[218:219], 0, s[24:25]
	s_mov_b32 m0, s85
	s_nop 0
	global_load_lds_dwordx4 v[214:215], off
	v_lshl_add_u64 v[214:215], v[220:221], 0, s[24:25]
	s_mov_b32 m0, s86
	s_nop 0
	global_load_lds_dwordx4 v[214:215], off
	s_waitcnt vmcnt(8)
	s_waitcnt lgkmcnt(0)
	s_barrier
	s_setprio 0
	s_waitcnt lgkmcnt(0)
	v_mfma_f32_16x16x32_bf16 v[62:65], v[142:145], v[182:185], v[62:65]
	v_mfma_f32_16x16x32_bf16 v[58:61], v[150:153], v[182:185], v[58:61]
	v_mfma_f32_16x16x32_bf16 v[46:49], v[142:145], v[190:193], v[46:49]
	v_mfma_f32_16x16x32_bf16 v[42:45], v[150:153], v[190:193], v[42:45]
	v_mfma_f32_16x16x32_bf16 v[30:33], v[142:145], v[198:201], v[30:33]
	v_mfma_f32_16x16x32_bf16 v[26:29], v[150:153], v[198:201], v[26:29]
	v_mfma_f32_16x16x32_bf16 v[14:17], v[142:145], v[206:209], v[14:17]
	v_mfma_f32_16x16x32_bf16 v[10:13], v[150:153], v[206:209], v[10:13]
	v_mfma_f32_16x16x32_bf16 v[62:65], v[146:149], v[186:189], v[62:65]
	v_mfma_f32_16x16x32_bf16 v[58:61], v[154:157], v[186:189], v[58:61]
	v_mfma_f32_16x16x32_bf16 v[46:49], v[146:149], v[194:197], v[46:49]
	v_mfma_f32_16x16x32_bf16 v[42:45], v[154:157], v[194:197], v[42:45]
	v_mfma_f32_16x16x32_bf16 v[30:33], v[146:149], v[202:205], v[30:33]
	v_mfma_f32_16x16x32_bf16 v[26:29], v[154:157], v[202:205], v[26:29]
	v_mfma_f32_16x16x32_bf16 v[14:17], v[146:149], v[210:213], v[14:17]
	v_mfma_f32_16x16x32_bf16 v[10:13], v[154:157], v[210:213], v[10:13]
	s_setprio 2
	s_setprio 0
	v_mfma_f32_16x16x32_bf16 v[54:57], v[166:169], v[182:185], v[54:57]
	v_mfma_f32_16x16x32_bf16 v[50:53], v[174:177], v[182:185], v[50:53]
	v_mfma_f32_16x16x32_bf16 v[38:41], v[166:169], v[190:193], v[38:41]
	v_mfma_f32_16x16x32_bf16 v[34:37], v[174:177], v[190:193], v[34:37]
	v_mfma_f32_16x16x32_bf16 v[22:25], v[166:169], v[198:201], v[22:25]
	v_mfma_f32_16x16x32_bf16 v[18:21], v[174:177], v[198:201], v[18:21]
	v_mfma_f32_16x16x32_bf16 v[6:9], v[166:169], v[206:209], v[6:9]
	v_mfma_f32_16x16x32_bf16 v[2:5], v[174:177], v[206:209], v[2:5]
	v_mfma_f32_16x16x32_bf16 v[54:57], v[170:173], v[186:189], v[54:57]
	v_mfma_f32_16x16x32_bf16 v[50:53], v[178:181], v[186:189], v[50:53]
	v_mfma_f32_16x16x32_bf16 v[38:41], v[170:173], v[194:197], v[38:41]
	v_mfma_f32_16x16x32_bf16 v[34:37], v[178:181], v[194:197], v[34:37]
	v_mfma_f32_16x16x32_bf16 v[22:25], v[170:173], v[202:205], v[22:25]
	v_mfma_f32_16x16x32_bf16 v[18:21], v[178:181], v[202:205], v[18:21]
	v_mfma_f32_16x16x32_bf16 v[6:9], v[170:173], v[210:213], v[6:9]
	v_mfma_f32_16x16x32_bf16 v[2:5], v[178:181], v[210:213], v[2:5]
	s_setprio 2
	s_barrier
	s_movk_i32 s38, 0x100
	s_andn2_b64 vcc, exec, s[4:5]
	s_mov_b64 s[10:11], -1
	s_mov_b64 s[4:5], 0
	s_cbranch_vccz .LBB0_390

; #define PG8_STAGE(bufoff, gbase, voff) do { _Pragma("unroll") for (int _i = 0; _i < 2; ++_i) \
;         __builtin_amdgcn_global_load_lds((const unsigned*)((const char*)(gbase) + (voff)[_i]), (LAS unsigned*)(lds + (bufoff) + ldsw + _i * 8192), 16, 0, 0); } while (0)
; #define PG8_LDA(dst, b, h) do { _Pragma("unroll") for (int m = 0; m < 4; ++m) _Pragma("unroll") for (int k = 0; k < 2; ++k) dst[m][k] = *(const LAS bf16x8*)(lds + PG8_SA(b, h) + aoff + m * 2048 + k * 1024); } while (0)
; #define PG8_LDB(dst, b, h) do { _Pragma("unroll") for (int n = 0; n < 2; ++n) _Pragma("unroll") for (int k = 0; k < 2; ++k) dst[n][k] = *(const LAS bf16x8*)(lds + PG8_SB(b, h) + boff + n * 2048 + k * 1024); } while (0)
; #define PG8_MMA(ai, bj, At, Bt) do { __builtin_amdgcn_s_setprio(1); _Pragma("unroll") for (int m = 0; m < 4; ++m) _Pragma("unroll") for (int n = 0; n < 2; ++n) _Pragma("unroll") for (int k = 0; k < 2; ++k) \
;         acc[ai][bj][m][n] = __builtin_amdgcn_mfma_f32_16x16x32_bf16(Bt[n][k], At[m][k], acc[ai][bj][m][n], 0, 0, 0); __builtin_amdgcn_s_setprio(0); } while (0)
; #define PG8_WAIT_V(n) asm volatile("s_waitcnt vmcnt(" #n ")" ::: "memory")
; #define PG8_WAIT_L(n) asm volatile("s_waitcnt lgkmcnt(" #n ")" ::: "memory")
; template <class Epi>
; __device__ __forceinline__ void gemm_phase(LAS unsigned char* lds, const Gemm g, int G, int c, const Epi& E) {
;     ...
; #pragma unroll
;     for (int a = 0; a < 2; ++a)
; #pragma unroll
;         for (int b = 0; b < 2; ++b)
; #pragma unroll
;             for (int m = 0; m < 4; ++m)
; #pragma unroll
;                 for (int n = 0; n < 2; ++n) acc[a][b][m][n] = (f32x4){0.f, 0.f, 0.f, 0.f};
;     ...
;             const bool last = (t == nt - 2);
;             const char* a1 = cA + (size_t)(t + 1) * kstep;
;             const char* a2 = last ? nA : cA + (size_t)(t + 2) * kstep; const char* b2 = last ? nB : cB + (size_t)(t + 2) * kstep;
;             const char* a3 = a2 + kstep; const char* b3 = b2 + kstep;
;             PG8_LDB(B0, 0, 0); PG8_LDB(B1, 0, 1); PG8_SCHED; PG8_LDA(At, 0, 0); PG8_STAGE(PG8_SA(1, 1), a1 + hstepA, voffA);
;             PG8_WAIT_V(8); PG8_WAIT_L(0); PG8_BAR; PG8_MMA(0, 0, At, B0); PG8_MMA(0, 1, At, B1); PG8_BAR; PG8_SCHED;
;             PG8_LDA(At, 0, 1); PG8_STAGE(PG8_SB(0, 0), b2, voffB); PG8_STAGE(PG8_SB(0, 1), b2 + hstepB, voffB); PG8_STAGE(PG8_SA(0, 0), a2, voffA);
.LBB0_475:
	s_mov_b32 s38, 0
	s_mov_b64 s[4:5], -1
	s_mov_b64 s[10:11], 0
	s_waitcnt lgkmcnt(0)
	s_add_u32 s33, s8, s38
	s_addc_u32 s39, s9, 0
	s_add_u32 s56, s33, 0x100
	s_addc_u32 s57, s39, 0
	s_and_b64 s[54:55], s[10:11], exec
	s_cselect_b32 s57, s47, s57
	s_cselect_b32 s56, s46, s56
	s_add_u32 s38, s6, s38
	s_addc_u32 s54, s7, 0
	s_add_u32 s38, s38, 0x100
	s_addc_u32 s54, s54, 0
	s_and_b64 s[10:11], s[10:11], exec
	s_cselect_b32 s59, s53, s54
	s_cselect_b32 s58, s52, s38
	s_add_u32 s66, s33, 0xb0080
	ds_read_b128 v[130:133], v166
	ds_read_b128 v[134:137], v166 offset:1024
	ds_read_b128 v[150:153], v166 offset:2048
	ds_read_b128 v[154:157], v166 offset:3072
	ds_read_b128 v[158:161], v167
	ds_read_b128 v[172:175], v167 offset:1024
	ds_read_b128 v[176:179], v167 offset:2048
	ds_read_b128 v[180:183], v167 offset:3072
	s_addc_u32 s67, s39, 0
	s_add_i32 s63, s95, s83
	s_add_i32 m0, s86, 0xc000
	s_add_i32 s64, s86, 0xe000
	s_add_i32 s74, s63, 0x2000
	s_add_u32 s60, s58, 0xb0000
	s_addc_u32 s61, s59, 0
	s_add_i32 s75, s96, s83
	s_add_i32 s62, s75, 0x2000
	s_add_i32 vcc_hi, 0, 0x18000
	s_add_i32 vcc_lo, 0, 0x1c000
	s_add_u32 s54, s56, 0xb0000
	s_addc_u32 s55, s57, 0
	s_add_i32 s39, vcc_hi, s83
	s_add_i32 s73, s39, 0x2000
	s_add_u32 s10, s58, 0xb0080
	s_addc_u32 s11, s59, 0
	s_add_i32 s38, vcc_lo, s83
	s_add_i32 s33, s38, 0x2000
	v_lshl_add_u64 v[162:163], s[66:67], 0, v[138:139]
	ds_read_b128 v[184:187], v168
	ds_read_b128 v[188:191], v168 offset:1024
	ds_read_b128 v[192:195], v168 offset:2048
	ds_read_b128 v[196:199], v168 offset:3072
	ds_read_b128 v[200:203], v168 offset:4096
	ds_read_b128 v[204:207], v168 offset:5120
	ds_read_b128 v[208:211], v168 offset:6144
	ds_read_b128 v[212:215], v168 offset:7168
	global_load_lds_dwordx4 v[162:163], off
	v_lshl_add_u64 v[162:163], s[66:67], 0, v[142:143]
	s_mov_b32 m0, s64
	s_nop 0
	global_load_lds_dwordx4 v[162:163], off
	s_waitcnt vmcnt(8)
	s_waitcnt lgkmcnt(0)
	s_barrier
	s_setprio 0
	s_waitcnt lgkmcnt(0)
	v_mfma_f32_16x16x32_bf16 v[126:129], v[130:133], v[184:187], 0
	v_mfma_f32_16x16x32_bf16 v[122:125], v[150:153], v[184:187], 0
	v_mfma_f32_16x16x32_bf16 v[110:113], v[130:133], v[192:195], 0
	v_mfma_f32_16x16x32_bf16 v[106:109], v[150:153], v[192:195], 0
	v_mfma_f32_16x16x32_bf16 v[94:97], v[130:133], v[200:203], 0
	v_mfma_f32_16x16x32_bf16 v[90:93], v[150:153], v[200:203], 0
	v_mfma_f32_16x16x32_bf16 v[78:81], v[130:133], v[208:211], 0
	v_mfma_f32_16x16x32_bf16 v[74:77], v[150:153], v[208:211], 0
	v_mfma_f32_16x16x32_bf16 v[126:129], v[134:137], v[188:191], v[126:129]
	v_mfma_f32_16x16x32_bf16 v[122:125], v[154:157], v[188:191], v[122:125]
	v_mfma_f32_16x16x32_bf16 v[110:113], v[134:137], v[196:199], v[110:113]
	v_mfma_f32_16x16x32_bf16 v[106:109], v[154:157], v[196:199], v[106:109]
	v_mfma_f32_16x16x32_bf16 v[94:97], v[134:137], v[204:207], v[94:97]
	v_mfma_f32_16x16x32_bf16 v[90:93], v[154:157], v[204:207], v[90:93]
	v_mfma_f32_16x16x32_bf16 v[78:81], v[134:137], v[212:215], v[78:81]
	v_mfma_f32_16x16x32_bf16 v[74:77], v[154:157], v[212:215], v[74:77]
	s_setprio 2
	s_setprio 0
	v_mfma_f32_16x16x32_bf16 v[118:121], v[158:161], v[184:187], 0
	v_mfma_f32_16x16x32_bf16 v[114:117], v[176:179], v[184:187], 0
	v_mfma_f32_16x16x32_bf16 v[102:105], v[158:161], v[192:195], 0
	v_mfma_f32_16x16x32_bf16 v[98:101], v[176:179], v[192:195], 0
	v_mfma_f32_16x16x32_bf16 v[86:89], v[158:161], v[200:203], 0
	v_mfma_f32_16x16x32_bf16 v[82:85], v[176:179], v[200:203], 0
	v_mfma_f32_16x16x32_bf16 v[70:73], v[158:161], v[208:211], 0
	v_mfma_f32_16x16x32_bf16 v[66:69], v[176:179], v[208:211], 0
	v_mfma_f32_16x16x32_bf16 v[118:121], v[172:175], v[188:191], v[118:121]
	v_mfma_f32_16x16x32_bf16 v[114:117], v[180:183], v[188:191], v[114:117]
	v_mfma_f32_16x16x32_bf16 v[102:105], v[172:175], v[196:199], v[102:105]
	v_mfma_f32_16x16x32_bf16 v[98:101], v[180:183], v[196:199], v[98:101]
	v_mfma_f32_16x16x32_bf16 v[86:89], v[172:175], v[204:207], v[86:89]
	v_mfma_f32_16x16x32_bf16 v[82:85], v[180:183], v[204:207], v[82:85]
	v_mfma_f32_16x16x32_bf16 v[70:73], v[172:175], v[212:215], v[70:73]
	v_mfma_f32_16x16x32_bf16 v[66:69], v[180:183], v[212:215], v[66:69]
	s_setprio 2
	s_barrier
	s_mov_b32 m0, s63
	v_lshl_add_u64 v[162:163], s[58:59], 0, v[140:141]
	ds_read_b128 v[184:187], v168 offset:16384
	ds_read_b128 v[188:191], v168 offset:17408
	ds_read_b128 v[192:195], v168 offset:18432
	ds_read_b128 v[196:199], v168 offset:19456
	ds_read_b128 v[200:203], v168 offset:20480
	ds_read_b128 v[204:207], v168 offset:21504
	ds_read_b128 v[208:211], v168 offset:22528
	ds_read_b128 v[212:215], v168 offset:23552
	global_load_lds_dwordx4 v[162:163], off
	v_lshl_add_u64 v[216:217], s[58:59], 0, v[144:145]
	s_mov_b32 m0, s74
	v_lshl_add_u64 v[218:219], s[60:61], 0, v[140:141]
	global_load_lds_dwordx4 v[216:217], off
	s_mov_b32 m0, s75
	v_lshl_add_u64 v[220:221], s[56:57], 0, v[142:143]
	global_load_lds_dwordx4 v[218:219], off
	v_lshl_add_u64 v[218:219], s[60:61], 0, v[144:145]
	s_mov_b32 m0, s62
	s_nop 0
	global_load_lds_dwordx4 v[218:219], off
	v_lshl_add_u64 v[218:219], s[56:57], 0, v[138:139]
	s_mov_b32 m0, s86
	s_nop 0
	global_load_lds_dwordx4 v[218:219], off
	s_mov_b32 m0, s87
	s_nop 0
	global_load_lds_dwordx4 v[220:221], off
	s_waitcnt vmcnt(8)
	s_waitcnt lgkmcnt(0)
	s_barrier
; #define PG8_STAGE(bufoff, gbase, voff) do { _Pragma("unroll") for (int _i = 0; _i < 2; ++_i) \
;         __builtin_amdgcn_global_load_lds((const unsigned*)((const char*)(gbase) + (voff)[_i]), (LAS unsigned*)(lds + (bufoff) + ldsw + _i * 8192), 16, 0, 0); } while (0)
; #define PG8_LDA(dst, b, h) do { _Pragma("unroll") for (int m = 0; m < 4; ++m) _Pragma("unroll") for (int k = 0; k < 2; ++k) dst[m][k] = *(const LAS bf16x8*)(lds + PG8_SA(b, h) + aoff + m * 2048 + k * 1024); } while (0)
; #define PG8_LDB(dst, b, h) do { _Pragma("unroll") for (int n = 0; n < 2; ++n) _Pragma("unroll") for (int k = 0; k < 2; ++k) dst[n][k] = *(const LAS bf16x8*)(lds + PG8_SB(b, h) + boff + n * 2048 + k * 1024); } while (0)
; #define PG8_MMA(ai, bj, At, Bt) do { __builtin_amdgcn_s_setprio(1); _Pragma("unroll") for (int m = 0; m < 4; ++m) _Pragma("unroll") for (int n = 0; n < 2; ++n) _Pragma("unroll") for (int k = 0; k < 2; ++k) \
;         acc[ai][bj][m][n] = __builtin_amdgcn_mfma_f32_16x16x32_bf16(Bt[n][k], At[m][k], acc[ai][bj][m][n], 0, 0, 0); __builtin_amdgcn_s_setprio(0); } while (0)
; #define PG8_WAIT_V(n) asm volatile("s_waitcnt vmcnt(" #n ")" ::: "memory")
; #define PG8_WAIT_L(n) asm volatile("s_waitcnt lgkmcnt(" #n ")" ::: "memory")
; #define PG8_BAR __builtin_amdgcn_s_barrier()
; #define PG8_SCHED __builtin_amdgcn_sched_barrier(0)
; template <class Epi>
; __device__ __forceinline__ void gemm_phase(LAS unsigned char* lds, const Gemm g, int G, int c, const Epi& E) {
;     ...
;             PG8_WAIT_V(8); PG8_WAIT_L(0); PG8_BAR; PG8_MMA(1, 0, At, B0); PG8_MMA(1, 1, At, B1); PG8_BAR; PG8_SCHED;
;             PG8_LDB(B0, 1, 0); PG8_LDB(B1, 1, 1); PG8_SCHED; PG8_LDA(At, 1, 0); PG8_STAGE(PG8_SA(0, 1), a2 + hstepA, voffA);
;             PG8_WAIT_V(8); PG8_WAIT_L(0); PG8_BAR; PG8_MMA(0, 0, At, B0); PG8_MMA(0, 1, At, B1); PG8_BAR; PG8_SCHED;
	s_setprio 0
	s_waitcnt lgkmcnt(0)
	v_mfma_f32_16x16x32_bf16 v[62:65], v[130:133], v[184:187], 0
	v_mfma_f32_16x16x32_bf16 v[58:61], v[150:153], v[184:187], 0
	v_mfma_f32_16x16x32_bf16 v[46:49], v[130:133], v[192:195], 0
	v_mfma_f32_16x16x32_bf16 v[42:45], v[150:153], v[192:195], 0
	v_mfma_f32_16x16x32_bf16 v[30:33], v[130:133], v[200:203], 0
	v_mfma_f32_16x16x32_bf16 v[26:29], v[150:153], v[200:203], 0
	v_mfma_f32_16x16x32_bf16 v[14:17], v[130:133], v[208:211], 0
	v_mfma_f32_16x16x32_bf16 v[10:13], v[150:153], v[208:211], 0
	v_mfma_f32_16x16x32_bf16 v[62:65], v[134:137], v[188:191], v[62:65]
	v_mfma_f32_16x16x32_bf16 v[58:61], v[154:157], v[188:191], v[58:61]
	v_mfma_f32_16x16x32_bf16 v[46:49], v[134:137], v[196:199], v[46:49]
	v_mfma_f32_16x16x32_bf16 v[42:45], v[154:157], v[196:199], v[42:45]
	v_mfma_f32_16x16x32_bf16 v[30:33], v[134:137], v[204:207], v[30:33]
	v_mfma_f32_16x16x32_bf16 v[26:29], v[154:157], v[204:207], v[26:29]
	v_mfma_f32_16x16x32_bf16 v[14:17], v[134:137], v[212:215], v[14:17]
	v_mfma_f32_16x16x32_bf16 v[10:13], v[154:157], v[212:215], v[10:13]
	s_setprio 2
	s_setprio 0
	v_mfma_f32_16x16x32_bf16 v[54:57], v[158:161], v[184:187], 0
	v_mfma_f32_16x16x32_bf16 v[50:53], v[176:179], v[184:187], 0
	v_mfma_f32_16x16x32_bf16 v[38:41], v[158:161], v[192:195], 0
	v_mfma_f32_16x16x32_bf16 v[34:37], v[176:179], v[192:195], 0
	v_mfma_f32_16x16x32_bf16 v[22:25], v[158:161], v[200:203], 0
	v_mfma_f32_16x16x32_bf16 v[18:21], v[176:179], v[200:203], 0
	v_mfma_f32_16x16x32_bf16 v[6:9], v[158:161], v[208:211], 0
	v_mfma_f32_16x16x32_bf16 v[2:5], v[176:179], v[208:211], 0
	v_mfma_f32_16x16x32_bf16 v[54:57], v[172:175], v[188:191], v[54:57]
	v_mfma_f32_16x16x32_bf16 v[50:53], v[180:183], v[188:191], v[50:53]
	v_mfma_f32_16x16x32_bf16 v[38:41], v[172:175], v[196:199], v[38:41]
	v_mfma_f32_16x16x32_bf16 v[34:37], v[180:183], v[196:199], v[34:37]
	v_mfma_f32_16x16x32_bf16 v[22:25], v[172:175], v[204:207], v[22:25]
	v_mfma_f32_16x16x32_bf16 v[18:21], v[180:183], v[204:207], v[18:21]
	v_mfma_f32_16x16x32_bf16 v[6:9], v[172:175], v[212:215], v[6:9]
	v_mfma_f32_16x16x32_bf16 v[2:5], v[180:183], v[212:215], v[2:5]
	s_setprio 2
	s_barrier
	v_add_u32_e32 v154, vcc_hi, v165
	v_add_u32_e32 v180, vcc_lo, v165
	ds_read_b128 v[130:133], v154
	ds_read_b128 v[134:137], v154 offset:1024
	ds_read_b128 v[150:153], v154 offset:2048
	ds_read_b128 v[154:157], v154 offset:3072
	ds_read_b128 v[158:161], v180
	ds_read_b128 v[172:175], v180 offset:1024
	ds_read_b128 v[176:179], v180 offset:2048
	ds_read_b128 v[180:183], v180 offset:3072
	s_mov_b32 m0, s88
	v_lshl_add_u64 v[222:223], s[54:55], 0, v[138:139]
	ds_read_b128 v[184:187], v168 offset:32768
	ds_read_b128 v[188:191], v168 offset:33792
	ds_read_b128 v[192:195], v168 offset:34816
	ds_read_b128 v[196:199], v168 offset:35840
	ds_read_b128 v[200:203], v168 offset:36864
	ds_read_b128 v[204:207], v168 offset:37888
	ds_read_b128 v[208:211], v168 offset:38912
	ds_read_b128 v[212:215], v168 offset:39936
	global_load_lds_dwordx4 v[222:223], off
	v_lshl_add_u64 v[222:223], s[54:55], 0, v[142:143]
	s_mov_b32 m0, s89
	s_nop 0
	global_load_lds_dwordx4 v[222:223], off
	s_waitcnt vmcnt(8)
	s_waitcnt lgkmcnt(0)
	s_barrier
	s_setprio 0
	s_waitcnt lgkmcnt(0)
	v_mfma_f32_16x16x32_bf16 v[126:129], v[130:133], v[184:187], v[126:129]
	v_mfma_f32_16x16x32_bf16 v[122:125], v[150:153], v[184:187], v[122:125]
	v_mfma_f32_16x16x32_bf16 v[110:113], v[130:133], v[192:195], v[110:113]
	v_mfma_f32_16x16x32_bf16 v[106:109], v[150:153], v[192:195], v[106:109]
	v_mfma_f32_16x16x32_bf16 v[94:97], v[130:133], v[200:203], v[94:97]
	v_mfma_f32_16x16x32_bf16 v[90:93], v[150:153], v[200:203], v[90:93]
	v_mfma_f32_16x16x32_bf16 v[78:81], v[130:133], v[208:211], v[78:81]
	v_mfma_f32_16x16x32_bf16 v[74:77], v[150:153], v[208:211], v[74:77]
	v_mfma_f32_16x16x32_bf16 v[126:129], v[134:137], v[188:191], v[126:129]
	v_mfma_f32_16x16x32_bf16 v[122:125], v[154:157], v[188:191], v[122:125]
	v_mfma_f32_16x16x32_bf16 v[110:113], v[134:137], v[196:199], v[110:113]
	v_mfma_f32_16x16x32_bf16 v[106:109], v[154:157], v[196:199], v[106:109]
	v_mfma_f32_16x16x32_bf16 v[94:97], v[134:137], v[204:207], v[94:97]
	v_mfma_f32_16x16x32_bf16 v[90:93], v[154:157], v[204:207], v[90:93]
	v_mfma_f32_16x16x32_bf16 v[78:81], v[134:137], v[212:215], v[78:81]
	v_mfma_f32_16x16x32_bf16 v[74:77], v[154:157], v[212:215], v[74:77]
	s_setprio 2
	s_setprio 0
	v_mfma_f32_16x16x32_bf16 v[118:121], v[158:161], v[184:187], v[118:121]
	v_mfma_f32_16x16x32_bf16 v[114:117], v[176:179], v[184:187], v[114:117]
	v_mfma_f32_16x16x32_bf16 v[102:105], v[158:161], v[192:195], v[102:105]
	v_mfma_f32_16x16x32_bf16 v[98:101], v[176:179], v[192:195], v[98:101]
	v_mfma_f32_16x16x32_bf16 v[86:89], v[158:161], v[200:203], v[86:89]
	v_mfma_f32_16x16x32_bf16 v[82:85], v[176:179], v[200:203], v[82:85]
	v_mfma_f32_16x16x32_bf16 v[70:73], v[158:161], v[208:211], v[70:73]
	v_mfma_f32_16x16x32_bf16 v[66:69], v[176:179], v[208:211], v[66:69]
	v_mfma_f32_16x16x32_bf16 v[118:121], v[172:175], v[188:191], v[118:121]
	v_mfma_f32_16x16x32_bf16 v[114:117], v[180:183], v[188:191], v[114:117]
	v_mfma_f32_16x16x32_bf16 v[102:105], v[172:175], v[196:199], v[102:105]
	v_mfma_f32_16x16x32_bf16 v[98:101], v[180:183], v[196:199], v[98:101]
	v_mfma_f32_16x16x32_bf16 v[86:89], v[172:175], v[204:207], v[86:89]
	v_mfma_f32_16x16x32_bf16 v[82:85], v[180:183], v[204:207], v[82:85]
	v_mfma_f32_16x16x32_bf16 v[70:73], v[172:175], v[212:215], v[70:73]
	v_mfma_f32_16x16x32_bf16 v[66:69], v[180:183], v[212:215], v[66:69]
	s_setprio 2
	s_barrier
; #define PG8_STAGE(bufoff, gbase, voff) do { _Pragma("unroll") for (int _i = 0; _i < 2; ++_i) \
;         __builtin_amdgcn_global_load_lds((const unsigned*)((const char*)(gbase) + (voff)[_i]), (LAS unsigned*)(lds + (bufoff) + ldsw + _i * 8192), 16, 0, 0); } while (0)
; #define PG8_LDA(dst, b, h) do { _Pragma("unroll") for (int m = 0; m < 4; ++m) _Pragma("unroll") for (int k = 0; k < 2; ++k) dst[m][k] = *(const LAS bf16x8*)(lds + PG8_SA(b, h) + aoff + m * 2048 + k * 1024); } while (0)
; #define PG8_MMA(ai, bj, At, Bt) do { __builtin_amdgcn_s_setprio(1); _Pragma("unroll") for (int m = 0; m < 4; ++m) _Pragma("unroll") for (int n = 0; n < 2; ++n) _Pragma("unroll") for (int k = 0; k < 2; ++k) \
;         acc[ai][bj][m][n] = __builtin_amdgcn_mfma_f32_16x16x32_bf16(Bt[n][k], At[m][k], acc[ai][bj][m][n], 0, 0, 0); __builtin_amdgcn_s_setprio(0); } while (0)
; #define PG8_WAIT_V(n) asm volatile("s_waitcnt vmcnt(" #n ")" ::: "memory")
; #define PG8_WAIT_L(n) asm volatile("s_waitcnt lgkmcnt(" #n ")" ::: "memory")
; #define PG8_BAR __builtin_amdgcn_s_barrier()
; #define PG8_SCHED __builtin_amdgcn_sched_barrier(0)
; template <class Epi>
; __device__ __forceinline__ void gemm_phase(LAS unsigned char* lds, const Gemm g, int G, int c, const Epi& E) {
;     ...
;         for (int t = 0; t < nt; t += 2) {
;     ...
;             PG8_LDA(At, 1, 1); PG8_STAGE(PG8_SB(1, 0), b3, voffB); PG8_STAGE(PG8_SB(1, 1), b3 + hstepB, voffB); PG8_STAGE(PG8_SA(1, 0), a3, voffA);
;             PG8_WAIT_V(8); PG8_WAIT_L(0); PG8_BAR; PG8_MMA(1, 0, At, B0); PG8_MMA(1, 1, At, B1); PG8_BAR; PG8_SCHED;
	s_mov_b32 m0, s39
	v_lshl_add_u64 v[162:163], v[162:163], 0, s[24:25]
	ds_read_b128 v[184:187], v168 offset:49152
	ds_read_b128 v[188:191], v168 offset:50176
	ds_read_b128 v[192:195], v168 offset:51200
	ds_read_b128 v[196:199], v168 offset:52224
	ds_read_b128 v[200:203], v168 offset:53248
	ds_read_b128 v[204:207], v168 offset:54272
	ds_read_b128 v[208:211], v168 offset:55296
	ds_read_b128 v[212:215], v168 offset:56320
	global_load_lds_dwordx4 v[162:163], off
	v_lshl_add_u64 v[162:163], v[216:217], 0, s[24:25]
	s_mov_b32 m0, s73
	s_nop 0
	global_load_lds_dwordx4 v[162:163], off
	v_lshl_add_u64 v[162:163], s[10:11], 0, v[140:141]
	s_mov_b32 m0, s38
	s_nop 0
	global_load_lds_dwordx4 v[162:163], off
	v_lshl_add_u64 v[162:163], s[10:11], 0, v[144:145]
	s_mov_b32 m0, s33
	s_nop 0
	global_load_lds_dwordx4 v[162:163], off
	v_lshl_add_u64 v[162:163], v[218:219], 0, s[24:25]
	s_mov_b32 m0, s93
	s_nop 0
	global_load_lds_dwordx4 v[162:163], off
	v_lshl_add_u64 v[162:163], v[220:221], 0, s[24:25]
	s_mov_b32 m0, s94
	s_nop 0
	global_load_lds_dwordx4 v[162:163], off
	s_waitcnt vmcnt(8)
	s_waitcnt lgkmcnt(0)
	s_barrier
	s_setprio 0
	s_waitcnt lgkmcnt(0)
	v_mfma_f32_16x16x32_bf16 v[62:65], v[130:133], v[184:187], v[62:65]
	v_mfma_f32_16x16x32_bf16 v[58:61], v[150:153], v[184:187], v[58:61]
	v_mfma_f32_16x16x32_bf16 v[46:49], v[130:133], v[192:195], v[46:49]
	v_mfma_f32_16x16x32_bf16 v[42:45], v[150:153], v[192:195], v[42:45]
	v_mfma_f32_16x16x32_bf16 v[30:33], v[130:133], v[200:203], v[30:33]
	v_mfma_f32_16x16x32_bf16 v[26:29], v[150:153], v[200:203], v[26:29]
	v_mfma_f32_16x16x32_bf16 v[14:17], v[130:133], v[208:211], v[14:17]
	v_mfma_f32_16x16x32_bf16 v[10:13], v[150:153], v[208:211], v[10:13]
	v_mfma_f32_16x16x32_bf16 v[62:65], v[134:137], v[188:191], v[62:65]
	v_mfma_f32_16x16x32_bf16 v[58:61], v[154:157], v[188:191], v[58:61]
	v_mfma_f32_16x16x32_bf16 v[46:49], v[134:137], v[196:199], v[46:49]
	v_mfma_f32_16x16x32_bf16 v[42:45], v[154:157], v[196:199], v[42:45]
	v_mfma_f32_16x16x32_bf16 v[30:33], v[134:137], v[204:207], v[30:33]
	v_mfma_f32_16x16x32_bf16 v[26:29], v[154:157], v[204:207], v[26:29]
	v_mfma_f32_16x16x32_bf16 v[14:17], v[134:137], v[212:215], v[14:17]
	v_mfma_f32_16x16x32_bf16 v[10:13], v[154:157], v[212:215], v[10:13]
	s_setprio 2
	s_setprio 0
	v_mfma_f32_16x16x32_bf16 v[54:57], v[158:161], v[184:187], v[54:57]
	v_mfma_f32_16x16x32_bf16 v[50:53], v[176:179], v[184:187], v[50:53]
	v_mfma_f32_16x16x32_bf16 v[38:41], v[158:161], v[192:195], v[38:41]
	v_mfma_f32_16x16x32_bf16 v[34:37], v[176:179], v[192:195], v[34:37]
	v_mfma_f32_16x16x32_bf16 v[22:25], v[158:161], v[200:203], v[22:25]
	v_mfma_f32_16x16x32_bf16 v[18:21], v[176:179], v[200:203], v[18:21]
	v_mfma_f32_16x16x32_bf16 v[6:9], v[158:161], v[208:211], v[6:9]
	v_mfma_f32_16x16x32_bf16 v[2:5], v[176:179], v[208:211], v[2:5]
	v_mfma_f32_16x16x32_bf16 v[54:57], v[172:175], v[188:191], v[54:57]
	v_mfma_f32_16x16x32_bf16 v[50:53], v[180:183], v[188:191], v[50:53]
	v_mfma_f32_16x16x32_bf16 v[38:41], v[172:175], v[196:199], v[38:41]
	v_mfma_f32_16x16x32_bf16 v[34:37], v[180:183], v[196:199], v[34:37]
	v_mfma_f32_16x16x32_bf16 v[22:25], v[172:175], v[204:207], v[22:25]
	v_mfma_f32_16x16x32_bf16 v[18:21], v[180:183], v[204:207], v[18:21]
	v_mfma_f32_16x16x32_bf16 v[6:9], v[172:175], v[212:215], v[6:9]
	v_mfma_f32_16x16x32_bf16 v[2:5], v[180:183], v[212:215], v[2:5]
	s_setprio 2
	s_barrier
	s_movk_i32 s38, 0x100
	s_andn2_b64 vcc, exec, s[4:5]
	s_mov_b64 s[10:11], -1
	s_mov_b64 s[4:5], 0
	s_cbranch_vccz .LBB0_476

; #define PG8_STAGE(bufoff, gbase, voff) do { _Pragma("unroll") for (int _i = 0; _i < 2; ++_i) \
;         __builtin_amdgcn_global_load_lds((const unsigned*)((const char*)(gbase) + (voff)[_i]), (LAS unsigned*)(lds + (bufoff) + ldsw + _i * 8192), 16, 0, 0); } while (0)
; #define PG8_LDA(dst, b, h) do { _Pragma("unroll") for (int m = 0; m < 4; ++m) _Pragma("unroll") for (int k = 0; k < 2; ++k) dst[m][k] = *(const LAS bf16x8*)(lds + PG8_SA(b, h) + aoff + m * 2048 + k * 1024); } while (0)
; #define PG8_LDB(dst, b, h) do { _Pragma("unroll") for (int n = 0; n < 2; ++n) _Pragma("unroll") for (int k = 0; k < 2; ++k) dst[n][k] = *(const LAS bf16x8*)(lds + PG8_SB(b, h) + boff + n * 2048 + k * 1024); } while (0)
; #define PG8_MMA(ai, bj, At, Bt) do { __builtin_amdgcn_s_setprio(1); _Pragma("unroll") for (int m = 0; m < 4; ++m) _Pragma("unroll") for (int n = 0; n < 2; ++n) _Pragma("unroll") for (int k = 0; k < 2; ++k) \
;         acc[ai][bj][m][n] = __builtin_amdgcn_mfma_f32_16x16x32_bf16(Bt[n][k], At[m][k], acc[ai][bj][m][n], 0, 0, 0); __builtin_amdgcn_s_setprio(0); } while (0)
; #define PG8_WAIT_V(n) asm volatile("s_waitcnt vmcnt(" #n ")" ::: "memory")
; #define PG8_WAIT_L(n) asm volatile("s_waitcnt lgkmcnt(" #n ")" ::: "memory")
; template <class Epi>
; __device__ __forceinline__ void gemm_phase(LAS unsigned char* lds, const Gemm g, int G, int c, const Epi& E) {
;     ...
; #pragma unroll
;     for (int a = 0; a < 2; ++a)
; #pragma unroll
;         for (int b = 0; b < 2; ++b)
; #pragma unroll
;             for (int m = 0; m < 4; ++m)
; #pragma unroll
;                 for (int n = 0; n < 2; ++n) acc[a][b][m][n] = (f32x4){0.f, 0.f, 0.f, 0.f};
;     ...
;             const bool last = (t == nt - 2);
;             const char* a1 = cA + (size_t)(t + 1) * kstep;
;             const char* a2 = last ? nA : cA + (size_t)(t + 2) * kstep; const char* b2 = last ? nB : cB + (size_t)(t + 2) * kstep;
;             const char* a3 = a2 + kstep; const char* b3 = b2 + kstep;
;             PG8_LDB(B0, 0, 0); PG8_LDB(B1, 0, 1); PG8_SCHED; PG8_LDA(At, 0, 0); PG8_STAGE(PG8_SA(1, 1), a1 + hstepA, voffA);
;             PG8_WAIT_V(8); PG8_WAIT_L(0); PG8_BAR; PG8_MMA(0, 0, At, B0); PG8_MMA(0, 1, At, B1); PG8_BAR; PG8_SCHED;
;             PG8_LDA(At, 0, 1); PG8_STAGE(PG8_SB(0, 0), b2, voffB); PG8_STAGE(PG8_SB(0, 1), b2 + hstepB, voffB); PG8_STAGE(PG8_SA(0, 0), a2, voffA);
.LBB0_593:
	s_mov_b32 s38, 0
	s_mov_b64 s[4:5], -1
	s_mov_b64 s[54:55], 0
	s_waitcnt lgkmcnt(0)
	s_add_u32 s33, s8, s38
	s_addc_u32 s62, s9, 0
	s_add_u32 s39, s33, 0x100
	s_addc_u32 s58, s62, 0
	s_and_b64 s[56:57], s[54:55], exec
	s_cselect_b32 s59, s45, s58
	s_cselect_b32 s58, s44, s39
	s_add_u32 s38, s6, s38
	s_addc_u32 s39, s7, 0
	s_add_u32 s56, s38, 0x100
	s_addc_u32 s57, s39, 0
	s_and_b64 s[38:39], s[54:55], exec
	s_cselect_b32 s61, s47, s57
	s_cselect_b32 s60, s46, s56
	s_add_u32 s68, s33, 0xb0080
	s_addc_u32 s69, s62, 0
	s_add_i32 s63, s86, s23
	ds_read_b128 v[142:145], v166
	ds_read_b128 v[146:149], v166 offset:1024
	ds_read_b128 v[150:153], v166 offset:2048
	ds_read_b128 v[154:157], v166 offset:3072
	ds_read_b128 v[158:161], v167
	ds_read_b128 v[170:173], v167 offset:1024
	ds_read_b128 v[174:177], v167 offset:2048
	ds_read_b128 v[178:181], v167 offset:3072
	s_add_i32 m0, s72, 0xc000
	s_add_i32 s64, s72, 0xe000
	s_add_i32 s74, s63, 0x2000
	s_add_u32 s66, s60, 0xb0000
	s_addc_u32 s67, s61, 0
	s_add_i32 s62, s87, s23
	s_add_i32 s75, s62, 0x2000
	s_add_i32 s97, 0, 0x18000
	s_add_i32 s33, 0, 0x1c000
	s_add_u32 s56, s58, 0xb0000
	s_addc_u32 s57, s59, 0
	s_add_i32 s96, s97, s23
	s_add_i32 s39, s96, 0x2000
	s_add_u32 s54, s60, 0xb0080
	s_addc_u32 s55, s61, 0
	s_add_i32 s95, s33, s23
	s_add_i32 s38, s95, 0x2000
	v_lshl_add_u64 v[162:163], s[68:69], 0, v[136:137]
	ds_read_b128 v[182:185], v168
	ds_read_b128 v[186:189], v168 offset:1024
	ds_read_b128 v[190:193], v168 offset:2048
	ds_read_b128 v[194:197], v168 offset:3072
	ds_read_b128 v[198:201], v168 offset:4096
	ds_read_b128 v[202:205], v168 offset:5120
	ds_read_b128 v[206:209], v168 offset:6144
	ds_read_b128 v[210:213], v168 offset:7168
	global_load_lds_dwordx4 v[162:163], off
	v_lshl_add_u64 v[162:163], s[68:69], 0, v[132:133]
	s_mov_b32 m0, s64
	s_nop 0
	global_load_lds_dwordx4 v[162:163], off
	s_waitcnt vmcnt(8)
	s_waitcnt lgkmcnt(0)
	s_barrier
	s_setprio 0
	s_waitcnt lgkmcnt(0)
	v_mfma_f32_16x16x32_bf16 v[126:129], v[142:145], v[182:185], 0
	v_mfma_f32_16x16x32_bf16 v[122:125], v[150:153], v[182:185], 0
	v_mfma_f32_16x16x32_bf16 v[110:113], v[142:145], v[190:193], 0
	v_mfma_f32_16x16x32_bf16 v[106:109], v[150:153], v[190:193], 0
	v_mfma_f32_16x16x32_bf16 v[94:97], v[142:145], v[198:201], 0
	v_mfma_f32_16x16x32_bf16 v[90:93], v[150:153], v[198:201], 0
	v_mfma_f32_16x16x32_bf16 v[78:81], v[142:145], v[206:209], 0
	v_mfma_f32_16x16x32_bf16 v[74:77], v[150:153], v[206:209], 0
	v_mfma_f32_16x16x32_bf16 v[126:129], v[146:149], v[186:189], v[126:129]
	v_mfma_f32_16x16x32_bf16 v[122:125], v[154:157], v[186:189], v[122:125]
	v_mfma_f32_16x16x32_bf16 v[110:113], v[146:149], v[194:197], v[110:113]
	v_mfma_f32_16x16x32_bf16 v[106:109], v[154:157], v[194:197], v[106:109]
	v_mfma_f32_16x16x32_bf16 v[94:97], v[146:149], v[202:205], v[94:97]
	v_mfma_f32_16x16x32_bf16 v[90:93], v[154:157], v[202:205], v[90:93]
	v_mfma_f32_16x16x32_bf16 v[78:81], v[146:149], v[210:213], v[78:81]
	v_mfma_f32_16x16x32_bf16 v[74:77], v[154:157], v[210:213], v[74:77]
	s_setprio 2
	s_setprio 0
	v_mfma_f32_16x16x32_bf16 v[118:121], v[158:161], v[182:185], 0
	v_mfma_f32_16x16x32_bf16 v[114:117], v[174:177], v[182:185], 0
	v_mfma_f32_16x16x32_bf16 v[102:105], v[158:161], v[190:193], 0
	v_mfma_f32_16x16x32_bf16 v[98:101], v[174:177], v[190:193], 0
	v_mfma_f32_16x16x32_bf16 v[86:89], v[158:161], v[198:201], 0
	v_mfma_f32_16x16x32_bf16 v[82:85], v[174:177], v[198:201], 0
	v_mfma_f32_16x16x32_bf16 v[70:73], v[158:161], v[206:209], 0
	v_mfma_f32_16x16x32_bf16 v[66:69], v[174:177], v[206:209], 0
	v_mfma_f32_16x16x32_bf16 v[118:121], v[170:173], v[186:189], v[118:121]
	v_mfma_f32_16x16x32_bf16 v[114:117], v[178:181], v[186:189], v[114:117]
	v_mfma_f32_16x16x32_bf16 v[102:105], v[170:173], v[194:197], v[102:105]
	v_mfma_f32_16x16x32_bf16 v[98:101], v[178:181], v[194:197], v[98:101]
	v_mfma_f32_16x16x32_bf16 v[86:89], v[170:173], v[202:205], v[86:89]
	v_mfma_f32_16x16x32_bf16 v[82:85], v[178:181], v[202:205], v[82:85]
	v_mfma_f32_16x16x32_bf16 v[70:73], v[170:173], v[210:213], v[70:73]
	v_mfma_f32_16x16x32_bf16 v[66:69], v[178:181], v[210:213], v[66:69]
	s_setprio 2
	s_barrier
	s_mov_b32 m0, s63
	v_lshl_add_u64 v[162:163], s[60:61], 0, v[134:135]
	ds_read_b128 v[182:185], v168 offset:16384
	ds_read_b128 v[186:189], v168 offset:17408
	ds_read_b128 v[190:193], v168 offset:18432
	ds_read_b128 v[194:197], v168 offset:19456
	ds_read_b128 v[198:201], v168 offset:20480
	ds_read_b128 v[202:205], v168 offset:21504
	ds_read_b128 v[206:209], v168 offset:22528
	ds_read_b128 v[210:213], v168 offset:23552
	global_load_lds_dwordx4 v[162:163], off
	v_lshl_add_u64 v[214:215], s[60:61], 0, v[130:131]
	s_mov_b32 m0, s74
	v_lshl_add_u64 v[216:217], s[66:67], 0, v[134:135]
	global_load_lds_dwordx4 v[214:215], off
	s_mov_b32 m0, s62
	v_lshl_add_u64 v[218:219], s[58:59], 0, v[132:133]
	global_load_lds_dwordx4 v[216:217], off
	v_lshl_add_u64 v[216:217], s[66:67], 0, v[130:131]
	s_mov_b32 m0, s75
	s_nop 0
	global_load_lds_dwordx4 v[216:217], off
	v_lshl_add_u64 v[216:217], s[58:59], 0, v[136:137]
	s_mov_b32 m0, s72
	s_nop 0
	global_load_lds_dwordx4 v[216:217], off
	s_mov_b32 m0, s73
	s_nop 0
	global_load_lds_dwordx4 v[218:219], off
	s_waitcnt vmcnt(8)
	s_waitcnt lgkmcnt(0)
	s_barrier
; #define PG8_STAGE(bufoff, gbase, voff) do { _Pragma("unroll") for (int _i = 0; _i < 2; ++_i) \
;         __builtin_amdgcn_global_load_lds((const unsigned*)((const char*)(gbase) + (voff)[_i]), (LAS unsigned*)(lds + (bufoff) + ldsw + _i * 8192), 16, 0, 0); } while (0)
; #define PG8_LDA(dst, b, h) do { _Pragma("unroll") for (int m = 0; m < 4; ++m) _Pragma("unroll") for (int k = 0; k < 2; ++k) dst[m][k] = *(const LAS bf16x8*)(lds + PG8_SA(b, h) + aoff + m * 2048 + k * 1024); } while (0)
; #define PG8_LDB(dst, b, h) do { _Pragma("unroll") for (int n = 0; n < 2; ++n) _Pragma("unroll") for (int k = 0; k < 2; ++k) dst[n][k] = *(const LAS bf16x8*)(lds + PG8_SB(b, h) + boff + n * 2048 + k * 1024); } while (0)
; #define PG8_MMA(ai, bj, At, Bt) do { __builtin_amdgcn_s_setprio(1); _Pragma("unroll") for (int m = 0; m < 4; ++m) _Pragma("unroll") for (int n = 0; n < 2; ++n) _Pragma("unroll") for (int k = 0; k < 2; ++k) \
;         acc[ai][bj][m][n] = __builtin_amdgcn_mfma_f32_16x16x32_bf16(Bt[n][k], At[m][k], acc[ai][bj][m][n], 0, 0, 0); __builtin_amdgcn_s_setprio(0); } while (0)
; #define PG8_WAIT_V(n) asm volatile("s_waitcnt vmcnt(" #n ")" ::: "memory")
; #define PG8_WAIT_L(n) asm volatile("s_waitcnt lgkmcnt(" #n ")" ::: "memory")
; #define PG8_BAR __builtin_amdgcn_s_barrier()
; #define PG8_SCHED __builtin_amdgcn_sched_barrier(0)
; template <class Epi>
; __device__ __forceinline__ void gemm_phase(LAS unsigned char* lds, const Gemm g, int G, int c, const Epi& E) {
;     ...
;             PG8_WAIT_V(8); PG8_WAIT_L(0); PG8_BAR; PG8_MMA(1, 0, At, B0); PG8_MMA(1, 1, At, B1); PG8_BAR; PG8_SCHED;
;             PG8_LDB(B0, 1, 0); PG8_LDB(B1, 1, 1); PG8_SCHED; PG8_LDA(At, 1, 0); PG8_STAGE(PG8_SA(0, 1), a2 + hstepA, voffA);
;             PG8_WAIT_V(8); PG8_WAIT_L(0); PG8_BAR; PG8_MMA(0, 0, At, B0); PG8_MMA(0, 1, At, B1); PG8_BAR; PG8_SCHED;
	s_setprio 0
	s_waitcnt lgkmcnt(0)
	v_mfma_f32_16x16x32_bf16 v[62:65], v[142:145], v[182:185], 0
	v_mfma_f32_16x16x32_bf16 v[58:61], v[150:153], v[182:185], 0
	v_mfma_f32_16x16x32_bf16 v[46:49], v[142:145], v[190:193], 0
	v_mfma_f32_16x16x32_bf16 v[42:45], v[150:153], v[190:193], 0
	v_mfma_f32_16x16x32_bf16 v[30:33], v[142:145], v[198:201], 0
	v_mfma_f32_16x16x32_bf16 v[26:29], v[150:153], v[198:201], 0
	v_mfma_f32_16x16x32_bf16 v[14:17], v[142:145], v[206:209], 0
	v_mfma_f32_16x16x32_bf16 v[10:13], v[150:153], v[206:209], 0
	v_mfma_f32_16x16x32_bf16 v[62:65], v[146:149], v[186:189], v[62:65]
	v_mfma_f32_16x16x32_bf16 v[58:61], v[154:157], v[186:189], v[58:61]
	v_mfma_f32_16x16x32_bf16 v[46:49], v[146:149], v[194:197], v[46:49]
	v_mfma_f32_16x16x32_bf16 v[42:45], v[154:157], v[194:197], v[42:45]
	v_mfma_f32_16x16x32_bf16 v[30:33], v[146:149], v[202:205], v[30:33]
	v_mfma_f32_16x16x32_bf16 v[26:29], v[154:157], v[202:205], v[26:29]
	v_mfma_f32_16x16x32_bf16 v[14:17], v[146:149], v[210:213], v[14:17]
	v_mfma_f32_16x16x32_bf16 v[10:13], v[154:157], v[210:213], v[10:13]
	s_setprio 2
	s_setprio 0
	v_mfma_f32_16x16x32_bf16 v[54:57], v[158:161], v[182:185], 0
	v_mfma_f32_16x16x32_bf16 v[50:53], v[174:177], v[182:185], 0
	v_mfma_f32_16x16x32_bf16 v[38:41], v[158:161], v[190:193], 0
	v_mfma_f32_16x16x32_bf16 v[34:37], v[174:177], v[190:193], 0
	v_mfma_f32_16x16x32_bf16 v[22:25], v[158:161], v[198:201], 0
	v_mfma_f32_16x16x32_bf16 v[18:21], v[174:177], v[198:201], 0
	v_mfma_f32_16x16x32_bf16 v[6:9], v[158:161], v[206:209], 0
	v_mfma_f32_16x16x32_bf16 v[2:5], v[174:177], v[206:209], 0
	v_mfma_f32_16x16x32_bf16 v[54:57], v[170:173], v[186:189], v[54:57]
	v_mfma_f32_16x16x32_bf16 v[50:53], v[178:181], v[186:189], v[50:53]
	v_mfma_f32_16x16x32_bf16 v[38:41], v[170:173], v[194:197], v[38:41]
	v_mfma_f32_16x16x32_bf16 v[34:37], v[178:181], v[194:197], v[34:37]
	v_mfma_f32_16x16x32_bf16 v[22:25], v[170:173], v[202:205], v[22:25]
	v_mfma_f32_16x16x32_bf16 v[18:21], v[178:181], v[202:205], v[18:21]
	v_mfma_f32_16x16x32_bf16 v[6:9], v[170:173], v[210:213], v[6:9]
	v_mfma_f32_16x16x32_bf16 v[2:5], v[178:181], v[210:213], v[2:5]
	s_setprio 2
	s_barrier
	v_add_u32_e32 v154, s97, v165
	v_add_u32_e32 v178, s33, v165
	ds_read_b128 v[142:145], v154
	ds_read_b128 v[146:149], v154 offset:1024
	ds_read_b128 v[150:153], v154 offset:2048
	ds_read_b128 v[154:157], v154 offset:3072
	ds_read_b128 v[158:161], v178
	ds_read_b128 v[170:173], v178 offset:1024
	ds_read_b128 v[174:177], v178 offset:2048
	ds_read_b128 v[178:181], v178 offset:3072
	s_mov_b32 m0, s78
	v_lshl_add_u64 v[220:221], s[56:57], 0, v[136:137]
	ds_read_b128 v[182:185], v168 offset:32768
	ds_read_b128 v[186:189], v168 offset:33792
	ds_read_b128 v[190:193], v168 offset:34816
	ds_read_b128 v[194:197], v168 offset:35840
	ds_read_b128 v[198:201], v168 offset:36864
	ds_read_b128 v[202:205], v168 offset:37888
	ds_read_b128 v[206:209], v168 offset:38912
	ds_read_b128 v[210:213], v168 offset:39936
	global_load_lds_dwordx4 v[220:221], off
	v_lshl_add_u64 v[220:221], s[56:57], 0, v[132:133]
	s_mov_b32 m0, s81
	s_nop 0
	global_load_lds_dwordx4 v[220:221], off
	s_waitcnt vmcnt(8)
	s_waitcnt lgkmcnt(0)
	s_barrier
	s_setprio 0
	s_waitcnt lgkmcnt(0)
	v_mfma_f32_16x16x32_bf16 v[126:129], v[142:145], v[182:185], v[126:129]
	v_mfma_f32_16x16x32_bf16 v[122:125], v[150:153], v[182:185], v[122:125]
	v_mfma_f32_16x16x32_bf16 v[110:113], v[142:145], v[190:193], v[110:113]
	v_mfma_f32_16x16x32_bf16 v[106:109], v[150:153], v[190:193], v[106:109]
	v_mfma_f32_16x16x32_bf16 v[94:97], v[142:145], v[198:201], v[94:97]
	v_mfma_f32_16x16x32_bf16 v[90:93], v[150:153], v[198:201], v[90:93]
	v_mfma_f32_16x16x32_bf16 v[78:81], v[142:145], v[206:209], v[78:81]
	v_mfma_f32_16x16x32_bf16 v[74:77], v[150:153], v[206:209], v[74:77]
	v_mfma_f32_16x16x32_bf16 v[126:129], v[146:149], v[186:189], v[126:129]
	v_mfma_f32_16x16x32_bf16 v[122:125], v[154:157], v[186:189], v[122:125]
	v_mfma_f32_16x16x32_bf16 v[110:113], v[146:149], v[194:197], v[110:113]
	v_mfma_f32_16x16x32_bf16 v[106:109], v[154:157], v[194:197], v[106:109]
	v_mfma_f32_16x16x32_bf16 v[94:97], v[146:149], v[202:205], v[94:97]
	v_mfma_f32_16x16x32_bf16 v[90:93], v[154:157], v[202:205], v[90:93]
	v_mfma_f32_16x16x32_bf16 v[78:81], v[146:149], v[210:213], v[78:81]
	v_mfma_f32_16x16x32_bf16 v[74:77], v[154:157], v[210:213], v[74:77]
	s_setprio 2
	s_setprio 0
	v_mfma_f32_16x16x32_bf16 v[118:121], v[158:161], v[182:185], v[118:121]
	v_mfma_f32_16x16x32_bf16 v[114:117], v[174:177], v[182:185], v[114:117]
	v_mfma_f32_16x16x32_bf16 v[102:105], v[158:161], v[190:193], v[102:105]
	v_mfma_f32_16x16x32_bf16 v[98:101], v[174:177], v[190:193], v[98:101]
	v_mfma_f32_16x16x32_bf16 v[86:89], v[158:161], v[198:201], v[86:89]
	v_mfma_f32_16x16x32_bf16 v[82:85], v[174:177], v[198:201], v[82:85]
	v_mfma_f32_16x16x32_bf16 v[70:73], v[158:161], v[206:209], v[70:73]
	v_mfma_f32_16x16x32_bf16 v[66:69], v[174:177], v[206:209], v[66:69]
	v_mfma_f32_16x16x32_bf16 v[118:121], v[170:173], v[186:189], v[118:121]
	v_mfma_f32_16x16x32_bf16 v[114:117], v[178:181], v[186:189], v[114:117]
	v_mfma_f32_16x16x32_bf16 v[102:105], v[170:173], v[194:197], v[102:105]
	v_mfma_f32_16x16x32_bf16 v[98:101], v[178:181], v[194:197], v[98:101]
	v_mfma_f32_16x16x32_bf16 v[86:89], v[170:173], v[202:205], v[86:89]
	v_mfma_f32_16x16x32_bf16 v[82:85], v[178:181], v[202:205], v[82:85]
	v_mfma_f32_16x16x32_bf16 v[70:73], v[170:173], v[210:213], v[70:73]
	v_mfma_f32_16x16x32_bf16 v[66:69], v[178:181], v[210:213], v[66:69]
	s_setprio 2
	s_barrier
; #define PG8_STAGE(bufoff, gbase, voff) do { _Pragma("unroll") for (int _i = 0; _i < 2; ++_i) \
;         __builtin_amdgcn_global_load_lds((const unsigned*)((const char*)(gbase) + (voff)[_i]), (LAS unsigned*)(lds + (bufoff) + ldsw + _i * 8192), 16, 0, 0); } while (0)
; #define PG8_LDA(dst, b, h) do { _Pragma("unroll") for (int m = 0; m < 4; ++m) _Pragma("unroll") for (int k = 0; k < 2; ++k) dst[m][k] = *(const LAS bf16x8*)(lds + PG8_SA(b, h) + aoff + m * 2048 + k * 1024); } while (0)
; #define PG8_MMA(ai, bj, At, Bt) do { __builtin_amdgcn_s_setprio(1); _Pragma("unroll") for (int m = 0; m < 4; ++m) _Pragma("unroll") for (int n = 0; n < 2; ++n) _Pragma("unroll") for (int k = 0; k < 2; ++k) \
;         acc[ai][bj][m][n] = __builtin_amdgcn_mfma_f32_16x16x32_bf16(Bt[n][k], At[m][k], acc[ai][bj][m][n], 0, 0, 0); __builtin_amdgcn_s_setprio(0); } while (0)
; #define PG8_WAIT_V(n) asm volatile("s_waitcnt vmcnt(" #n ")" ::: "memory")
; #define PG8_WAIT_L(n) asm volatile("s_waitcnt lgkmcnt(" #n ")" ::: "memory")
; #define PG8_BAR __builtin_amdgcn_s_barrier()
; #define PG8_SCHED __builtin_amdgcn_sched_barrier(0)
; template <class Epi>
; __device__ __forceinline__ void gemm_phase(LAS unsigned char* lds, const Gemm g, int G, int c, const Epi& E) {
;     ...
;         for (int t = 0; t < nt; t += 2) {
;     ...
;             PG8_LDA(At, 1, 1); PG8_STAGE(PG8_SB(1, 0), b3, voffB); PG8_STAGE(PG8_SB(1, 1), b3 + hstepB, voffB); PG8_STAGE(PG8_SA(1, 0), a3, voffA);
;             PG8_WAIT_V(8); PG8_WAIT_L(0); PG8_BAR; PG8_MMA(1, 0, At, B0); PG8_MMA(1, 1, At, B1); PG8_BAR; PG8_SCHED;
	s_mov_b32 m0, s96
	v_lshl_add_u64 v[162:163], v[162:163], 0, s[18:19]
	ds_read_b128 v[182:185], v168 offset:49152
	ds_read_b128 v[186:189], v168 offset:50176
	ds_read_b128 v[190:193], v168 offset:51200
	ds_read_b128 v[194:197], v168 offset:52224
	ds_read_b128 v[198:201], v168 offset:53248
	ds_read_b128 v[202:205], v168 offset:54272
	ds_read_b128 v[206:209], v168 offset:55296
	ds_read_b128 v[210:213], v168 offset:56320
	global_load_lds_dwordx4 v[162:163], off
	v_lshl_add_u64 v[162:163], v[214:215], 0, s[18:19]
	s_mov_b32 m0, s39
	s_nop 0
	global_load_lds_dwordx4 v[162:163], off
	v_lshl_add_u64 v[162:163], s[54:55], 0, v[134:135]
	s_mov_b32 m0, s95
	s_nop 0
	global_load_lds_dwordx4 v[162:163], off
	v_lshl_add_u64 v[162:163], s[54:55], 0, v[130:131]
	s_mov_b32 m0, s38
	s_nop 0
	global_load_lds_dwordx4 v[162:163], off
	v_lshl_add_u64 v[162:163], v[216:217], 0, s[18:19]
	s_mov_b32 m0, s84
	s_nop 0
	global_load_lds_dwordx4 v[162:163], off
	v_lshl_add_u64 v[162:163], v[218:219], 0, s[18:19]
	s_mov_b32 m0, s85
	s_nop 0
	global_load_lds_dwordx4 v[162:163], off
	s_waitcnt vmcnt(8)
	s_waitcnt lgkmcnt(0)
	s_barrier
	s_setprio 0
	s_waitcnt lgkmcnt(0)
	v_mfma_f32_16x16x32_bf16 v[62:65], v[142:145], v[182:185], v[62:65]
	v_mfma_f32_16x16x32_bf16 v[58:61], v[150:153], v[182:185], v[58:61]
	v_mfma_f32_16x16x32_bf16 v[46:49], v[142:145], v[190:193], v[46:49]
	v_mfma_f32_16x16x32_bf16 v[42:45], v[150:153], v[190:193], v[42:45]
	v_mfma_f32_16x16x32_bf16 v[30:33], v[142:145], v[198:201], v[30:33]
	v_mfma_f32_16x16x32_bf16 v[26:29], v[150:153], v[198:201], v[26:29]
	v_mfma_f32_16x16x32_bf16 v[14:17], v[142:145], v[206:209], v[14:17]
	v_mfma_f32_16x16x32_bf16 v[10:13], v[150:153], v[206:209], v[10:13]
	v_mfma_f32_16x16x32_bf16 v[62:65], v[146:149], v[186:189], v[62:65]
	v_mfma_f32_16x16x32_bf16 v[58:61], v[154:157], v[186:189], v[58:61]
	v_mfma_f32_16x16x32_bf16 v[46:49], v[146:149], v[194:197], v[46:49]
	v_mfma_f32_16x16x32_bf16 v[42:45], v[154:157], v[194:197], v[42:45]
	v_mfma_f32_16x16x32_bf16 v[30:33], v[146:149], v[202:205], v[30:33]
	v_mfma_f32_16x16x32_bf16 v[26:29], v[154:157], v[202:205], v[26:29]
	v_mfma_f32_16x16x32_bf16 v[14:17], v[146:149], v[210:213], v[14:17]
	v_mfma_f32_16x16x32_bf16 v[10:13], v[154:157], v[210:213], v[10:13]
	s_setprio 2
	s_setprio 0
	v_mfma_f32_16x16x32_bf16 v[54:57], v[158:161], v[182:185], v[54:57]
	v_mfma_f32_16x16x32_bf16 v[50:53], v[174:177], v[182:185], v[50:53]
	v_mfma_f32_16x16x32_bf16 v[38:41], v[158:161], v[190:193], v[38:41]
	v_mfma_f32_16x16x32_bf16 v[34:37], v[174:177], v[190:193], v[34:37]
	v_mfma_f32_16x16x32_bf16 v[22:25], v[158:161], v[198:201], v[22:25]
	v_mfma_f32_16x16x32_bf16 v[18:21], v[174:177], v[198:201], v[18:21]
	v_mfma_f32_16x16x32_bf16 v[6:9], v[158:161], v[206:209], v[6:9]
	v_mfma_f32_16x16x32_bf16 v[2:5], v[174:177], v[206:209], v[2:5]
	v_mfma_f32_16x16x32_bf16 v[54:57], v[170:173], v[186:189], v[54:57]
	v_mfma_f32_16x16x32_bf16 v[50:53], v[178:181], v[186:189], v[50:53]
	v_mfma_f32_16x16x32_bf16 v[38:41], v[170:173], v[194:197], v[38:41]
	v_mfma_f32_16x16x32_bf16 v[34:37], v[178:181], v[194:197], v[34:37]
	v_mfma_f32_16x16x32_bf16 v[22:25], v[170:173], v[202:205], v[22:25]
	v_mfma_f32_16x16x32_bf16 v[18:21], v[178:181], v[202:205], v[18:21]
	v_mfma_f32_16x16x32_bf16 v[6:9], v[170:173], v[210:213], v[6:9]
	v_mfma_f32_16x16x32_bf16 v[2:5], v[178:181], v[210:213], v[2:5]
	s_setprio 2
	s_barrier
	s_movk_i32 s38, 0x100
	s_andn2_b64 vcc, exec, s[4:5]
	s_mov_b64 s[54:55], -1
	s_mov_b64 s[4:5], 0
	s_cbranch_vccz .LBB0_594

; #define PG8_STAGE(bufoff, gbase, voff) do { _Pragma("unroll") for (int _i = 0; _i < 2; ++_i) \
;         __builtin_amdgcn_global_load_lds((const unsigned*)((const char*)(gbase) + (voff)[_i]), (LAS unsigned*)(lds + (bufoff) + ldsw + _i * 8192), 16, 0, 0); } while (0)
; #define PG8_LDA(dst, b, h) do { _Pragma("unroll") for (int m = 0; m < 4; ++m) _Pragma("unroll") for (int k = 0; k < 2; ++k) dst[m][k] = *(const LAS bf16x8*)(lds + PG8_SA(b, h) + aoff + m * 2048 + k * 1024); } while (0)
; #define PG8_LDB(dst, b, h) do { _Pragma("unroll") for (int n = 0; n < 2; ++n) _Pragma("unroll") for (int k = 0; k < 2; ++k) dst[n][k] = *(const LAS bf16x8*)(lds + PG8_SB(b, h) + boff + n * 2048 + k * 1024); } while (0)
; #define PG8_MMA(ai, bj, At, Bt) do { __builtin_amdgcn_s_setprio(1); _Pragma("unroll") for (int m = 0; m < 4; ++m) _Pragma("unroll") for (int n = 0; n < 2; ++n) _Pragma("unroll") for (int k = 0; k < 2; ++k) \
;         acc[ai][bj][m][n] = __builtin_amdgcn_mfma_f32_16x16x32_bf16(Bt[n][k], At[m][k], acc[ai][bj][m][n], 0, 0, 0); __builtin_amdgcn_s_setprio(0); } while (0)
; #define PG8_WAIT_V(n) asm volatile("s_waitcnt vmcnt(" #n ")" ::: "memory")
; #define PG8_WAIT_L(n) asm volatile("s_waitcnt lgkmcnt(" #n ")" ::: "memory")
; template <class Epi>
; __device__ __forceinline__ void gemm_phase(LAS unsigned char* lds, const Gemm g, int G, int c, const Epi& E) {
;     ...
; #pragma unroll
;     for (int a = 0; a < 2; ++a)
; #pragma unroll
;         for (int b = 0; b < 2; ++b)
; #pragma unroll
;             for (int m = 0; m < 4; ++m)
; #pragma unroll
;                 for (int n = 0; n < 2; ++n) acc[a][b][m][n] = (f32x4){0.f, 0.f, 0.f, 0.f};
;     ...
;             const bool last = (t == nt - 2);
;             const char* a1 = cA + (size_t)(t + 1) * kstep;
;             const char* a2 = last ? nA : cA + (size_t)(t + 2) * kstep; const char* b2 = last ? nB : cB + (size_t)(t + 2) * kstep;
;             const char* a3 = a2 + kstep; const char* b3 = b2 + kstep;
;             PG8_LDB(B0, 0, 0); PG8_LDB(B1, 0, 1); PG8_SCHED; PG8_LDA(At, 0, 0); PG8_STAGE(PG8_SA(1, 1), a1 + hstepA, voffA);
;             PG8_WAIT_V(8); PG8_WAIT_L(0); PG8_BAR; PG8_MMA(0, 0, At, B0); PG8_MMA(0, 1, At, B1); PG8_BAR; PG8_SCHED;
;             PG8_LDA(At, 0, 1); PG8_STAGE(PG8_SB(0, 0), b2, voffB); PG8_STAGE(PG8_SB(0, 1), b2 + hstepB, voffB); PG8_STAGE(PG8_SA(0, 0), a2, voffA);
.LBB0_764:
	s_ashr_i32 s15, s14, 31
	s_lshl_b64 s[18:19], s[14:15], 21
	s_add_u32 s18, s57, s18
	s_addc_u32 s19, s58, s19
	s_and_b64 s[24:25], s[2:3], exec
	s_cselect_b32 s15, s19, s45
	s_cselect_b32 s78, s18, s44
	s_ashr_i32 s11, s10, 31
	s_lshl_b64 s[24:25], s[10:11], 21
	s_add_u32 s11, s59, s24
	s_addc_u32 s33, s60, s25
	s_ashr_i32 s13, s12, 31
	s_lshl_b64 s[24:25], s[12:13], 21
	s_add_u32 s24, s11, s24
	s_addc_u32 s25, s33, s25
	s_and_b64 s[52:53], s[2:3], exec
	s_cselect_b32 s11, s25, s47
	s_cselect_b32 s13, s24, s46
	s_add_u32 s44, s44, 0x100080
	s_addc_u32 s45, s45, 0
	s_add_u32 s81, s46, 0x100
	s_addc_u32 s82, s47, 0
	s_mov_b32 s83, -2
	ds_read_b128 v[146:149], v152
	ds_read_b128 v[156:159], v152 offset:1024
	ds_read_b128 v[160:163], v152 offset:2048
	ds_read_b128 v[164:167], v152 offset:3072
	ds_read_b128 v[168:171], v153
	ds_read_b128 v[172:175], v153 offset:1024
	ds_read_b128 v[176:179], v153 offset:2048
	ds_read_b128 v[180:183], v153 offset:3072
	s_add_u32 s33, s44, 0xfff00080
	s_addc_u32 s46, s45, -1
	s_cmp_eq_u32 s83, 60
	s_cselect_b32 s53, s15, s46
	s_cselect_b32 s52, s78, s33
	s_cselect_b32 s47, s11, s82
	s_cselect_b32 s46, s13, s81
	v_lshl_add_u64 v[216:217], s[44:45], 0, v[138:139]
	s_add_i32 m0, s17, 0xc000
	ds_read_b128 v[184:187], v154
	ds_read_b128 v[188:191], v154 offset:1024
	ds_read_b128 v[192:195], v154 offset:2048
	ds_read_b128 v[196:199], v154 offset:3072
	ds_read_b128 v[200:203], v154 offset:4096
	ds_read_b128 v[204:207], v154 offset:5120
	ds_read_b128 v[208:211], v154 offset:6144
	ds_read_b128 v[212:215], v154 offset:7168
	global_load_lds_dwordx4 v[216:217], off
	v_lshl_add_u64 v[216:217], s[44:45], 0, v[140:141]
	s_add_i32 m0, s17, 0xe000
	s_nop 0
	global_load_lds_dwordx4 v[216:217], off
	s_waitcnt vmcnt(8)
	s_waitcnt lgkmcnt(0)
	s_barrier
	s_setprio 0
	s_waitcnt lgkmcnt(0)
	v_mfma_f32_16x16x32_bf16 v[126:129], v[146:149], v[184:187], 0
	v_mfma_f32_16x16x32_bf16 v[122:125], v[160:163], v[184:187], 0
	v_mfma_f32_16x16x32_bf16 v[118:121], v[146:149], v[192:195], 0
	v_mfma_f32_16x16x32_bf16 v[110:113], v[160:163], v[192:195], 0
	v_mfma_f32_16x16x32_bf16 v[102:105], v[146:149], v[200:203], 0
	v_mfma_f32_16x16x32_bf16 v[94:97], v[160:163], v[200:203], 0
	v_mfma_f32_16x16x32_bf16 v[86:89], v[146:149], v[208:211], 0
	v_mfma_f32_16x16x32_bf16 v[78:81], v[160:163], v[208:211], 0
	v_mfma_f32_16x16x32_bf16 v[126:129], v[156:159], v[188:191], v[126:129]
	v_mfma_f32_16x16x32_bf16 v[122:125], v[164:167], v[188:191], v[122:125]
	v_mfma_f32_16x16x32_bf16 v[118:121], v[156:159], v[196:199], v[118:121]
	v_mfma_f32_16x16x32_bf16 v[110:113], v[164:167], v[196:199], v[110:113]
	v_mfma_f32_16x16x32_bf16 v[102:105], v[156:159], v[204:207], v[102:105]
	v_mfma_f32_16x16x32_bf16 v[94:97], v[164:167], v[204:207], v[94:97]
	v_mfma_f32_16x16x32_bf16 v[86:89], v[156:159], v[212:215], v[86:89]
	v_mfma_f32_16x16x32_bf16 v[78:81], v[164:167], v[212:215], v[78:81]
	s_setprio 2
	s_setprio 0
	v_mfma_f32_16x16x32_bf16 v[114:117], v[168:171], v[184:187], 0
	v_mfma_f32_16x16x32_bf16 v[106:109], v[176:179], v[184:187], 0
	v_mfma_f32_16x16x32_bf16 v[98:101], v[168:171], v[192:195], 0
	v_mfma_f32_16x16x32_bf16 v[90:93], v[176:179], v[192:195], 0
	v_mfma_f32_16x16x32_bf16 v[82:85], v[168:171], v[200:203], 0
	v_mfma_f32_16x16x32_bf16 v[74:77], v[176:179], v[200:203], 0
	v_mfma_f32_16x16x32_bf16 v[70:73], v[168:171], v[208:211], 0
	v_mfma_f32_16x16x32_bf16 v[66:69], v[176:179], v[208:211], 0
	v_mfma_f32_16x16x32_bf16 v[114:117], v[172:175], v[188:191], v[114:117]
	v_mfma_f32_16x16x32_bf16 v[106:109], v[180:183], v[188:191], v[106:109]
	v_mfma_f32_16x16x32_bf16 v[98:101], v[172:175], v[196:199], v[98:101]
	v_mfma_f32_16x16x32_bf16 v[90:93], v[180:183], v[196:199], v[90:93]
	v_mfma_f32_16x16x32_bf16 v[82:85], v[172:175], v[204:207], v[82:85]
	v_mfma_f32_16x16x32_bf16 v[74:77], v[180:183], v[204:207], v[74:77]
	v_mfma_f32_16x16x32_bf16 v[70:73], v[172:175], v[212:215], v[70:73]
	v_mfma_f32_16x16x32_bf16 v[66:69], v[180:183], v[212:215], v[66:69]
	s_setprio 2
	s_barrier
	s_add_i32 s33, s72, s61
	v_lshl_add_u64 v[216:217], s[46:47], 0, v[134:135]
	s_mov_b32 m0, s33
	ds_read_b128 v[184:187], v154 offset:16384
	ds_read_b128 v[188:191], v154 offset:17408
	ds_read_b128 v[192:195], v154 offset:18432
	ds_read_b128 v[196:199], v154 offset:19456
	ds_read_b128 v[200:203], v154 offset:20480
	ds_read_b128 v[204:207], v154 offset:21504
	ds_read_b128 v[208:211], v154 offset:22528
	ds_read_b128 v[212:215], v154 offset:23552
	global_load_lds_dwordx4 v[216:217], off
	s_add_i32 m0, s33, 0x2000
	s_add_u32 s62, s46, 0x100000
	v_lshl_add_u64 v[218:219], s[46:47], 0, v[130:131]
	s_addc_u32 s63, s47, 0
	s_add_i32 s33, s73, s61
	global_load_lds_dwordx4 v[218:219], off
	v_lshl_add_u64 v[220:221], s[62:63], 0, v[134:135]
	s_mov_b32 m0, s33
	v_lshl_add_u64 v[224:225], s[52:53], 0, v[132:133]
	global_load_lds_dwordx4 v[220:221], off
	v_lshl_add_u64 v[220:221], s[62:63], 0, v[130:131]
	s_add_i32 m0, s33, 0x2000
	s_nop 0
	global_load_lds_dwordx4 v[220:221], off
	v_lshl_add_u64 v[220:221], s[52:53], 0, v[136:137]
	s_mov_b32 m0, s17
	s_nop 0
	global_load_lds_dwordx4 v[220:221], off
	s_mov_b32 m0, s39
	s_nop 0
	global_load_lds_dwordx4 v[224:225], off
	s_waitcnt vmcnt(8)
	s_waitcnt lgkmcnt(0)
	s_barrier
; #define PG8_STAGE(bufoff, gbase, voff) do { _Pragma("unroll") for (int _i = 0; _i < 2; ++_i) \
;         __builtin_amdgcn_global_load_lds((const unsigned*)((const char*)(gbase) + (voff)[_i]), (LAS unsigned*)(lds + (bufoff) + ldsw + _i * 8192), 16, 0, 0); } while (0)
; #define PG8_LDA(dst, b, h) do { _Pragma("unroll") for (int m = 0; m < 4; ++m) _Pragma("unroll") for (int k = 0; k < 2; ++k) dst[m][k] = *(const LAS bf16x8*)(lds + PG8_SA(b, h) + aoff + m * 2048 + k * 1024); } while (0)
; #define PG8_LDB(dst, b, h) do { _Pragma("unroll") for (int n = 0; n < 2; ++n) _Pragma("unroll") for (int k = 0; k < 2; ++k) dst[n][k] = *(const LAS bf16x8*)(lds + PG8_SB(b, h) + boff + n * 2048 + k * 1024); } while (0)
; #define PG8_MMA(ai, bj, At, Bt) do { __builtin_amdgcn_s_setprio(1); _Pragma("unroll") for (int m = 0; m < 4; ++m) _Pragma("unroll") for (int n = 0; n < 2; ++n) _Pragma("unroll") for (int k = 0; k < 2; ++k) \
;         acc[ai][bj][m][n] = __builtin_amdgcn_mfma_f32_16x16x32_bf16(Bt[n][k], At[m][k], acc[ai][bj][m][n], 0, 0, 0); __builtin_amdgcn_s_setprio(0); } while (0)
; #define PG8_WAIT_V(n) asm volatile("s_waitcnt vmcnt(" #n ")" ::: "memory")
; #define PG8_WAIT_L(n) asm volatile("s_waitcnt lgkmcnt(" #n ")" ::: "memory")
; #define PG8_BAR __builtin_amdgcn_s_barrier()
; #define PG8_SCHED __builtin_amdgcn_sched_barrier(0)
; template <class Epi>
; __device__ __forceinline__ void gemm_phase(LAS unsigned char* lds, const Gemm g, int G, int c, const Epi& E) {
;     ...
;             PG8_WAIT_V(8); PG8_WAIT_L(0); PG8_BAR; PG8_MMA(1, 0, At, B0); PG8_MMA(1, 1, At, B1); PG8_BAR; PG8_SCHED;
;             PG8_LDB(B0, 1, 0); PG8_LDB(B1, 1, 1); PG8_SCHED; PG8_LDA(At, 1, 0); PG8_STAGE(PG8_SA(0, 1), a2 + hstepA, voffA);
;             PG8_WAIT_V(8); PG8_WAIT_L(0); PG8_BAR; PG8_MMA(0, 0, At, B0); PG8_MMA(0, 1, At, B1); PG8_BAR; PG8_SCHED;
	s_setprio 0
	s_waitcnt lgkmcnt(0)
	v_mfma_f32_16x16x32_bf16 v[62:65], v[146:149], v[184:187], 0
	v_mfma_f32_16x16x32_bf16 v[58:61], v[160:163], v[184:187], 0
	v_mfma_f32_16x16x32_bf16 v[54:57], v[146:149], v[192:195], 0
	v_mfma_f32_16x16x32_bf16 v[46:49], v[160:163], v[192:195], 0
	v_mfma_f32_16x16x32_bf16 v[38:41], v[146:149], v[200:203], 0
	v_mfma_f32_16x16x32_bf16 v[30:33], v[160:163], v[200:203], 0
	v_mfma_f32_16x16x32_bf16 v[22:25], v[146:149], v[208:211], 0
	v_mfma_f32_16x16x32_bf16 v[14:17], v[160:163], v[208:211], 0
	v_mfma_f32_16x16x32_bf16 v[62:65], v[156:159], v[188:191], v[62:65]
	v_mfma_f32_16x16x32_bf16 v[58:61], v[164:167], v[188:191], v[58:61]
	v_mfma_f32_16x16x32_bf16 v[54:57], v[156:159], v[196:199], v[54:57]
	v_mfma_f32_16x16x32_bf16 v[46:49], v[164:167], v[196:199], v[46:49]
	v_mfma_f32_16x16x32_bf16 v[38:41], v[156:159], v[204:207], v[38:41]
	v_mfma_f32_16x16x32_bf16 v[30:33], v[164:167], v[204:207], v[30:33]
	v_mfma_f32_16x16x32_bf16 v[22:25], v[156:159], v[212:215], v[22:25]
	v_mfma_f32_16x16x32_bf16 v[14:17], v[164:167], v[212:215], v[14:17]
	s_setprio 2
	s_setprio 0
	v_mfma_f32_16x16x32_bf16 v[50:53], v[168:171], v[184:187], 0
	v_mfma_f32_16x16x32_bf16 v[42:45], v[176:179], v[184:187], 0
	v_mfma_f32_16x16x32_bf16 v[34:37], v[168:171], v[192:195], 0
	v_mfma_f32_16x16x32_bf16 v[26:29], v[176:179], v[192:195], 0
	v_mfma_f32_16x16x32_bf16 v[18:21], v[168:171], v[200:203], 0
	v_mfma_f32_16x16x32_bf16 v[10:13], v[176:179], v[200:203], 0
	v_mfma_f32_16x16x32_bf16 v[6:9], v[168:171], v[208:211], 0
	v_mfma_f32_16x16x32_bf16 v[2:5], v[176:179], v[208:211], 0
	v_mfma_f32_16x16x32_bf16 v[50:53], v[172:175], v[188:191], v[50:53]
	v_mfma_f32_16x16x32_bf16 v[42:45], v[180:183], v[188:191], v[42:45]
	v_mfma_f32_16x16x32_bf16 v[34:37], v[172:175], v[196:199], v[34:37]
	v_mfma_f32_16x16x32_bf16 v[26:29], v[180:183], v[196:199], v[26:29]
	v_mfma_f32_16x16x32_bf16 v[18:21], v[172:175], v[204:207], v[18:21]
	v_mfma_f32_16x16x32_bf16 v[10:13], v[180:183], v[204:207], v[10:13]
	v_mfma_f32_16x16x32_bf16 v[6:9], v[172:175], v[212:215], v[6:9]
	v_mfma_f32_16x16x32_bf16 v[2:5], v[180:183], v[212:215], v[2:5]
	s_setprio 2
	s_barrier
	s_add_i32 s33, 0, 0x18000
	v_add_u32_e32 v155, s33, v151
	s_add_i32 s62, 0, 0x1c000
	ds_read_b128 v[146:149], v155
	ds_read_b128 v[156:159], v155 offset:1024
	ds_read_b128 v[160:163], v155 offset:2048
	ds_read_b128 v[164:167], v155 offset:3072
	v_add_u32_e32 v155, s62, v151
	ds_read_b128 v[168:171], v155
	ds_read_b128 v[172:175], v155 offset:1024
	ds_read_b128 v[176:179], v155 offset:2048
	ds_read_b128 v[180:183], v155 offset:3072
	s_add_u32 s52, s52, 0x100000
	s_addc_u32 s53, s53, 0
	s_mov_b32 m0, s43
	v_lshl_add_u64 v[226:227], s[52:53], 0, v[136:137]
	ds_read_b128 v[184:187], v154 offset:32768
	ds_read_b128 v[188:191], v154 offset:33792
	ds_read_b128 v[192:195], v154 offset:34816
	ds_read_b128 v[196:199], v154 offset:35840
	ds_read_b128 v[200:203], v154 offset:36864
	ds_read_b128 v[204:207], v154 offset:37888
	ds_read_b128 v[208:211], v154 offset:38912
	ds_read_b128 v[212:215], v154 offset:39936
	global_load_lds_dwordx4 v[226:227], off
	v_lshl_add_u64 v[226:227], s[52:53], 0, v[132:133]
	s_mov_b32 m0, s66
	s_nop 0
	global_load_lds_dwordx4 v[226:227], off
	s_waitcnt vmcnt(8)
	s_waitcnt lgkmcnt(0)
	s_barrier
	s_setprio 0
	s_waitcnt lgkmcnt(0)
	v_mfma_f32_16x16x32_bf16 v[126:129], v[146:149], v[184:187], v[126:129]
	v_mfma_f32_16x16x32_bf16 v[122:125], v[160:163], v[184:187], v[122:125]
	v_mfma_f32_16x16x32_bf16 v[118:121], v[146:149], v[192:195], v[118:121]
	v_mfma_f32_16x16x32_bf16 v[110:113], v[160:163], v[192:195], v[110:113]
	v_mfma_f32_16x16x32_bf16 v[102:105], v[146:149], v[200:203], v[102:105]
	v_mfma_f32_16x16x32_bf16 v[94:97], v[160:163], v[200:203], v[94:97]
	v_mfma_f32_16x16x32_bf16 v[86:89], v[146:149], v[208:211], v[86:89]
	v_mfma_f32_16x16x32_bf16 v[78:81], v[160:163], v[208:211], v[78:81]
	v_mfma_f32_16x16x32_bf16 v[126:129], v[156:159], v[188:191], v[126:129]
	v_mfma_f32_16x16x32_bf16 v[122:125], v[164:167], v[188:191], v[122:125]
	v_mfma_f32_16x16x32_bf16 v[118:121], v[156:159], v[196:199], v[118:121]
	v_mfma_f32_16x16x32_bf16 v[110:113], v[164:167], v[196:199], v[110:113]
	v_mfma_f32_16x16x32_bf16 v[102:105], v[156:159], v[204:207], v[102:105]
	v_mfma_f32_16x16x32_bf16 v[94:97], v[164:167], v[204:207], v[94:97]
	v_mfma_f32_16x16x32_bf16 v[86:89], v[156:159], v[212:215], v[86:89]
	v_mfma_f32_16x16x32_bf16 v[78:81], v[164:167], v[212:215], v[78:81]
	s_setprio 2
	s_setprio 0
	v_mfma_f32_16x16x32_bf16 v[114:117], v[168:171], v[184:187], v[114:117]
	v_mfma_f32_16x16x32_bf16 v[106:109], v[176:179], v[184:187], v[106:109]
	v_mfma_f32_16x16x32_bf16 v[98:101], v[168:171], v[192:195], v[98:101]
	v_mfma_f32_16x16x32_bf16 v[90:93], v[176:179], v[192:195], v[90:93]
	v_mfma_f32_16x16x32_bf16 v[82:85], v[168:171], v[200:203], v[82:85]
	v_mfma_f32_16x16x32_bf16 v[74:77], v[176:179], v[200:203], v[74:77]
	v_mfma_f32_16x16x32_bf16 v[70:73], v[168:171], v[208:211], v[70:73]
	v_mfma_f32_16x16x32_bf16 v[66:69], v[176:179], v[208:211], v[66:69]
	v_mfma_f32_16x16x32_bf16 v[114:117], v[172:175], v[188:191], v[114:117]
	v_mfma_f32_16x16x32_bf16 v[106:109], v[180:183], v[188:191], v[106:109]
	v_mfma_f32_16x16x32_bf16 v[98:101], v[172:175], v[196:199], v[98:101]
	v_mfma_f32_16x16x32_bf16 v[90:93], v[180:183], v[196:199], v[90:93]
	v_mfma_f32_16x16x32_bf16 v[82:85], v[172:175], v[204:207], v[82:85]
	v_mfma_f32_16x16x32_bf16 v[74:77], v[180:183], v[204:207], v[74:77]
	v_mfma_f32_16x16x32_bf16 v[70:73], v[172:175], v[212:215], v[70:73]
	v_mfma_f32_16x16x32_bf16 v[66:69], v[180:183], v[212:215], v[66:69]
	s_setprio 2
	s_barrier
; #define PG8_STAGE(bufoff, gbase, voff) do { _Pragma("unroll") for (int _i = 0; _i < 2; ++_i) \
;         __builtin_amdgcn_global_load_lds((const unsigned*)((const char*)(gbase) + (voff)[_i]), (LAS unsigned*)(lds + (bufoff) + ldsw + _i * 8192), 16, 0, 0); } while (0)
; #define PG8_LDA(dst, b, h) do { _Pragma("unroll") for (int m = 0; m < 4; ++m) _Pragma("unroll") for (int k = 0; k < 2; ++k) dst[m][k] = *(const LAS bf16x8*)(lds + PG8_SA(b, h) + aoff + m * 2048 + k * 1024); } while (0)
; #define PG8_MMA(ai, bj, At, Bt) do { __builtin_amdgcn_s_setprio(1); _Pragma("unroll") for (int m = 0; m < 4; ++m) _Pragma("unroll") for (int n = 0; n < 2; ++n) _Pragma("unroll") for (int k = 0; k < 2; ++k) \
;         acc[ai][bj][m][n] = __builtin_amdgcn_mfma_f32_16x16x32_bf16(Bt[n][k], At[m][k], acc[ai][bj][m][n], 0, 0, 0); __builtin_amdgcn_s_setprio(0); } while (0)
; #define PG8_WAIT_V(n) asm volatile("s_waitcnt vmcnt(" #n ")" ::: "memory")
; #define PG8_WAIT_L(n) asm volatile("s_waitcnt lgkmcnt(" #n ")" ::: "memory")
; #define PG8_BAR __builtin_amdgcn_s_barrier()
; #define PG8_SCHED __builtin_amdgcn_sched_barrier(0)
; template <class Epi>
; __device__ __forceinline__ void gemm_phase(LAS unsigned char* lds, const Gemm g, int G, int c, const Epi& E) {
;     ...
;         for (int t = 0; t < nt; t += 2) {
;     ...
;             PG8_LDA(At, 1, 1); PG8_STAGE(PG8_SB(1, 0), b3, voffB); PG8_STAGE(PG8_SB(1, 1), b3 + hstepB, voffB); PG8_STAGE(PG8_SA(1, 0), a3, voffA);
;             PG8_WAIT_V(8); PG8_WAIT_L(0); PG8_BAR; PG8_MMA(1, 0, At, B0); PG8_MMA(1, 1, At, B1); PG8_BAR; PG8_SCHED;
	s_add_i32 s33, s33, s61
	v_lshl_add_u64 v[216:217], v[216:217], 0, s[6:7]
	s_mov_b32 m0, s33
	ds_read_b128 v[184:187], v154 offset:49152
	ds_read_b128 v[188:191], v154 offset:50176
	ds_read_b128 v[192:195], v154 offset:51200
	ds_read_b128 v[196:199], v154 offset:52224
	ds_read_b128 v[200:203], v154 offset:53248
	ds_read_b128 v[204:207], v154 offset:54272
	ds_read_b128 v[208:211], v154 offset:55296
	ds_read_b128 v[212:215], v154 offset:56320
	global_load_lds_dwordx4 v[216:217], off
	s_add_i32 m0, s33, 0x2000
	s_add_u32 s46, s46, 0x100080
	v_lshl_add_u64 v[216:217], v[218:219], 0, s[6:7]
	s_addc_u32 s47, s47, 0
	s_add_i32 s33, s62, s61
	global_load_lds_dwordx4 v[216:217], off
	v_lshl_add_u64 v[216:217], s[46:47], 0, v[134:135]
	s_mov_b32 m0, s33
	s_nop 0
	global_load_lds_dwordx4 v[216:217], off
	v_lshl_add_u64 v[216:217], s[46:47], 0, v[130:131]
	s_add_i32 m0, s33, 0x2000
	s_nop 0
	global_load_lds_dwordx4 v[216:217], off
	v_lshl_add_u64 v[216:217], v[220:221], 0, s[6:7]
	s_mov_b32 m0, s70
	s_nop 0
	global_load_lds_dwordx4 v[216:217], off
	v_lshl_add_u64 v[216:217], v[224:225], 0, s[6:7]
	s_mov_b32 m0, s71
	s_nop 0
	global_load_lds_dwordx4 v[216:217], off
	s_waitcnt vmcnt(8)
	s_waitcnt lgkmcnt(0)
	s_barrier
	s_setprio 0
	s_waitcnt lgkmcnt(0)
	v_mfma_f32_16x16x32_bf16 v[62:65], v[146:149], v[184:187], v[62:65]
	v_mfma_f32_16x16x32_bf16 v[58:61], v[160:163], v[184:187], v[58:61]
	v_mfma_f32_16x16x32_bf16 v[54:57], v[146:149], v[192:195], v[54:57]
	v_mfma_f32_16x16x32_bf16 v[46:49], v[160:163], v[192:195], v[46:49]
	v_mfma_f32_16x16x32_bf16 v[38:41], v[146:149], v[200:203], v[38:41]
	v_mfma_f32_16x16x32_bf16 v[30:33], v[160:163], v[200:203], v[30:33]
	v_mfma_f32_16x16x32_bf16 v[22:25], v[146:149], v[208:211], v[22:25]
	v_mfma_f32_16x16x32_bf16 v[14:17], v[160:163], v[208:211], v[14:17]
	v_mfma_f32_16x16x32_bf16 v[62:65], v[156:159], v[188:191], v[62:65]
	v_mfma_f32_16x16x32_bf16 v[58:61], v[164:167], v[188:191], v[58:61]
	v_mfma_f32_16x16x32_bf16 v[54:57], v[156:159], v[196:199], v[54:57]
	v_mfma_f32_16x16x32_bf16 v[46:49], v[164:167], v[196:199], v[46:49]
	v_mfma_f32_16x16x32_bf16 v[38:41], v[156:159], v[204:207], v[38:41]
	v_mfma_f32_16x16x32_bf16 v[30:33], v[164:167], v[204:207], v[30:33]
	v_mfma_f32_16x16x32_bf16 v[22:25], v[156:159], v[212:215], v[22:25]
	v_mfma_f32_16x16x32_bf16 v[14:17], v[164:167], v[212:215], v[14:17]
	s_setprio 2
	s_setprio 0
	v_mfma_f32_16x16x32_bf16 v[50:53], v[168:171], v[184:187], v[50:53]
	v_mfma_f32_16x16x32_bf16 v[42:45], v[176:179], v[184:187], v[42:45]
	v_mfma_f32_16x16x32_bf16 v[34:37], v[168:171], v[192:195], v[34:37]
	v_mfma_f32_16x16x32_bf16 v[26:29], v[176:179], v[192:195], v[26:29]
	v_mfma_f32_16x16x32_bf16 v[18:21], v[168:171], v[200:203], v[18:21]
	v_mfma_f32_16x16x32_bf16 v[10:13], v[176:179], v[200:203], v[10:13]
	v_mfma_f32_16x16x32_bf16 v[6:9], v[168:171], v[208:211], v[6:9]
	v_mfma_f32_16x16x32_bf16 v[2:5], v[176:179], v[208:211], v[2:5]
	v_mfma_f32_16x16x32_bf16 v[50:53], v[172:175], v[188:191], v[50:53]
	v_mfma_f32_16x16x32_bf16 v[42:45], v[180:183], v[188:191], v[42:45]
	v_mfma_f32_16x16x32_bf16 v[34:37], v[172:175], v[196:199], v[34:37]
	v_mfma_f32_16x16x32_bf16 v[26:29], v[180:183], v[196:199], v[26:29]
	v_mfma_f32_16x16x32_bf16 v[18:21], v[172:175], v[204:207], v[18:21]
	v_mfma_f32_16x16x32_bf16 v[10:13], v[180:183], v[204:207], v[10:13]
	v_mfma_f32_16x16x32_bf16 v[6:9], v[172:175], v[212:215], v[6:9]
	v_mfma_f32_16x16x32_bf16 v[2:5], v[180:183], v[212:215], v[2:5]
	s_setprio 2
	s_barrier
	s_add_i32 s83, s83, 2
	s_add_u32 s44, s44, 0x100
	s_addc_u32 s45, s45, 0
	s_add_u32 s81, s81, 0x100
	s_addc_u32 s82, s82, 0
	s_cmp_gt_u32 s83, 61
	s_cbranch_scc0 .LBB0_765

; #define PG8_STAGE(bufoff, gbase, voff) do { _Pragma("unroll") for (int _i = 0; _i < 2; ++_i) \
;         __builtin_amdgcn_global_load_lds((const unsigned*)((const char*)(gbase) + (voff)[_i]), (LAS unsigned*)(lds + (bufoff) + ldsw + _i * 8192), 16, 0, 0); } while (0)
; #define PG8_LDA(dst, b, h) do { _Pragma("unroll") for (int m = 0; m < 4; ++m) _Pragma("unroll") for (int k = 0; k < 2; ++k) dst[m][k] = *(const LAS bf16x8*)(lds + PG8_SA(b, h) + aoff + m * 2048 + k * 1024); } while (0)
; #define PG8_LDB(dst, b, h) do { _Pragma("unroll") for (int n = 0; n < 2; ++n) _Pragma("unroll") for (int k = 0; k < 2; ++k) dst[n][k] = *(const LAS bf16x8*)(lds + PG8_SB(b, h) + boff + n * 2048 + k * 1024); } while (0)
; #define PG8_MMA(ai, bj, At, Bt) do { __builtin_amdgcn_s_setprio(1); _Pragma("unroll") for (int m = 0; m < 4; ++m) _Pragma("unroll") for (int n = 0; n < 2; ++n) _Pragma("unroll") for (int k = 0; k < 2; ++k) \
;         acc[ai][bj][m][n] = __builtin_amdgcn_mfma_f32_16x16x32_bf16(Bt[n][k], At[m][k], acc[ai][bj][m][n], 0, 0, 0); __builtin_amdgcn_s_setprio(0); } while (0)
; #define PG8_WAIT_V(n) asm volatile("s_waitcnt vmcnt(" #n ")" ::: "memory")
; #define PG8_WAIT_L(n) asm volatile("s_waitcnt lgkmcnt(" #n ")" ::: "memory")
; template <class Epi>
; __device__ __forceinline__ void gemm_phase(LAS unsigned char* lds, const Gemm g, int G, int c, const Epi& E) {
;     ...
; #pragma unroll
;     for (int a = 0; a < 2; ++a)
; #pragma unroll
;         for (int b = 0; b < 2; ++b)
; #pragma unroll
;             for (int m = 0; m < 4; ++m)
; #pragma unroll
;                 for (int n = 0; n < 2; ++n) acc[a][b][m][n] = (f32x4){0.f, 0.f, 0.f, 0.f};
;     ...
;             const bool last = (t == nt - 2);
;             const char* a1 = cA + (size_t)(t + 1) * kstep;
;             const char* a2 = last ? nA : cA + (size_t)(t + 2) * kstep; const char* b2 = last ? nB : cB + (size_t)(t + 2) * kstep;
;             const char* a3 = a2 + kstep; const char* b3 = b2 + kstep;
;             PG8_LDB(B0, 0, 0); PG8_LDB(B1, 0, 1); PG8_SCHED; PG8_LDA(At, 0, 0); PG8_STAGE(PG8_SA(1, 1), a1 + hstepA, voffA);
;             PG8_WAIT_V(8); PG8_WAIT_L(0); PG8_BAR; PG8_MMA(0, 0, At, B0); PG8_MMA(0, 1, At, B1); PG8_BAR; PG8_SCHED;
;             PG8_LDA(At, 0, 1); PG8_STAGE(PG8_SB(0, 0), b2, voffB); PG8_STAGE(PG8_SB(0, 1), b2 + hstepB, voffB); PG8_STAGE(PG8_SA(0, 0), a2, voffA);
.LBB0_780:
	s_ashr_i32 s25, s24, 31
	s_lshl_b64 s[42:43], s[24:25], 18
	s_add_u32 s42, s59, s42
	s_addc_u32 s43, s60, s43
	s_and_b64 s[52:53], s[38:39], exec
	s_cselect_b32 s25, s43, s47
	s_cselect_b32 s89, s42, s46
	s_add_u32 s90, s46, 0x100
	s_addc_u32 s91, s47, 0
	s_mov_b32 s92, -2
	s_mov_b64 s[46:47], 0
	ds_read_b128 v[150:153], v146
	ds_read_b128 v[154:157], v146 offset:1024
	ds_read_b128 v[158:161], v146 offset:2048
	ds_read_b128 v[162:165], v146 offset:3072
	ds_read_b128 v[166:169], v147
	ds_read_b128 v[170:173], v147 offset:1024
	ds_read_b128 v[174:177], v147 offset:2048
	ds_read_b128 v[178:181], v147 offset:3072
	s_add_u32 s52, s46, 0x100
	s_addc_u32 s53, s47, 0
	s_add_u32 s33, s90, s46
	s_addc_u32 s55, s91, s47
	s_cmp_eq_u32 s92, 4
	s_cselect_b32 s56, 0, s52
	s_cselect_b32 s57, 0, s53
	s_cselect_b32 s54, s89, s33
	s_cselect_b32 s55, s25, s55
	s_add_u32 s56, s2, s56
	s_addc_u32 s57, s3, s57
	s_mov_b32 m0, s83
	v_lshl_add_u64 v[142:143], v[138:139], 0, s[46:47]
	ds_read_b128 v[182:185], v148
	ds_read_b128 v[186:189], v148 offset:1024
	ds_read_b128 v[190:193], v148 offset:2048
	ds_read_b128 v[194:197], v148 offset:3072
	ds_read_b128 v[198:201], v148 offset:4096
	ds_read_b128 v[202:205], v148 offset:5120
	ds_read_b128 v[206:209], v148 offset:6144
	ds_read_b128 v[210:213], v148 offset:7168
	global_load_lds_dwordx4 v[142:143], off
	v_lshl_add_u64 v[142:143], v[140:141], 0, s[46:47]
	s_mov_b32 m0, s84
	s_nop 0
	global_load_lds_dwordx4 v[142:143], off
	s_waitcnt vmcnt(8)
	s_waitcnt lgkmcnt(0)
	s_barrier
	s_setprio 0
	s_waitcnt lgkmcnt(0)
	v_mfma_f32_16x16x32_bf16 v[126:129], v[150:153], v[182:185], 0
	v_mfma_f32_16x16x32_bf16 v[122:125], v[158:161], v[182:185], 0
	v_mfma_f32_16x16x32_bf16 v[118:121], v[150:153], v[190:193], 0
	v_mfma_f32_16x16x32_bf16 v[110:113], v[158:161], v[190:193], 0
	v_mfma_f32_16x16x32_bf16 v[102:105], v[150:153], v[198:201], 0
	v_mfma_f32_16x16x32_bf16 v[94:97], v[158:161], v[198:201], 0
	v_mfma_f32_16x16x32_bf16 v[86:89], v[150:153], v[206:209], 0
	v_mfma_f32_16x16x32_bf16 v[78:81], v[158:161], v[206:209], 0
	v_mfma_f32_16x16x32_bf16 v[126:129], v[154:157], v[186:189], v[126:129]
	v_mfma_f32_16x16x32_bf16 v[122:125], v[162:165], v[186:189], v[122:125]
	v_mfma_f32_16x16x32_bf16 v[118:121], v[154:157], v[194:197], v[118:121]
	v_mfma_f32_16x16x32_bf16 v[110:113], v[162:165], v[194:197], v[110:113]
	v_mfma_f32_16x16x32_bf16 v[102:105], v[154:157], v[202:205], v[102:105]
	v_mfma_f32_16x16x32_bf16 v[94:97], v[162:165], v[202:205], v[94:97]
	v_mfma_f32_16x16x32_bf16 v[86:89], v[154:157], v[210:213], v[86:89]
	v_mfma_f32_16x16x32_bf16 v[78:81], v[162:165], v[210:213], v[78:81]
	s_setprio 2
	s_setprio 0
	v_mfma_f32_16x16x32_bf16 v[114:117], v[166:169], v[182:185], 0
	v_mfma_f32_16x16x32_bf16 v[106:109], v[174:177], v[182:185], 0
	v_mfma_f32_16x16x32_bf16 v[98:101], v[166:169], v[190:193], 0
	v_mfma_f32_16x16x32_bf16 v[90:93], v[174:177], v[190:193], 0
	v_mfma_f32_16x16x32_bf16 v[82:85], v[166:169], v[198:201], 0
	v_mfma_f32_16x16x32_bf16 v[74:77], v[174:177], v[198:201], 0
	v_mfma_f32_16x16x32_bf16 v[70:73], v[166:169], v[206:209], 0
	v_mfma_f32_16x16x32_bf16 v[66:69], v[174:177], v[206:209], 0
	v_mfma_f32_16x16x32_bf16 v[114:117], v[170:173], v[186:189], v[114:117]
	v_mfma_f32_16x16x32_bf16 v[106:109], v[178:181], v[186:189], v[106:109]
	v_mfma_f32_16x16x32_bf16 v[98:101], v[170:173], v[194:197], v[98:101]
	v_mfma_f32_16x16x32_bf16 v[90:93], v[178:181], v[194:197], v[90:93]
	v_mfma_f32_16x16x32_bf16 v[82:85], v[170:173], v[202:205], v[82:85]
	v_mfma_f32_16x16x32_bf16 v[74:77], v[178:181], v[202:205], v[74:77]
	v_mfma_f32_16x16x32_bf16 v[70:73], v[170:173], v[210:213], v[70:73]
	v_mfma_f32_16x16x32_bf16 v[66:69], v[178:181], v[210:213], v[66:69]
	s_setprio 2
	s_barrier
	s_mov_b32 m0, s85
	v_lshl_add_u64 v[142:143], s[54:55], 0, v[134:135]
	s_add_u32 s46, s54, 0x20000
	ds_read_b128 v[182:185], v148 offset:16384
	ds_read_b128 v[186:189], v148 offset:17408
	ds_read_b128 v[190:193], v148 offset:18432
	ds_read_b128 v[194:197], v148 offset:19456
	ds_read_b128 v[198:201], v148 offset:20480
	ds_read_b128 v[202:205], v148 offset:21504
	ds_read_b128 v[206:209], v148 offset:22528
	ds_read_b128 v[210:213], v148 offset:23552
	global_load_lds_dwordx4 v[142:143], off
	v_lshl_add_u64 v[214:215], s[54:55], 0, v[130:131]
	s_mov_b32 m0, s86
	s_addc_u32 s47, s55, 0
	global_load_lds_dwordx4 v[214:215], off
	v_lshl_add_u64 v[216:217], s[46:47], 0, v[134:135]
	s_mov_b32 m0, s87
	v_lshl_add_u64 v[218:219], s[56:57], 0, v[132:133]
	global_load_lds_dwordx4 v[216:217], off
	v_lshl_add_u64 v[216:217], s[46:47], 0, v[130:131]
	s_mov_b32 m0, s88
	s_nop 0
	global_load_lds_dwordx4 v[216:217], off
	v_lshl_add_u64 v[216:217], s[56:57], 0, v[136:137]
	s_mov_b32 m0, s45
	s_nop 0
	global_load_lds_dwordx4 v[216:217], off
	s_mov_b32 m0, s61
	s_nop 0
	global_load_lds_dwordx4 v[218:219], off
	s_waitcnt vmcnt(8)
	s_waitcnt lgkmcnt(0)
	s_barrier
; #define PG8_STAGE(bufoff, gbase, voff) do { _Pragma("unroll") for (int _i = 0; _i < 2; ++_i) \
;         __builtin_amdgcn_global_load_lds((const unsigned*)((const char*)(gbase) + (voff)[_i]), (LAS unsigned*)(lds + (bufoff) + ldsw + _i * 8192), 16, 0, 0); } while (0)
; #define PG8_LDA(dst, b, h) do { _Pragma("unroll") for (int m = 0; m < 4; ++m) _Pragma("unroll") for (int k = 0; k < 2; ++k) dst[m][k] = *(const LAS bf16x8*)(lds + PG8_SA(b, h) + aoff + m * 2048 + k * 1024); } while (0)
; #define PG8_LDB(dst, b, h) do { _Pragma("unroll") for (int n = 0; n < 2; ++n) _Pragma("unroll") for (int k = 0; k < 2; ++k) dst[n][k] = *(const LAS bf16x8*)(lds + PG8_SB(b, h) + boff + n * 2048 + k * 1024); } while (0)
; #define PG8_MMA(ai, bj, At, Bt) do { __builtin_amdgcn_s_setprio(1); _Pragma("unroll") for (int m = 0; m < 4; ++m) _Pragma("unroll") for (int n = 0; n < 2; ++n) _Pragma("unroll") for (int k = 0; k < 2; ++k) \
;         acc[ai][bj][m][n] = __builtin_amdgcn_mfma_f32_16x16x32_bf16(Bt[n][k], At[m][k], acc[ai][bj][m][n], 0, 0, 0); __builtin_amdgcn_s_setprio(0); } while (0)
; #define PG8_WAIT_V(n) asm volatile("s_waitcnt vmcnt(" #n ")" ::: "memory")
; #define PG8_WAIT_L(n) asm volatile("s_waitcnt lgkmcnt(" #n ")" ::: "memory")
; #define PG8_BAR __builtin_amdgcn_s_barrier()
; #define PG8_SCHED __builtin_amdgcn_sched_barrier(0)
; template <class Epi>
; __device__ __forceinline__ void gemm_phase(LAS unsigned char* lds, const Gemm g, int G, int c, const Epi& E) {
;     ...
;             PG8_WAIT_V(8); PG8_WAIT_L(0); PG8_BAR; PG8_MMA(1, 0, At, B0); PG8_MMA(1, 1, At, B1); PG8_BAR; PG8_SCHED;
;             PG8_LDB(B0, 1, 0); PG8_LDB(B1, 1, 1); PG8_SCHED; PG8_LDA(At, 1, 0); PG8_STAGE(PG8_SA(0, 1), a2 + hstepA, voffA);
;             PG8_WAIT_V(8); PG8_WAIT_L(0); PG8_BAR; PG8_MMA(0, 0, At, B0); PG8_MMA(0, 1, At, B1); PG8_BAR; PG8_SCHED;
	s_setprio 0
	s_waitcnt lgkmcnt(0)
	v_mfma_f32_16x16x32_bf16 v[62:65], v[150:153], v[182:185], 0
	v_mfma_f32_16x16x32_bf16 v[58:61], v[158:161], v[182:185], 0
	v_mfma_f32_16x16x32_bf16 v[54:57], v[150:153], v[190:193], 0
	v_mfma_f32_16x16x32_bf16 v[46:49], v[158:161], v[190:193], 0
	v_mfma_f32_16x16x32_bf16 v[38:41], v[150:153], v[198:201], 0
	v_mfma_f32_16x16x32_bf16 v[30:33], v[158:161], v[198:201], 0
	v_mfma_f32_16x16x32_bf16 v[22:25], v[150:153], v[206:209], 0
	v_mfma_f32_16x16x32_bf16 v[14:17], v[158:161], v[206:209], 0
	v_mfma_f32_16x16x32_bf16 v[62:65], v[154:157], v[186:189], v[62:65]
	v_mfma_f32_16x16x32_bf16 v[58:61], v[162:165], v[186:189], v[58:61]
	v_mfma_f32_16x16x32_bf16 v[54:57], v[154:157], v[194:197], v[54:57]
	v_mfma_f32_16x16x32_bf16 v[46:49], v[162:165], v[194:197], v[46:49]
	v_mfma_f32_16x16x32_bf16 v[38:41], v[154:157], v[202:205], v[38:41]
	v_mfma_f32_16x16x32_bf16 v[30:33], v[162:165], v[202:205], v[30:33]
	v_mfma_f32_16x16x32_bf16 v[22:25], v[154:157], v[210:213], v[22:25]
	v_mfma_f32_16x16x32_bf16 v[14:17], v[162:165], v[210:213], v[14:17]
	s_setprio 2
	s_setprio 0
	v_mfma_f32_16x16x32_bf16 v[50:53], v[166:169], v[182:185], 0
	v_mfma_f32_16x16x32_bf16 v[42:45], v[174:177], v[182:185], 0
	v_mfma_f32_16x16x32_bf16 v[34:37], v[166:169], v[190:193], 0
	v_mfma_f32_16x16x32_bf16 v[26:29], v[174:177], v[190:193], 0
	v_mfma_f32_16x16x32_bf16 v[18:21], v[166:169], v[198:201], 0
	v_mfma_f32_16x16x32_bf16 v[10:13], v[174:177], v[198:201], 0
	v_mfma_f32_16x16x32_bf16 v[6:9], v[166:169], v[206:209], 0
	v_mfma_f32_16x16x32_bf16 v[2:5], v[174:177], v[206:209], 0
	v_mfma_f32_16x16x32_bf16 v[50:53], v[170:173], v[186:189], v[50:53]
	v_mfma_f32_16x16x32_bf16 v[42:45], v[178:181], v[186:189], v[42:45]
	v_mfma_f32_16x16x32_bf16 v[34:37], v[170:173], v[194:197], v[34:37]
	v_mfma_f32_16x16x32_bf16 v[26:29], v[178:181], v[194:197], v[26:29]
	v_mfma_f32_16x16x32_bf16 v[18:21], v[170:173], v[202:205], v[18:21]
	v_mfma_f32_16x16x32_bf16 v[10:13], v[178:181], v[202:205], v[10:13]
	v_mfma_f32_16x16x32_bf16 v[6:9], v[170:173], v[210:213], v[6:9]
	v_mfma_f32_16x16x32_bf16 v[2:5], v[178:181], v[210:213], v[2:5]
	s_setprio 2
	s_barrier
	s_add_i32 s33, 0, 0x18000
	v_add_u32_e32 v149, s33, v145
	s_add_i32 s62, 0, 0x1c000
	ds_read_b128 v[150:153], v149
	ds_read_b128 v[154:157], v149 offset:1024
	ds_read_b128 v[158:161], v149 offset:2048
	ds_read_b128 v[162:165], v149 offset:3072
	v_add_u32_e32 v149, s62, v145
	ds_read_b128 v[166:169], v149
	ds_read_b128 v[170:173], v149 offset:1024
	ds_read_b128 v[174:177], v149 offset:2048
	ds_read_b128 v[178:181], v149 offset:3072
	s_add_u32 s46, s56, 0x20000
	s_addc_u32 s47, s57, 0
	s_mov_b32 m0, s66
	v_lshl_add_u64 v[220:221], s[46:47], 0, v[136:137]
	ds_read_b128 v[182:185], v148 offset:32768
	ds_read_b128 v[186:189], v148 offset:33792
	ds_read_b128 v[190:193], v148 offset:34816
	ds_read_b128 v[194:197], v148 offset:35840
	ds_read_b128 v[198:201], v148 offset:36864
	ds_read_b128 v[202:205], v148 offset:37888
	ds_read_b128 v[206:209], v148 offset:38912
	ds_read_b128 v[210:213], v148 offset:39936
	global_load_lds_dwordx4 v[220:221], off
	v_lshl_add_u64 v[220:221], s[46:47], 0, v[132:133]
	s_mov_b32 m0, s67
	s_nop 0
	global_load_lds_dwordx4 v[220:221], off
	s_waitcnt vmcnt(8)
	s_waitcnt lgkmcnt(0)
	s_barrier
	s_setprio 0
	s_waitcnt lgkmcnt(0)
	v_mfma_f32_16x16x32_bf16 v[126:129], v[150:153], v[182:185], v[126:129]
	v_mfma_f32_16x16x32_bf16 v[122:125], v[158:161], v[182:185], v[122:125]
	v_mfma_f32_16x16x32_bf16 v[118:121], v[150:153], v[190:193], v[118:121]
	v_mfma_f32_16x16x32_bf16 v[110:113], v[158:161], v[190:193], v[110:113]
	v_mfma_f32_16x16x32_bf16 v[102:105], v[150:153], v[198:201], v[102:105]
	v_mfma_f32_16x16x32_bf16 v[94:97], v[158:161], v[198:201], v[94:97]
	v_mfma_f32_16x16x32_bf16 v[86:89], v[150:153], v[206:209], v[86:89]
	v_mfma_f32_16x16x32_bf16 v[78:81], v[158:161], v[206:209], v[78:81]
	v_mfma_f32_16x16x32_bf16 v[126:129], v[154:157], v[186:189], v[126:129]
	v_mfma_f32_16x16x32_bf16 v[122:125], v[162:165], v[186:189], v[122:125]
	v_mfma_f32_16x16x32_bf16 v[118:121], v[154:157], v[194:197], v[118:121]
	v_mfma_f32_16x16x32_bf16 v[110:113], v[162:165], v[194:197], v[110:113]
	v_mfma_f32_16x16x32_bf16 v[102:105], v[154:157], v[202:205], v[102:105]
	v_mfma_f32_16x16x32_bf16 v[94:97], v[162:165], v[202:205], v[94:97]
	v_mfma_f32_16x16x32_bf16 v[86:89], v[154:157], v[210:213], v[86:89]
	v_mfma_f32_16x16x32_bf16 v[78:81], v[162:165], v[210:213], v[78:81]
	s_setprio 2
	s_setprio 0
	v_mfma_f32_16x16x32_bf16 v[114:117], v[166:169], v[182:185], v[114:117]
	v_mfma_f32_16x16x32_bf16 v[106:109], v[174:177], v[182:185], v[106:109]
	v_mfma_f32_16x16x32_bf16 v[98:101], v[166:169], v[190:193], v[98:101]
	v_mfma_f32_16x16x32_bf16 v[90:93], v[174:177], v[190:193], v[90:93]
	v_mfma_f32_16x16x32_bf16 v[82:85], v[166:169], v[198:201], v[82:85]
	v_mfma_f32_16x16x32_bf16 v[74:77], v[174:177], v[198:201], v[74:77]
	v_mfma_f32_16x16x32_bf16 v[70:73], v[166:169], v[206:209], v[70:73]
	v_mfma_f32_16x16x32_bf16 v[66:69], v[174:177], v[206:209], v[66:69]
	v_mfma_f32_16x16x32_bf16 v[114:117], v[170:173], v[186:189], v[114:117]
	v_mfma_f32_16x16x32_bf16 v[106:109], v[178:181], v[186:189], v[106:109]
	v_mfma_f32_16x16x32_bf16 v[98:101], v[170:173], v[194:197], v[98:101]
	v_mfma_f32_16x16x32_bf16 v[90:93], v[178:181], v[194:197], v[90:93]
	v_mfma_f32_16x16x32_bf16 v[82:85], v[170:173], v[202:205], v[82:85]
	v_mfma_f32_16x16x32_bf16 v[74:77], v[178:181], v[202:205], v[74:77]
	v_mfma_f32_16x16x32_bf16 v[70:73], v[170:173], v[210:213], v[70:73]
	v_mfma_f32_16x16x32_bf16 v[66:69], v[178:181], v[210:213], v[66:69]
	s_setprio 2
	s_barrier
; #define PG8_STAGE(bufoff, gbase, voff) do { _Pragma("unroll") for (int _i = 0; _i < 2; ++_i) \
;         __builtin_amdgcn_global_load_lds((const unsigned*)((const char*)(gbase) + (voff)[_i]), (LAS unsigned*)(lds + (bufoff) + ldsw + _i * 8192), 16, 0, 0); } while (0)
; #define PG8_LDA(dst, b, h) do { _Pragma("unroll") for (int m = 0; m < 4; ++m) _Pragma("unroll") for (int k = 0; k < 2; ++k) dst[m][k] = *(const LAS bf16x8*)(lds + PG8_SA(b, h) + aoff + m * 2048 + k * 1024); } while (0)
; #define PG8_MMA(ai, bj, At, Bt) do { __builtin_amdgcn_s_setprio(1); _Pragma("unroll") for (int m = 0; m < 4; ++m) _Pragma("unroll") for (int n = 0; n < 2; ++n) _Pragma("unroll") for (int k = 0; k < 2; ++k) \
;         acc[ai][bj][m][n] = __builtin_amdgcn_mfma_f32_16x16x32_bf16(Bt[n][k], At[m][k], acc[ai][bj][m][n], 0, 0, 0); __builtin_amdgcn_s_setprio(0); } while (0)
; #define PG8_WAIT_V(n) asm volatile("s_waitcnt vmcnt(" #n ")" ::: "memory")
; #define PG8_WAIT_L(n) asm volatile("s_waitcnt lgkmcnt(" #n ")" ::: "memory")
; #define PG8_BAR __builtin_amdgcn_s_barrier()
; #define PG8_SCHED __builtin_amdgcn_sched_barrier(0)
; template <class Epi>
; __device__ __forceinline__ void gemm_phase(LAS unsigned char* lds, const Gemm g, int G, int c, const Epi& E) {
;     ...
;         for (int t = 0; t < nt; t += 2) {
;     ...
;             PG8_LDA(At, 1, 1); PG8_STAGE(PG8_SB(1, 0), b3, voffB); PG8_STAGE(PG8_SB(1, 1), b3 + hstepB, voffB); PG8_STAGE(PG8_SA(1, 0), a3, voffA);
;             PG8_WAIT_V(8); PG8_WAIT_L(0); PG8_BAR; PG8_MMA(1, 0, At, B0); PG8_MMA(1, 1, At, B1); PG8_BAR; PG8_SCHED;
	s_add_i32 s33, s33, s58
	v_lshl_add_u64 v[142:143], v[142:143], 0, s[6:7]
	s_mov_b32 m0, s33
	ds_read_b128 v[182:185], v148 offset:49152
	ds_read_b128 v[186:189], v148 offset:50176
	ds_read_b128 v[190:193], v148 offset:51200
	ds_read_b128 v[194:197], v148 offset:52224
	ds_read_b128 v[198:201], v148 offset:53248
	ds_read_b128 v[202:205], v148 offset:54272
	ds_read_b128 v[206:209], v148 offset:55296
	ds_read_b128 v[210:213], v148 offset:56320
	global_load_lds_dwordx4 v[142:143], off
	s_add_i32 m0, s33, 0x2000
	s_add_u32 s46, s54, 0x20080
	v_lshl_add_u64 v[142:143], v[214:215], 0, s[6:7]
	s_addc_u32 s47, s55, 0
	s_add_i32 s33, s62, s58
	global_load_lds_dwordx4 v[142:143], off
	v_lshl_add_u64 v[142:143], s[46:47], 0, v[134:135]
	s_mov_b32 m0, s33
	s_nop 0
	global_load_lds_dwordx4 v[142:143], off
	v_lshl_add_u64 v[142:143], s[46:47], 0, v[130:131]
	s_add_i32 m0, s33, 0x2000
	s_nop 0
	global_load_lds_dwordx4 v[142:143], off
	v_lshl_add_u64 v[142:143], v[216:217], 0, s[6:7]
	s_mov_b32 m0, s71
	s_nop 0
	global_load_lds_dwordx4 v[142:143], off
	v_lshl_add_u64 v[142:143], v[218:219], 0, s[6:7]
	s_mov_b32 m0, s72
	s_nop 0
	global_load_lds_dwordx4 v[142:143], off
	s_waitcnt vmcnt(8)
	s_waitcnt lgkmcnt(0)
	s_barrier
	s_setprio 0
	s_waitcnt lgkmcnt(0)
	v_mfma_f32_16x16x32_bf16 v[62:65], v[150:153], v[182:185], v[62:65]
	v_mfma_f32_16x16x32_bf16 v[58:61], v[158:161], v[182:185], v[58:61]
	v_mfma_f32_16x16x32_bf16 v[54:57], v[150:153], v[190:193], v[54:57]
	v_mfma_f32_16x16x32_bf16 v[46:49], v[158:161], v[190:193], v[46:49]
	v_mfma_f32_16x16x32_bf16 v[38:41], v[150:153], v[198:201], v[38:41]
	v_mfma_f32_16x16x32_bf16 v[30:33], v[158:161], v[198:201], v[30:33]
	v_mfma_f32_16x16x32_bf16 v[22:25], v[150:153], v[206:209], v[22:25]
	v_mfma_f32_16x16x32_bf16 v[14:17], v[158:161], v[206:209], v[14:17]
	v_mfma_f32_16x16x32_bf16 v[62:65], v[154:157], v[186:189], v[62:65]
	v_mfma_f32_16x16x32_bf16 v[58:61], v[162:165], v[186:189], v[58:61]
	v_mfma_f32_16x16x32_bf16 v[54:57], v[154:157], v[194:197], v[54:57]
	v_mfma_f32_16x16x32_bf16 v[46:49], v[162:165], v[194:197], v[46:49]
	v_mfma_f32_16x16x32_bf16 v[38:41], v[154:157], v[202:205], v[38:41]
	v_mfma_f32_16x16x32_bf16 v[30:33], v[162:165], v[202:205], v[30:33]
	v_mfma_f32_16x16x32_bf16 v[22:25], v[154:157], v[210:213], v[22:25]
	v_mfma_f32_16x16x32_bf16 v[14:17], v[162:165], v[210:213], v[14:17]
	s_setprio 2
	s_setprio 0
	v_mfma_f32_16x16x32_bf16 v[50:53], v[166:169], v[182:185], v[50:53]
	v_mfma_f32_16x16x32_bf16 v[42:45], v[174:177], v[182:185], v[42:45]
	v_mfma_f32_16x16x32_bf16 v[34:37], v[166:169], v[190:193], v[34:37]
	v_mfma_f32_16x16x32_bf16 v[26:29], v[174:177], v[190:193], v[26:29]
	v_mfma_f32_16x16x32_bf16 v[18:21], v[166:169], v[198:201], v[18:21]
	v_mfma_f32_16x16x32_bf16 v[10:13], v[174:177], v[198:201], v[10:13]
	v_mfma_f32_16x16x32_bf16 v[6:9], v[166:169], v[206:209], v[6:9]
	v_mfma_f32_16x16x32_bf16 v[2:5], v[174:177], v[206:209], v[2:5]
	v_mfma_f32_16x16x32_bf16 v[50:53], v[170:173], v[186:189], v[50:53]
	v_mfma_f32_16x16x32_bf16 v[42:45], v[178:181], v[186:189], v[42:45]
	v_mfma_f32_16x16x32_bf16 v[34:37], v[170:173], v[194:197], v[34:37]
	v_mfma_f32_16x16x32_bf16 v[26:29], v[178:181], v[194:197], v[26:29]
	v_mfma_f32_16x16x32_bf16 v[18:21], v[170:173], v[202:205], v[18:21]
	v_mfma_f32_16x16x32_bf16 v[10:13], v[178:181], v[202:205], v[10:13]
	v_mfma_f32_16x16x32_bf16 v[6:9], v[170:173], v[210:213], v[6:9]
	v_mfma_f32_16x16x32_bf16 v[2:5], v[178:181], v[210:213], v[2:5]
	s_setprio 2
	s_barrier
	s_add_i32 s92, s92, 2
	s_cmp_gt_u32 s92, 5
	s_mov_b64 s[46:47], s[52:53]
	s_cbranch_scc0 .LBB0_781

; #define PG8_STAGE(bufoff, gbase, voff) do { _Pragma("unroll") for (int _i = 0; _i < 2; ++_i) \
;         __builtin_amdgcn_global_load_lds((const unsigned*)((const char*)(gbase) + (voff)[_i]), (LAS unsigned*)(lds + (bufoff) + ldsw + _i * 8192), 16, 0, 0); } while (0)
; #define PG8_LDA(dst, b, h) do { _Pragma("unroll") for (int m = 0; m < 4; ++m) _Pragma("unroll") for (int k = 0; k < 2; ++k) dst[m][k] = *(const LAS bf16x8*)(lds + PG8_SA(b, h) + aoff + m * 2048 + k * 1024); } while (0)
; #define PG8_LDB(dst, b, h) do { _Pragma("unroll") for (int n = 0; n < 2; ++n) _Pragma("unroll") for (int k = 0; k < 2; ++k) dst[n][k] = *(const LAS bf16x8*)(lds + PG8_SB(b, h) + boff + n * 2048 + k * 1024); } while (0)
; #define PG8_MMA(ai, bj, At, Bt) do { __builtin_amdgcn_s_setprio(1); _Pragma("unroll") for (int m = 0; m < 4; ++m) _Pragma("unroll") for (int n = 0; n < 2; ++n) _Pragma("unroll") for (int k = 0; k < 2; ++k) \
;         acc[ai][bj][m][n] = __builtin_amdgcn_mfma_f32_16x16x32_bf16(Bt[n][k], At[m][k], acc[ai][bj][m][n], 0, 0, 0); __builtin_amdgcn_s_setprio(0); } while (0)
; #define PG8_WAIT_V(n) asm volatile("s_waitcnt vmcnt(" #n ")" ::: "memory")
; #define PG8_WAIT_L(n) asm volatile("s_waitcnt lgkmcnt(" #n ")" ::: "memory")
; template <class Epi>
; __device__ __forceinline__ void gemm_phase(LAS unsigned char* lds, const Gemm g, int G, int c, const Epi& E) {
;     ...
; #pragma unroll
;     for (int a = 0; a < 2; ++a)
; #pragma unroll
;         for (int b = 0; b < 2; ++b)
; #pragma unroll
;             for (int m = 0; m < 4; ++m)
; #pragma unroll
;                 for (int n = 0; n < 2; ++n) acc[a][b][m][n] = (f32x4){0.f, 0.f, 0.f, 0.f};
;     ...
;             const bool last = (t == nt - 2);
;             const char* a1 = cA + (size_t)(t + 1) * kstep;
;             const char* a2 = last ? nA : cA + (size_t)(t + 2) * kstep; const char* b2 = last ? nB : cB + (size_t)(t + 2) * kstep;
;             const char* a3 = a2 + kstep; const char* b3 = b2 + kstep;
;             PG8_LDB(B0, 0, 0); PG8_LDB(B1, 0, 1); PG8_SCHED; PG8_LDA(At, 0, 0); PG8_STAGE(PG8_SA(1, 1), a1 + hstepA, voffA);
;             PG8_WAIT_V(8); PG8_WAIT_L(0); PG8_BAR; PG8_MMA(0, 0, At, B0); PG8_MMA(0, 1, At, B1); PG8_BAR; PG8_SCHED;
;             PG8_LDA(At, 0, 1); PG8_STAGE(PG8_SB(0, 0), b2, voffB); PG8_STAGE(PG8_SB(0, 1), b2 + hstepB, voffB); PG8_STAGE(PG8_SA(0, 0), a2, voffA);
.LBB0_902:
	s_ashr_i32 s15, s14, 31
	s_lshl_b64 s[20:21], s[14:15], 19
	s_add_u32 s20, s34, s20
	s_addc_u32 s21, s35, s21
	s_and_b64 s[4:5], s[4:5], exec
	s_cselect_b32 s15, s21, s43
	s_cselect_b32 s17, s20, s42
	s_add_u32 s4, s44, 0x40080
	s_addc_u32 s5, s45, 0
	s_add_u32 s23, s42, 0x100
	s_addc_u32 s39, s43, 0
	s_mov_b32 s46, -2
	s_waitcnt vmcnt(0)
	ds_read_b128 v[130:133], v170
	ds_read_b128 v[134:137], v170 offset:1024
	ds_read_b128 v[138:141], v170 offset:2048
	ds_read_b128 v[142:145], v170 offset:3072
	ds_read_b128 v[162:165], v171
	ds_read_b128 v[174:177], v171 offset:1024
	ds_read_b128 v[178:181], v171 offset:2048
	ds_read_b128 v[182:185], v171 offset:3072
	s_add_u32 s33, s4, 0xfffc0080
	s_addc_u32 s42, s5, -1
	s_cmp_eq_u32 s46, 12
	s_cselect_b32 s45, s19, s42
	s_cselect_b32 s44, s18, s33
	s_cselect_b32 s43, s15, s39
	s_cselect_b32 s42, s17, s23
	v_lshl_add_u64 v[166:167], s[4:5], 0, v[154:155]
	s_add_i32 m0, s25, 0xc000
	ds_read_b128 v[186:189], v172
	ds_read_b128 v[190:193], v172 offset:1024
	ds_read_b128 v[194:197], v172 offset:2048
	ds_read_b128 v[198:201], v172 offset:3072
	ds_read_b128 v[202:205], v172 offset:4096
	ds_read_b128 v[206:209], v172 offset:5120
	ds_read_b128 v[210:213], v172 offset:6144
	ds_read_b128 v[214:217], v172 offset:7168
	global_load_lds_dwordx4 v[166:167], off
	v_lshl_add_u64 v[166:167], s[4:5], 0, v[156:157]
	s_add_i32 m0, s25, 0xe000
	s_nop 0
	global_load_lds_dwordx4 v[166:167], off
	s_waitcnt vmcnt(8)
	s_waitcnt lgkmcnt(0)
	s_barrier
	s_setprio 0
	s_waitcnt lgkmcnt(0)
	v_mfma_f32_16x16x32_bf16 v[126:129], v[130:133], v[186:189], 0
	v_mfma_f32_16x16x32_bf16 v[122:125], v[138:141], v[186:189], 0
	v_mfma_f32_16x16x32_bf16 v[110:113], v[130:133], v[194:197], 0
	v_mfma_f32_16x16x32_bf16 v[106:109], v[138:141], v[194:197], 0
	v_mfma_f32_16x16x32_bf16 v[94:97], v[130:133], v[202:205], 0
	v_mfma_f32_16x16x32_bf16 v[90:93], v[138:141], v[202:205], 0
	v_mfma_f32_16x16x32_bf16 v[78:81], v[130:133], v[210:213], 0
	v_mfma_f32_16x16x32_bf16 v[74:77], v[138:141], v[210:213], 0
	v_mfma_f32_16x16x32_bf16 v[126:129], v[134:137], v[190:193], v[126:129]
	v_mfma_f32_16x16x32_bf16 v[122:125], v[142:145], v[190:193], v[122:125]
	v_mfma_f32_16x16x32_bf16 v[110:113], v[134:137], v[198:201], v[110:113]
	v_mfma_f32_16x16x32_bf16 v[106:109], v[142:145], v[198:201], v[106:109]
	v_mfma_f32_16x16x32_bf16 v[94:97], v[134:137], v[206:209], v[94:97]
	v_mfma_f32_16x16x32_bf16 v[90:93], v[142:145], v[206:209], v[90:93]
	v_mfma_f32_16x16x32_bf16 v[78:81], v[134:137], v[214:217], v[78:81]
	v_mfma_f32_16x16x32_bf16 v[74:77], v[142:145], v[214:217], v[74:77]
	s_setprio 2
	s_setprio 0
	v_mfma_f32_16x16x32_bf16 v[118:121], v[162:165], v[186:189], 0
	v_mfma_f32_16x16x32_bf16 v[114:117], v[178:181], v[186:189], 0
	v_mfma_f32_16x16x32_bf16 v[102:105], v[162:165], v[194:197], 0
	v_mfma_f32_16x16x32_bf16 v[98:101], v[178:181], v[194:197], 0
	v_mfma_f32_16x16x32_bf16 v[86:89], v[162:165], v[202:205], 0
	v_mfma_f32_16x16x32_bf16 v[82:85], v[178:181], v[202:205], 0
	v_mfma_f32_16x16x32_bf16 v[70:73], v[162:165], v[210:213], 0
	v_mfma_f32_16x16x32_bf16 v[66:69], v[178:181], v[210:213], 0
	v_mfma_f32_16x16x32_bf16 v[118:121], v[174:177], v[190:193], v[118:121]
	v_mfma_f32_16x16x32_bf16 v[114:117], v[182:185], v[190:193], v[114:117]
	v_mfma_f32_16x16x32_bf16 v[102:105], v[174:177], v[198:201], v[102:105]
	v_mfma_f32_16x16x32_bf16 v[98:101], v[182:185], v[198:201], v[98:101]
	v_mfma_f32_16x16x32_bf16 v[86:89], v[174:177], v[206:209], v[86:89]
	v_mfma_f32_16x16x32_bf16 v[82:85], v[182:185], v[206:209], v[82:85]
	v_mfma_f32_16x16x32_bf16 v[70:73], v[174:177], v[214:217], v[70:73]
	v_mfma_f32_16x16x32_bf16 v[66:69], v[182:185], v[214:217], v[66:69]
	s_setprio 2
	s_barrier
	s_add_i32 s33, s72, s54
	v_lshl_add_u64 v[166:167], s[42:43], 0, v[150:151]
	s_mov_b32 m0, s33
	ds_read_b128 v[186:189], v172 offset:16384
	ds_read_b128 v[190:193], v172 offset:17408
	ds_read_b128 v[194:197], v172 offset:18432
	ds_read_b128 v[198:201], v172 offset:19456
	ds_read_b128 v[202:205], v172 offset:20480
	ds_read_b128 v[206:209], v172 offset:21504
	ds_read_b128 v[210:213], v172 offset:22528
	ds_read_b128 v[214:217], v172 offset:23552
	global_load_lds_dwordx4 v[166:167], off
	s_add_i32 m0, s33, 0x2000
	s_add_u32 s62, s42, 0x40000
	v_lshl_add_u64 v[218:219], s[42:43], 0, v[146:147]
	s_addc_u32 s63, s43, 0
	s_add_i32 s33, s73, s54
	global_load_lds_dwordx4 v[218:219], off
	v_lshl_add_u64 v[220:221], s[62:63], 0, v[150:151]
	s_mov_b32 m0, s33
	v_lshl_add_u64 v[222:223], s[44:45], 0, v[148:149]
	global_load_lds_dwordx4 v[220:221], off
	v_lshl_add_u64 v[220:221], s[62:63], 0, v[146:147]
	s_add_i32 m0, s33, 0x2000
	s_nop 0
	global_load_lds_dwordx4 v[220:221], off
	v_lshl_add_u64 v[220:221], s[44:45], 0, v[152:153]
	s_mov_b32 m0, s25
	s_nop 0
	global_load_lds_dwordx4 v[220:221], off
	s_mov_b32 m0, s57
	s_nop 0
	global_load_lds_dwordx4 v[222:223], off
	s_waitcnt vmcnt(8)
	s_waitcnt lgkmcnt(0)
	s_barrier
; #define PG8_STAGE(bufoff, gbase, voff) do { _Pragma("unroll") for (int _i = 0; _i < 2; ++_i) \
;         __builtin_amdgcn_global_load_lds((const unsigned*)((const char*)(gbase) + (voff)[_i]), (LAS unsigned*)(lds + (bufoff) + ldsw + _i * 8192), 16, 0, 0); } while (0)
; #define PG8_LDA(dst, b, h) do { _Pragma("unroll") for (int m = 0; m < 4; ++m) _Pragma("unroll") for (int k = 0; k < 2; ++k) dst[m][k] = *(const LAS bf16x8*)(lds + PG8_SA(b, h) + aoff + m * 2048 + k * 1024); } while (0)
; #define PG8_LDB(dst, b, h) do { _Pragma("unroll") for (int n = 0; n < 2; ++n) _Pragma("unroll") for (int k = 0; k < 2; ++k) dst[n][k] = *(const LAS bf16x8*)(lds + PG8_SB(b, h) + boff + n * 2048 + k * 1024); } while (0)
; #define PG8_MMA(ai, bj, At, Bt) do { __builtin_amdgcn_s_setprio(1); _Pragma("unroll") for (int m = 0; m < 4; ++m) _Pragma("unroll") for (int n = 0; n < 2; ++n) _Pragma("unroll") for (int k = 0; k < 2; ++k) \
;         acc[ai][bj][m][n] = __builtin_amdgcn_mfma_f32_16x16x32_bf16(Bt[n][k], At[m][k], acc[ai][bj][m][n], 0, 0, 0); __builtin_amdgcn_s_setprio(0); } while (0)
; #define PG8_WAIT_V(n) asm volatile("s_waitcnt vmcnt(" #n ")" ::: "memory")
; #define PG8_WAIT_L(n) asm volatile("s_waitcnt lgkmcnt(" #n ")" ::: "memory")
; #define PG8_BAR __builtin_amdgcn_s_barrier()
; #define PG8_SCHED __builtin_amdgcn_sched_barrier(0)
; template <class Epi>
; __device__ __forceinline__ void gemm_phase(LAS unsigned char* lds, const Gemm g, int G, int c, const Epi& E) {
;     ...
;             PG8_WAIT_V(8); PG8_WAIT_L(0); PG8_BAR; PG8_MMA(1, 0, At, B0); PG8_MMA(1, 1, At, B1); PG8_BAR; PG8_SCHED;
;             PG8_LDB(B0, 1, 0); PG8_LDB(B1, 1, 1); PG8_SCHED; PG8_LDA(At, 1, 0); PG8_STAGE(PG8_SA(0, 1), a2 + hstepA, voffA);
;             PG8_WAIT_V(8); PG8_WAIT_L(0); PG8_BAR; PG8_MMA(0, 0, At, B0); PG8_MMA(0, 1, At, B1); PG8_BAR; PG8_SCHED;
	s_setprio 0
	s_waitcnt lgkmcnt(0)
	v_mfma_f32_16x16x32_bf16 v[62:65], v[130:133], v[186:189], 0
	v_mfma_f32_16x16x32_bf16 v[58:61], v[138:141], v[186:189], 0
	v_mfma_f32_16x16x32_bf16 v[46:49], v[130:133], v[194:197], 0
	v_mfma_f32_16x16x32_bf16 v[42:45], v[138:141], v[194:197], 0
	v_mfma_f32_16x16x32_bf16 v[30:33], v[130:133], v[202:205], 0
	v_mfma_f32_16x16x32_bf16 v[26:29], v[138:141], v[202:205], 0
	v_mfma_f32_16x16x32_bf16 v[14:17], v[130:133], v[210:213], 0
	v_mfma_f32_16x16x32_bf16 v[10:13], v[138:141], v[210:213], 0
	v_mfma_f32_16x16x32_bf16 v[62:65], v[134:137], v[190:193], v[62:65]
	v_mfma_f32_16x16x32_bf16 v[58:61], v[142:145], v[190:193], v[58:61]
	v_mfma_f32_16x16x32_bf16 v[46:49], v[134:137], v[198:201], v[46:49]
	v_mfma_f32_16x16x32_bf16 v[42:45], v[142:145], v[198:201], v[42:45]
	v_mfma_f32_16x16x32_bf16 v[30:33], v[134:137], v[206:209], v[30:33]
	v_mfma_f32_16x16x32_bf16 v[26:29], v[142:145], v[206:209], v[26:29]
	v_mfma_f32_16x16x32_bf16 v[14:17], v[134:137], v[214:217], v[14:17]
	v_mfma_f32_16x16x32_bf16 v[10:13], v[142:145], v[214:217], v[10:13]
	s_setprio 2
	s_setprio 0
	v_mfma_f32_16x16x32_bf16 v[54:57], v[162:165], v[186:189], 0
	v_mfma_f32_16x16x32_bf16 v[50:53], v[178:181], v[186:189], 0
	v_mfma_f32_16x16x32_bf16 v[38:41], v[162:165], v[194:197], 0
	v_mfma_f32_16x16x32_bf16 v[34:37], v[178:181], v[194:197], 0
	v_mfma_f32_16x16x32_bf16 v[22:25], v[162:165], v[202:205], 0
	v_mfma_f32_16x16x32_bf16 v[18:21], v[178:181], v[202:205], 0
	v_mfma_f32_16x16x32_bf16 v[6:9], v[162:165], v[210:213], 0
	v_mfma_f32_16x16x32_bf16 v[2:5], v[178:181], v[210:213], 0
	v_mfma_f32_16x16x32_bf16 v[54:57], v[174:177], v[190:193], v[54:57]
	v_mfma_f32_16x16x32_bf16 v[50:53], v[182:185], v[190:193], v[50:53]
	v_mfma_f32_16x16x32_bf16 v[38:41], v[174:177], v[198:201], v[38:41]
	v_mfma_f32_16x16x32_bf16 v[34:37], v[182:185], v[198:201], v[34:37]
	v_mfma_f32_16x16x32_bf16 v[22:25], v[174:177], v[206:209], v[22:25]
	v_mfma_f32_16x16x32_bf16 v[18:21], v[182:185], v[206:209], v[18:21]
	v_mfma_f32_16x16x32_bf16 v[6:9], v[174:177], v[214:217], v[6:9]
	v_mfma_f32_16x16x32_bf16 v[2:5], v[182:185], v[214:217], v[2:5]
	s_setprio 2
	s_barrier
	s_add_i32 s33, 0, 0x18000
	s_add_i32 s47, 0, 0x1c000
	v_add_u32_e32 v142, s33, v169
	v_add_u32_e32 v173, s47, v169
	ds_read_b128 v[130:133], v142
	ds_read_b128 v[134:137], v142 offset:1024
	ds_read_b128 v[138:141], v142 offset:2048
	ds_read_b128 v[142:145], v142 offset:3072
	ds_read_b128 v[162:165], v173
	ds_read_b128 v[174:177], v173 offset:1024
	ds_read_b128 v[178:181], v173 offset:2048
	ds_read_b128 v[182:185], v173 offset:3072
	s_add_u32 s44, s44, 0x40000
	s_addc_u32 s45, s45, 0
	s_mov_b32 m0, s58
	v_lshl_add_u64 v[224:225], s[44:45], 0, v[152:153]
	ds_read_b128 v[186:189], v172 offset:32768
	ds_read_b128 v[190:193], v172 offset:33792
	ds_read_b128 v[194:197], v172 offset:34816
	ds_read_b128 v[198:201], v172 offset:35840
	ds_read_b128 v[202:205], v172 offset:36864
	ds_read_b128 v[206:209], v172 offset:37888
	ds_read_b128 v[210:213], v172 offset:38912
	ds_read_b128 v[214:217], v172 offset:39936
	global_load_lds_dwordx4 v[224:225], off
	v_lshl_add_u64 v[224:225], s[44:45], 0, v[148:149]
	s_mov_b32 m0, s59
	s_nop 0
	global_load_lds_dwordx4 v[224:225], off
	s_waitcnt vmcnt(8)
	s_waitcnt lgkmcnt(0)
	s_barrier
	s_setprio 0
	s_waitcnt lgkmcnt(0)
	v_mfma_f32_16x16x32_bf16 v[126:129], v[130:133], v[186:189], v[126:129]
	v_mfma_f32_16x16x32_bf16 v[122:125], v[138:141], v[186:189], v[122:125]
	v_mfma_f32_16x16x32_bf16 v[110:113], v[130:133], v[194:197], v[110:113]
	v_mfma_f32_16x16x32_bf16 v[106:109], v[138:141], v[194:197], v[106:109]
	v_mfma_f32_16x16x32_bf16 v[94:97], v[130:133], v[202:205], v[94:97]
	v_mfma_f32_16x16x32_bf16 v[90:93], v[138:141], v[202:205], v[90:93]
	v_mfma_f32_16x16x32_bf16 v[78:81], v[130:133], v[210:213], v[78:81]
	v_mfma_f32_16x16x32_bf16 v[74:77], v[138:141], v[210:213], v[74:77]
	v_mfma_f32_16x16x32_bf16 v[126:129], v[134:137], v[190:193], v[126:129]
	v_mfma_f32_16x16x32_bf16 v[122:125], v[142:145], v[190:193], v[122:125]
	v_mfma_f32_16x16x32_bf16 v[110:113], v[134:137], v[198:201], v[110:113]
	v_mfma_f32_16x16x32_bf16 v[106:109], v[142:145], v[198:201], v[106:109]
	v_mfma_f32_16x16x32_bf16 v[94:97], v[134:137], v[206:209], v[94:97]
	v_mfma_f32_16x16x32_bf16 v[90:93], v[142:145], v[206:209], v[90:93]
	v_mfma_f32_16x16x32_bf16 v[78:81], v[134:137], v[214:217], v[78:81]
	v_mfma_f32_16x16x32_bf16 v[74:77], v[142:145], v[214:217], v[74:77]
	s_setprio 2
	s_setprio 0
	v_mfma_f32_16x16x32_bf16 v[118:121], v[162:165], v[186:189], v[118:121]
	v_mfma_f32_16x16x32_bf16 v[114:117], v[178:181], v[186:189], v[114:117]
	v_mfma_f32_16x16x32_bf16 v[102:105], v[162:165], v[194:197], v[102:105]
	v_mfma_f32_16x16x32_bf16 v[98:101], v[178:181], v[194:197], v[98:101]
	v_mfma_f32_16x16x32_bf16 v[86:89], v[162:165], v[202:205], v[86:89]
	v_mfma_f32_16x16x32_bf16 v[82:85], v[178:181], v[202:205], v[82:85]
	v_mfma_f32_16x16x32_bf16 v[70:73], v[162:165], v[210:213], v[70:73]
	v_mfma_f32_16x16x32_bf16 v[66:69], v[178:181], v[210:213], v[66:69]
	v_mfma_f32_16x16x32_bf16 v[118:121], v[174:177], v[190:193], v[118:121]
	v_mfma_f32_16x16x32_bf16 v[114:117], v[182:185], v[190:193], v[114:117]
	v_mfma_f32_16x16x32_bf16 v[102:105], v[174:177], v[198:201], v[102:105]
	v_mfma_f32_16x16x32_bf16 v[98:101], v[182:185], v[198:201], v[98:101]
	v_mfma_f32_16x16x32_bf16 v[86:89], v[174:177], v[206:209], v[86:89]
	v_mfma_f32_16x16x32_bf16 v[82:85], v[182:185], v[206:209], v[82:85]
	v_mfma_f32_16x16x32_bf16 v[70:73], v[174:177], v[214:217], v[70:73]
	v_mfma_f32_16x16x32_bf16 v[66:69], v[182:185], v[214:217], v[66:69]
	s_setprio 2
	s_barrier
; #define PG8_STAGE(bufoff, gbase, voff) do { _Pragma("unroll") for (int _i = 0; _i < 2; ++_i) \
;         __builtin_amdgcn_global_load_lds((const unsigned*)((const char*)(gbase) + (voff)[_i]), (LAS unsigned*)(lds + (bufoff) + ldsw + _i * 8192), 16, 0, 0); } while (0)
; #define PG8_LDA(dst, b, h) do { _Pragma("unroll") for (int m = 0; m < 4; ++m) _Pragma("unroll") for (int k = 0; k < 2; ++k) dst[m][k] = *(const LAS bf16x8*)(lds + PG8_SA(b, h) + aoff + m * 2048 + k * 1024); } while (0)
; #define PG8_MMA(ai, bj, At, Bt) do { __builtin_amdgcn_s_setprio(1); _Pragma("unroll") for (int m = 0; m < 4; ++m) _Pragma("unroll") for (int n = 0; n < 2; ++n) _Pragma("unroll") for (int k = 0; k < 2; ++k) \
;         acc[ai][bj][m][n] = __builtin_amdgcn_mfma_f32_16x16x32_bf16(Bt[n][k], At[m][k], acc[ai][bj][m][n], 0, 0, 0); __builtin_amdgcn_s_setprio(0); } while (0)
; #define PG8_WAIT_V(n) asm volatile("s_waitcnt vmcnt(" #n ")" ::: "memory")
; #define PG8_WAIT_L(n) asm volatile("s_waitcnt lgkmcnt(" #n ")" ::: "memory")
; #define PG8_BAR __builtin_amdgcn_s_barrier()
; #define PG8_SCHED __builtin_amdgcn_sched_barrier(0)
; template <class Epi>
; __device__ __forceinline__ void gemm_phase(LAS unsigned char* lds, const Gemm g, int G, int c, const Epi& E) {
;     ...
;         for (int t = 0; t < nt; t += 2) {
;     ...
;             PG8_LDA(At, 1, 1); PG8_STAGE(PG8_SB(1, 0), b3, voffB); PG8_STAGE(PG8_SB(1, 1), b3 + hstepB, voffB); PG8_STAGE(PG8_SA(1, 0), a3, voffA);
;             PG8_WAIT_V(8); PG8_WAIT_L(0); PG8_BAR; PG8_MMA(1, 0, At, B0); PG8_MMA(1, 1, At, B1); PG8_BAR; PG8_SCHED;
	s_add_i32 s33, s33, s54
	v_lshl_add_u64 v[166:167], v[166:167], 0, s[10:11]
	s_mov_b32 m0, s33
	ds_read_b128 v[186:189], v172 offset:49152
	ds_read_b128 v[190:193], v172 offset:50176
	ds_read_b128 v[194:197], v172 offset:51200
	ds_read_b128 v[198:201], v172 offset:52224
	ds_read_b128 v[202:205], v172 offset:53248
	ds_read_b128 v[206:209], v172 offset:54272
	ds_read_b128 v[210:213], v172 offset:55296
	ds_read_b128 v[214:217], v172 offset:56320
	global_load_lds_dwordx4 v[166:167], off
	s_add_i32 m0, s33, 0x2000
	s_add_u32 s42, s42, 0x40080
	v_lshl_add_u64 v[166:167], v[218:219], 0, s[10:11]
	s_addc_u32 s43, s43, 0
	s_add_i32 s33, s47, s54
	global_load_lds_dwordx4 v[166:167], off
	v_lshl_add_u64 v[166:167], s[42:43], 0, v[150:151]
	s_mov_b32 m0, s33
	s_nop 0
	global_load_lds_dwordx4 v[166:167], off
	v_lshl_add_u64 v[166:167], s[42:43], 0, v[146:147]
	s_add_i32 m0, s33, 0x2000
	s_nop 0
	global_load_lds_dwordx4 v[166:167], off
	v_lshl_add_u64 v[166:167], v[220:221], 0, s[10:11]
	s_mov_b32 m0, s69
	s_nop 0
	global_load_lds_dwordx4 v[166:167], off
	v_lshl_add_u64 v[166:167], v[222:223], 0, s[10:11]
	s_mov_b32 m0, s70
	s_nop 0
	global_load_lds_dwordx4 v[166:167], off
	s_waitcnt vmcnt(8)
	s_waitcnt lgkmcnt(0)
	s_barrier
	s_setprio 0
	s_waitcnt lgkmcnt(0)
	v_mfma_f32_16x16x32_bf16 v[62:65], v[130:133], v[186:189], v[62:65]
	v_mfma_f32_16x16x32_bf16 v[58:61], v[138:141], v[186:189], v[58:61]
	v_mfma_f32_16x16x32_bf16 v[46:49], v[130:133], v[194:197], v[46:49]
	v_mfma_f32_16x16x32_bf16 v[42:45], v[138:141], v[194:197], v[42:45]
	v_mfma_f32_16x16x32_bf16 v[30:33], v[130:133], v[202:205], v[30:33]
	v_mfma_f32_16x16x32_bf16 v[26:29], v[138:141], v[202:205], v[26:29]
	v_mfma_f32_16x16x32_bf16 v[14:17], v[130:133], v[210:213], v[14:17]
	v_mfma_f32_16x16x32_bf16 v[10:13], v[138:141], v[210:213], v[10:13]
	v_mfma_f32_16x16x32_bf16 v[62:65], v[134:137], v[190:193], v[62:65]
	v_mfma_f32_16x16x32_bf16 v[58:61], v[142:145], v[190:193], v[58:61]
	v_mfma_f32_16x16x32_bf16 v[46:49], v[134:137], v[198:201], v[46:49]
	v_mfma_f32_16x16x32_bf16 v[42:45], v[142:145], v[198:201], v[42:45]
	v_mfma_f32_16x16x32_bf16 v[30:33], v[134:137], v[206:209], v[30:33]
	v_mfma_f32_16x16x32_bf16 v[26:29], v[142:145], v[206:209], v[26:29]
	v_mfma_f32_16x16x32_bf16 v[14:17], v[134:137], v[214:217], v[14:17]
	v_mfma_f32_16x16x32_bf16 v[10:13], v[142:145], v[214:217], v[10:13]
	s_setprio 2
	s_setprio 0
	v_mfma_f32_16x16x32_bf16 v[54:57], v[162:165], v[186:189], v[54:57]
	v_mfma_f32_16x16x32_bf16 v[50:53], v[178:181], v[186:189], v[50:53]
	v_mfma_f32_16x16x32_bf16 v[38:41], v[162:165], v[194:197], v[38:41]
	v_mfma_f32_16x16x32_bf16 v[34:37], v[178:181], v[194:197], v[34:37]
	v_mfma_f32_16x16x32_bf16 v[22:25], v[162:165], v[202:205], v[22:25]
	v_mfma_f32_16x16x32_bf16 v[18:21], v[178:181], v[202:205], v[18:21]
	v_mfma_f32_16x16x32_bf16 v[6:9], v[162:165], v[210:213], v[6:9]
	v_mfma_f32_16x16x32_bf16 v[2:5], v[178:181], v[210:213], v[2:5]
	v_mfma_f32_16x16x32_bf16 v[54:57], v[174:177], v[190:193], v[54:57]
	v_mfma_f32_16x16x32_bf16 v[50:53], v[182:185], v[190:193], v[50:53]
	v_mfma_f32_16x16x32_bf16 v[38:41], v[174:177], v[198:201], v[38:41]
	v_mfma_f32_16x16x32_bf16 v[34:37], v[182:185], v[198:201], v[34:37]
	v_mfma_f32_16x16x32_bf16 v[22:25], v[174:177], v[206:209], v[22:25]
	v_mfma_f32_16x16x32_bf16 v[18:21], v[182:185], v[206:209], v[18:21]
	v_mfma_f32_16x16x32_bf16 v[6:9], v[174:177], v[214:217], v[6:9]
	v_mfma_f32_16x16x32_bf16 v[2:5], v[182:185], v[214:217], v[2:5]
	s_setprio 2
	s_barrier
	s_add_i32 s46, s46, 2
	s_add_u32 s4, s4, 0x100
	s_addc_u32 s5, s5, 0
	s_add_u32 s23, s23, 0x100
	s_addc_u32 s39, s39, 0
	s_cmp_gt_u32 s46, 13
	s_cbranch_scc0 .LBB0_903

; #define PG8_STAGE(bufoff, gbase, voff) do { _Pragma("unroll") for (int _i = 0; _i < 2; ++_i) \
;         __builtin_amdgcn_global_load_lds((const unsigned*)((const char*)(gbase) + (voff)[_i]), (LAS unsigned*)(lds + (bufoff) + ldsw + _i * 8192), 16, 0, 0); } while (0)
; #define PG8_LDA(dst, b, h) do { _Pragma("unroll") for (int m = 0; m < 4; ++m) _Pragma("unroll") for (int k = 0; k < 2; ++k) dst[m][k] = *(const LAS bf16x8*)(lds + PG8_SA(b, h) + aoff + m * 2048 + k * 1024); } while (0)
; #define PG8_LDB(dst, b, h) do { _Pragma("unroll") for (int n = 0; n < 2; ++n) _Pragma("unroll") for (int k = 0; k < 2; ++k) dst[n][k] = *(const LAS bf16x8*)(lds + PG8_SB(b, h) + boff + n * 2048 + k * 1024); } while (0)
; #define PG8_MMA(ai, bj, At, Bt) do { __builtin_amdgcn_s_setprio(1); _Pragma("unroll") for (int m = 0; m < 4; ++m) _Pragma("unroll") for (int n = 0; n < 2; ++n) _Pragma("unroll") for (int k = 0; k < 2; ++k) \
;         acc[ai][bj][m][n] = __builtin_amdgcn_mfma_f32_16x16x32_bf16(Bt[n][k], At[m][k], acc[ai][bj][m][n], 0, 0, 0); __builtin_amdgcn_s_setprio(0); } while (0)
; #define PG8_WAIT_V(n) asm volatile("s_waitcnt vmcnt(" #n ")" ::: "memory")
; #define PG8_WAIT_L(n) asm volatile("s_waitcnt lgkmcnt(" #n ")" ::: "memory")
; template <class Epi>
; __device__ __forceinline__ void gemm_phase(LAS unsigned char* lds, const Gemm g, int G, int c, const Epi& E) {
;     ...
; #pragma unroll
;     for (int a = 0; a < 2; ++a)
; #pragma unroll
;         for (int b = 0; b < 2; ++b)
; #pragma unroll
;             for (int m = 0; m < 4; ++m)
; #pragma unroll
;                 for (int n = 0; n < 2; ++n) acc[a][b][m][n] = (f32x4){0.f, 0.f, 0.f, 0.f};
;     ...
;             const bool last = (t == nt - 2);
;             const char* a1 = cA + (size_t)(t + 1) * kstep;
;             const char* a2 = last ? nA : cA + (size_t)(t + 2) * kstep; const char* b2 = last ? nB : cB + (size_t)(t + 2) * kstep;
;             const char* a3 = a2 + kstep; const char* b3 = b2 + kstep;
;             PG8_LDB(B0, 0, 0); PG8_LDB(B1, 0, 1); PG8_SCHED; PG8_LDA(At, 0, 0); PG8_STAGE(PG8_SA(1, 1), a1 + hstepA, voffA);
;             PG8_WAIT_V(8); PG8_WAIT_L(0); PG8_BAR; PG8_MMA(0, 0, At, B0); PG8_MMA(0, 1, At, B1); PG8_BAR; PG8_SCHED;
;             PG8_LDA(At, 0, 1); PG8_STAGE(PG8_SB(0, 0), b2, voffB); PG8_STAGE(PG8_SB(0, 1), b2 + hstepB, voffB); PG8_STAGE(PG8_SA(0, 0), a2, voffA);
.LBB0_1057:
	s_ashr_i32 s17, s16, 31
	s_lshl_b64 s[22:23], s[16:17], 19
	s_add_u32 s22, s35, s22
	s_addc_u32 s23, s42, s23
	s_and_b64 s[4:5], s[4:5], exec
	s_cselect_b32 s17, s23, s39
	s_cselect_b32 s19, s22, s38
	s_add_u32 s4, s40, 0x40080
	s_addc_u32 s5, s41, 0
	s_add_u32 s78, s38, 0x100
	s_addc_u32 s79, s39, 0
	s_mov_b32 s80, -2
	ds_read_b128 v[152:155], v148
	ds_read_b128 v[156:159], v148 offset:1024
	ds_read_b128 v[160:163], v148 offset:2048
	ds_read_b128 v[164:167], v148 offset:3072
	ds_read_b128 v[168:171], v149
	ds_read_b128 v[172:175], v149 offset:1024
	ds_read_b128 v[176:179], v149 offset:2048
	ds_read_b128 v[180:183], v149 offset:3072
	s_add_u32 s33, s4, 0xfffc0080
	s_addc_u32 s38, s5, -1
	s_cmp_eq_u32 s80, 12
	s_cselect_b32 s41, s21, s38
	s_cselect_b32 s40, s20, s33
	s_cselect_b32 s39, s17, s79
	s_cselect_b32 s38, s19, s78
	v_lshl_add_u64 v[216:217], s[4:5], 0, v[138:139]
	s_add_i32 m0, s25, 0xc000
	ds_read_b128 v[184:187], v150
	ds_read_b128 v[188:191], v150 offset:1024
	ds_read_b128 v[192:195], v150 offset:2048
	ds_read_b128 v[196:199], v150 offset:3072
	ds_read_b128 v[200:203], v150 offset:4096
	ds_read_b128 v[204:207], v150 offset:5120
	ds_read_b128 v[208:211], v150 offset:6144
	ds_read_b128 v[212:215], v150 offset:7168
	global_load_lds_dwordx4 v[216:217], off
	v_lshl_add_u64 v[216:217], s[4:5], 0, v[140:141]
	s_add_i32 m0, s25, 0xe000
	s_nop 0
	global_load_lds_dwordx4 v[216:217], off
	s_waitcnt vmcnt(8)
	s_waitcnt lgkmcnt(0)
	s_barrier
	s_setprio 0
	s_waitcnt lgkmcnt(0)
	v_mfma_f32_16x16x32_bf16 v[126:129], v[152:155], v[184:187], 0
	v_mfma_f32_16x16x32_bf16 v[122:125], v[160:163], v[184:187], 0
	v_mfma_f32_16x16x32_bf16 v[110:113], v[152:155], v[192:195], 0
	v_mfma_f32_16x16x32_bf16 v[106:109], v[160:163], v[192:195], 0
	v_mfma_f32_16x16x32_bf16 v[94:97], v[152:155], v[200:203], 0
	v_mfma_f32_16x16x32_bf16 v[90:93], v[160:163], v[200:203], 0
	v_mfma_f32_16x16x32_bf16 v[78:81], v[152:155], v[208:211], 0
	v_mfma_f32_16x16x32_bf16 v[74:77], v[160:163], v[208:211], 0
	v_mfma_f32_16x16x32_bf16 v[126:129], v[156:159], v[188:191], v[126:129]
	v_mfma_f32_16x16x32_bf16 v[122:125], v[164:167], v[188:191], v[122:125]
	v_mfma_f32_16x16x32_bf16 v[110:113], v[156:159], v[196:199], v[110:113]
	v_mfma_f32_16x16x32_bf16 v[106:109], v[164:167], v[196:199], v[106:109]
	v_mfma_f32_16x16x32_bf16 v[94:97], v[156:159], v[204:207], v[94:97]
	v_mfma_f32_16x16x32_bf16 v[90:93], v[164:167], v[204:207], v[90:93]
	v_mfma_f32_16x16x32_bf16 v[78:81], v[156:159], v[212:215], v[78:81]
	v_mfma_f32_16x16x32_bf16 v[74:77], v[164:167], v[212:215], v[74:77]
	s_setprio 2
	s_setprio 0
	v_mfma_f32_16x16x32_bf16 v[118:121], v[168:171], v[184:187], 0
	v_mfma_f32_16x16x32_bf16 v[114:117], v[176:179], v[184:187], 0
	v_mfma_f32_16x16x32_bf16 v[102:105], v[168:171], v[192:195], 0
	v_mfma_f32_16x16x32_bf16 v[98:101], v[176:179], v[192:195], 0
	v_mfma_f32_16x16x32_bf16 v[86:89], v[168:171], v[200:203], 0
	v_mfma_f32_16x16x32_bf16 v[82:85], v[176:179], v[200:203], 0
	v_mfma_f32_16x16x32_bf16 v[70:73], v[168:171], v[208:211], 0
	v_mfma_f32_16x16x32_bf16 v[66:69], v[176:179], v[208:211], 0
	v_mfma_f32_16x16x32_bf16 v[118:121], v[172:175], v[188:191], v[118:121]
	v_mfma_f32_16x16x32_bf16 v[114:117], v[180:183], v[188:191], v[114:117]
	v_mfma_f32_16x16x32_bf16 v[102:105], v[172:175], v[196:199], v[102:105]
	v_mfma_f32_16x16x32_bf16 v[98:101], v[180:183], v[196:199], v[98:101]
	v_mfma_f32_16x16x32_bf16 v[86:89], v[172:175], v[204:207], v[86:89]
	v_mfma_f32_16x16x32_bf16 v[82:85], v[180:183], v[204:207], v[82:85]
	v_mfma_f32_16x16x32_bf16 v[70:73], v[172:175], v[212:215], v[70:73]
	v_mfma_f32_16x16x32_bf16 v[66:69], v[180:183], v[212:215], v[66:69]
	s_setprio 2
	s_barrier
	s_add_i32 s33, s60, s46
	v_lshl_add_u64 v[216:217], s[38:39], 0, v[134:135]
	s_mov_b32 m0, s33
	ds_read_b128 v[184:187], v150 offset:16384
	ds_read_b128 v[188:191], v150 offset:17408
	ds_read_b128 v[192:195], v150 offset:18432
	ds_read_b128 v[196:199], v150 offset:19456
	ds_read_b128 v[200:203], v150 offset:20480
	ds_read_b128 v[204:207], v150 offset:21504
	ds_read_b128 v[208:211], v150 offset:22528
	ds_read_b128 v[212:215], v150 offset:23552
	global_load_lds_dwordx4 v[216:217], off
	s_add_i32 m0, s33, 0x2000
	s_add_u32 s62, s38, 0x40000
	v_lshl_add_u64 v[218:219], s[38:39], 0, v[130:131]
	s_addc_u32 s63, s39, 0
	s_add_i32 s33, s61, s46
	global_load_lds_dwordx4 v[218:219], off
	v_lshl_add_u64 v[220:221], s[62:63], 0, v[134:135]
	s_mov_b32 m0, s33
	v_lshl_add_u64 v[222:223], s[40:41], 0, v[132:133]
	global_load_lds_dwordx4 v[220:221], off
	v_lshl_add_u64 v[220:221], s[62:63], 0, v[130:131]
	s_add_i32 m0, s33, 0x2000
	s_nop 0
	global_load_lds_dwordx4 v[220:221], off
	v_lshl_add_u64 v[220:221], s[40:41], 0, v[136:137]
	s_mov_b32 m0, s25
	s_nop 0
	global_load_lds_dwordx4 v[220:221], off
	s_mov_b32 m0, s37
	s_nop 0
	global_load_lds_dwordx4 v[222:223], off
	s_waitcnt vmcnt(8)
	s_waitcnt lgkmcnt(0)
	s_barrier
; #define PG8_STAGE(bufoff, gbase, voff) do { _Pragma("unroll") for (int _i = 0; _i < 2; ++_i) \
;         __builtin_amdgcn_global_load_lds((const unsigned*)((const char*)(gbase) + (voff)[_i]), (LAS unsigned*)(lds + (bufoff) + ldsw + _i * 8192), 16, 0, 0); } while (0)
; #define PG8_LDA(dst, b, h) do { _Pragma("unroll") for (int m = 0; m < 4; ++m) _Pragma("unroll") for (int k = 0; k < 2; ++k) dst[m][k] = *(const LAS bf16x8*)(lds + PG8_SA(b, h) + aoff + m * 2048 + k * 1024); } while (0)
; #define PG8_LDB(dst, b, h) do { _Pragma("unroll") for (int n = 0; n < 2; ++n) _Pragma("unroll") for (int k = 0; k < 2; ++k) dst[n][k] = *(const LAS bf16x8*)(lds + PG8_SB(b, h) + boff + n * 2048 + k * 1024); } while (0)
; #define PG8_MMA(ai, bj, At, Bt) do { __builtin_amdgcn_s_setprio(1); _Pragma("unroll") for (int m = 0; m < 4; ++m) _Pragma("unroll") for (int n = 0; n < 2; ++n) _Pragma("unroll") for (int k = 0; k < 2; ++k) \
;         acc[ai][bj][m][n] = __builtin_amdgcn_mfma_f32_16x16x32_bf16(Bt[n][k], At[m][k], acc[ai][bj][m][n], 0, 0, 0); __builtin_amdgcn_s_setprio(0); } while (0)
; #define PG8_WAIT_V(n) asm volatile("s_waitcnt vmcnt(" #n ")" ::: "memory")
; #define PG8_WAIT_L(n) asm volatile("s_waitcnt lgkmcnt(" #n ")" ::: "memory")
; #define PG8_BAR __builtin_amdgcn_s_barrier()
; #define PG8_SCHED __builtin_amdgcn_sched_barrier(0)
; template <class Epi>
; __device__ __forceinline__ void gemm_phase(LAS unsigned char* lds, const Gemm g, int G, int c, const Epi& E) {
;     ...
;             PG8_WAIT_V(8); PG8_WAIT_L(0); PG8_BAR; PG8_MMA(1, 0, At, B0); PG8_MMA(1, 1, At, B1); PG8_BAR; PG8_SCHED;
;             PG8_LDB(B0, 1, 0); PG8_LDB(B1, 1, 1); PG8_SCHED; PG8_LDA(At, 1, 0); PG8_STAGE(PG8_SA(0, 1), a2 + hstepA, voffA);
;             PG8_WAIT_V(8); PG8_WAIT_L(0); PG8_BAR; PG8_MMA(0, 0, At, B0); PG8_MMA(0, 1, At, B1); PG8_BAR; PG8_SCHED;
	s_setprio 0
	s_waitcnt lgkmcnt(0)
	v_mfma_f32_16x16x32_bf16 v[62:65], v[152:155], v[184:187], 0
	v_mfma_f32_16x16x32_bf16 v[58:61], v[160:163], v[184:187], 0
	v_mfma_f32_16x16x32_bf16 v[46:49], v[152:155], v[192:195], 0
	v_mfma_f32_16x16x32_bf16 v[42:45], v[160:163], v[192:195], 0
	v_mfma_f32_16x16x32_bf16 v[30:33], v[152:155], v[200:203], 0
	v_mfma_f32_16x16x32_bf16 v[26:29], v[160:163], v[200:203], 0
	v_mfma_f32_16x16x32_bf16 v[14:17], v[152:155], v[208:211], 0
	v_mfma_f32_16x16x32_bf16 v[10:13], v[160:163], v[208:211], 0
	v_mfma_f32_16x16x32_bf16 v[62:65], v[156:159], v[188:191], v[62:65]
	v_mfma_f32_16x16x32_bf16 v[58:61], v[164:167], v[188:191], v[58:61]
	v_mfma_f32_16x16x32_bf16 v[46:49], v[156:159], v[196:199], v[46:49]
	v_mfma_f32_16x16x32_bf16 v[42:45], v[164:167], v[196:199], v[42:45]
	v_mfma_f32_16x16x32_bf16 v[30:33], v[156:159], v[204:207], v[30:33]
	v_mfma_f32_16x16x32_bf16 v[26:29], v[164:167], v[204:207], v[26:29]
	v_mfma_f32_16x16x32_bf16 v[14:17], v[156:159], v[212:215], v[14:17]
	v_mfma_f32_16x16x32_bf16 v[10:13], v[164:167], v[212:215], v[10:13]
	s_setprio 2
	s_setprio 0
	v_mfma_f32_16x16x32_bf16 v[54:57], v[168:171], v[184:187], 0
	v_mfma_f32_16x16x32_bf16 v[50:53], v[176:179], v[184:187], 0
	v_mfma_f32_16x16x32_bf16 v[38:41], v[168:171], v[192:195], 0
	v_mfma_f32_16x16x32_bf16 v[34:37], v[176:179], v[192:195], 0
	v_mfma_f32_16x16x32_bf16 v[22:25], v[168:171], v[200:203], 0
	v_mfma_f32_16x16x32_bf16 v[18:21], v[176:179], v[200:203], 0
	v_mfma_f32_16x16x32_bf16 v[6:9], v[168:171], v[208:211], 0
	v_mfma_f32_16x16x32_bf16 v[2:5], v[176:179], v[208:211], 0
	v_mfma_f32_16x16x32_bf16 v[54:57], v[172:175], v[188:191], v[54:57]
	v_mfma_f32_16x16x32_bf16 v[50:53], v[180:183], v[188:191], v[50:53]
	v_mfma_f32_16x16x32_bf16 v[38:41], v[172:175], v[196:199], v[38:41]
	v_mfma_f32_16x16x32_bf16 v[34:37], v[180:183], v[196:199], v[34:37]
	v_mfma_f32_16x16x32_bf16 v[22:25], v[172:175], v[204:207], v[22:25]
	v_mfma_f32_16x16x32_bf16 v[18:21], v[180:183], v[204:207], v[18:21]
	v_mfma_f32_16x16x32_bf16 v[6:9], v[172:175], v[212:215], v[6:9]
	v_mfma_f32_16x16x32_bf16 v[2:5], v[180:183], v[212:215], v[2:5]
	s_setprio 2
	s_barrier
	s_add_i32 s33, 0, 0x18000
	s_add_i32 s62, 0, 0x1c000
	v_add_u32_e32 v164, s33, v147
	v_add_u32_e32 v180, s62, v147
	ds_read_b128 v[152:155], v164
	ds_read_b128 v[156:159], v164 offset:1024
	ds_read_b128 v[160:163], v164 offset:2048
	ds_read_b128 v[164:167], v164 offset:3072
	ds_read_b128 v[168:171], v180
	ds_read_b128 v[172:175], v180 offset:1024
	ds_read_b128 v[176:179], v180 offset:2048
	ds_read_b128 v[180:183], v180 offset:3072
	s_add_u32 s40, s40, 0x40000
	s_addc_u32 s41, s41, 0
	s_mov_b32 m0, s47
	v_lshl_add_u64 v[224:225], s[40:41], 0, v[136:137]
	ds_read_b128 v[184:187], v150 offset:32768
	ds_read_b128 v[188:191], v150 offset:33792
	ds_read_b128 v[192:195], v150 offset:34816
	ds_read_b128 v[196:199], v150 offset:35840
	ds_read_b128 v[200:203], v150 offset:36864
	ds_read_b128 v[204:207], v150 offset:37888
	ds_read_b128 v[208:211], v150 offset:38912
	ds_read_b128 v[212:215], v150 offset:39936
	global_load_lds_dwordx4 v[224:225], off
	v_lshl_add_u64 v[224:225], s[40:41], 0, v[132:133]
	s_mov_b32 m0, s52
	s_nop 0
	global_load_lds_dwordx4 v[224:225], off
	s_waitcnt vmcnt(8)
	s_waitcnt lgkmcnt(0)
	s_barrier
	s_setprio 0
	s_waitcnt lgkmcnt(0)
	v_mfma_f32_16x16x32_bf16 v[126:129], v[152:155], v[184:187], v[126:129]
	v_mfma_f32_16x16x32_bf16 v[122:125], v[160:163], v[184:187], v[122:125]
	v_mfma_f32_16x16x32_bf16 v[110:113], v[152:155], v[192:195], v[110:113]
	v_mfma_f32_16x16x32_bf16 v[106:109], v[160:163], v[192:195], v[106:109]
	v_mfma_f32_16x16x32_bf16 v[94:97], v[152:155], v[200:203], v[94:97]
	v_mfma_f32_16x16x32_bf16 v[90:93], v[160:163], v[200:203], v[90:93]
	v_mfma_f32_16x16x32_bf16 v[78:81], v[152:155], v[208:211], v[78:81]
	v_mfma_f32_16x16x32_bf16 v[74:77], v[160:163], v[208:211], v[74:77]
	v_mfma_f32_16x16x32_bf16 v[126:129], v[156:159], v[188:191], v[126:129]
	v_mfma_f32_16x16x32_bf16 v[122:125], v[164:167], v[188:191], v[122:125]
	v_mfma_f32_16x16x32_bf16 v[110:113], v[156:159], v[196:199], v[110:113]
	v_mfma_f32_16x16x32_bf16 v[106:109], v[164:167], v[196:199], v[106:109]
	v_mfma_f32_16x16x32_bf16 v[94:97], v[156:159], v[204:207], v[94:97]
	v_mfma_f32_16x16x32_bf16 v[90:93], v[164:167], v[204:207], v[90:93]
	v_mfma_f32_16x16x32_bf16 v[78:81], v[156:159], v[212:215], v[78:81]
	v_mfma_f32_16x16x32_bf16 v[74:77], v[164:167], v[212:215], v[74:77]
	s_setprio 2
	s_setprio 0
	v_mfma_f32_16x16x32_bf16 v[118:121], v[168:171], v[184:187], v[118:121]
	v_mfma_f32_16x16x32_bf16 v[114:117], v[176:179], v[184:187], v[114:117]
	v_mfma_f32_16x16x32_bf16 v[102:105], v[168:171], v[192:195], v[102:105]
	v_mfma_f32_16x16x32_bf16 v[98:101], v[176:179], v[192:195], v[98:101]
	v_mfma_f32_16x16x32_bf16 v[86:89], v[168:171], v[200:203], v[86:89]
	v_mfma_f32_16x16x32_bf16 v[82:85], v[176:179], v[200:203], v[82:85]
	v_mfma_f32_16x16x32_bf16 v[70:73], v[168:171], v[208:211], v[70:73]
	v_mfma_f32_16x16x32_bf16 v[66:69], v[176:179], v[208:211], v[66:69]
	v_mfma_f32_16x16x32_bf16 v[118:121], v[172:175], v[188:191], v[118:121]
	v_mfma_f32_16x16x32_bf16 v[114:117], v[180:183], v[188:191], v[114:117]
	v_mfma_f32_16x16x32_bf16 v[102:105], v[172:175], v[196:199], v[102:105]
	v_mfma_f32_16x16x32_bf16 v[98:101], v[180:183], v[196:199], v[98:101]
	v_mfma_f32_16x16x32_bf16 v[86:89], v[172:175], v[204:207], v[86:89]
	v_mfma_f32_16x16x32_bf16 v[82:85], v[180:183], v[204:207], v[82:85]
	v_mfma_f32_16x16x32_bf16 v[70:73], v[172:175], v[212:215], v[70:73]
	v_mfma_f32_16x16x32_bf16 v[66:69], v[180:183], v[212:215], v[66:69]
	s_setprio 2
	s_barrier
; #define PG8_STAGE(bufoff, gbase, voff) do { _Pragma("unroll") for (int _i = 0; _i < 2; ++_i) \
;         __builtin_amdgcn_global_load_lds((const unsigned*)((const char*)(gbase) + (voff)[_i]), (LAS unsigned*)(lds + (bufoff) + ldsw + _i * 8192), 16, 0, 0); } while (0)
; #define PG8_LDA(dst, b, h) do { _Pragma("unroll") for (int m = 0; m < 4; ++m) _Pragma("unroll") for (int k = 0; k < 2; ++k) dst[m][k] = *(const LAS bf16x8*)(lds + PG8_SA(b, h) + aoff + m * 2048 + k * 1024); } while (0)
; #define PG8_MMA(ai, bj, At, Bt) do { __builtin_amdgcn_s_setprio(1); _Pragma("unroll") for (int m = 0; m < 4; ++m) _Pragma("unroll") for (int n = 0; n < 2; ++n) _Pragma("unroll") for (int k = 0; k < 2; ++k) \
;         acc[ai][bj][m][n] = __builtin_amdgcn_mfma_f32_16x16x32_bf16(Bt[n][k], At[m][k], acc[ai][bj][m][n], 0, 0, 0); __builtin_amdgcn_s_setprio(0); } while (0)
; #define PG8_WAIT_V(n) asm volatile("s_waitcnt vmcnt(" #n ")" ::: "memory")
; #define PG8_WAIT_L(n) asm volatile("s_waitcnt lgkmcnt(" #n ")" ::: "memory")
; #define PG8_BAR __builtin_amdgcn_s_barrier()
; #define PG8_SCHED __builtin_amdgcn_sched_barrier(0)
; template <class Epi>
; __device__ __forceinline__ void gemm_phase(LAS unsigned char* lds, const Gemm g, int G, int c, const Epi& E) {
;     ...
;         for (int t = 0; t < nt; t += 2) {
;     ...
;             PG8_LDA(At, 1, 1); PG8_STAGE(PG8_SB(1, 0), b3, voffB); PG8_STAGE(PG8_SB(1, 1), b3 + hstepB, voffB); PG8_STAGE(PG8_SA(1, 0), a3, voffA);
;             PG8_WAIT_V(8); PG8_WAIT_L(0); PG8_BAR; PG8_MMA(1, 0, At, B0); PG8_MMA(1, 1, At, B1); PG8_BAR; PG8_SCHED;
	s_add_i32 s33, s33, s46
	v_lshl_add_u64 v[216:217], v[216:217], 0, s[12:13]
	s_mov_b32 m0, s33
	ds_read_b128 v[184:187], v150 offset:49152
	ds_read_b128 v[188:191], v150 offset:50176
	ds_read_b128 v[192:195], v150 offset:51200
	ds_read_b128 v[196:199], v150 offset:52224
	ds_read_b128 v[200:203], v150 offset:53248
	ds_read_b128 v[204:207], v150 offset:54272
	ds_read_b128 v[208:211], v150 offset:55296
	ds_read_b128 v[212:215], v150 offset:56320
	global_load_lds_dwordx4 v[216:217], off
	s_add_i32 m0, s33, 0x2000
	s_add_u32 s38, s38, 0x40080
	v_lshl_add_u64 v[216:217], v[218:219], 0, s[12:13]
	s_addc_u32 s39, s39, 0
	s_add_i32 s33, s62, s46
	global_load_lds_dwordx4 v[216:217], off
	v_lshl_add_u64 v[216:217], s[38:39], 0, v[134:135]
	s_mov_b32 m0, s33
	s_nop 0
	global_load_lds_dwordx4 v[216:217], off
	v_lshl_add_u64 v[216:217], s[38:39], 0, v[130:131]
	s_add_i32 m0, s33, 0x2000
	s_nop 0
	global_load_lds_dwordx4 v[216:217], off
	v_lshl_add_u64 v[216:217], v[220:221], 0, s[12:13]
	s_mov_b32 m0, s57
	s_nop 0
	global_load_lds_dwordx4 v[216:217], off
	v_lshl_add_u64 v[216:217], v[222:223], 0, s[12:13]
	s_mov_b32 m0, s58
	s_nop 0
	global_load_lds_dwordx4 v[216:217], off
	s_waitcnt vmcnt(8)
	s_waitcnt lgkmcnt(0)
	s_barrier
	s_setprio 0
	s_waitcnt lgkmcnt(0)
	v_mfma_f32_16x16x32_bf16 v[62:65], v[152:155], v[184:187], v[62:65]
	v_mfma_f32_16x16x32_bf16 v[58:61], v[160:163], v[184:187], v[58:61]
	v_mfma_f32_16x16x32_bf16 v[46:49], v[152:155], v[192:195], v[46:49]
	v_mfma_f32_16x16x32_bf16 v[42:45], v[160:163], v[192:195], v[42:45]
	v_mfma_f32_16x16x32_bf16 v[30:33], v[152:155], v[200:203], v[30:33]
	v_mfma_f32_16x16x32_bf16 v[26:29], v[160:163], v[200:203], v[26:29]
	v_mfma_f32_16x16x32_bf16 v[14:17], v[152:155], v[208:211], v[14:17]
	v_mfma_f32_16x16x32_bf16 v[10:13], v[160:163], v[208:211], v[10:13]
	v_mfma_f32_16x16x32_bf16 v[62:65], v[156:159], v[188:191], v[62:65]
	v_mfma_f32_16x16x32_bf16 v[58:61], v[164:167], v[188:191], v[58:61]
	v_mfma_f32_16x16x32_bf16 v[46:49], v[156:159], v[196:199], v[46:49]
	v_mfma_f32_16x16x32_bf16 v[42:45], v[164:167], v[196:199], v[42:45]
	v_mfma_f32_16x16x32_bf16 v[30:33], v[156:159], v[204:207], v[30:33]
	v_mfma_f32_16x16x32_bf16 v[26:29], v[164:167], v[204:207], v[26:29]
	v_mfma_f32_16x16x32_bf16 v[14:17], v[156:159], v[212:215], v[14:17]
	v_mfma_f32_16x16x32_bf16 v[10:13], v[164:167], v[212:215], v[10:13]
	s_setprio 2
	s_setprio 0
	v_mfma_f32_16x16x32_bf16 v[54:57], v[168:171], v[184:187], v[54:57]
	v_mfma_f32_16x16x32_bf16 v[50:53], v[176:179], v[184:187], v[50:53]
	v_mfma_f32_16x16x32_bf16 v[38:41], v[168:171], v[192:195], v[38:41]
	v_mfma_f32_16x16x32_bf16 v[34:37], v[176:179], v[192:195], v[34:37]
	v_mfma_f32_16x16x32_bf16 v[22:25], v[168:171], v[200:203], v[22:25]
	v_mfma_f32_16x16x32_bf16 v[18:21], v[176:179], v[200:203], v[18:21]
	v_mfma_f32_16x16x32_bf16 v[6:9], v[168:171], v[208:211], v[6:9]
	v_mfma_f32_16x16x32_bf16 v[2:5], v[176:179], v[208:211], v[2:5]
	v_mfma_f32_16x16x32_bf16 v[54:57], v[172:175], v[188:191], v[54:57]
	v_mfma_f32_16x16x32_bf16 v[50:53], v[180:183], v[188:191], v[50:53]
	v_mfma_f32_16x16x32_bf16 v[38:41], v[172:175], v[196:199], v[38:41]
	v_mfma_f32_16x16x32_bf16 v[34:37], v[180:183], v[196:199], v[34:37]
	v_mfma_f32_16x16x32_bf16 v[22:25], v[172:175], v[204:207], v[22:25]
	v_mfma_f32_16x16x32_bf16 v[18:21], v[180:183], v[204:207], v[18:21]
	v_mfma_f32_16x16x32_bf16 v[6:9], v[172:175], v[212:215], v[6:9]
	v_mfma_f32_16x16x32_bf16 v[2:5], v[180:183], v[212:215], v[2:5]
	s_setprio 2
	s_barrier
	s_add_i32 s80, s80, 2
	s_add_u32 s4, s4, 0x100
	s_addc_u32 s5, s5, 0
	s_add_u32 s78, s78, 0x100
	s_addc_u32 s79, s79, 0
	s_cmp_gt_u32 s80, 13
	s_cbranch_scc0 .LBB0_1058

; #define PG8_STAGE(bufoff, gbase, voff) do { _Pragma("unroll") for (int _i = 0; _i < 2; ++_i) \
;         __builtin_amdgcn_global_load_lds((const unsigned*)((const char*)(gbase) + (voff)[_i]), (LAS unsigned*)(lds + (bufoff) + ldsw + _i * 8192), 16, 0, 0); } while (0)
; #define PG8_LDA(dst, b, h) do { _Pragma("unroll") for (int m = 0; m < 4; ++m) _Pragma("unroll") for (int k = 0; k < 2; ++k) dst[m][k] = *(const LAS bf16x8*)(lds + PG8_SA(b, h) + aoff + m * 2048 + k * 1024); } while (0)
; #define PG8_LDB(dst, b, h) do { _Pragma("unroll") for (int n = 0; n < 2; ++n) _Pragma("unroll") for (int k = 0; k < 2; ++k) dst[n][k] = *(const LAS bf16x8*)(lds + PG8_SB(b, h) + boff + n * 2048 + k * 1024); } while (0)
; #define PG8_MMA(ai, bj, At, Bt) do { __builtin_amdgcn_s_setprio(1); _Pragma("unroll") for (int m = 0; m < 4; ++m) _Pragma("unroll") for (int n = 0; n < 2; ++n) _Pragma("unroll") for (int k = 0; k < 2; ++k) \
;         acc[ai][bj][m][n] = __builtin_amdgcn_mfma_f32_16x16x32_bf16(Bt[n][k], At[m][k], acc[ai][bj][m][n], 0, 0, 0); __builtin_amdgcn_s_setprio(0); } while (0)
; template <class Epi>
; __device__ __forceinline__ void gemm_phase(LAS unsigned char* lds, const Gemm g, int G, int c, const Epi& E) {
;     ...
;         const bool has_next = S.next(ui + 1, nxt);
;         const char* nA = has_next ? (const char*)(g.A + (size_t)nxt.pb * g.sA) + (size_t)nxt.pm * 2 * hstepA : cA;
;         const char* nB = has_next ? (const char*)(g.Bt + (size_t)nxt.pb * g.sB) + (size_t)nxt.pn * 2 * hstepB : cB;
; #pragma nounroll
;         for (int t = 0; t < nt; t += 2) {
;             const bool last = (t == nt - 2);
;             const char* a1 = cA + (size_t)(t + 1) * kstep;
;             const char* a2 = last ? nA : cA + (size_t)(t + 2) * kstep; const char* b2 = last ? nB : cB + (size_t)(t + 2) * kstep;
;             const char* a3 = a2 + kstep; const char* b3 = b2 + kstep;
;             PG8_LDB(B0, 0, 0); PG8_LDB(B1, 0, 1); PG8_SCHED; PG8_LDA(At, 0, 0); PG8_STAGE(PG8_SA(1, 1), a1 + hstepA, voffA);
;             PG8_WAIT_V(8); PG8_WAIT_L(0); PG8_BAR; PG8_MMA(0, 0, At, B0); PG8_MMA(0, 1, At, B1); PG8_BAR; PG8_SCHED;
;             PG8_LDA(At, 0, 1); PG8_STAGE(PG8_SB(0, 0), b2, voffB); PG8_STAGE(PG8_SB(0, 1), b2 + hstepB, voffB); PG8_STAGE(PG8_SA(0, 0), a2, voffA);
;             PG8_WAIT_V(8); PG8_WAIT_L(0); PG8_BAR; PG8_MMA(1, 0, At, B0); PG8_MMA(1, 1, At, B1); PG8_BAR; PG8_SCHED;
.LBB0_1142:
	s_add_u32 s66, s18, 0x100
	s_addc_u32 s67, s19, 0
	s_mov_b32 s68, -2
	s_waitcnt vmcnt(0)
	ds_read_b128 v[122:125], v168
	ds_read_b128 v[126:129], v168 offset:1024
	ds_read_b128 v[130:133], v168 offset:2048
	ds_read_b128 v[134:137], v168 offset:3072
	ds_read_b128 v[162:165], v169
	ds_read_b128 v[172:175], v169 offset:1024
	ds_read_b128 v[176:179], v169 offset:2048
	ds_read_b128 v[180:183], v169 offset:3072
	s_add_u32 s18, s16, 0x100
	s_addc_u32 s19, s17, 0
	s_cmp_eq_u32 s68, 40
	s_cselect_b32 s23, s5, s19
	s_cselect_b32 s22, s4, s18
	s_cselect_b32 s21, s15, s67
	s_cselect_b32 s20, s14, s66
	v_lshl_add_u64 v[216:217], s[16:17], 0, v[154:155]
	s_add_i32 m0, s38, 0xc000
	ds_read_b128 v[184:187], v170
	ds_read_b128 v[188:191], v170 offset:1024
	ds_read_b128 v[192:195], v170 offset:2048
	ds_read_b128 v[196:199], v170 offset:3072
	ds_read_b128 v[200:203], v170 offset:4096
	ds_read_b128 v[204:207], v170 offset:5120
	ds_read_b128 v[208:211], v170 offset:6144
	ds_read_b128 v[212:215], v170 offset:7168
	global_load_lds_dwordx4 v[216:217], off
	v_lshl_add_u64 v[216:217], s[16:17], 0, v[156:157]
	s_add_i32 m0, s38, 0xe000
	s_nop 0
	global_load_lds_dwordx4 v[216:217], off
	s_waitcnt vmcnt(8)
	s_waitcnt lgkmcnt(0)
	s_barrier
	s_setprio 0
	s_waitcnt lgkmcnt(0)
	v_mfma_f32_16x16x32_bf16 v[142:145], v[122:125], v[184:187], 0
	v_mfma_f32_16x16x32_bf16 v[138:141], v[130:133], v[184:187], 0
	v_mfma_f32_16x16x32_bf16 v[118:121], v[122:125], v[192:195], 0
	v_mfma_f32_16x16x32_bf16 v[106:109], v[130:133], v[192:195], 0
	v_mfma_f32_16x16x32_bf16 v[102:105], v[122:125], v[200:203], 0
	v_mfma_f32_16x16x32_bf16 v[90:93], v[130:133], v[200:203], 0
	v_mfma_f32_16x16x32_bf16 v[86:89], v[122:125], v[208:211], 0
	v_mfma_f32_16x16x32_bf16 v[74:77], v[130:133], v[208:211], 0
	v_mfma_f32_16x16x32_bf16 v[142:145], v[126:129], v[188:191], v[142:145]
	v_mfma_f32_16x16x32_bf16 v[138:141], v[134:137], v[188:191], v[138:141]
	v_mfma_f32_16x16x32_bf16 v[118:121], v[126:129], v[196:199], v[118:121]
	v_mfma_f32_16x16x32_bf16 v[106:109], v[134:137], v[196:199], v[106:109]
	v_mfma_f32_16x16x32_bf16 v[102:105], v[126:129], v[204:207], v[102:105]
	v_mfma_f32_16x16x32_bf16 v[90:93], v[134:137], v[204:207], v[90:93]
	v_mfma_f32_16x16x32_bf16 v[86:89], v[126:129], v[212:215], v[86:89]
	v_mfma_f32_16x16x32_bf16 v[74:77], v[134:137], v[212:215], v[74:77]
	s_setprio 2
	s_setprio 0
	v_mfma_f32_16x16x32_bf16 v[114:117], v[162:165], v[184:187], 0
	v_mfma_f32_16x16x32_bf16 v[110:113], v[176:179], v[184:187], 0
	v_mfma_f32_16x16x32_bf16 v[98:101], v[162:165], v[192:195], 0
	v_mfma_f32_16x16x32_bf16 v[94:97], v[176:179], v[192:195], 0
	v_mfma_f32_16x16x32_bf16 v[82:85], v[162:165], v[200:203], 0
	v_mfma_f32_16x16x32_bf16 v[78:81], v[176:179], v[200:203], 0
	v_mfma_f32_16x16x32_bf16 v[70:73], v[162:165], v[208:211], 0
	v_mfma_f32_16x16x32_bf16 v[66:69], v[176:179], v[208:211], 0
	v_mfma_f32_16x16x32_bf16 v[114:117], v[172:175], v[188:191], v[114:117]
	v_mfma_f32_16x16x32_bf16 v[110:113], v[180:183], v[188:191], v[110:113]
	v_mfma_f32_16x16x32_bf16 v[98:101], v[172:175], v[196:199], v[98:101]
	v_mfma_f32_16x16x32_bf16 v[94:97], v[180:183], v[196:199], v[94:97]
	v_mfma_f32_16x16x32_bf16 v[82:85], v[172:175], v[204:207], v[82:85]
	v_mfma_f32_16x16x32_bf16 v[78:81], v[180:183], v[204:207], v[78:81]
	v_mfma_f32_16x16x32_bf16 v[70:73], v[172:175], v[212:215], v[70:73]
	v_mfma_f32_16x16x32_bf16 v[66:69], v[180:183], v[212:215], v[66:69]
	s_setprio 2
	s_barrier
	s_add_i32 s16, s54, s36
	v_lshl_add_u64 v[216:217], s[20:21], 0, v[150:151]
	s_mov_b32 m0, s16
	ds_read_b128 v[184:187], v170 offset:16384
	ds_read_b128 v[188:191], v170 offset:17408
	ds_read_b128 v[192:195], v170 offset:18432
	ds_read_b128 v[196:199], v170 offset:19456
	ds_read_b128 v[200:203], v170 offset:20480
	ds_read_b128 v[204:207], v170 offset:21504
	ds_read_b128 v[208:211], v170 offset:22528
	ds_read_b128 v[212:215], v170 offset:23552
	global_load_lds_dwordx4 v[216:217], off
	s_add_i32 m0, s16, 0x2000
	s_add_u32 s16, s20, 0xb0000
	v_lshl_add_u64 v[218:219], s[20:21], 0, v[146:147]
	s_addc_u32 s17, s21, 0
	s_add_i32 s33, s55, s36
	global_load_lds_dwordx4 v[218:219], off
	v_lshl_add_u64 v[220:221], s[16:17], 0, v[150:151]
	s_mov_b32 m0, s33
	v_lshl_add_u64 v[222:223], s[22:23], 0, v[148:149]
	global_load_lds_dwordx4 v[220:221], off
	v_lshl_add_u64 v[220:221], s[16:17], 0, v[146:147]
	s_add_i32 m0, s33, 0x2000
	s_nop 0
	global_load_lds_dwordx4 v[220:221], off
	v_lshl_add_u64 v[220:221], s[22:23], 0, v[152:153]
	s_mov_b32 m0, s38
	s_nop 0
	global_load_lds_dwordx4 v[220:221], off
	s_mov_b32 m0, s39
	s_nop 0
	global_load_lds_dwordx4 v[222:223], off
	s_waitcnt vmcnt(8)
	s_waitcnt lgkmcnt(0)
	s_barrier
; #define PG8_STAGE(bufoff, gbase, voff) do { _Pragma("unroll") for (int _i = 0; _i < 2; ++_i) \
;         __builtin_amdgcn_global_load_lds((const unsigned*)((const char*)(gbase) + (voff)[_i]), (LAS unsigned*)(lds + (bufoff) + ldsw + _i * 8192), 16, 0, 0); } while (0)
; #define PG8_LDA(dst, b, h) do { _Pragma("unroll") for (int m = 0; m < 4; ++m) _Pragma("unroll") for (int k = 0; k < 2; ++k) dst[m][k] = *(const LAS bf16x8*)(lds + PG8_SA(b, h) + aoff + m * 2048 + k * 1024); } while (0)
; #define PG8_LDB(dst, b, h) do { _Pragma("unroll") for (int n = 0; n < 2; ++n) _Pragma("unroll") for (int k = 0; k < 2; ++k) dst[n][k] = *(const LAS bf16x8*)(lds + PG8_SB(b, h) + boff + n * 2048 + k * 1024); } while (0)
; #define PG8_MMA(ai, bj, At, Bt) do { __builtin_amdgcn_s_setprio(1); _Pragma("unroll") for (int m = 0; m < 4; ++m) _Pragma("unroll") for (int n = 0; n < 2; ++n) _Pragma("unroll") for (int k = 0; k < 2; ++k) \
;         acc[ai][bj][m][n] = __builtin_amdgcn_mfma_f32_16x16x32_bf16(Bt[n][k], At[m][k], acc[ai][bj][m][n], 0, 0, 0); __builtin_amdgcn_s_setprio(0); } while (0)
; #define PG8_WAIT_V(n) asm volatile("s_waitcnt vmcnt(" #n ")" ::: "memory")
; #define PG8_WAIT_L(n) asm volatile("s_waitcnt lgkmcnt(" #n ")" ::: "memory")
; #define PG8_BAR __builtin_amdgcn_s_barrier()
; #define PG8_SCHED __builtin_amdgcn_sched_barrier(0)
; template <class Epi>
; __device__ __forceinline__ void gemm_phase(LAS unsigned char* lds, const Gemm g, int G, int c, const Epi& E) {
;     ...
;             PG8_WAIT_V(8); PG8_WAIT_L(0); PG8_BAR; PG8_MMA(1, 0, At, B0); PG8_MMA(1, 1, At, B1); PG8_BAR; PG8_SCHED;
;             PG8_LDB(B0, 1, 0); PG8_LDB(B1, 1, 1); PG8_SCHED; PG8_LDA(At, 1, 0); PG8_STAGE(PG8_SA(0, 1), a2 + hstepA, voffA);
;             PG8_WAIT_V(8); PG8_WAIT_L(0); PG8_BAR; PG8_MMA(0, 0, At, B0); PG8_MMA(0, 1, At, B1); PG8_BAR; PG8_SCHED;
	s_setprio 0
	s_waitcnt lgkmcnt(0)
	v_mfma_f32_16x16x32_bf16 v[62:65], v[122:125], v[184:187], 0
	v_mfma_f32_16x16x32_bf16 v[58:61], v[130:133], v[184:187], 0
	v_mfma_f32_16x16x32_bf16 v[54:57], v[122:125], v[192:195], 0
	v_mfma_f32_16x16x32_bf16 v[42:45], v[130:133], v[192:195], 0
	v_mfma_f32_16x16x32_bf16 v[38:41], v[122:125], v[200:203], 0
	v_mfma_f32_16x16x32_bf16 v[26:29], v[130:133], v[200:203], 0
	v_mfma_f32_16x16x32_bf16 v[22:25], v[122:125], v[208:211], 0
	v_mfma_f32_16x16x32_bf16 v[10:13], v[130:133], v[208:211], 0
	v_mfma_f32_16x16x32_bf16 v[62:65], v[126:129], v[188:191], v[62:65]
	v_mfma_f32_16x16x32_bf16 v[58:61], v[134:137], v[188:191], v[58:61]
	v_mfma_f32_16x16x32_bf16 v[54:57], v[126:129], v[196:199], v[54:57]
	v_mfma_f32_16x16x32_bf16 v[42:45], v[134:137], v[196:199], v[42:45]
	v_mfma_f32_16x16x32_bf16 v[38:41], v[126:129], v[204:207], v[38:41]
	v_mfma_f32_16x16x32_bf16 v[26:29], v[134:137], v[204:207], v[26:29]
	v_mfma_f32_16x16x32_bf16 v[22:25], v[126:129], v[212:215], v[22:25]
	v_mfma_f32_16x16x32_bf16 v[10:13], v[134:137], v[212:215], v[10:13]
	s_setprio 2
	s_setprio 0
	v_mfma_f32_16x16x32_bf16 v[50:53], v[162:165], v[184:187], 0
	v_mfma_f32_16x16x32_bf16 v[46:49], v[176:179], v[184:187], 0
	v_mfma_f32_16x16x32_bf16 v[34:37], v[162:165], v[192:195], 0
	v_mfma_f32_16x16x32_bf16 v[30:33], v[176:179], v[192:195], 0
	v_mfma_f32_16x16x32_bf16 v[18:21], v[162:165], v[200:203], 0
	v_mfma_f32_16x16x32_bf16 v[14:17], v[176:179], v[200:203], 0
	v_mfma_f32_16x16x32_bf16 v[6:9], v[162:165], v[208:211], 0
	v_mfma_f32_16x16x32_bf16 v[2:5], v[176:179], v[208:211], 0
	v_mfma_f32_16x16x32_bf16 v[50:53], v[172:175], v[188:191], v[50:53]
	v_mfma_f32_16x16x32_bf16 v[46:49], v[180:183], v[188:191], v[46:49]
	v_mfma_f32_16x16x32_bf16 v[34:37], v[172:175], v[196:199], v[34:37]
	v_mfma_f32_16x16x32_bf16 v[30:33], v[180:183], v[196:199], v[30:33]
	v_mfma_f32_16x16x32_bf16 v[18:21], v[172:175], v[204:207], v[18:21]
	v_mfma_f32_16x16x32_bf16 v[14:17], v[180:183], v[204:207], v[14:17]
	v_mfma_f32_16x16x32_bf16 v[6:9], v[172:175], v[212:215], v[6:9]
	v_mfma_f32_16x16x32_bf16 v[2:5], v[180:183], v[212:215], v[2:5]
	s_setprio 2
	s_barrier
	s_add_i32 s33, 0, 0x18000
	s_add_i32 s62, 0, 0x1c000
	v_add_u32_e32 v134, s33, v167
	v_add_u32_e32 v171, s62, v167
	ds_read_b128 v[122:125], v134
	ds_read_b128 v[126:129], v134 offset:1024
	ds_read_b128 v[130:133], v134 offset:2048
	ds_read_b128 v[134:137], v134 offset:3072
	ds_read_b128 v[162:165], v171
	ds_read_b128 v[172:175], v171 offset:1024
	ds_read_b128 v[176:179], v171 offset:2048
	ds_read_b128 v[180:183], v171 offset:3072
	s_add_u32 s16, s22, 0xb0000
	s_addc_u32 s17, s23, 0
	s_mov_b32 m0, s40
	v_lshl_add_u64 v[224:225], s[16:17], 0, v[152:153]
	ds_read_b128 v[184:187], v170 offset:32768
	ds_read_b128 v[188:191], v170 offset:33792
	ds_read_b128 v[192:195], v170 offset:34816
	ds_read_b128 v[196:199], v170 offset:35840
	ds_read_b128 v[200:203], v170 offset:36864
	ds_read_b128 v[204:207], v170 offset:37888
	ds_read_b128 v[208:211], v170 offset:38912
	ds_read_b128 v[212:215], v170 offset:39936
	global_load_lds_dwordx4 v[224:225], off
	v_lshl_add_u64 v[224:225], s[16:17], 0, v[148:149]
	s_mov_b32 m0, s41
	s_nop 0
	global_load_lds_dwordx4 v[224:225], off
	s_waitcnt vmcnt(8)
	s_waitcnt lgkmcnt(0)
	s_barrier
	s_setprio 0
	s_waitcnt lgkmcnt(0)
	v_mfma_f32_16x16x32_bf16 v[142:145], v[122:125], v[184:187], v[142:145]
	v_mfma_f32_16x16x32_bf16 v[138:141], v[130:133], v[184:187], v[138:141]
	v_mfma_f32_16x16x32_bf16 v[118:121], v[122:125], v[192:195], v[118:121]
	v_mfma_f32_16x16x32_bf16 v[106:109], v[130:133], v[192:195], v[106:109]
	v_mfma_f32_16x16x32_bf16 v[102:105], v[122:125], v[200:203], v[102:105]
	v_mfma_f32_16x16x32_bf16 v[90:93], v[130:133], v[200:203], v[90:93]
	v_mfma_f32_16x16x32_bf16 v[86:89], v[122:125], v[208:211], v[86:89]
	v_mfma_f32_16x16x32_bf16 v[74:77], v[130:133], v[208:211], v[74:77]
	v_mfma_f32_16x16x32_bf16 v[142:145], v[126:129], v[188:191], v[142:145]
	v_mfma_f32_16x16x32_bf16 v[138:141], v[134:137], v[188:191], v[138:141]
	v_mfma_f32_16x16x32_bf16 v[118:121], v[126:129], v[196:199], v[118:121]
	v_mfma_f32_16x16x32_bf16 v[106:109], v[134:137], v[196:199], v[106:109]
	v_mfma_f32_16x16x32_bf16 v[102:105], v[126:129], v[204:207], v[102:105]
	v_mfma_f32_16x16x32_bf16 v[90:93], v[134:137], v[204:207], v[90:93]
	v_mfma_f32_16x16x32_bf16 v[86:89], v[126:129], v[212:215], v[86:89]
	v_mfma_f32_16x16x32_bf16 v[74:77], v[134:137], v[212:215], v[74:77]
	s_setprio 2
	s_setprio 0
	v_mfma_f32_16x16x32_bf16 v[114:117], v[162:165], v[184:187], v[114:117]
	v_mfma_f32_16x16x32_bf16 v[110:113], v[176:179], v[184:187], v[110:113]
	v_mfma_f32_16x16x32_bf16 v[98:101], v[162:165], v[192:195], v[98:101]
	v_mfma_f32_16x16x32_bf16 v[94:97], v[176:179], v[192:195], v[94:97]
	v_mfma_f32_16x16x32_bf16 v[82:85], v[162:165], v[200:203], v[82:85]
	v_mfma_f32_16x16x32_bf16 v[78:81], v[176:179], v[200:203], v[78:81]
	v_mfma_f32_16x16x32_bf16 v[70:73], v[162:165], v[208:211], v[70:73]
	v_mfma_f32_16x16x32_bf16 v[66:69], v[176:179], v[208:211], v[66:69]
	v_mfma_f32_16x16x32_bf16 v[114:117], v[172:175], v[188:191], v[114:117]
	v_mfma_f32_16x16x32_bf16 v[110:113], v[180:183], v[188:191], v[110:113]
	v_mfma_f32_16x16x32_bf16 v[98:101], v[172:175], v[196:199], v[98:101]
	v_mfma_f32_16x16x32_bf16 v[94:97], v[180:183], v[196:199], v[94:97]
	v_mfma_f32_16x16x32_bf16 v[82:85], v[172:175], v[204:207], v[82:85]
	v_mfma_f32_16x16x32_bf16 v[78:81], v[180:183], v[204:207], v[78:81]
	v_mfma_f32_16x16x32_bf16 v[70:73], v[172:175], v[212:215], v[70:73]
	v_mfma_f32_16x16x32_bf16 v[66:69], v[180:183], v[212:215], v[66:69]
	s_setprio 2
	s_barrier
; #define PG8_STAGE(bufoff, gbase, voff) do { _Pragma("unroll") for (int _i = 0; _i < 2; ++_i) \
;         __builtin_amdgcn_global_load_lds((const unsigned*)((const char*)(gbase) + (voff)[_i]), (LAS unsigned*)(lds + (bufoff) + ldsw + _i * 8192), 16, 0, 0); } while (0)
; #define PG8_LDA(dst, b, h) do { _Pragma("unroll") for (int m = 0; m < 4; ++m) _Pragma("unroll") for (int k = 0; k < 2; ++k) dst[m][k] = *(const LAS bf16x8*)(lds + PG8_SA(b, h) + aoff + m * 2048 + k * 1024); } while (0)
; #define PG8_MMA(ai, bj, At, Bt) do { __builtin_amdgcn_s_setprio(1); _Pragma("unroll") for (int m = 0; m < 4; ++m) _Pragma("unroll") for (int n = 0; n < 2; ++n) _Pragma("unroll") for (int k = 0; k < 2; ++k) \
;         acc[ai][bj][m][n] = __builtin_amdgcn_mfma_f32_16x16x32_bf16(Bt[n][k], At[m][k], acc[ai][bj][m][n], 0, 0, 0); __builtin_amdgcn_s_setprio(0); } while (0)
; #define PG8_WAIT_V(n) asm volatile("s_waitcnt vmcnt(" #n ")" ::: "memory")
; #define PG8_WAIT_L(n) asm volatile("s_waitcnt lgkmcnt(" #n ")" ::: "memory")
; #define PG8_BAR __builtin_amdgcn_s_barrier()
; #define PG8_SCHED __builtin_amdgcn_sched_barrier(0)
; template <class Epi>
; __device__ __forceinline__ void gemm_phase(LAS unsigned char* lds, const Gemm g, int G, int c, const Epi& E) {
;     ...
;             PG8_LDA(At, 1, 1); PG8_STAGE(PG8_SB(1, 0), b3, voffB); PG8_STAGE(PG8_SB(1, 1), b3 + hstepB, voffB); PG8_STAGE(PG8_SA(1, 0), a3, voffA);
;             PG8_WAIT_V(8); PG8_WAIT_L(0); PG8_BAR; PG8_MMA(1, 0, At, B0); PG8_MMA(1, 1, At, B1); PG8_BAR; PG8_SCHED;
;         }
	s_add_i32 s16, s33, s36
	v_lshl_add_u64 v[216:217], v[216:217], 0, s[10:11]
	s_mov_b32 m0, s16
	ds_read_b128 v[184:187], v170 offset:49152
	ds_read_b128 v[188:191], v170 offset:50176
	ds_read_b128 v[192:195], v170 offset:51200
	ds_read_b128 v[196:199], v170 offset:52224
	ds_read_b128 v[200:203], v170 offset:53248
	ds_read_b128 v[204:207], v170 offset:54272
	ds_read_b128 v[208:211], v170 offset:55296
	ds_read_b128 v[212:215], v170 offset:56320
	global_load_lds_dwordx4 v[216:217], off
	s_add_i32 m0, s16, 0x2000
	s_add_u32 s16, s20, 0xb0080
	v_lshl_add_u64 v[216:217], v[218:219], 0, s[10:11]
	s_addc_u32 s17, s21, 0
	s_add_i32 s20, s62, s36
	global_load_lds_dwordx4 v[216:217], off
	v_lshl_add_u64 v[216:217], s[16:17], 0, v[150:151]
	s_mov_b32 m0, s20
	s_nop 0
	global_load_lds_dwordx4 v[216:217], off
	v_lshl_add_u64 v[216:217], s[16:17], 0, v[146:147]
	s_add_i32 m0, s20, 0x2000
	s_nop 0
	global_load_lds_dwordx4 v[216:217], off
	v_lshl_add_u64 v[216:217], v[220:221], 0, s[10:11]
	s_mov_b32 m0, s47
	s_nop 0
	global_load_lds_dwordx4 v[216:217], off
	v_lshl_add_u64 v[216:217], v[222:223], 0, s[10:11]
	s_mov_b32 m0, s52
	s_nop 0
	global_load_lds_dwordx4 v[216:217], off
	s_waitcnt vmcnt(8)
	s_waitcnt lgkmcnt(0)
	s_barrier
	s_setprio 0
	s_waitcnt lgkmcnt(0)
	v_mfma_f32_16x16x32_bf16 v[62:65], v[122:125], v[184:187], v[62:65]
	v_mfma_f32_16x16x32_bf16 v[58:61], v[130:133], v[184:187], v[58:61]
	v_mfma_f32_16x16x32_bf16 v[54:57], v[122:125], v[192:195], v[54:57]
	v_mfma_f32_16x16x32_bf16 v[42:45], v[130:133], v[192:195], v[42:45]
	v_mfma_f32_16x16x32_bf16 v[38:41], v[122:125], v[200:203], v[38:41]
	v_mfma_f32_16x16x32_bf16 v[26:29], v[130:133], v[200:203], v[26:29]
	v_mfma_f32_16x16x32_bf16 v[22:25], v[122:125], v[208:211], v[22:25]
	v_mfma_f32_16x16x32_bf16 v[10:13], v[130:133], v[208:211], v[10:13]
	v_mfma_f32_16x16x32_bf16 v[62:65], v[126:129], v[188:191], v[62:65]
	v_mfma_f32_16x16x32_bf16 v[58:61], v[134:137], v[188:191], v[58:61]
	v_mfma_f32_16x16x32_bf16 v[54:57], v[126:129], v[196:199], v[54:57]
	v_mfma_f32_16x16x32_bf16 v[42:45], v[134:137], v[196:199], v[42:45]
	v_mfma_f32_16x16x32_bf16 v[38:41], v[126:129], v[204:207], v[38:41]
	v_mfma_f32_16x16x32_bf16 v[26:29], v[134:137], v[204:207], v[26:29]
	v_mfma_f32_16x16x32_bf16 v[22:25], v[126:129], v[212:215], v[22:25]
	v_mfma_f32_16x16x32_bf16 v[10:13], v[134:137], v[212:215], v[10:13]
	s_setprio 2
	s_setprio 0
	v_mfma_f32_16x16x32_bf16 v[50:53], v[162:165], v[184:187], v[50:53]
	v_mfma_f32_16x16x32_bf16 v[46:49], v[176:179], v[184:187], v[46:49]
	v_mfma_f32_16x16x32_bf16 v[34:37], v[162:165], v[192:195], v[34:37]
	v_mfma_f32_16x16x32_bf16 v[30:33], v[176:179], v[192:195], v[30:33]
	v_mfma_f32_16x16x32_bf16 v[18:21], v[162:165], v[200:203], v[18:21]
	v_mfma_f32_16x16x32_bf16 v[14:17], v[176:179], v[200:203], v[14:17]
	v_mfma_f32_16x16x32_bf16 v[6:9], v[162:165], v[208:211], v[6:9]
	v_mfma_f32_16x16x32_bf16 v[2:5], v[176:179], v[208:211], v[2:5]
	v_mfma_f32_16x16x32_bf16 v[50:53], v[172:175], v[188:191], v[50:53]
	v_mfma_f32_16x16x32_bf16 v[46:49], v[180:183], v[188:191], v[46:49]
	v_mfma_f32_16x16x32_bf16 v[34:37], v[172:175], v[196:199], v[34:37]
	v_mfma_f32_16x16x32_bf16 v[30:33], v[180:183], v[196:199], v[30:33]
	v_mfma_f32_16x16x32_bf16 v[18:21], v[172:175], v[204:207], v[18:21]
	v_mfma_f32_16x16x32_bf16 v[14:17], v[180:183], v[204:207], v[14:17]
	v_mfma_f32_16x16x32_bf16 v[6:9], v[172:175], v[212:215], v[6:9]
	v_mfma_f32_16x16x32_bf16 v[2:5], v[180:183], v[212:215], v[2:5]
	s_setprio 2
	s_barrier
	s_add_i32 s68, s68, 2
	s_add_u32 s66, s66, 0x100
	s_addc_u32 s67, s67, 0
	s_cmp_gt_u32 s68, 41
	s_mov_b64 s[16:17], s[18:19]
	s_cbranch_scc0 .LBB0_1143

; #define PG8_STAGE(bufoff, gbase, voff) do { _Pragma("unroll") for (int _i = 0; _i < 2; ++_i) \
;         __builtin_amdgcn_global_load_lds((const unsigned*)((const char*)(gbase) + (voff)[_i]), (LAS unsigned*)(lds + (bufoff) + ldsw + _i * 8192), 16, 0, 0); } while (0)
; #define PG8_LDA(dst, b, h) do { _Pragma("unroll") for (int m = 0; m < 4; ++m) _Pragma("unroll") for (int k = 0; k < 2; ++k) dst[m][k] = *(const LAS bf16x8*)(lds + PG8_SA(b, h) + aoff + m * 2048 + k * 1024); } while (0)
; #define PG8_LDB(dst, b, h) do { _Pragma("unroll") for (int n = 0; n < 2; ++n) _Pragma("unroll") for (int k = 0; k < 2; ++k) dst[n][k] = *(const LAS bf16x8*)(lds + PG8_SB(b, h) + boff + n * 2048 + k * 1024); } while (0)
; #define PG8_MMA(ai, bj, At, Bt) do { __builtin_amdgcn_s_setprio(1); _Pragma("unroll") for (int m = 0; m < 4; ++m) _Pragma("unroll") for (int n = 0; n < 2; ++n) _Pragma("unroll") for (int k = 0; k < 2; ++k) \
;         acc[ai][bj][m][n] = __builtin_amdgcn_mfma_f32_16x16x32_bf16(Bt[n][k], At[m][k], acc[ai][bj][m][n], 0, 0, 0); __builtin_amdgcn_s_setprio(0); } while (0)
; template <class Epi>
; __device__ __forceinline__ void gemm_phase(LAS unsigned char* lds, const Gemm g, int G, int c, const Epi& E) {
;     ...
;         const bool has_next = S.next(ui + 1, nxt);
;         const char* nA = has_next ? (const char*)(g.A + (size_t)nxt.pb * g.sA) + (size_t)nxt.pm * 2 * hstepA : cA;
;         const char* nB = has_next ? (const char*)(g.Bt + (size_t)nxt.pb * g.sB) + (size_t)nxt.pn * 2 * hstepB : cB;
; #pragma nounroll
;         for (int t = 0; t < nt; t += 2) {
;             const bool last = (t == nt - 2);
;             const char* a1 = cA + (size_t)(t + 1) * kstep;
;             const char* a2 = last ? nA : cA + (size_t)(t + 2) * kstep; const char* b2 = last ? nB : cB + (size_t)(t + 2) * kstep;
;             const char* a3 = a2 + kstep; const char* b3 = b2 + kstep;
;             PG8_LDB(B0, 0, 0); PG8_LDB(B1, 0, 1); PG8_SCHED; PG8_LDA(At, 0, 0); PG8_STAGE(PG8_SA(1, 1), a1 + hstepA, voffA);
;             PG8_WAIT_V(8); PG8_WAIT_L(0); PG8_BAR; PG8_MMA(0, 0, At, B0); PG8_MMA(0, 1, At, B1); PG8_BAR; PG8_SCHED;
;             PG8_LDA(At, 0, 1); PG8_STAGE(PG8_SB(0, 0), b2, voffB); PG8_STAGE(PG8_SB(0, 1), b2 + hstepB, voffB); PG8_STAGE(PG8_SA(0, 0), a2, voffA);
;             PG8_WAIT_V(8); PG8_WAIT_L(0); PG8_BAR; PG8_MMA(1, 0, At, B0); PG8_MMA(1, 1, At, B1); PG8_BAR; PG8_SCHED;
.LBB0_1296:
	s_ashr_i32 s39, s38, 31
	s_lshl_b64 s[44:45], s[38:39], 19
	s_add_u32 s44, s54, s44
	s_addc_u32 s45, s55, s45
	s_and_b64 s[4:5], s[4:5], exec
	s_cselect_b32 s7, s45, s47
	s_cselect_b32 s39, s44, s46
	s_add_u32 s4, s48, 0x40080
	s_addc_u32 s5, s49, 0
	s_add_u32 s41, s46, 0x100
	s_addc_u32 s80, s47, 0
	s_mov_b32 s81, -2
	s_waitcnt lgkmcnt(0)
	ds_read_b128 v[146:149], v152
	ds_read_b128 v[158:161], v152 offset:1024
	ds_read_b128 v[162:165], v152 offset:2048
	ds_read_b128 v[166:169], v152 offset:3072
	ds_read_b128 v[170:173], v153
	ds_read_b128 v[174:177], v153 offset:1024
	ds_read_b128 v[178:181], v153 offset:2048
	ds_read_b128 v[182:185], v153 offset:3072
	s_add_u32 s33, s4, 0xfffc0080
	s_addc_u32 s46, s5, -1
	s_cmp_eq_u32 s81, 12
	s_cselect_b32 s49, s43, s46
	s_cselect_b32 s48, s42, s33
	s_cselect_b32 s47, s7, s80
	s_cselect_b32 s46, s39, s41
	v_lshl_add_u64 v[218:219], s[4:5], 0, v[138:139]
	s_add_i32 m0, s11, 0xc000
	ds_read_b128 v[186:189], v154
	ds_read_b128 v[190:193], v154 offset:1024
	ds_read_b128 v[194:197], v154 offset:2048
	ds_read_b128 v[198:201], v154 offset:3072
	ds_read_b128 v[202:205], v154 offset:4096
	ds_read_b128 v[206:209], v154 offset:5120
	ds_read_b128 v[210:213], v154 offset:6144
	ds_read_b128 v[214:217], v154 offset:7168
	global_load_lds_dwordx4 v[218:219], off
	v_lshl_add_u64 v[218:219], s[4:5], 0, v[140:141]
	s_add_i32 m0, s11, 0xe000
	s_nop 0
	global_load_lds_dwordx4 v[218:219], off
	s_waitcnt vmcnt(8)
	s_waitcnt lgkmcnt(0)
	s_barrier
	s_setprio 0
	s_waitcnt lgkmcnt(0)
	v_mfma_f32_16x16x32_bf16 v[126:129], v[146:149], v[186:189], 0
	v_mfma_f32_16x16x32_bf16 v[122:125], v[162:165], v[186:189], 0
	v_mfma_f32_16x16x32_bf16 v[110:113], v[146:149], v[194:197], 0
	v_mfma_f32_16x16x32_bf16 v[106:109], v[162:165], v[194:197], 0
	v_mfma_f32_16x16x32_bf16 v[94:97], v[146:149], v[202:205], 0
	v_mfma_f32_16x16x32_bf16 v[90:93], v[162:165], v[202:205], 0
	v_mfma_f32_16x16x32_bf16 v[78:81], v[146:149], v[210:213], 0
	v_mfma_f32_16x16x32_bf16 v[74:77], v[162:165], v[210:213], 0
	v_mfma_f32_16x16x32_bf16 v[126:129], v[158:161], v[190:193], v[126:129]
	v_mfma_f32_16x16x32_bf16 v[122:125], v[166:169], v[190:193], v[122:125]
	v_mfma_f32_16x16x32_bf16 v[110:113], v[158:161], v[198:201], v[110:113]
	v_mfma_f32_16x16x32_bf16 v[106:109], v[166:169], v[198:201], v[106:109]
	v_mfma_f32_16x16x32_bf16 v[94:97], v[158:161], v[206:209], v[94:97]
	v_mfma_f32_16x16x32_bf16 v[90:93], v[166:169], v[206:209], v[90:93]
	v_mfma_f32_16x16x32_bf16 v[78:81], v[158:161], v[214:217], v[78:81]
	v_mfma_f32_16x16x32_bf16 v[74:77], v[166:169], v[214:217], v[74:77]
	s_setprio 2
	s_setprio 0
	v_mfma_f32_16x16x32_bf16 v[118:121], v[170:173], v[186:189], 0
	v_mfma_f32_16x16x32_bf16 v[114:117], v[178:181], v[186:189], 0
	v_mfma_f32_16x16x32_bf16 v[102:105], v[170:173], v[194:197], 0
	v_mfma_f32_16x16x32_bf16 v[98:101], v[178:181], v[194:197], 0
	v_mfma_f32_16x16x32_bf16 v[86:89], v[170:173], v[202:205], 0
	v_mfma_f32_16x16x32_bf16 v[82:85], v[178:181], v[202:205], 0
	v_mfma_f32_16x16x32_bf16 v[70:73], v[170:173], v[210:213], 0
	v_mfma_f32_16x16x32_bf16 v[66:69], v[178:181], v[210:213], 0
	v_mfma_f32_16x16x32_bf16 v[118:121], v[174:177], v[190:193], v[118:121]
	v_mfma_f32_16x16x32_bf16 v[114:117], v[182:185], v[190:193], v[114:117]
	v_mfma_f32_16x16x32_bf16 v[102:105], v[174:177], v[198:201], v[102:105]
	v_mfma_f32_16x16x32_bf16 v[98:101], v[182:185], v[198:201], v[98:101]
	v_mfma_f32_16x16x32_bf16 v[86:89], v[174:177], v[206:209], v[86:89]
	v_mfma_f32_16x16x32_bf16 v[82:85], v[182:185], v[206:209], v[82:85]
	v_mfma_f32_16x16x32_bf16 v[70:73], v[174:177], v[214:217], v[70:73]
	v_mfma_f32_16x16x32_bf16 v[66:69], v[182:185], v[214:217], v[66:69]
	s_setprio 2
	s_barrier
	s_add_i32 s33, s71, s56
	v_lshl_add_u64 v[218:219], s[46:47], 0, v[132:133]
	s_mov_b32 m0, s33
	ds_read_b128 v[186:189], v154 offset:16384
	ds_read_b128 v[190:193], v154 offset:17408
	ds_read_b128 v[194:197], v154 offset:18432
	ds_read_b128 v[198:201], v154 offset:19456
	ds_read_b128 v[202:205], v154 offset:20480
	ds_read_b128 v[206:209], v154 offset:21504
	ds_read_b128 v[210:213], v154 offset:22528
	ds_read_b128 v[214:217], v154 offset:23552
	global_load_lds_dwordx4 v[218:219], off
	s_add_i32 m0, s33, 0x2000
	s_add_u32 s62, s46, 0x40000
	v_lshl_add_u64 v[220:221], s[46:47], 0, v[136:137]
	s_addc_u32 s63, s47, 0
	s_add_i32 s33, s72, s56
	global_load_lds_dwordx4 v[220:221], off
	v_lshl_add_u64 v[222:223], s[62:63], 0, v[132:133]
	s_mov_b32 m0, s33
	v_lshl_add_u64 v[224:225], s[48:49], 0, v[134:135]
	global_load_lds_dwordx4 v[222:223], off
	v_lshl_add_u64 v[222:223], s[62:63], 0, v[136:137]
	s_add_i32 m0, s33, 0x2000
	s_nop 0
	global_load_lds_dwordx4 v[222:223], off
	v_lshl_add_u64 v[222:223], s[48:49], 0, v[130:131]
	s_mov_b32 m0, s11
	s_nop 0
	global_load_lds_dwordx4 v[222:223], off
	s_mov_b32 m0, s57
	s_nop 0
	global_load_lds_dwordx4 v[224:225], off
	s_waitcnt vmcnt(8)
	s_waitcnt lgkmcnt(0)
	s_barrier
; #define PG8_STAGE(bufoff, gbase, voff) do { _Pragma("unroll") for (int _i = 0; _i < 2; ++_i) \
;         __builtin_amdgcn_global_load_lds((const unsigned*)((const char*)(gbase) + (voff)[_i]), (LAS unsigned*)(lds + (bufoff) + ldsw + _i * 8192), 16, 0, 0); } while (0)
; #define PG8_LDA(dst, b, h) do { _Pragma("unroll") for (int m = 0; m < 4; ++m) _Pragma("unroll") for (int k = 0; k < 2; ++k) dst[m][k] = *(const LAS bf16x8*)(lds + PG8_SA(b, h) + aoff + m * 2048 + k * 1024); } while (0)
; #define PG8_LDB(dst, b, h) do { _Pragma("unroll") for (int n = 0; n < 2; ++n) _Pragma("unroll") for (int k = 0; k < 2; ++k) dst[n][k] = *(const LAS bf16x8*)(lds + PG8_SB(b, h) + boff + n * 2048 + k * 1024); } while (0)
; #define PG8_MMA(ai, bj, At, Bt) do { __builtin_amdgcn_s_setprio(1); _Pragma("unroll") for (int m = 0; m < 4; ++m) _Pragma("unroll") for (int n = 0; n < 2; ++n) _Pragma("unroll") for (int k = 0; k < 2; ++k) \
;         acc[ai][bj][m][n] = __builtin_amdgcn_mfma_f32_16x16x32_bf16(Bt[n][k], At[m][k], acc[ai][bj][m][n], 0, 0, 0); __builtin_amdgcn_s_setprio(0); } while (0)
; #define PG8_WAIT_V(n) asm volatile("s_waitcnt vmcnt(" #n ")" ::: "memory")
; #define PG8_WAIT_L(n) asm volatile("s_waitcnt lgkmcnt(" #n ")" ::: "memory")
; #define PG8_BAR __builtin_amdgcn_s_barrier()
; #define PG8_SCHED __builtin_amdgcn_sched_barrier(0)
; template <class Epi>
; __device__ __forceinline__ void gemm_phase(LAS unsigned char* lds, const Gemm g, int G, int c, const Epi& E) {
;     ...
;             PG8_WAIT_V(8); PG8_WAIT_L(0); PG8_BAR; PG8_MMA(1, 0, At, B0); PG8_MMA(1, 1, At, B1); PG8_BAR; PG8_SCHED;
;             PG8_LDB(B0, 1, 0); PG8_LDB(B1, 1, 1); PG8_SCHED; PG8_LDA(At, 1, 0); PG8_STAGE(PG8_SA(0, 1), a2 + hstepA, voffA);
;             PG8_WAIT_V(8); PG8_WAIT_L(0); PG8_BAR; PG8_MMA(0, 0, At, B0); PG8_MMA(0, 1, At, B1); PG8_BAR; PG8_SCHED;
	s_setprio 0
	s_waitcnt lgkmcnt(0)
	v_mfma_f32_16x16x32_bf16 v[62:65], v[146:149], v[186:189], 0
	v_mfma_f32_16x16x32_bf16 v[58:61], v[162:165], v[186:189], 0
	v_mfma_f32_16x16x32_bf16 v[46:49], v[146:149], v[194:197], 0
	v_mfma_f32_16x16x32_bf16 v[42:45], v[162:165], v[194:197], 0
	v_mfma_f32_16x16x32_bf16 v[30:33], v[146:149], v[202:205], 0
	v_mfma_f32_16x16x32_bf16 v[26:29], v[162:165], v[202:205], 0
	v_mfma_f32_16x16x32_bf16 v[14:17], v[146:149], v[210:213], 0
	v_mfma_f32_16x16x32_bf16 v[10:13], v[162:165], v[210:213], 0
	v_mfma_f32_16x16x32_bf16 v[62:65], v[158:161], v[190:193], v[62:65]
	v_mfma_f32_16x16x32_bf16 v[58:61], v[166:169], v[190:193], v[58:61]
	v_mfma_f32_16x16x32_bf16 v[46:49], v[158:161], v[198:201], v[46:49]
	v_mfma_f32_16x16x32_bf16 v[42:45], v[166:169], v[198:201], v[42:45]
	v_mfma_f32_16x16x32_bf16 v[30:33], v[158:161], v[206:209], v[30:33]
	v_mfma_f32_16x16x32_bf16 v[26:29], v[166:169], v[206:209], v[26:29]
	v_mfma_f32_16x16x32_bf16 v[14:17], v[158:161], v[214:217], v[14:17]
	v_mfma_f32_16x16x32_bf16 v[10:13], v[166:169], v[214:217], v[10:13]
	s_setprio 2
	s_setprio 0
	v_mfma_f32_16x16x32_bf16 v[54:57], v[170:173], v[186:189], 0
	v_mfma_f32_16x16x32_bf16 v[50:53], v[178:181], v[186:189], 0
	v_mfma_f32_16x16x32_bf16 v[38:41], v[170:173], v[194:197], 0
	v_mfma_f32_16x16x32_bf16 v[34:37], v[178:181], v[194:197], 0
	v_mfma_f32_16x16x32_bf16 v[22:25], v[170:173], v[202:205], 0
	v_mfma_f32_16x16x32_bf16 v[18:21], v[178:181], v[202:205], 0
	v_mfma_f32_16x16x32_bf16 v[6:9], v[170:173], v[210:213], 0
	v_mfma_f32_16x16x32_bf16 v[2:5], v[178:181], v[210:213], 0
	v_mfma_f32_16x16x32_bf16 v[54:57], v[174:177], v[190:193], v[54:57]
	v_mfma_f32_16x16x32_bf16 v[50:53], v[182:185], v[190:193], v[50:53]
	v_mfma_f32_16x16x32_bf16 v[38:41], v[174:177], v[198:201], v[38:41]
	v_mfma_f32_16x16x32_bf16 v[34:37], v[182:185], v[198:201], v[34:37]
	v_mfma_f32_16x16x32_bf16 v[22:25], v[174:177], v[206:209], v[22:25]
	v_mfma_f32_16x16x32_bf16 v[18:21], v[182:185], v[206:209], v[18:21]
	v_mfma_f32_16x16x32_bf16 v[6:9], v[174:177], v[214:217], v[6:9]
	v_mfma_f32_16x16x32_bf16 v[2:5], v[182:185], v[214:217], v[2:5]
	s_setprio 2
	s_barrier
	s_add_i32 s33, 0, 0x18000
	v_add_u32_e32 v157, s33, v151
	s_add_i32 s62, 0, 0x1c000
	ds_read_b128 v[146:149], v157
	ds_read_b128 v[158:161], v157 offset:1024
	ds_read_b128 v[162:165], v157 offset:2048
	ds_read_b128 v[166:169], v157 offset:3072
	v_add_u32_e32 v157, s62, v151
	ds_read_b128 v[170:173], v157
	ds_read_b128 v[174:177], v157 offset:1024
	ds_read_b128 v[178:181], v157 offset:2048
	ds_read_b128 v[182:185], v157 offset:3072
	s_add_u32 s48, s48, 0x40000
	s_addc_u32 s49, s49, 0
	s_mov_b32 m0, s58
	v_lshl_add_u64 v[226:227], s[48:49], 0, v[130:131]
	ds_read_b128 v[186:189], v154 offset:32768
	ds_read_b128 v[190:193], v154 offset:33792
	ds_read_b128 v[194:197], v154 offset:34816
	ds_read_b128 v[198:201], v154 offset:35840
	ds_read_b128 v[202:205], v154 offset:36864
	ds_read_b128 v[206:209], v154 offset:37888
	ds_read_b128 v[210:213], v154 offset:38912
	ds_read_b128 v[214:217], v154 offset:39936
	global_load_lds_dwordx4 v[226:227], off
	v_lshl_add_u64 v[226:227], s[48:49], 0, v[134:135]
	s_mov_b32 m0, s59
	s_nop 0
	global_load_lds_dwordx4 v[226:227], off
	s_waitcnt vmcnt(8)
	s_waitcnt lgkmcnt(0)
	s_barrier
	s_setprio 0
	s_waitcnt lgkmcnt(0)
	v_mfma_f32_16x16x32_bf16 v[126:129], v[146:149], v[186:189], v[126:129]
	v_mfma_f32_16x16x32_bf16 v[122:125], v[162:165], v[186:189], v[122:125]
	v_mfma_f32_16x16x32_bf16 v[110:113], v[146:149], v[194:197], v[110:113]
	v_mfma_f32_16x16x32_bf16 v[106:109], v[162:165], v[194:197], v[106:109]
	v_mfma_f32_16x16x32_bf16 v[94:97], v[146:149], v[202:205], v[94:97]
	v_mfma_f32_16x16x32_bf16 v[90:93], v[162:165], v[202:205], v[90:93]
	v_mfma_f32_16x16x32_bf16 v[78:81], v[146:149], v[210:213], v[78:81]
	v_mfma_f32_16x16x32_bf16 v[74:77], v[162:165], v[210:213], v[74:77]
	v_mfma_f32_16x16x32_bf16 v[126:129], v[158:161], v[190:193], v[126:129]
	v_mfma_f32_16x16x32_bf16 v[122:125], v[166:169], v[190:193], v[122:125]
	v_mfma_f32_16x16x32_bf16 v[110:113], v[158:161], v[198:201], v[110:113]
	v_mfma_f32_16x16x32_bf16 v[106:109], v[166:169], v[198:201], v[106:109]
	v_mfma_f32_16x16x32_bf16 v[94:97], v[158:161], v[206:209], v[94:97]
	v_mfma_f32_16x16x32_bf16 v[90:93], v[166:169], v[206:209], v[90:93]
	v_mfma_f32_16x16x32_bf16 v[78:81], v[158:161], v[214:217], v[78:81]
	v_mfma_f32_16x16x32_bf16 v[74:77], v[166:169], v[214:217], v[74:77]
	s_setprio 2
	s_setprio 0
	v_mfma_f32_16x16x32_bf16 v[118:121], v[170:173], v[186:189], v[118:121]
	v_mfma_f32_16x16x32_bf16 v[114:117], v[178:181], v[186:189], v[114:117]
	v_mfma_f32_16x16x32_bf16 v[102:105], v[170:173], v[194:197], v[102:105]
	v_mfma_f32_16x16x32_bf16 v[98:101], v[178:181], v[194:197], v[98:101]
	v_mfma_f32_16x16x32_bf16 v[86:89], v[170:173], v[202:205], v[86:89]
	v_mfma_f32_16x16x32_bf16 v[82:85], v[178:181], v[202:205], v[82:85]
	v_mfma_f32_16x16x32_bf16 v[70:73], v[170:173], v[210:213], v[70:73]
	v_mfma_f32_16x16x32_bf16 v[66:69], v[178:181], v[210:213], v[66:69]
	v_mfma_f32_16x16x32_bf16 v[118:121], v[174:177], v[190:193], v[118:121]
	v_mfma_f32_16x16x32_bf16 v[114:117], v[182:185], v[190:193], v[114:117]
	v_mfma_f32_16x16x32_bf16 v[102:105], v[174:177], v[198:201], v[102:105]
	v_mfma_f32_16x16x32_bf16 v[98:101], v[182:185], v[198:201], v[98:101]
	v_mfma_f32_16x16x32_bf16 v[86:89], v[174:177], v[206:209], v[86:89]
	v_mfma_f32_16x16x32_bf16 v[82:85], v[182:185], v[206:209], v[82:85]
	v_mfma_f32_16x16x32_bf16 v[70:73], v[174:177], v[214:217], v[70:73]
	v_mfma_f32_16x16x32_bf16 v[66:69], v[182:185], v[214:217], v[66:69]
	s_setprio 2
	s_barrier
; #define PG8_STAGE(bufoff, gbase, voff) do { _Pragma("unroll") for (int _i = 0; _i < 2; ++_i) \
;         __builtin_amdgcn_global_load_lds((const unsigned*)((const char*)(gbase) + (voff)[_i]), (LAS unsigned*)(lds + (bufoff) + ldsw + _i * 8192), 16, 0, 0); } while (0)
; #define PG8_LDA(dst, b, h) do { _Pragma("unroll") for (int m = 0; m < 4; ++m) _Pragma("unroll") for (int k = 0; k < 2; ++k) dst[m][k] = *(const LAS bf16x8*)(lds + PG8_SA(b, h) + aoff + m * 2048 + k * 1024); } while (0)
; #define PG8_MMA(ai, bj, At, Bt) do { __builtin_amdgcn_s_setprio(1); _Pragma("unroll") for (int m = 0; m < 4; ++m) _Pragma("unroll") for (int n = 0; n < 2; ++n) _Pragma("unroll") for (int k = 0; k < 2; ++k) \
;         acc[ai][bj][m][n] = __builtin_amdgcn_mfma_f32_16x16x32_bf16(Bt[n][k], At[m][k], acc[ai][bj][m][n], 0, 0, 0); __builtin_amdgcn_s_setprio(0); } while (0)
; #define PG8_WAIT_V(n) asm volatile("s_waitcnt vmcnt(" #n ")" ::: "memory")
; #define PG8_WAIT_L(n) asm volatile("s_waitcnt lgkmcnt(" #n ")" ::: "memory")
; #define PG8_BAR __builtin_amdgcn_s_barrier()
; #define PG8_SCHED __builtin_amdgcn_sched_barrier(0)
; template <class Epi>
; __device__ __forceinline__ void gemm_phase(LAS unsigned char* lds, const Gemm g, int G, int c, const Epi& E) {
;     ...
;             PG8_LDA(At, 1, 1); PG8_STAGE(PG8_SB(1, 0), b3, voffB); PG8_STAGE(PG8_SB(1, 1), b3 + hstepB, voffB); PG8_STAGE(PG8_SA(1, 0), a3, voffA);
;             PG8_WAIT_V(8); PG8_WAIT_L(0); PG8_BAR; PG8_MMA(1, 0, At, B0); PG8_MMA(1, 1, At, B1); PG8_BAR; PG8_SCHED;
;         }
	s_add_i32 s33, s33, s56
	v_lshl_add_u64 v[218:219], v[218:219], 0, s[20:21]
	s_mov_b32 m0, s33
	ds_read_b128 v[186:189], v154 offset:49152
	ds_read_b128 v[190:193], v154 offset:50176
	ds_read_b128 v[194:197], v154 offset:51200
	ds_read_b128 v[198:201], v154 offset:52224
	ds_read_b128 v[202:205], v154 offset:53248
	ds_read_b128 v[206:209], v154 offset:54272
	ds_read_b128 v[210:213], v154 offset:55296
	ds_read_b128 v[214:217], v154 offset:56320
	global_load_lds_dwordx4 v[218:219], off
	s_add_i32 m0, s33, 0x2000
	s_add_u32 s46, s46, 0x40080
	v_lshl_add_u64 v[218:219], v[220:221], 0, s[20:21]
	s_addc_u32 s47, s47, 0
	s_add_i32 s33, s62, s56
	global_load_lds_dwordx4 v[218:219], off
	v_lshl_add_u64 v[218:219], s[46:47], 0, v[132:133]
	s_mov_b32 m0, s33
	s_nop 0
	global_load_lds_dwordx4 v[218:219], off
	v_lshl_add_u64 v[218:219], s[46:47], 0, v[136:137]
	s_add_i32 m0, s33, 0x2000
	s_nop 0
	global_load_lds_dwordx4 v[218:219], off
	v_lshl_add_u64 v[218:219], v[222:223], 0, s[20:21]
	s_mov_b32 m0, s67
	s_nop 0
	global_load_lds_dwordx4 v[218:219], off
	v_lshl_add_u64 v[218:219], v[224:225], 0, s[20:21]
	s_mov_b32 m0, s68
	s_nop 0
	global_load_lds_dwordx4 v[218:219], off
	s_waitcnt vmcnt(8)
	s_waitcnt lgkmcnt(0)
	s_barrier
	s_setprio 0
	s_waitcnt lgkmcnt(0)
	v_mfma_f32_16x16x32_bf16 v[62:65], v[146:149], v[186:189], v[62:65]
	v_mfma_f32_16x16x32_bf16 v[58:61], v[162:165], v[186:189], v[58:61]
	v_mfma_f32_16x16x32_bf16 v[46:49], v[146:149], v[194:197], v[46:49]
	v_mfma_f32_16x16x32_bf16 v[42:45], v[162:165], v[194:197], v[42:45]
	v_mfma_f32_16x16x32_bf16 v[30:33], v[146:149], v[202:205], v[30:33]
	v_mfma_f32_16x16x32_bf16 v[26:29], v[162:165], v[202:205], v[26:29]
	v_mfma_f32_16x16x32_bf16 v[14:17], v[146:149], v[210:213], v[14:17]
	v_mfma_f32_16x16x32_bf16 v[10:13], v[162:165], v[210:213], v[10:13]
	v_mfma_f32_16x16x32_bf16 v[62:65], v[158:161], v[190:193], v[62:65]
	v_mfma_f32_16x16x32_bf16 v[58:61], v[166:169], v[190:193], v[58:61]
	v_mfma_f32_16x16x32_bf16 v[46:49], v[158:161], v[198:201], v[46:49]
	v_mfma_f32_16x16x32_bf16 v[42:45], v[166:169], v[198:201], v[42:45]
	v_mfma_f32_16x16x32_bf16 v[30:33], v[158:161], v[206:209], v[30:33]
	v_mfma_f32_16x16x32_bf16 v[26:29], v[166:169], v[206:209], v[26:29]
	v_mfma_f32_16x16x32_bf16 v[14:17], v[158:161], v[214:217], v[14:17]
	v_mfma_f32_16x16x32_bf16 v[10:13], v[166:169], v[214:217], v[10:13]
	s_setprio 2
	s_setprio 0
	v_mfma_f32_16x16x32_bf16 v[54:57], v[170:173], v[186:189], v[54:57]
	v_mfma_f32_16x16x32_bf16 v[50:53], v[178:181], v[186:189], v[50:53]
	v_mfma_f32_16x16x32_bf16 v[38:41], v[170:173], v[194:197], v[38:41]
	v_mfma_f32_16x16x32_bf16 v[34:37], v[178:181], v[194:197], v[34:37]
	v_mfma_f32_16x16x32_bf16 v[22:25], v[170:173], v[202:205], v[22:25]
	v_mfma_f32_16x16x32_bf16 v[18:21], v[178:181], v[202:205], v[18:21]
	v_mfma_f32_16x16x32_bf16 v[6:9], v[170:173], v[210:213], v[6:9]
	v_mfma_f32_16x16x32_bf16 v[2:5], v[178:181], v[210:213], v[2:5]
	v_mfma_f32_16x16x32_bf16 v[54:57], v[174:177], v[190:193], v[54:57]
	v_mfma_f32_16x16x32_bf16 v[50:53], v[182:185], v[190:193], v[50:53]
	v_mfma_f32_16x16x32_bf16 v[38:41], v[174:177], v[198:201], v[38:41]
	v_mfma_f32_16x16x32_bf16 v[34:37], v[182:185], v[198:201], v[34:37]
	v_mfma_f32_16x16x32_bf16 v[22:25], v[174:177], v[206:209], v[22:25]
	v_mfma_f32_16x16x32_bf16 v[18:21], v[182:185], v[206:209], v[18:21]
	v_mfma_f32_16x16x32_bf16 v[6:9], v[174:177], v[214:217], v[6:9]
	v_mfma_f32_16x16x32_bf16 v[2:5], v[182:185], v[214:217], v[2:5]
	s_setprio 2
	s_barrier
	s_add_i32 s81, s81, 2
	s_add_u32 s4, s4, 0x100
	s_addc_u32 s5, s5, 0
	s_add_u32 s41, s41, 0x100
	s_addc_u32 s80, s80, 0
	s_cmp_gt_u32 s81, 13
	s_cbranch_scc0 .LBB0_1297

; #define PG8_STAGE(bufoff, gbase, voff) do { _Pragma("unroll") for (int _i = 0; _i < 2; ++_i) \
;         __builtin_amdgcn_global_load_lds((const unsigned*)((const char*)(gbase) + (voff)[_i]), (LAS unsigned*)(lds + (bufoff) + ldsw + _i * 8192), 16, 0, 0); } while (0)
; #define PG8_LDA(dst, b, h) do { _Pragma("unroll") for (int m = 0; m < 4; ++m) _Pragma("unroll") for (int k = 0; k < 2; ++k) dst[m][k] = *(const LAS bf16x8*)(lds + PG8_SA(b, h) + aoff + m * 2048 + k * 1024); } while (0)
; #define PG8_LDB(dst, b, h) do { _Pragma("unroll") for (int n = 0; n < 2; ++n) _Pragma("unroll") for (int k = 0; k < 2; ++k) dst[n][k] = *(const LAS bf16x8*)(lds + PG8_SB(b, h) + boff + n * 2048 + k * 1024); } while (0)
; #define PG8_MMA(ai, bj, At, Bt) do { __builtin_amdgcn_s_setprio(1); _Pragma("unroll") for (int m = 0; m < 4; ++m) _Pragma("unroll") for (int n = 0; n < 2; ++n) _Pragma("unroll") for (int k = 0; k < 2; ++k) \
;         acc[ai][bj][m][n] = __builtin_amdgcn_mfma_f32_16x16x32_bf16(Bt[n][k], At[m][k], acc[ai][bj][m][n], 0, 0, 0); __builtin_amdgcn_s_setprio(0); } while (0)
; template <class Epi>
; __device__ __forceinline__ void gemm_phase(LAS unsigned char* lds, const Gemm g, int G, int c, const Epi& E) {
;     ...
;         const bool has_next = S.next(ui + 1, nxt);
;         const char* nA = has_next ? (const char*)(g.A + (size_t)nxt.pb * g.sA) + (size_t)nxt.pm * 2 * hstepA : cA;
;         const char* nB = has_next ? (const char*)(g.Bt + (size_t)nxt.pb * g.sB) + (size_t)nxt.pn * 2 * hstepB : cB;
; #pragma nounroll
;         for (int t = 0; t < nt; t += 2) {
;             const bool last = (t == nt - 2);
;             const char* a1 = cA + (size_t)(t + 1) * kstep;
;             const char* a2 = last ? nA : cA + (size_t)(t + 2) * kstep; const char* b2 = last ? nB : cB + (size_t)(t + 2) * kstep;
;             const char* a3 = a2 + kstep; const char* b3 = b2 + kstep;
;             PG8_LDB(B0, 0, 0); PG8_LDB(B1, 0, 1); PG8_SCHED; PG8_LDA(At, 0, 0); PG8_STAGE(PG8_SA(1, 1), a1 + hstepA, voffA);
;             PG8_WAIT_V(8); PG8_WAIT_L(0); PG8_BAR; PG8_MMA(0, 0, At, B0); PG8_MMA(0, 1, At, B1); PG8_BAR; PG8_SCHED;
;             PG8_LDA(At, 0, 1); PG8_STAGE(PG8_SB(0, 0), b2, voffB); PG8_STAGE(PG8_SB(0, 1), b2 + hstepB, voffB); PG8_STAGE(PG8_SA(0, 0), a2, voffA);
;             PG8_WAIT_V(8); PG8_WAIT_L(0); PG8_BAR; PG8_MMA(1, 0, At, B0); PG8_MMA(1, 1, At, B1); PG8_BAR; PG8_SCHED;
.LBB0_1428:
	s_mov_b32 s13, 0
	s_mov_b64 s[20:21], -1
	s_mov_b64 s[22:23], 0
	s_add_u32 s33, s18, s13
	s_addc_u32 s42, s19, 0
	s_add_u32 s38, s33, 0x100
	s_addc_u32 s39, s42, 0
	s_and_b64 s[24:25], s[22:23], exec
	s_cselect_b32 s39, s5, s39
	s_cselect_b32 s38, s4, s38
	s_add_u32 s13, s16, s13
	s_addc_u32 s24, s17, 0
	s_add_u32 s13, s13, 0x100
	s_addc_u32 s24, s24, 0
	s_and_b64 s[22:23], s[22:23], exec
	s_cselect_b32 s41, s15, s24
	s_cselect_b32 s40, s14, s13
	s_add_u32 s44, s33, 0xb0080
	ds_read_b128 v[142:145], v148
	ds_read_b128 v[152:155], v148 offset:1024
	ds_read_b128 v[156:159], v148 offset:2048
	ds_read_b128 v[160:163], v148 offset:3072
	ds_read_b128 v[164:167], v149
	ds_read_b128 v[168:171], v149 offset:1024
	ds_read_b128 v[172:175], v149 offset:2048
	ds_read_b128 v[176:179], v149 offset:3072
	s_addc_u32 s45, s42, 0
	s_add_i32 s65, s72, s48
	s_add_i32 m0, s49, 0xc000
	s_add_i32 s85, s49, 0xe000
	s_add_i32 s62, s65, 0x2000
	s_add_u32 s42, s40, 0xb0000
	s_addc_u32 s43, s41, 0
	s_add_i32 s64, s73, s48
	s_add_i32 s63, s64, 0x2000
	s_add_i32 s84, 0, 0x18000
	s_add_i32 s33, 0, 0x1c000
	s_add_u32 s24, s38, 0xb0000
	s_addc_u32 s25, s39, 0
	s_add_i32 s83, s84, s48
	s_add_i32 s13, s83, 0x2000
	s_add_u32 s22, s40, 0xb0080
	s_addc_u32 s23, s41, 0
	s_add_i32 s75, s33, s48
	s_add_i32 s74, s75, 0x2000
	v_lshl_add_u64 v[212:213], s[44:45], 0, v[136:137]
	ds_read_b128 v[180:183], v150
	ds_read_b128 v[184:187], v150 offset:1024
	ds_read_b128 v[188:191], v150 offset:2048
	ds_read_b128 v[192:195], v150 offset:3072
	ds_read_b128 v[196:199], v150 offset:4096
	ds_read_b128 v[200:203], v150 offset:5120
	ds_read_b128 v[204:207], v150 offset:6144
	ds_read_b128 v[208:211], v150 offset:7168
	global_load_lds_dwordx4 v[212:213], off
	v_lshl_add_u64 v[212:213], s[44:45], 0, v[132:133]
	s_mov_b32 m0, s85
	s_nop 0
	global_load_lds_dwordx4 v[212:213], off
	s_waitcnt vmcnt(8)
	s_waitcnt lgkmcnt(0)
	s_barrier
	s_setprio 0
	s_waitcnt lgkmcnt(0)
	v_mfma_f32_16x16x32_bf16 v[126:129], v[142:145], v[180:183], 0
	v_mfma_f32_16x16x32_bf16 v[122:125], v[156:159], v[180:183], 0
	v_mfma_f32_16x16x32_bf16 v[118:121], v[142:145], v[188:191], 0
	v_mfma_f32_16x16x32_bf16 v[110:113], v[156:159], v[188:191], 0
	v_mfma_f32_16x16x32_bf16 v[102:105], v[142:145], v[196:199], 0
	v_mfma_f32_16x16x32_bf16 v[94:97], v[156:159], v[196:199], 0
	v_mfma_f32_16x16x32_bf16 v[86:89], v[142:145], v[204:207], 0
	v_mfma_f32_16x16x32_bf16 v[78:81], v[156:159], v[204:207], 0
	v_mfma_f32_16x16x32_bf16 v[126:129], v[152:155], v[184:187], v[126:129]
	v_mfma_f32_16x16x32_bf16 v[122:125], v[160:163], v[184:187], v[122:125]
	v_mfma_f32_16x16x32_bf16 v[118:121], v[152:155], v[192:195], v[118:121]
	v_mfma_f32_16x16x32_bf16 v[110:113], v[160:163], v[192:195], v[110:113]
	v_mfma_f32_16x16x32_bf16 v[102:105], v[152:155], v[200:203], v[102:105]
	v_mfma_f32_16x16x32_bf16 v[94:97], v[160:163], v[200:203], v[94:97]
	v_mfma_f32_16x16x32_bf16 v[86:89], v[152:155], v[208:211], v[86:89]
	v_mfma_f32_16x16x32_bf16 v[78:81], v[160:163], v[208:211], v[78:81]
	s_setprio 2
	s_setprio 0
	v_mfma_f32_16x16x32_bf16 v[114:117], v[164:167], v[180:183], 0
	v_mfma_f32_16x16x32_bf16 v[106:109], v[172:175], v[180:183], 0
	v_mfma_f32_16x16x32_bf16 v[98:101], v[164:167], v[188:191], 0
	v_mfma_f32_16x16x32_bf16 v[90:93], v[172:175], v[188:191], 0
	v_mfma_f32_16x16x32_bf16 v[82:85], v[164:167], v[196:199], 0
	v_mfma_f32_16x16x32_bf16 v[74:77], v[172:175], v[196:199], 0
	v_mfma_f32_16x16x32_bf16 v[70:73], v[164:167], v[204:207], 0
	v_mfma_f32_16x16x32_bf16 v[66:69], v[172:175], v[204:207], 0
	v_mfma_f32_16x16x32_bf16 v[114:117], v[168:171], v[184:187], v[114:117]
	v_mfma_f32_16x16x32_bf16 v[106:109], v[176:179], v[184:187], v[106:109]
	v_mfma_f32_16x16x32_bf16 v[98:101], v[168:171], v[192:195], v[98:101]
	v_mfma_f32_16x16x32_bf16 v[90:93], v[176:179], v[192:195], v[90:93]
	v_mfma_f32_16x16x32_bf16 v[82:85], v[168:171], v[200:203], v[82:85]
	v_mfma_f32_16x16x32_bf16 v[74:77], v[176:179], v[200:203], v[74:77]
	v_mfma_f32_16x16x32_bf16 v[70:73], v[168:171], v[208:211], v[70:73]
	v_mfma_f32_16x16x32_bf16 v[66:69], v[176:179], v[208:211], v[66:69]
	s_setprio 2
	s_barrier
	s_mov_b32 m0, s65
	v_lshl_add_u64 v[212:213], s[40:41], 0, v[134:135]
	ds_read_b128 v[180:183], v150 offset:16384
	ds_read_b128 v[184:187], v150 offset:17408
	ds_read_b128 v[188:191], v150 offset:18432
	ds_read_b128 v[192:195], v150 offset:19456
	ds_read_b128 v[196:199], v150 offset:20480
	ds_read_b128 v[200:203], v150 offset:21504
	ds_read_b128 v[204:207], v150 offset:22528
	ds_read_b128 v[208:211], v150 offset:23552
	global_load_lds_dwordx4 v[212:213], off
	v_lshl_add_u64 v[214:215], s[40:41], 0, v[130:131]
	s_mov_b32 m0, s62
	v_lshl_add_u64 v[216:217], s[42:43], 0, v[134:135]
	global_load_lds_dwordx4 v[214:215], off
	s_mov_b32 m0, s64
	v_lshl_add_u64 v[218:219], s[38:39], 0, v[132:133]
	global_load_lds_dwordx4 v[216:217], off
	v_lshl_add_u64 v[216:217], s[42:43], 0, v[130:131]
	s_mov_b32 m0, s63
	s_nop 0
	global_load_lds_dwordx4 v[216:217], off
	v_lshl_add_u64 v[216:217], s[38:39], 0, v[136:137]
	s_mov_b32 m0, s49
	s_nop 0
	global_load_lds_dwordx4 v[216:217], off
	s_mov_b32 m0, s52
	s_nop 0
	global_load_lds_dwordx4 v[218:219], off
	s_waitcnt vmcnt(8)
	s_waitcnt lgkmcnt(0)
	s_barrier
; #define PG8_STAGE(bufoff, gbase, voff) do { _Pragma("unroll") for (int _i = 0; _i < 2; ++_i) \
;         __builtin_amdgcn_global_load_lds((const unsigned*)((const char*)(gbase) + (voff)[_i]), (LAS unsigned*)(lds + (bufoff) + ldsw + _i * 8192), 16, 0, 0); } while (0)
; #define PG8_LDA(dst, b, h) do { _Pragma("unroll") for (int m = 0; m < 4; ++m) _Pragma("unroll") for (int k = 0; k < 2; ++k) dst[m][k] = *(const LAS bf16x8*)(lds + PG8_SA(b, h) + aoff + m * 2048 + k * 1024); } while (0)
; #define PG8_LDB(dst, b, h) do { _Pragma("unroll") for (int n = 0; n < 2; ++n) _Pragma("unroll") for (int k = 0; k < 2; ++k) dst[n][k] = *(const LAS bf16x8*)(lds + PG8_SB(b, h) + boff + n * 2048 + k * 1024); } while (0)
; #define PG8_MMA(ai, bj, At, Bt) do { __builtin_amdgcn_s_setprio(1); _Pragma("unroll") for (int m = 0; m < 4; ++m) _Pragma("unroll") for (int n = 0; n < 2; ++n) _Pragma("unroll") for (int k = 0; k < 2; ++k) \
;         acc[ai][bj][m][n] = __builtin_amdgcn_mfma_f32_16x16x32_bf16(Bt[n][k], At[m][k], acc[ai][bj][m][n], 0, 0, 0); __builtin_amdgcn_s_setprio(0); } while (0)
; #define PG8_WAIT_V(n) asm volatile("s_waitcnt vmcnt(" #n ")" ::: "memory")
; #define PG8_WAIT_L(n) asm volatile("s_waitcnt lgkmcnt(" #n ")" ::: "memory")
; #define PG8_BAR __builtin_amdgcn_s_barrier()
; #define PG8_SCHED __builtin_amdgcn_sched_barrier(0)
; template <class Epi>
; __device__ __forceinline__ void gemm_phase(LAS unsigned char* lds, const Gemm g, int G, int c, const Epi& E) {
;     ...
;             PG8_WAIT_V(8); PG8_WAIT_L(0); PG8_BAR; PG8_MMA(1, 0, At, B0); PG8_MMA(1, 1, At, B1); PG8_BAR; PG8_SCHED;
;             PG8_LDB(B0, 1, 0); PG8_LDB(B1, 1, 1); PG8_SCHED; PG8_LDA(At, 1, 0); PG8_STAGE(PG8_SA(0, 1), a2 + hstepA, voffA);
;             PG8_WAIT_V(8); PG8_WAIT_L(0); PG8_BAR; PG8_MMA(0, 0, At, B0); PG8_MMA(0, 1, At, B1); PG8_BAR; PG8_SCHED;
	s_setprio 0
	s_waitcnt lgkmcnt(0)
	v_mfma_f32_16x16x32_bf16 v[62:65], v[142:145], v[180:183], 0
	v_mfma_f32_16x16x32_bf16 v[58:61], v[156:159], v[180:183], 0
	v_mfma_f32_16x16x32_bf16 v[54:57], v[142:145], v[188:191], 0
	v_mfma_f32_16x16x32_bf16 v[46:49], v[156:159], v[188:191], 0
	v_mfma_f32_16x16x32_bf16 v[38:41], v[142:145], v[196:199], 0
	v_mfma_f32_16x16x32_bf16 v[30:33], v[156:159], v[196:199], 0
	v_mfma_f32_16x16x32_bf16 v[22:25], v[142:145], v[204:207], 0
	v_mfma_f32_16x16x32_bf16 v[14:17], v[156:159], v[204:207], 0
	v_mfma_f32_16x16x32_bf16 v[62:65], v[152:155], v[184:187], v[62:65]
	v_mfma_f32_16x16x32_bf16 v[58:61], v[160:163], v[184:187], v[58:61]
	v_mfma_f32_16x16x32_bf16 v[54:57], v[152:155], v[192:195], v[54:57]
	v_mfma_f32_16x16x32_bf16 v[46:49], v[160:163], v[192:195], v[46:49]
	v_mfma_f32_16x16x32_bf16 v[38:41], v[152:155], v[200:203], v[38:41]
	v_mfma_f32_16x16x32_bf16 v[30:33], v[160:163], v[200:203], v[30:33]
	v_mfma_f32_16x16x32_bf16 v[22:25], v[152:155], v[208:211], v[22:25]
	v_mfma_f32_16x16x32_bf16 v[14:17], v[160:163], v[208:211], v[14:17]
	s_setprio 2
	s_setprio 0
	v_mfma_f32_16x16x32_bf16 v[50:53], v[164:167], v[180:183], 0
	v_mfma_f32_16x16x32_bf16 v[42:45], v[172:175], v[180:183], 0
	v_mfma_f32_16x16x32_bf16 v[34:37], v[164:167], v[188:191], 0
	v_mfma_f32_16x16x32_bf16 v[26:29], v[172:175], v[188:191], 0
	v_mfma_f32_16x16x32_bf16 v[18:21], v[164:167], v[196:199], 0
	v_mfma_f32_16x16x32_bf16 v[10:13], v[172:175], v[196:199], 0
	v_mfma_f32_16x16x32_bf16 v[6:9], v[164:167], v[204:207], 0
	v_mfma_f32_16x16x32_bf16 v[2:5], v[172:175], v[204:207], 0
	v_mfma_f32_16x16x32_bf16 v[50:53], v[168:171], v[184:187], v[50:53]
	v_mfma_f32_16x16x32_bf16 v[42:45], v[176:179], v[184:187], v[42:45]
	v_mfma_f32_16x16x32_bf16 v[34:37], v[168:171], v[192:195], v[34:37]
	v_mfma_f32_16x16x32_bf16 v[26:29], v[176:179], v[192:195], v[26:29]
	v_mfma_f32_16x16x32_bf16 v[18:21], v[168:171], v[200:203], v[18:21]
	v_mfma_f32_16x16x32_bf16 v[10:13], v[176:179], v[200:203], v[10:13]
	v_mfma_f32_16x16x32_bf16 v[6:9], v[168:171], v[208:211], v[6:9]
	v_mfma_f32_16x16x32_bf16 v[2:5], v[176:179], v[208:211], v[2:5]
	s_setprio 2
	s_barrier
	v_add_u32_e32 v151, s84, v147
	ds_read_b128 v[142:145], v151
	ds_read_b128 v[152:155], v151 offset:1024
	ds_read_b128 v[156:159], v151 offset:2048
	ds_read_b128 v[160:163], v151 offset:3072
	v_add_u32_e32 v151, s33, v147
	ds_read_b128 v[164:167], v151
	ds_read_b128 v[168:171], v151 offset:1024
	ds_read_b128 v[172:175], v151 offset:2048
	ds_read_b128 v[176:179], v151 offset:3072
	s_mov_b32 m0, s53
	v_lshl_add_u64 v[220:221], s[24:25], 0, v[136:137]
	ds_read_b128 v[180:183], v150 offset:32768
	ds_read_b128 v[184:187], v150 offset:33792
	ds_read_b128 v[188:191], v150 offset:34816
	ds_read_b128 v[192:195], v150 offset:35840
	ds_read_b128 v[196:199], v150 offset:36864
	ds_read_b128 v[200:203], v150 offset:37888
	ds_read_b128 v[204:207], v150 offset:38912
	ds_read_b128 v[208:211], v150 offset:39936
	global_load_lds_dwordx4 v[220:221], off
	v_lshl_add_u64 v[220:221], s[24:25], 0, v[132:133]
	s_mov_b32 m0, s54
	s_nop 0
	global_load_lds_dwordx4 v[220:221], off
	s_waitcnt vmcnt(8)
	s_waitcnt lgkmcnt(0)
	s_barrier
	s_setprio 0
	s_waitcnt lgkmcnt(0)
	v_mfma_f32_16x16x32_bf16 v[126:129], v[142:145], v[180:183], v[126:129]
	v_mfma_f32_16x16x32_bf16 v[122:125], v[156:159], v[180:183], v[122:125]
	v_mfma_f32_16x16x32_bf16 v[118:121], v[142:145], v[188:191], v[118:121]
	v_mfma_f32_16x16x32_bf16 v[110:113], v[156:159], v[188:191], v[110:113]
	v_mfma_f32_16x16x32_bf16 v[102:105], v[142:145], v[196:199], v[102:105]
	v_mfma_f32_16x16x32_bf16 v[94:97], v[156:159], v[196:199], v[94:97]
	v_mfma_f32_16x16x32_bf16 v[86:89], v[142:145], v[204:207], v[86:89]
	v_mfma_f32_16x16x32_bf16 v[78:81], v[156:159], v[204:207], v[78:81]
	v_mfma_f32_16x16x32_bf16 v[126:129], v[152:155], v[184:187], v[126:129]
	v_mfma_f32_16x16x32_bf16 v[122:125], v[160:163], v[184:187], v[122:125]
	v_mfma_f32_16x16x32_bf16 v[118:121], v[152:155], v[192:195], v[118:121]
	v_mfma_f32_16x16x32_bf16 v[110:113], v[160:163], v[192:195], v[110:113]
	v_mfma_f32_16x16x32_bf16 v[102:105], v[152:155], v[200:203], v[102:105]
	v_mfma_f32_16x16x32_bf16 v[94:97], v[160:163], v[200:203], v[94:97]
	v_mfma_f32_16x16x32_bf16 v[86:89], v[152:155], v[208:211], v[86:89]
	v_mfma_f32_16x16x32_bf16 v[78:81], v[160:163], v[208:211], v[78:81]
	s_setprio 2
	s_setprio 0
	v_mfma_f32_16x16x32_bf16 v[114:117], v[164:167], v[180:183], v[114:117]
	v_mfma_f32_16x16x32_bf16 v[106:109], v[172:175], v[180:183], v[106:109]
	v_mfma_f32_16x16x32_bf16 v[98:101], v[164:167], v[188:191], v[98:101]
	v_mfma_f32_16x16x32_bf16 v[90:93], v[172:175], v[188:191], v[90:93]
	v_mfma_f32_16x16x32_bf16 v[82:85], v[164:167], v[196:199], v[82:85]
	v_mfma_f32_16x16x32_bf16 v[74:77], v[172:175], v[196:199], v[74:77]
	v_mfma_f32_16x16x32_bf16 v[70:73], v[164:167], v[204:207], v[70:73]
	v_mfma_f32_16x16x32_bf16 v[66:69], v[172:175], v[204:207], v[66:69]
	v_mfma_f32_16x16x32_bf16 v[114:117], v[168:171], v[184:187], v[114:117]
	v_mfma_f32_16x16x32_bf16 v[106:109], v[176:179], v[184:187], v[106:109]
	v_mfma_f32_16x16x32_bf16 v[98:101], v[168:171], v[192:195], v[98:101]
	v_mfma_f32_16x16x32_bf16 v[90:93], v[176:179], v[192:195], v[90:93]
	v_mfma_f32_16x16x32_bf16 v[82:85], v[168:171], v[200:203], v[82:85]
	v_mfma_f32_16x16x32_bf16 v[74:77], v[176:179], v[200:203], v[74:77]
	v_mfma_f32_16x16x32_bf16 v[70:73], v[168:171], v[208:211], v[70:73]
	v_mfma_f32_16x16x32_bf16 v[66:69], v[176:179], v[208:211], v[66:69]
	s_setprio 2
	s_barrier
; #define PG8_STAGE(bufoff, gbase, voff) do { _Pragma("unroll") for (int _i = 0; _i < 2; ++_i) \
;         __builtin_amdgcn_global_load_lds((const unsigned*)((const char*)(gbase) + (voff)[_i]), (LAS unsigned*)(lds + (bufoff) + ldsw + _i * 8192), 16, 0, 0); } while (0)
; #define PG8_LDA(dst, b, h) do { _Pragma("unroll") for (int m = 0; m < 4; ++m) _Pragma("unroll") for (int k = 0; k < 2; ++k) dst[m][k] = *(const LAS bf16x8*)(lds + PG8_SA(b, h) + aoff + m * 2048 + k * 1024); } while (0)
; #define PG8_MMA(ai, bj, At, Bt) do { __builtin_amdgcn_s_setprio(1); _Pragma("unroll") for (int m = 0; m < 4; ++m) _Pragma("unroll") for (int n = 0; n < 2; ++n) _Pragma("unroll") for (int k = 0; k < 2; ++k) \
;         acc[ai][bj][m][n] = __builtin_amdgcn_mfma_f32_16x16x32_bf16(Bt[n][k], At[m][k], acc[ai][bj][m][n], 0, 0, 0); __builtin_amdgcn_s_setprio(0); } while (0)
; #define PG8_WAIT_V(n) asm volatile("s_waitcnt vmcnt(" #n ")" ::: "memory")
; #define PG8_WAIT_L(n) asm volatile("s_waitcnt lgkmcnt(" #n ")" ::: "memory")
; #define PG8_BAR __builtin_amdgcn_s_barrier()
; #define PG8_SCHED __builtin_amdgcn_sched_barrier(0)
; template <class Epi>
; __device__ __forceinline__ void gemm_phase(LAS unsigned char* lds, const Gemm g, int G, int c, const Epi& E) {
;     ...
;             PG8_LDA(At, 1, 1); PG8_STAGE(PG8_SB(1, 0), b3, voffB); PG8_STAGE(PG8_SB(1, 1), b3 + hstepB, voffB); PG8_STAGE(PG8_SA(1, 0), a3, voffA);
;             PG8_WAIT_V(8); PG8_WAIT_L(0); PG8_BAR; PG8_MMA(1, 0, At, B0); PG8_MMA(1, 1, At, B1); PG8_BAR; PG8_SCHED;
;         }
	s_mov_b32 m0, s83
	v_lshl_add_u64 v[212:213], v[212:213], 0, s[8:9]
	ds_read_b128 v[180:183], v150 offset:49152
	ds_read_b128 v[184:187], v150 offset:50176
	ds_read_b128 v[188:191], v150 offset:51200
	ds_read_b128 v[192:195], v150 offset:52224
	ds_read_b128 v[196:199], v150 offset:53248
	ds_read_b128 v[200:203], v150 offset:54272
	ds_read_b128 v[204:207], v150 offset:55296
	ds_read_b128 v[208:211], v150 offset:56320
	global_load_lds_dwordx4 v[212:213], off
	v_lshl_add_u64 v[212:213], v[214:215], 0, s[8:9]
	s_mov_b32 m0, s13
	s_nop 0
	global_load_lds_dwordx4 v[212:213], off
	v_lshl_add_u64 v[212:213], s[22:23], 0, v[134:135]
	s_mov_b32 m0, s75
	s_nop 0
	global_load_lds_dwordx4 v[212:213], off
	v_lshl_add_u64 v[212:213], s[22:23], 0, v[130:131]
	s_mov_b32 m0, s74
	s_nop 0
	global_load_lds_dwordx4 v[212:213], off
	v_lshl_add_u64 v[212:213], v[216:217], 0, s[8:9]
	s_mov_b32 m0, s70
	s_nop 0
	global_load_lds_dwordx4 v[212:213], off
	v_lshl_add_u64 v[212:213], v[218:219], 0, s[8:9]
	s_mov_b32 m0, s71
	s_nop 0
	global_load_lds_dwordx4 v[212:213], off
	s_waitcnt vmcnt(8)
	s_waitcnt lgkmcnt(0)
	s_barrier
	s_setprio 0
	s_waitcnt lgkmcnt(0)
	v_mfma_f32_16x16x32_bf16 v[62:65], v[142:145], v[180:183], v[62:65]
	v_mfma_f32_16x16x32_bf16 v[58:61], v[156:159], v[180:183], v[58:61]
	v_mfma_f32_16x16x32_bf16 v[54:57], v[142:145], v[188:191], v[54:57]
	v_mfma_f32_16x16x32_bf16 v[46:49], v[156:159], v[188:191], v[46:49]
	v_mfma_f32_16x16x32_bf16 v[38:41], v[142:145], v[196:199], v[38:41]
	v_mfma_f32_16x16x32_bf16 v[30:33], v[156:159], v[196:199], v[30:33]
	v_mfma_f32_16x16x32_bf16 v[22:25], v[142:145], v[204:207], v[22:25]
	v_mfma_f32_16x16x32_bf16 v[14:17], v[156:159], v[204:207], v[14:17]
	v_mfma_f32_16x16x32_bf16 v[62:65], v[152:155], v[184:187], v[62:65]
	v_mfma_f32_16x16x32_bf16 v[58:61], v[160:163], v[184:187], v[58:61]
	v_mfma_f32_16x16x32_bf16 v[54:57], v[152:155], v[192:195], v[54:57]
	v_mfma_f32_16x16x32_bf16 v[46:49], v[160:163], v[192:195], v[46:49]
	v_mfma_f32_16x16x32_bf16 v[38:41], v[152:155], v[200:203], v[38:41]
	v_mfma_f32_16x16x32_bf16 v[30:33], v[160:163], v[200:203], v[30:33]
	v_mfma_f32_16x16x32_bf16 v[22:25], v[152:155], v[208:211], v[22:25]
	v_mfma_f32_16x16x32_bf16 v[14:17], v[160:163], v[208:211], v[14:17]
	s_setprio 2
	s_setprio 0
	v_mfma_f32_16x16x32_bf16 v[50:53], v[164:167], v[180:183], v[50:53]
	v_mfma_f32_16x16x32_bf16 v[42:45], v[172:175], v[180:183], v[42:45]
	v_mfma_f32_16x16x32_bf16 v[34:37], v[164:167], v[188:191], v[34:37]
	v_mfma_f32_16x16x32_bf16 v[26:29], v[172:175], v[188:191], v[26:29]
	v_mfma_f32_16x16x32_bf16 v[18:21], v[164:167], v[196:199], v[18:21]
	v_mfma_f32_16x16x32_bf16 v[10:13], v[172:175], v[196:199], v[10:13]
	v_mfma_f32_16x16x32_bf16 v[6:9], v[164:167], v[204:207], v[6:9]
	v_mfma_f32_16x16x32_bf16 v[2:5], v[172:175], v[204:207], v[2:5]
	v_mfma_f32_16x16x32_bf16 v[50:53], v[168:171], v[184:187], v[50:53]
	v_mfma_f32_16x16x32_bf16 v[42:45], v[176:179], v[184:187], v[42:45]
	v_mfma_f32_16x16x32_bf16 v[34:37], v[168:171], v[192:195], v[34:37]
	v_mfma_f32_16x16x32_bf16 v[26:29], v[176:179], v[192:195], v[26:29]
	v_mfma_f32_16x16x32_bf16 v[18:21], v[168:171], v[200:203], v[18:21]
	v_mfma_f32_16x16x32_bf16 v[10:13], v[176:179], v[200:203], v[10:13]
	v_mfma_f32_16x16x32_bf16 v[6:9], v[168:171], v[208:211], v[6:9]
	v_mfma_f32_16x16x32_bf16 v[2:5], v[176:179], v[208:211], v[2:5]
	s_setprio 2
	s_barrier
	s_movk_i32 s13, 0x100
	s_andn2_b64 vcc, exec, s[20:21]
	s_mov_b64 s[22:23], -1
	s_mov_b64 s[20:21], 0
	s_cbranch_vccz .LBB0_1429

; #define PG8_STAGE(bufoff, gbase, voff) do { _Pragma("unroll") for (int _i = 0; _i < 2; ++_i) \
;         __builtin_amdgcn_global_load_lds((const unsigned*)((const char*)(gbase) + (voff)[_i]), (LAS unsigned*)(lds + (bufoff) + ldsw + _i * 8192), 16, 0, 0); } while (0)
; #define PG8_LDA(dst, b, h) do { _Pragma("unroll") for (int m = 0; m < 4; ++m) _Pragma("unroll") for (int k = 0; k < 2; ++k) dst[m][k] = *(const LAS bf16x8*)(lds + PG8_SA(b, h) + aoff + m * 2048 + k * 1024); } while (0)
; #define PG8_LDB(dst, b, h) do { _Pragma("unroll") for (int n = 0; n < 2; ++n) _Pragma("unroll") for (int k = 0; k < 2; ++k) dst[n][k] = *(const LAS bf16x8*)(lds + PG8_SB(b, h) + boff + n * 2048 + k * 1024); } while (0)
; #define PG8_MMA(ai, bj, At, Bt) do { __builtin_amdgcn_s_setprio(1); _Pragma("unroll") for (int m = 0; m < 4; ++m) _Pragma("unroll") for (int n = 0; n < 2; ++n) _Pragma("unroll") for (int k = 0; k < 2; ++k) \
;         acc[ai][bj][m][n] = __builtin_amdgcn_mfma_f32_16x16x32_bf16(Bt[n][k], At[m][k], acc[ai][bj][m][n], 0, 0, 0); __builtin_amdgcn_s_setprio(0); } while (0)
; template <class Epi>
; __device__ __forceinline__ void gemm_phase(LAS unsigned char* lds, const Gemm g, int G, int c, const Epi& E) {
;     ...
;         const bool has_next = S.next(ui + 1, nxt);
;         const char* nA = has_next ? (const char*)(g.A + (size_t)nxt.pb * g.sA) + (size_t)nxt.pm * 2 * hstepA : cA;
;         const char* nB = has_next ? (const char*)(g.Bt + (size_t)nxt.pb * g.sB) + (size_t)nxt.pn * 2 * hstepB : cB;
; #pragma nounroll
;         for (int t = 0; t < nt; t += 2) {
;             const bool last = (t == nt - 2);
;             const char* a1 = cA + (size_t)(t + 1) * kstep;
;             const char* a2 = last ? nA : cA + (size_t)(t + 2) * kstep; const char* b2 = last ? nB : cB + (size_t)(t + 2) * kstep;
;             const char* a3 = a2 + kstep; const char* b3 = b2 + kstep;
;             PG8_LDB(B0, 0, 0); PG8_LDB(B1, 0, 1); PG8_SCHED; PG8_LDA(At, 0, 0); PG8_STAGE(PG8_SA(1, 1), a1 + hstepA, voffA);
;             PG8_WAIT_V(8); PG8_WAIT_L(0); PG8_BAR; PG8_MMA(0, 0, At, B0); PG8_MMA(0, 1, At, B1); PG8_BAR; PG8_SCHED;
;             PG8_LDA(At, 0, 1); PG8_STAGE(PG8_SB(0, 0), b2, voffB); PG8_STAGE(PG8_SB(0, 1), b2 + hstepB, voffB); PG8_STAGE(PG8_SA(0, 0), a2, voffA);
;             PG8_WAIT_V(8); PG8_WAIT_L(0); PG8_BAR; PG8_MMA(1, 0, At, B0); PG8_MMA(1, 1, At, B1); PG8_BAR; PG8_SCHED;
.LBB0_1450:
	s_mov_b32 s44, 0
	s_mov_b64 s[4:5], -1
	s_mov_b64 s[10:11], 0
	s_waitcnt vmcnt(0)
	s_add_u32 s33, s8, s44
	s_addc_u32 s45, s9, 0
	s_add_u32 s48, s33, 0x100
	s_addc_u32 s49, s45, 0
	s_and_b64 s[46:47], s[10:11], exec
	s_cselect_b32 s47, s41, s49
	s_cselect_b32 s46, s40, s48
	s_add_u32 s44, s6, s44
	s_addc_u32 s48, s7, 0
	s_add_u32 s44, s44, 0x100
	s_addc_u32 s48, s48, 0
	s_and_b64 s[10:11], s[10:11], exec
	s_cselect_b32 s49, s43, s48
	s_cselect_b32 s48, s42, s44
	s_add_u32 s54, s33, 0xb0080
	ds_read_b128 v[142:145], v160
	ds_read_b128 v[146:149], v160 offset:1024
	ds_read_b128 v[150:153], v160 offset:2048
	ds_read_b128 v[154:157], v160 offset:3072
	ds_read_b128 v[166:169], v161
	ds_read_b128 v[170:173], v161 offset:1024
	ds_read_b128 v[174:177], v161 offset:2048
	ds_read_b128 v[178:181], v161 offset:3072
	s_addc_u32 s55, s45, 0
	s_add_i32 s65, s82, s66
	s_add_i32 m0, s69, 0xc000
	s_add_i32 s74, s69, 0xe000
	s_add_i32 s62, s65, 0x2000
	s_add_u32 s52, s48, 0xb0000
	s_addc_u32 s53, s49, 0
	s_add_i32 s64, s83, s66
	s_add_i32 s63, s64, 0x2000
	s_add_i32 s97, 0, 0x18000
	s_add_i32 s33, 0, 0x1c000
	s_add_u32 s44, s46, 0xb0000
	s_addc_u32 s45, s47, 0
	s_add_i32 s96, s97, s66
	s_add_i32 s94, s96, 0x2000
	s_add_u32 s10, s48, 0xb0080
	s_addc_u32 s11, s49, 0
	s_add_i32 s95, s33, s66
	s_add_i32 s93, s95, 0x2000
	v_lshl_add_u64 v[214:215], s[54:55], 0, v[130:131]
	ds_read_b128 v[182:185], v162
	ds_read_b128 v[186:189], v162 offset:1024
	ds_read_b128 v[190:193], v162 offset:2048
	ds_read_b128 v[194:197], v162 offset:3072
	ds_read_b128 v[198:201], v162 offset:4096
	ds_read_b128 v[202:205], v162 offset:5120
	ds_read_b128 v[206:209], v162 offset:6144
	ds_read_b128 v[210:213], v162 offset:7168
	global_load_lds_dwordx4 v[214:215], off
	v_lshl_add_u64 v[214:215], s[54:55], 0, v[134:135]
	s_mov_b32 m0, s74
	s_nop 0
	global_load_lds_dwordx4 v[214:215], off
	s_waitcnt vmcnt(8)
	s_waitcnt lgkmcnt(0)
	s_barrier
	s_setprio 0
	s_waitcnt lgkmcnt(0)
	v_mfma_f32_16x16x32_bf16 v[126:129], v[142:145], v[182:185], 0
	v_mfma_f32_16x16x32_bf16 v[122:125], v[150:153], v[182:185], 0
	v_mfma_f32_16x16x32_bf16 v[110:113], v[142:145], v[190:193], 0
	v_mfma_f32_16x16x32_bf16 v[106:109], v[150:153], v[190:193], 0
	v_mfma_f32_16x16x32_bf16 v[94:97], v[142:145], v[198:201], 0
	v_mfma_f32_16x16x32_bf16 v[90:93], v[150:153], v[198:201], 0
	v_mfma_f32_16x16x32_bf16 v[78:81], v[142:145], v[206:209], 0
	v_mfma_f32_16x16x32_bf16 v[74:77], v[150:153], v[206:209], 0
	v_mfma_f32_16x16x32_bf16 v[126:129], v[146:149], v[186:189], v[126:129]
	v_mfma_f32_16x16x32_bf16 v[122:125], v[154:157], v[186:189], v[122:125]
	v_mfma_f32_16x16x32_bf16 v[110:113], v[146:149], v[194:197], v[110:113]
	v_mfma_f32_16x16x32_bf16 v[106:109], v[154:157], v[194:197], v[106:109]
	v_mfma_f32_16x16x32_bf16 v[94:97], v[146:149], v[202:205], v[94:97]
	v_mfma_f32_16x16x32_bf16 v[90:93], v[154:157], v[202:205], v[90:93]
	v_mfma_f32_16x16x32_bf16 v[78:81], v[146:149], v[210:213], v[78:81]
	v_mfma_f32_16x16x32_bf16 v[74:77], v[154:157], v[210:213], v[74:77]
	s_setprio 2
	s_setprio 0
	v_mfma_f32_16x16x32_bf16 v[118:121], v[166:169], v[182:185], 0
	v_mfma_f32_16x16x32_bf16 v[114:117], v[174:177], v[182:185], 0
	v_mfma_f32_16x16x32_bf16 v[102:105], v[166:169], v[190:193], 0
	v_mfma_f32_16x16x32_bf16 v[98:101], v[174:177], v[190:193], 0
	v_mfma_f32_16x16x32_bf16 v[86:89], v[166:169], v[198:201], 0
	v_mfma_f32_16x16x32_bf16 v[82:85], v[174:177], v[198:201], 0
	v_mfma_f32_16x16x32_bf16 v[70:73], v[166:169], v[206:209], 0
	v_mfma_f32_16x16x32_bf16 v[66:69], v[174:177], v[206:209], 0
	v_mfma_f32_16x16x32_bf16 v[118:121], v[170:173], v[186:189], v[118:121]
	v_mfma_f32_16x16x32_bf16 v[114:117], v[178:181], v[186:189], v[114:117]
	v_mfma_f32_16x16x32_bf16 v[102:105], v[170:173], v[194:197], v[102:105]
	v_mfma_f32_16x16x32_bf16 v[98:101], v[178:181], v[194:197], v[98:101]
	v_mfma_f32_16x16x32_bf16 v[86:89], v[170:173], v[202:205], v[86:89]
	v_mfma_f32_16x16x32_bf16 v[82:85], v[178:181], v[202:205], v[82:85]
	v_mfma_f32_16x16x32_bf16 v[70:73], v[170:173], v[210:213], v[70:73]
	v_mfma_f32_16x16x32_bf16 v[66:69], v[178:181], v[210:213], v[66:69]
	s_setprio 2
	s_barrier
	s_mov_b32 m0, s65
	v_lshl_add_u64 v[214:215], s[48:49], 0, v[132:133]
	ds_read_b128 v[182:185], v162 offset:16384
	ds_read_b128 v[186:189], v162 offset:17408
	ds_read_b128 v[190:193], v162 offset:18432
	ds_read_b128 v[194:197], v162 offset:19456
	ds_read_b128 v[198:201], v162 offset:20480
	ds_read_b128 v[202:205], v162 offset:21504
	ds_read_b128 v[206:209], v162 offset:22528
	ds_read_b128 v[210:213], v162 offset:23552
	global_load_lds_dwordx4 v[214:215], off
	v_lshl_add_u64 v[216:217], s[48:49], 0, v[136:137]
	s_mov_b32 m0, s62
	v_lshl_add_u64 v[218:219], s[52:53], 0, v[132:133]
	global_load_lds_dwordx4 v[216:217], off
	s_mov_b32 m0, s64
	v_lshl_add_u64 v[220:221], s[46:47], 0, v[134:135]
	global_load_lds_dwordx4 v[218:219], off
	v_lshl_add_u64 v[218:219], s[52:53], 0, v[136:137]
	s_mov_b32 m0, s63
	s_nop 0
	global_load_lds_dwordx4 v[218:219], off
	v_lshl_add_u64 v[218:219], s[46:47], 0, v[130:131]
	s_mov_b32 m0, s69
	s_nop 0
	global_load_lds_dwordx4 v[218:219], off
	s_mov_b32 m0, s70
	s_nop 0
	global_load_lds_dwordx4 v[220:221], off
	s_waitcnt vmcnt(8)
	s_waitcnt lgkmcnt(0)
	s_barrier
; #define PG8_STAGE(bufoff, gbase, voff) do { _Pragma("unroll") for (int _i = 0; _i < 2; ++_i) \
;         __builtin_amdgcn_global_load_lds((const unsigned*)((const char*)(gbase) + (voff)[_i]), (LAS unsigned*)(lds + (bufoff) + ldsw + _i * 8192), 16, 0, 0); } while (0)
; #define PG8_LDA(dst, b, h) do { _Pragma("unroll") for (int m = 0; m < 4; ++m) _Pragma("unroll") for (int k = 0; k < 2; ++k) dst[m][k] = *(const LAS bf16x8*)(lds + PG8_SA(b, h) + aoff + m * 2048 + k * 1024); } while (0)
; #define PG8_LDB(dst, b, h) do { _Pragma("unroll") for (int n = 0; n < 2; ++n) _Pragma("unroll") for (int k = 0; k < 2; ++k) dst[n][k] = *(const LAS bf16x8*)(lds + PG8_SB(b, h) + boff + n * 2048 + k * 1024); } while (0)
; #define PG8_MMA(ai, bj, At, Bt) do { __builtin_amdgcn_s_setprio(1); _Pragma("unroll") for (int m = 0; m < 4; ++m) _Pragma("unroll") for (int n = 0; n < 2; ++n) _Pragma("unroll") for (int k = 0; k < 2; ++k) \
;         acc[ai][bj][m][n] = __builtin_amdgcn_mfma_f32_16x16x32_bf16(Bt[n][k], At[m][k], acc[ai][bj][m][n], 0, 0, 0); __builtin_amdgcn_s_setprio(0); } while (0)
; #define PG8_WAIT_V(n) asm volatile("s_waitcnt vmcnt(" #n ")" ::: "memory")
; #define PG8_WAIT_L(n) asm volatile("s_waitcnt lgkmcnt(" #n ")" ::: "memory")
; #define PG8_BAR __builtin_amdgcn_s_barrier()
; #define PG8_SCHED __builtin_amdgcn_sched_barrier(0)
; template <class Epi>
; __device__ __forceinline__ void gemm_phase(LAS unsigned char* lds, const Gemm g, int G, int c, const Epi& E) {
;     ...
;             PG8_WAIT_V(8); PG8_WAIT_L(0); PG8_BAR; PG8_MMA(1, 0, At, B0); PG8_MMA(1, 1, At, B1); PG8_BAR; PG8_SCHED;
;             PG8_LDB(B0, 1, 0); PG8_LDB(B1, 1, 1); PG8_SCHED; PG8_LDA(At, 1, 0); PG8_STAGE(PG8_SA(0, 1), a2 + hstepA, voffA);
;             PG8_WAIT_V(8); PG8_WAIT_L(0); PG8_BAR; PG8_MMA(0, 0, At, B0); PG8_MMA(0, 1, At, B1); PG8_BAR; PG8_SCHED;
	s_setprio 0
	s_waitcnt lgkmcnt(0)
	v_mfma_f32_16x16x32_bf16 v[62:65], v[142:145], v[182:185], 0
	v_mfma_f32_16x16x32_bf16 v[58:61], v[150:153], v[182:185], 0
	v_mfma_f32_16x16x32_bf16 v[46:49], v[142:145], v[190:193], 0
	v_mfma_f32_16x16x32_bf16 v[42:45], v[150:153], v[190:193], 0
	v_mfma_f32_16x16x32_bf16 v[30:33], v[142:145], v[198:201], 0
	v_mfma_f32_16x16x32_bf16 v[26:29], v[150:153], v[198:201], 0
	v_mfma_f32_16x16x32_bf16 v[14:17], v[142:145], v[206:209], 0
	v_mfma_f32_16x16x32_bf16 v[10:13], v[150:153], v[206:209], 0
	v_mfma_f32_16x16x32_bf16 v[62:65], v[146:149], v[186:189], v[62:65]
	v_mfma_f32_16x16x32_bf16 v[58:61], v[154:157], v[186:189], v[58:61]
	v_mfma_f32_16x16x32_bf16 v[46:49], v[146:149], v[194:197], v[46:49]
	v_mfma_f32_16x16x32_bf16 v[42:45], v[154:157], v[194:197], v[42:45]
	v_mfma_f32_16x16x32_bf16 v[30:33], v[146:149], v[202:205], v[30:33]
	v_mfma_f32_16x16x32_bf16 v[26:29], v[154:157], v[202:205], v[26:29]
	v_mfma_f32_16x16x32_bf16 v[14:17], v[146:149], v[210:213], v[14:17]
	v_mfma_f32_16x16x32_bf16 v[10:13], v[154:157], v[210:213], v[10:13]
	s_setprio 2
	s_setprio 0
	v_mfma_f32_16x16x32_bf16 v[54:57], v[166:169], v[182:185], 0
	v_mfma_f32_16x16x32_bf16 v[50:53], v[174:177], v[182:185], 0
	v_mfma_f32_16x16x32_bf16 v[38:41], v[166:169], v[190:193], 0
	v_mfma_f32_16x16x32_bf16 v[34:37], v[174:177], v[190:193], 0
	v_mfma_f32_16x16x32_bf16 v[22:25], v[166:169], v[198:201], 0
	v_mfma_f32_16x16x32_bf16 v[18:21], v[174:177], v[198:201], 0
	v_mfma_f32_16x16x32_bf16 v[6:9], v[166:169], v[206:209], 0
	v_mfma_f32_16x16x32_bf16 v[2:5], v[174:177], v[206:209], 0
	v_mfma_f32_16x16x32_bf16 v[54:57], v[170:173], v[186:189], v[54:57]
	v_mfma_f32_16x16x32_bf16 v[50:53], v[178:181], v[186:189], v[50:53]
	v_mfma_f32_16x16x32_bf16 v[38:41], v[170:173], v[194:197], v[38:41]
	v_mfma_f32_16x16x32_bf16 v[34:37], v[178:181], v[194:197], v[34:37]
	v_mfma_f32_16x16x32_bf16 v[22:25], v[170:173], v[202:205], v[22:25]
	v_mfma_f32_16x16x32_bf16 v[18:21], v[178:181], v[202:205], v[18:21]
	v_mfma_f32_16x16x32_bf16 v[6:9], v[170:173], v[210:213], v[6:9]
	v_mfma_f32_16x16x32_bf16 v[2:5], v[178:181], v[210:213], v[2:5]
	s_setprio 2
	s_barrier
	v_add_u32_e32 v154, s97, v159
	v_add_u32_e32 v178, s33, v159
	ds_read_b128 v[142:145], v154
	ds_read_b128 v[146:149], v154 offset:1024
	ds_read_b128 v[150:153], v154 offset:2048
	ds_read_b128 v[154:157], v154 offset:3072
	ds_read_b128 v[166:169], v178
	ds_read_b128 v[170:173], v178 offset:1024
	ds_read_b128 v[174:177], v178 offset:2048
	ds_read_b128 v[178:181], v178 offset:3072
	s_mov_b32 m0, s71
	v_lshl_add_u64 v[222:223], s[44:45], 0, v[130:131]
	ds_read_b128 v[182:185], v162 offset:32768
	ds_read_b128 v[186:189], v162 offset:33792
	ds_read_b128 v[190:193], v162 offset:34816
	ds_read_b128 v[194:197], v162 offset:35840
	ds_read_b128 v[198:201], v162 offset:36864
	ds_read_b128 v[202:205], v162 offset:37888
	ds_read_b128 v[206:209], v162 offset:38912
	ds_read_b128 v[210:213], v162 offset:39936
	global_load_lds_dwordx4 v[222:223], off
	v_lshl_add_u64 v[222:223], s[44:45], 0, v[134:135]
	s_mov_b32 m0, s72
	s_nop 0
	global_load_lds_dwordx4 v[222:223], off
	s_waitcnt vmcnt(8)
	s_waitcnt lgkmcnt(0)
	s_barrier
	s_setprio 0
	s_waitcnt lgkmcnt(0)
	v_mfma_f32_16x16x32_bf16 v[126:129], v[142:145], v[182:185], v[126:129]
	v_mfma_f32_16x16x32_bf16 v[122:125], v[150:153], v[182:185], v[122:125]
	v_mfma_f32_16x16x32_bf16 v[110:113], v[142:145], v[190:193], v[110:113]
	v_mfma_f32_16x16x32_bf16 v[106:109], v[150:153], v[190:193], v[106:109]
	v_mfma_f32_16x16x32_bf16 v[94:97], v[142:145], v[198:201], v[94:97]
	v_mfma_f32_16x16x32_bf16 v[90:93], v[150:153], v[198:201], v[90:93]
	v_mfma_f32_16x16x32_bf16 v[78:81], v[142:145], v[206:209], v[78:81]
	v_mfma_f32_16x16x32_bf16 v[74:77], v[150:153], v[206:209], v[74:77]
	v_mfma_f32_16x16x32_bf16 v[126:129], v[146:149], v[186:189], v[126:129]
	v_mfma_f32_16x16x32_bf16 v[122:125], v[154:157], v[186:189], v[122:125]
	v_mfma_f32_16x16x32_bf16 v[110:113], v[146:149], v[194:197], v[110:113]
	v_mfma_f32_16x16x32_bf16 v[106:109], v[154:157], v[194:197], v[106:109]
	v_mfma_f32_16x16x32_bf16 v[94:97], v[146:149], v[202:205], v[94:97]
	v_mfma_f32_16x16x32_bf16 v[90:93], v[154:157], v[202:205], v[90:93]
	v_mfma_f32_16x16x32_bf16 v[78:81], v[146:149], v[210:213], v[78:81]
	v_mfma_f32_16x16x32_bf16 v[74:77], v[154:157], v[210:213], v[74:77]
	s_setprio 2
	s_setprio 0
	v_mfma_f32_16x16x32_bf16 v[118:121], v[166:169], v[182:185], v[118:121]
	v_mfma_f32_16x16x32_bf16 v[114:117], v[174:177], v[182:185], v[114:117]
	v_mfma_f32_16x16x32_bf16 v[102:105], v[166:169], v[190:193], v[102:105]
	v_mfma_f32_16x16x32_bf16 v[98:101], v[174:177], v[190:193], v[98:101]
	v_mfma_f32_16x16x32_bf16 v[86:89], v[166:169], v[198:201], v[86:89]
	v_mfma_f32_16x16x32_bf16 v[82:85], v[174:177], v[198:201], v[82:85]
	v_mfma_f32_16x16x32_bf16 v[70:73], v[166:169], v[206:209], v[70:73]
	v_mfma_f32_16x16x32_bf16 v[66:69], v[174:177], v[206:209], v[66:69]
	v_mfma_f32_16x16x32_bf16 v[118:121], v[170:173], v[186:189], v[118:121]
	v_mfma_f32_16x16x32_bf16 v[114:117], v[178:181], v[186:189], v[114:117]
	v_mfma_f32_16x16x32_bf16 v[102:105], v[170:173], v[194:197], v[102:105]
	v_mfma_f32_16x16x32_bf16 v[98:101], v[178:181], v[194:197], v[98:101]
	v_mfma_f32_16x16x32_bf16 v[86:89], v[170:173], v[202:205], v[86:89]
	v_mfma_f32_16x16x32_bf16 v[82:85], v[178:181], v[202:205], v[82:85]
	v_mfma_f32_16x16x32_bf16 v[70:73], v[170:173], v[210:213], v[70:73]
	v_mfma_f32_16x16x32_bf16 v[66:69], v[178:181], v[210:213], v[66:69]
	s_setprio 2
	s_barrier
; #define PG8_STAGE(bufoff, gbase, voff) do { _Pragma("unroll") for (int _i = 0; _i < 2; ++_i) \
;         __builtin_amdgcn_global_load_lds((const unsigned*)((const char*)(gbase) + (voff)[_i]), (LAS unsigned*)(lds + (bufoff) + ldsw + _i * 8192), 16, 0, 0); } while (0)
; #define PG8_LDA(dst, b, h) do { _Pragma("unroll") for (int m = 0; m < 4; ++m) _Pragma("unroll") for (int k = 0; k < 2; ++k) dst[m][k] = *(const LAS bf16x8*)(lds + PG8_SA(b, h) + aoff + m * 2048 + k * 1024); } while (0)
; #define PG8_MMA(ai, bj, At, Bt) do { __builtin_amdgcn_s_setprio(1); _Pragma("unroll") for (int m = 0; m < 4; ++m) _Pragma("unroll") for (int n = 0; n < 2; ++n) _Pragma("unroll") for (int k = 0; k < 2; ++k) \
;         acc[ai][bj][m][n] = __builtin_amdgcn_mfma_f32_16x16x32_bf16(Bt[n][k], At[m][k], acc[ai][bj][m][n], 0, 0, 0); __builtin_amdgcn_s_setprio(0); } while (0)
; #define PG8_WAIT_V(n) asm volatile("s_waitcnt vmcnt(" #n ")" ::: "memory")
; #define PG8_WAIT_L(n) asm volatile("s_waitcnt lgkmcnt(" #n ")" ::: "memory")
; #define PG8_BAR __builtin_amdgcn_s_barrier()
; #define PG8_SCHED __builtin_amdgcn_sched_barrier(0)
; template <class Epi>
; __device__ __forceinline__ void gemm_phase(LAS unsigned char* lds, const Gemm g, int G, int c, const Epi& E) {
;     ...
;             PG8_LDA(At, 1, 1); PG8_STAGE(PG8_SB(1, 0), b3, voffB); PG8_STAGE(PG8_SB(1, 1), b3 + hstepB, voffB); PG8_STAGE(PG8_SA(1, 0), a3, voffA);
;             PG8_WAIT_V(8); PG8_WAIT_L(0); PG8_BAR; PG8_MMA(1, 0, At, B0); PG8_MMA(1, 1, At, B1); PG8_BAR; PG8_SCHED;
;         }
	s_mov_b32 m0, s96
	v_lshl_add_u64 v[214:215], v[214:215], 0, s[22:23]
	ds_read_b128 v[182:185], v162 offset:49152
	ds_read_b128 v[186:189], v162 offset:50176
	ds_read_b128 v[190:193], v162 offset:51200
	ds_read_b128 v[194:197], v162 offset:52224
	ds_read_b128 v[198:201], v162 offset:53248
	ds_read_b128 v[202:205], v162 offset:54272
	ds_read_b128 v[206:209], v162 offset:55296
	ds_read_b128 v[210:213], v162 offset:56320
	global_load_lds_dwordx4 v[214:215], off
	v_lshl_add_u64 v[214:215], v[216:217], 0, s[22:23]
	s_mov_b32 m0, s94
	s_nop 0
	global_load_lds_dwordx4 v[214:215], off
	v_lshl_add_u64 v[214:215], s[10:11], 0, v[132:133]
	s_mov_b32 m0, s95
	s_nop 0
	global_load_lds_dwordx4 v[214:215], off
	v_lshl_add_u64 v[214:215], s[10:11], 0, v[136:137]
	s_mov_b32 m0, s93
	s_nop 0
	global_load_lds_dwordx4 v[214:215], off
	v_lshl_add_u64 v[214:215], v[218:219], 0, s[22:23]
	s_mov_b32 m0, s80
	s_nop 0
	global_load_lds_dwordx4 v[214:215], off
	v_lshl_add_u64 v[214:215], v[220:221], 0, s[22:23]
	s_mov_b32 m0, s81
	s_nop 0
	global_load_lds_dwordx4 v[214:215], off
	s_waitcnt vmcnt(8)
	s_waitcnt lgkmcnt(0)
	s_barrier
	s_setprio 0
	s_waitcnt lgkmcnt(0)
	v_mfma_f32_16x16x32_bf16 v[62:65], v[142:145], v[182:185], v[62:65]
	v_mfma_f32_16x16x32_bf16 v[58:61], v[150:153], v[182:185], v[58:61]
	v_mfma_f32_16x16x32_bf16 v[46:49], v[142:145], v[190:193], v[46:49]
	v_mfma_f32_16x16x32_bf16 v[42:45], v[150:153], v[190:193], v[42:45]
	v_mfma_f32_16x16x32_bf16 v[30:33], v[142:145], v[198:201], v[30:33]
	v_mfma_f32_16x16x32_bf16 v[26:29], v[150:153], v[198:201], v[26:29]
	v_mfma_f32_16x16x32_bf16 v[14:17], v[142:145], v[206:209], v[14:17]
	v_mfma_f32_16x16x32_bf16 v[10:13], v[150:153], v[206:209], v[10:13]
	v_mfma_f32_16x16x32_bf16 v[62:65], v[146:149], v[186:189], v[62:65]
	v_mfma_f32_16x16x32_bf16 v[58:61], v[154:157], v[186:189], v[58:61]
	v_mfma_f32_16x16x32_bf16 v[46:49], v[146:149], v[194:197], v[46:49]
	v_mfma_f32_16x16x32_bf16 v[42:45], v[154:157], v[194:197], v[42:45]
	v_mfma_f32_16x16x32_bf16 v[30:33], v[146:149], v[202:205], v[30:33]
	v_mfma_f32_16x16x32_bf16 v[26:29], v[154:157], v[202:205], v[26:29]
	v_mfma_f32_16x16x32_bf16 v[14:17], v[146:149], v[210:213], v[14:17]
	v_mfma_f32_16x16x32_bf16 v[10:13], v[154:157], v[210:213], v[10:13]
	s_setprio 2
	s_setprio 0
	v_mfma_f32_16x16x32_bf16 v[54:57], v[166:169], v[182:185], v[54:57]
	v_mfma_f32_16x16x32_bf16 v[50:53], v[174:177], v[182:185], v[50:53]
	v_mfma_f32_16x16x32_bf16 v[38:41], v[166:169], v[190:193], v[38:41]
	v_mfma_f32_16x16x32_bf16 v[34:37], v[174:177], v[190:193], v[34:37]
	v_mfma_f32_16x16x32_bf16 v[22:25], v[166:169], v[198:201], v[22:25]
	v_mfma_f32_16x16x32_bf16 v[18:21], v[174:177], v[198:201], v[18:21]
	v_mfma_f32_16x16x32_bf16 v[6:9], v[166:169], v[206:209], v[6:9]
	v_mfma_f32_16x16x32_bf16 v[2:5], v[174:177], v[206:209], v[2:5]
	v_mfma_f32_16x16x32_bf16 v[54:57], v[170:173], v[186:189], v[54:57]
	v_mfma_f32_16x16x32_bf16 v[50:53], v[178:181], v[186:189], v[50:53]
	v_mfma_f32_16x16x32_bf16 v[38:41], v[170:173], v[194:197], v[38:41]
	v_mfma_f32_16x16x32_bf16 v[34:37], v[178:181], v[194:197], v[34:37]
	v_mfma_f32_16x16x32_bf16 v[22:25], v[170:173], v[202:205], v[22:25]
	v_mfma_f32_16x16x32_bf16 v[18:21], v[178:181], v[202:205], v[18:21]
	v_mfma_f32_16x16x32_bf16 v[6:9], v[170:173], v[210:213], v[6:9]
	v_mfma_f32_16x16x32_bf16 v[2:5], v[178:181], v[210:213], v[2:5]
	s_setprio 2
	s_barrier
	s_movk_i32 s44, 0x100
	s_andn2_b64 vcc, exec, s[4:5]
	s_mov_b64 s[10:11], -1
	s_mov_b64 s[4:5], 0
	s_cbranch_vccz .LBB0_1451

; #define PG8_STAGE(bufoff, gbase, voff) do { _Pragma("unroll") for (int _i = 0; _i < 2; ++_i) \
;         __builtin_amdgcn_global_load_lds((const unsigned*)((const char*)(gbase) + (voff)[_i]), (LAS unsigned*)(lds + (bufoff) + ldsw + _i * 8192), 16, 0, 0); } while (0)
; #define PG8_LDA(dst, b, h) do { _Pragma("unroll") for (int m = 0; m < 4; ++m) _Pragma("unroll") for (int k = 0; k < 2; ++k) dst[m][k] = *(const LAS bf16x8*)(lds + PG8_SA(b, h) + aoff + m * 2048 + k * 1024); } while (0)
; #define PG8_LDB(dst, b, h) do { _Pragma("unroll") for (int n = 0; n < 2; ++n) _Pragma("unroll") for (int k = 0; k < 2; ++k) dst[n][k] = *(const LAS bf16x8*)(lds + PG8_SB(b, h) + boff + n * 2048 + k * 1024); } while (0)
; #define PG8_MMA(ai, bj, At, Bt) do { __builtin_amdgcn_s_setprio(1); _Pragma("unroll") for (int m = 0; m < 4; ++m) _Pragma("unroll") for (int n = 0; n < 2; ++n) _Pragma("unroll") for (int k = 0; k < 2; ++k) \
;         acc[ai][bj][m][n] = __builtin_amdgcn_mfma_f32_16x16x32_bf16(Bt[n][k], At[m][k], acc[ai][bj][m][n], 0, 0, 0); __builtin_amdgcn_s_setprio(0); } while (0)
; template <class Epi>
; __device__ __forceinline__ void gemm_phase(LAS unsigned char* lds, const Gemm g, int G, int c, const Epi& E) {
;     ...
;         const bool has_next = S.next(ui + 1, nxt);
;         const char* nA = has_next ? (const char*)(g.A + (size_t)nxt.pb * g.sA) + (size_t)nxt.pm * 2 * hstepA : cA;
;         const char* nB = has_next ? (const char*)(g.Bt + (size_t)nxt.pb * g.sB) + (size_t)nxt.pn * 2 * hstepB : cB;
; #pragma nounroll
;         for (int t = 0; t < nt; t += 2) {
;             const bool last = (t == nt - 2);
;             const char* a1 = cA + (size_t)(t + 1) * kstep;
;             const char* a2 = last ? nA : cA + (size_t)(t + 2) * kstep; const char* b2 = last ? nB : cB + (size_t)(t + 2) * kstep;
;             const char* a3 = a2 + kstep; const char* b3 = b2 + kstep;
;             PG8_LDB(B0, 0, 0); PG8_LDB(B1, 0, 1); PG8_SCHED; PG8_LDA(At, 0, 0); PG8_STAGE(PG8_SA(1, 1), a1 + hstepA, voffA);
;             PG8_WAIT_V(8); PG8_WAIT_L(0); PG8_BAR; PG8_MMA(0, 0, At, B0); PG8_MMA(0, 1, At, B1); PG8_BAR; PG8_SCHED;
;             PG8_LDA(At, 0, 1); PG8_STAGE(PG8_SB(0, 0), b2, voffB); PG8_STAGE(PG8_SB(0, 1), b2 + hstepB, voffB); PG8_STAGE(PG8_SA(0, 0), a2, voffA);
;             PG8_WAIT_V(8); PG8_WAIT_L(0); PG8_BAR; PG8_MMA(1, 0, At, B0); PG8_MMA(1, 1, At, B1); PG8_BAR; PG8_SCHED;
.LBB0_1536:
	s_mov_b32 s44, 0
	s_mov_b64 s[4:5], -1
	s_mov_b64 s[10:11], 0
	s_waitcnt lgkmcnt(0)
	s_waitcnt vmcnt(0)
	s_add_u32 s33, s8, s44
	s_addc_u32 s45, s9, 0
	s_add_u32 s48, s33, 0x100
	s_addc_u32 s49, s45, 0
	s_and_b64 s[46:47], s[10:11], exec
	s_cselect_b32 s47, s41, s49
	s_cselect_b32 s46, s40, s48
	s_add_u32 s44, s6, s44
	s_addc_u32 s48, s7, 0
	s_add_u32 s44, s44, 0x100
	s_addc_u32 s48, s48, 0
	s_and_b64 s[10:11], s[10:11], exec
	s_cselect_b32 s49, s43, s48
	s_cselect_b32 s48, s42, s44
	s_add_u32 s54, s33, 0xb0080
	ds_read_b128 v[130:133], v166
	ds_read_b128 v[134:137], v166 offset:1024
	ds_read_b128 v[150:153], v166 offset:2048
	ds_read_b128 v[154:157], v166 offset:3072
	ds_read_b128 v[158:161], v167
	ds_read_b128 v[172:175], v167 offset:1024
	ds_read_b128 v[176:179], v167 offset:2048
	ds_read_b128 v[180:183], v167 offset:3072
	s_addc_u32 s55, s45, 0
	s_add_i32 s63, s87, s70
	s_add_i32 m0, s73, 0xc000
	s_add_i32 s64, s73, 0xe000
	s_add_i32 s74, s63, 0x2000
	s_add_u32 s52, s48, 0xb0000
	s_addc_u32 s53, s49, 0
	s_add_i32 s62, s88, s70
	s_add_i32 s75, s62, 0x2000
	s_add_i32 s97, 0, 0x18000
	s_add_i32 s33, 0, 0x1c000
	s_add_u32 s44, s46, 0xb0000
	s_addc_u32 s45, s47, 0
	s_add_i32 s96, s97, s70
	s_add_i32 s94, s96, 0x2000
	s_add_u32 s10, s48, 0xb0080
	s_addc_u32 s11, s49, 0
	s_add_i32 s95, s33, s70
	s_add_i32 s93, s95, 0x2000
	v_lshl_add_u64 v[162:163], s[54:55], 0, v[138:139]
	ds_read_b128 v[184:187], v168
	ds_read_b128 v[188:191], v168 offset:1024
	ds_read_b128 v[192:195], v168 offset:2048
	ds_read_b128 v[196:199], v168 offset:3072
	ds_read_b128 v[200:203], v168 offset:4096
	ds_read_b128 v[204:207], v168 offset:5120
	ds_read_b128 v[208:211], v168 offset:6144
	ds_read_b128 v[212:215], v168 offset:7168
	global_load_lds_dwordx4 v[162:163], off
	v_lshl_add_u64 v[162:163], s[54:55], 0, v[142:143]
	s_mov_b32 m0, s64
	s_nop 0
	global_load_lds_dwordx4 v[162:163], off
	s_waitcnt vmcnt(8)
	s_waitcnt lgkmcnt(0)
	s_barrier
	s_setprio 0
	s_waitcnt lgkmcnt(0)
	v_mfma_f32_16x16x32_bf16 v[126:129], v[130:133], v[184:187], 0
	v_mfma_f32_16x16x32_bf16 v[122:125], v[150:153], v[184:187], 0
	v_mfma_f32_16x16x32_bf16 v[110:113], v[130:133], v[192:195], 0
	v_mfma_f32_16x16x32_bf16 v[106:109], v[150:153], v[192:195], 0
	v_mfma_f32_16x16x32_bf16 v[94:97], v[130:133], v[200:203], 0
	v_mfma_f32_16x16x32_bf16 v[90:93], v[150:153], v[200:203], 0
	v_mfma_f32_16x16x32_bf16 v[78:81], v[130:133], v[208:211], 0
	v_mfma_f32_16x16x32_bf16 v[74:77], v[150:153], v[208:211], 0
	v_mfma_f32_16x16x32_bf16 v[126:129], v[134:137], v[188:191], v[126:129]
	v_mfma_f32_16x16x32_bf16 v[122:125], v[154:157], v[188:191], v[122:125]
	v_mfma_f32_16x16x32_bf16 v[110:113], v[134:137], v[196:199], v[110:113]
	v_mfma_f32_16x16x32_bf16 v[106:109], v[154:157], v[196:199], v[106:109]
	v_mfma_f32_16x16x32_bf16 v[94:97], v[134:137], v[204:207], v[94:97]
	v_mfma_f32_16x16x32_bf16 v[90:93], v[154:157], v[204:207], v[90:93]
	v_mfma_f32_16x16x32_bf16 v[78:81], v[134:137], v[212:215], v[78:81]
	v_mfma_f32_16x16x32_bf16 v[74:77], v[154:157], v[212:215], v[74:77]
	s_setprio 2
	s_setprio 0
	v_mfma_f32_16x16x32_bf16 v[118:121], v[158:161], v[184:187], 0
	v_mfma_f32_16x16x32_bf16 v[114:117], v[176:179], v[184:187], 0
	v_mfma_f32_16x16x32_bf16 v[102:105], v[158:161], v[192:195], 0
	v_mfma_f32_16x16x32_bf16 v[98:101], v[176:179], v[192:195], 0
	v_mfma_f32_16x16x32_bf16 v[86:89], v[158:161], v[200:203], 0
	v_mfma_f32_16x16x32_bf16 v[82:85], v[176:179], v[200:203], 0
	v_mfma_f32_16x16x32_bf16 v[70:73], v[158:161], v[208:211], 0
	v_mfma_f32_16x16x32_bf16 v[66:69], v[176:179], v[208:211], 0
	v_mfma_f32_16x16x32_bf16 v[118:121], v[172:175], v[188:191], v[118:121]
	v_mfma_f32_16x16x32_bf16 v[114:117], v[180:183], v[188:191], v[114:117]
	v_mfma_f32_16x16x32_bf16 v[102:105], v[172:175], v[196:199], v[102:105]
	v_mfma_f32_16x16x32_bf16 v[98:101], v[180:183], v[196:199], v[98:101]
	v_mfma_f32_16x16x32_bf16 v[86:89], v[172:175], v[204:207], v[86:89]
	v_mfma_f32_16x16x32_bf16 v[82:85], v[180:183], v[204:207], v[82:85]
	v_mfma_f32_16x16x32_bf16 v[70:73], v[172:175], v[212:215], v[70:73]
	v_mfma_f32_16x16x32_bf16 v[66:69], v[180:183], v[212:215], v[66:69]
	s_setprio 2
	s_barrier
	s_mov_b32 m0, s63
	v_lshl_add_u64 v[162:163], s[48:49], 0, v[140:141]
	ds_read_b128 v[184:187], v168 offset:16384
	ds_read_b128 v[188:191], v168 offset:17408
	ds_read_b128 v[192:195], v168 offset:18432
	ds_read_b128 v[196:199], v168 offset:19456
	ds_read_b128 v[200:203], v168 offset:20480
	ds_read_b128 v[204:207], v168 offset:21504
	ds_read_b128 v[208:211], v168 offset:22528
	ds_read_b128 v[212:215], v168 offset:23552
	global_load_lds_dwordx4 v[162:163], off
	v_lshl_add_u64 v[216:217], s[48:49], 0, v[144:145]
	s_mov_b32 m0, s74
	v_lshl_add_u64 v[218:219], s[52:53], 0, v[140:141]
	global_load_lds_dwordx4 v[216:217], off
	s_mov_b32 m0, s62
	v_lshl_add_u64 v[220:221], s[46:47], 0, v[142:143]
	global_load_lds_dwordx4 v[218:219], off
	v_lshl_add_u64 v[218:219], s[52:53], 0, v[144:145]
	s_mov_b32 m0, s75
	s_nop 0
	global_load_lds_dwordx4 v[218:219], off
	v_lshl_add_u64 v[218:219], s[46:47], 0, v[138:139]
	s_mov_b32 m0, s73
	s_nop 0
	global_load_lds_dwordx4 v[218:219], off
	s_mov_b32 m0, s79
	s_nop 0
	global_load_lds_dwordx4 v[220:221], off
	s_waitcnt vmcnt(8)
	s_waitcnt lgkmcnt(0)
	s_barrier
; #define PG8_STAGE(bufoff, gbase, voff) do { _Pragma("unroll") for (int _i = 0; _i < 2; ++_i) \
;         __builtin_amdgcn_global_load_lds((const unsigned*)((const char*)(gbase) + (voff)[_i]), (LAS unsigned*)(lds + (bufoff) + ldsw + _i * 8192), 16, 0, 0); } while (0)
; #define PG8_LDA(dst, b, h) do { _Pragma("unroll") for (int m = 0; m < 4; ++m) _Pragma("unroll") for (int k = 0; k < 2; ++k) dst[m][k] = *(const LAS bf16x8*)(lds + PG8_SA(b, h) + aoff + m * 2048 + k * 1024); } while (0)
; #define PG8_LDB(dst, b, h) do { _Pragma("unroll") for (int n = 0; n < 2; ++n) _Pragma("unroll") for (int k = 0; k < 2; ++k) dst[n][k] = *(const LAS bf16x8*)(lds + PG8_SB(b, h) + boff + n * 2048 + k * 1024); } while (0)
; #define PG8_MMA(ai, bj, At, Bt) do { __builtin_amdgcn_s_setprio(1); _Pragma("unroll") for (int m = 0; m < 4; ++m) _Pragma("unroll") for (int n = 0; n < 2; ++n) _Pragma("unroll") for (int k = 0; k < 2; ++k) \
;         acc[ai][bj][m][n] = __builtin_amdgcn_mfma_f32_16x16x32_bf16(Bt[n][k], At[m][k], acc[ai][bj][m][n], 0, 0, 0); __builtin_amdgcn_s_setprio(0); } while (0)
; #define PG8_WAIT_V(n) asm volatile("s_waitcnt vmcnt(" #n ")" ::: "memory")
; #define PG8_WAIT_L(n) asm volatile("s_waitcnt lgkmcnt(" #n ")" ::: "memory")
; #define PG8_BAR __builtin_amdgcn_s_barrier()
; #define PG8_SCHED __builtin_amdgcn_sched_barrier(0)
; template <class Epi>
; __device__ __forceinline__ void gemm_phase(LAS unsigned char* lds, const Gemm g, int G, int c, const Epi& E) {
;     ...
;             PG8_WAIT_V(8); PG8_WAIT_L(0); PG8_BAR; PG8_MMA(1, 0, At, B0); PG8_MMA(1, 1, At, B1); PG8_BAR; PG8_SCHED;
;             PG8_LDB(B0, 1, 0); PG8_LDB(B1, 1, 1); PG8_SCHED; PG8_LDA(At, 1, 0); PG8_STAGE(PG8_SA(0, 1), a2 + hstepA, voffA);
;             PG8_WAIT_V(8); PG8_WAIT_L(0); PG8_BAR; PG8_MMA(0, 0, At, B0); PG8_MMA(0, 1, At, B1); PG8_BAR; PG8_SCHED;
	s_setprio 0
	s_waitcnt lgkmcnt(0)
	v_mfma_f32_16x16x32_bf16 v[62:65], v[130:133], v[184:187], 0
	v_mfma_f32_16x16x32_bf16 v[58:61], v[150:153], v[184:187], 0
	v_mfma_f32_16x16x32_bf16 v[46:49], v[130:133], v[192:195], 0
	v_mfma_f32_16x16x32_bf16 v[42:45], v[150:153], v[192:195], 0
	v_mfma_f32_16x16x32_bf16 v[30:33], v[130:133], v[200:203], 0
	v_mfma_f32_16x16x32_bf16 v[26:29], v[150:153], v[200:203], 0
	v_mfma_f32_16x16x32_bf16 v[14:17], v[130:133], v[208:211], 0
	v_mfma_f32_16x16x32_bf16 v[10:13], v[150:153], v[208:211], 0
	v_mfma_f32_16x16x32_bf16 v[62:65], v[134:137], v[188:191], v[62:65]
	v_mfma_f32_16x16x32_bf16 v[58:61], v[154:157], v[188:191], v[58:61]
	v_mfma_f32_16x16x32_bf16 v[46:49], v[134:137], v[196:199], v[46:49]
	v_mfma_f32_16x16x32_bf16 v[42:45], v[154:157], v[196:199], v[42:45]
	v_mfma_f32_16x16x32_bf16 v[30:33], v[134:137], v[204:207], v[30:33]
	v_mfma_f32_16x16x32_bf16 v[26:29], v[154:157], v[204:207], v[26:29]
	v_mfma_f32_16x16x32_bf16 v[14:17], v[134:137], v[212:215], v[14:17]
	v_mfma_f32_16x16x32_bf16 v[10:13], v[154:157], v[212:215], v[10:13]
	s_setprio 2
	s_setprio 0
	v_mfma_f32_16x16x32_bf16 v[54:57], v[158:161], v[184:187], 0
	v_mfma_f32_16x16x32_bf16 v[50:53], v[176:179], v[184:187], 0
	v_mfma_f32_16x16x32_bf16 v[38:41], v[158:161], v[192:195], 0
	v_mfma_f32_16x16x32_bf16 v[34:37], v[176:179], v[192:195], 0
	v_mfma_f32_16x16x32_bf16 v[22:25], v[158:161], v[200:203], 0
	v_mfma_f32_16x16x32_bf16 v[18:21], v[176:179], v[200:203], 0
	v_mfma_f32_16x16x32_bf16 v[6:9], v[158:161], v[208:211], 0
	v_mfma_f32_16x16x32_bf16 v[2:5], v[176:179], v[208:211], 0
	v_mfma_f32_16x16x32_bf16 v[54:57], v[172:175], v[188:191], v[54:57]
	v_mfma_f32_16x16x32_bf16 v[50:53], v[180:183], v[188:191], v[50:53]
	v_mfma_f32_16x16x32_bf16 v[38:41], v[172:175], v[196:199], v[38:41]
	v_mfma_f32_16x16x32_bf16 v[34:37], v[180:183], v[196:199], v[34:37]
	v_mfma_f32_16x16x32_bf16 v[22:25], v[172:175], v[204:207], v[22:25]
	v_mfma_f32_16x16x32_bf16 v[18:21], v[180:183], v[204:207], v[18:21]
	v_mfma_f32_16x16x32_bf16 v[6:9], v[172:175], v[212:215], v[6:9]
	v_mfma_f32_16x16x32_bf16 v[2:5], v[180:183], v[212:215], v[2:5]
	s_setprio 2
	s_barrier
	v_add_u32_e32 v154, s97, v165
	v_add_u32_e32 v180, s33, v165
	ds_read_b128 v[130:133], v154
	ds_read_b128 v[134:137], v154 offset:1024
	ds_read_b128 v[150:153], v154 offset:2048
	ds_read_b128 v[154:157], v154 offset:3072
	ds_read_b128 v[158:161], v180
	ds_read_b128 v[172:175], v180 offset:1024
	ds_read_b128 v[176:179], v180 offset:2048
	ds_read_b128 v[180:183], v180 offset:3072
	s_mov_b32 m0, s80
	v_lshl_add_u64 v[222:223], s[44:45], 0, v[138:139]
	ds_read_b128 v[184:187], v168 offset:32768
	ds_read_b128 v[188:191], v168 offset:33792
	ds_read_b128 v[192:195], v168 offset:34816
	ds_read_b128 v[196:199], v168 offset:35840
	ds_read_b128 v[200:203], v168 offset:36864
	ds_read_b128 v[204:207], v168 offset:37888
	ds_read_b128 v[208:211], v168 offset:38912
	ds_read_b128 v[212:215], v168 offset:39936
	global_load_lds_dwordx4 v[222:223], off
	v_lshl_add_u64 v[222:223], s[44:45], 0, v[142:143]
	s_mov_b32 m0, s81
	s_nop 0
	global_load_lds_dwordx4 v[222:223], off
	s_waitcnt vmcnt(8)
	s_waitcnt lgkmcnt(0)
	s_barrier
	s_setprio 0
	s_waitcnt lgkmcnt(0)
	v_mfma_f32_16x16x32_bf16 v[126:129], v[130:133], v[184:187], v[126:129]
	v_mfma_f32_16x16x32_bf16 v[122:125], v[150:153], v[184:187], v[122:125]
	v_mfma_f32_16x16x32_bf16 v[110:113], v[130:133], v[192:195], v[110:113]
	v_mfma_f32_16x16x32_bf16 v[106:109], v[150:153], v[192:195], v[106:109]
	v_mfma_f32_16x16x32_bf16 v[94:97], v[130:133], v[200:203], v[94:97]
	v_mfma_f32_16x16x32_bf16 v[90:93], v[150:153], v[200:203], v[90:93]
	v_mfma_f32_16x16x32_bf16 v[78:81], v[130:133], v[208:211], v[78:81]
	v_mfma_f32_16x16x32_bf16 v[74:77], v[150:153], v[208:211], v[74:77]
	v_mfma_f32_16x16x32_bf16 v[126:129], v[134:137], v[188:191], v[126:129]
	v_mfma_f32_16x16x32_bf16 v[122:125], v[154:157], v[188:191], v[122:125]
	v_mfma_f32_16x16x32_bf16 v[110:113], v[134:137], v[196:199], v[110:113]
	v_mfma_f32_16x16x32_bf16 v[106:109], v[154:157], v[196:199], v[106:109]
	v_mfma_f32_16x16x32_bf16 v[94:97], v[134:137], v[204:207], v[94:97]
	v_mfma_f32_16x16x32_bf16 v[90:93], v[154:157], v[204:207], v[90:93]
	v_mfma_f32_16x16x32_bf16 v[78:81], v[134:137], v[212:215], v[78:81]
	v_mfma_f32_16x16x32_bf16 v[74:77], v[154:157], v[212:215], v[74:77]
	s_setprio 2
	s_setprio 0
	v_mfma_f32_16x16x32_bf16 v[118:121], v[158:161], v[184:187], v[118:121]
	v_mfma_f32_16x16x32_bf16 v[114:117], v[176:179], v[184:187], v[114:117]
	v_mfma_f32_16x16x32_bf16 v[102:105], v[158:161], v[192:195], v[102:105]
	v_mfma_f32_16x16x32_bf16 v[98:101], v[176:179], v[192:195], v[98:101]
	v_mfma_f32_16x16x32_bf16 v[86:89], v[158:161], v[200:203], v[86:89]
	v_mfma_f32_16x16x32_bf16 v[82:85], v[176:179], v[200:203], v[82:85]
	v_mfma_f32_16x16x32_bf16 v[70:73], v[158:161], v[208:211], v[70:73]
	v_mfma_f32_16x16x32_bf16 v[66:69], v[176:179], v[208:211], v[66:69]
	v_mfma_f32_16x16x32_bf16 v[118:121], v[172:175], v[188:191], v[118:121]
	v_mfma_f32_16x16x32_bf16 v[114:117], v[180:183], v[188:191], v[114:117]
	v_mfma_f32_16x16x32_bf16 v[102:105], v[172:175], v[196:199], v[102:105]
	v_mfma_f32_16x16x32_bf16 v[98:101], v[180:183], v[196:199], v[98:101]
	v_mfma_f32_16x16x32_bf16 v[86:89], v[172:175], v[204:207], v[86:89]
	v_mfma_f32_16x16x32_bf16 v[82:85], v[180:183], v[204:207], v[82:85]
	v_mfma_f32_16x16x32_bf16 v[70:73], v[172:175], v[212:215], v[70:73]
	v_mfma_f32_16x16x32_bf16 v[66:69], v[180:183], v[212:215], v[66:69]
	s_setprio 2
	s_barrier
; #define PG8_STAGE(bufoff, gbase, voff) do { _Pragma("unroll") for (int _i = 0; _i < 2; ++_i) \
;         __builtin_amdgcn_global_load_lds((const unsigned*)((const char*)(gbase) + (voff)[_i]), (LAS unsigned*)(lds + (bufoff) + ldsw + _i * 8192), 16, 0, 0); } while (0)
; #define PG8_LDA(dst, b, h) do { _Pragma("unroll") for (int m = 0; m < 4; ++m) _Pragma("unroll") for (int k = 0; k < 2; ++k) dst[m][k] = *(const LAS bf16x8*)(lds + PG8_SA(b, h) + aoff + m * 2048 + k * 1024); } while (0)
; #define PG8_MMA(ai, bj, At, Bt) do { __builtin_amdgcn_s_setprio(1); _Pragma("unroll") for (int m = 0; m < 4; ++m) _Pragma("unroll") for (int n = 0; n < 2; ++n) _Pragma("unroll") for (int k = 0; k < 2; ++k) \
;         acc[ai][bj][m][n] = __builtin_amdgcn_mfma_f32_16x16x32_bf16(Bt[n][k], At[m][k], acc[ai][bj][m][n], 0, 0, 0); __builtin_amdgcn_s_setprio(0); } while (0)
; #define PG8_WAIT_V(n) asm volatile("s_waitcnt vmcnt(" #n ")" ::: "memory")
; #define PG8_WAIT_L(n) asm volatile("s_waitcnt lgkmcnt(" #n ")" ::: "memory")
; #define PG8_BAR __builtin_amdgcn_s_barrier()
; #define PG8_SCHED __builtin_amdgcn_sched_barrier(0)
; template <class Epi>
; __device__ __forceinline__ void gemm_phase(LAS unsigned char* lds, const Gemm g, int G, int c, const Epi& E) {
;     ...
;             PG8_LDA(At, 1, 1); PG8_STAGE(PG8_SB(1, 0), b3, voffB); PG8_STAGE(PG8_SB(1, 1), b3 + hstepB, voffB); PG8_STAGE(PG8_SA(1, 0), a3, voffA);
;             PG8_WAIT_V(8); PG8_WAIT_L(0); PG8_BAR; PG8_MMA(1, 0, At, B0); PG8_MMA(1, 1, At, B1); PG8_BAR; PG8_SCHED;
;         }
	s_mov_b32 m0, s96
	v_lshl_add_u64 v[162:163], v[162:163], 0, s[22:23]
	ds_read_b128 v[184:187], v168 offset:49152
	ds_read_b128 v[188:191], v168 offset:50176
	ds_read_b128 v[192:195], v168 offset:51200
	ds_read_b128 v[196:199], v168 offset:52224
	ds_read_b128 v[200:203], v168 offset:53248
	ds_read_b128 v[204:207], v168 offset:54272
	ds_read_b128 v[208:211], v168 offset:55296
	ds_read_b128 v[212:215], v168 offset:56320
	global_load_lds_dwordx4 v[162:163], off
	v_lshl_add_u64 v[162:163], v[216:217], 0, s[22:23]
	s_mov_b32 m0, s94
	s_nop 0
	global_load_lds_dwordx4 v[162:163], off
	v_lshl_add_u64 v[162:163], s[10:11], 0, v[140:141]
	s_mov_b32 m0, s95
	s_nop 0
	global_load_lds_dwordx4 v[162:163], off
	v_lshl_add_u64 v[162:163], s[10:11], 0, v[144:145]
	s_mov_b32 m0, s93
	s_nop 0
	global_load_lds_dwordx4 v[162:163], off
	v_lshl_add_u64 v[162:163], v[218:219], 0, s[22:23]
	s_mov_b32 m0, s85
	s_nop 0
	global_load_lds_dwordx4 v[162:163], off
	v_lshl_add_u64 v[162:163], v[220:221], 0, s[22:23]
	s_mov_b32 m0, s86
	s_nop 0
	global_load_lds_dwordx4 v[162:163], off
	s_waitcnt vmcnt(8)
	s_waitcnt lgkmcnt(0)
	s_barrier
	s_setprio 0
	s_waitcnt lgkmcnt(0)
	v_mfma_f32_16x16x32_bf16 v[62:65], v[130:133], v[184:187], v[62:65]
	v_mfma_f32_16x16x32_bf16 v[58:61], v[150:153], v[184:187], v[58:61]
	v_mfma_f32_16x16x32_bf16 v[46:49], v[130:133], v[192:195], v[46:49]
	v_mfma_f32_16x16x32_bf16 v[42:45], v[150:153], v[192:195], v[42:45]
	v_mfma_f32_16x16x32_bf16 v[30:33], v[130:133], v[200:203], v[30:33]
	v_mfma_f32_16x16x32_bf16 v[26:29], v[150:153], v[200:203], v[26:29]
	v_mfma_f32_16x16x32_bf16 v[14:17], v[130:133], v[208:211], v[14:17]
	v_mfma_f32_16x16x32_bf16 v[10:13], v[150:153], v[208:211], v[10:13]
	v_mfma_f32_16x16x32_bf16 v[62:65], v[134:137], v[188:191], v[62:65]
	v_mfma_f32_16x16x32_bf16 v[58:61], v[154:157], v[188:191], v[58:61]
	v_mfma_f32_16x16x32_bf16 v[46:49], v[134:137], v[196:199], v[46:49]
	v_mfma_f32_16x16x32_bf16 v[42:45], v[154:157], v[196:199], v[42:45]
	v_mfma_f32_16x16x32_bf16 v[30:33], v[134:137], v[204:207], v[30:33]
	v_mfma_f32_16x16x32_bf16 v[26:29], v[154:157], v[204:207], v[26:29]
	v_mfma_f32_16x16x32_bf16 v[14:17], v[134:137], v[212:215], v[14:17]
	v_mfma_f32_16x16x32_bf16 v[10:13], v[154:157], v[212:215], v[10:13]
	s_setprio 2
	s_setprio 0
	v_mfma_f32_16x16x32_bf16 v[54:57], v[158:161], v[184:187], v[54:57]
	v_mfma_f32_16x16x32_bf16 v[50:53], v[176:179], v[184:187], v[50:53]
	v_mfma_f32_16x16x32_bf16 v[38:41], v[158:161], v[192:195], v[38:41]
	v_mfma_f32_16x16x32_bf16 v[34:37], v[176:179], v[192:195], v[34:37]
	v_mfma_f32_16x16x32_bf16 v[22:25], v[158:161], v[200:203], v[22:25]
	v_mfma_f32_16x16x32_bf16 v[18:21], v[176:179], v[200:203], v[18:21]
	v_mfma_f32_16x16x32_bf16 v[6:9], v[158:161], v[208:211], v[6:9]
	v_mfma_f32_16x16x32_bf16 v[2:5], v[176:179], v[208:211], v[2:5]
	v_mfma_f32_16x16x32_bf16 v[54:57], v[172:175], v[188:191], v[54:57]
	v_mfma_f32_16x16x32_bf16 v[50:53], v[180:183], v[188:191], v[50:53]
	v_mfma_f32_16x16x32_bf16 v[38:41], v[172:175], v[196:199], v[38:41]
	v_mfma_f32_16x16x32_bf16 v[34:37], v[180:183], v[196:199], v[34:37]
	v_mfma_f32_16x16x32_bf16 v[22:25], v[172:175], v[204:207], v[22:25]
	v_mfma_f32_16x16x32_bf16 v[18:21], v[180:183], v[204:207], v[18:21]
	v_mfma_f32_16x16x32_bf16 v[6:9], v[172:175], v[212:215], v[6:9]
	v_mfma_f32_16x16x32_bf16 v[2:5], v[180:183], v[212:215], v[2:5]
	s_setprio 2
	s_barrier
	s_movk_i32 s44, 0x100
	s_andn2_b64 vcc, exec, s[4:5]
	s_mov_b64 s[10:11], -1
	s_mov_b64 s[4:5], 0
	s_cbranch_vccz .LBB0_1537

; #define PG8_STAGE(bufoff, gbase, voff) do { _Pragma("unroll") for (int _i = 0; _i < 2; ++_i) \
;         __builtin_amdgcn_global_load_lds((const unsigned*)((const char*)(gbase) + (voff)[_i]), (LAS unsigned*)(lds + (bufoff) + ldsw + _i * 8192), 16, 0, 0); } while (0)
; #define PG8_LDA(dst, b, h) do { _Pragma("unroll") for (int m = 0; m < 4; ++m) _Pragma("unroll") for (int k = 0; k < 2; ++k) dst[m][k] = *(const LAS bf16x8*)(lds + PG8_SA(b, h) + aoff + m * 2048 + k * 1024); } while (0)
; #define PG8_LDB(dst, b, h) do { _Pragma("unroll") for (int n = 0; n < 2; ++n) _Pragma("unroll") for (int k = 0; k < 2; ++k) dst[n][k] = *(const LAS bf16x8*)(lds + PG8_SB(b, h) + boff + n * 2048 + k * 1024); } while (0)
; #define PG8_MMA(ai, bj, At, Bt) do { __builtin_amdgcn_s_setprio(1); _Pragma("unroll") for (int m = 0; m < 4; ++m) _Pragma("unroll") for (int n = 0; n < 2; ++n) _Pragma("unroll") for (int k = 0; k < 2; ++k) \
;         acc[ai][bj][m][n] = __builtin_amdgcn_mfma_f32_16x16x32_bf16(Bt[n][k], At[m][k], acc[ai][bj][m][n], 0, 0, 0); __builtin_amdgcn_s_setprio(0); } while (0)
; template <class Epi>
; __device__ __forceinline__ void gemm_phase(LAS unsigned char* lds, const Gemm g, int G, int c, const Epi& E) {
;     ...
;         const bool has_next = S.next(ui + 1, nxt);
;         const char* nA = has_next ? (const char*)(g.A + (size_t)nxt.pb * g.sA) + (size_t)nxt.pm * 2 * hstepA : cA;
;         const char* nB = has_next ? (const char*)(g.Bt + (size_t)nxt.pb * g.sB) + (size_t)nxt.pn * 2 * hstepB : cB;
; #pragma nounroll
;         for (int t = 0; t < nt; t += 2) {
;             const bool last = (t == nt - 2);
;             const char* a1 = cA + (size_t)(t + 1) * kstep;
;             const char* a2 = last ? nA : cA + (size_t)(t + 2) * kstep; const char* b2 = last ? nB : cB + (size_t)(t + 2) * kstep;
;             const char* a3 = a2 + kstep; const char* b3 = b2 + kstep;
;             PG8_LDB(B0, 0, 0); PG8_LDB(B1, 0, 1); PG8_SCHED; PG8_LDA(At, 0, 0); PG8_STAGE(PG8_SA(1, 1), a1 + hstepA, voffA);
;             PG8_WAIT_V(8); PG8_WAIT_L(0); PG8_BAR; PG8_MMA(0, 0, At, B0); PG8_MMA(0, 1, At, B1); PG8_BAR; PG8_SCHED;
;             PG8_LDA(At, 0, 1); PG8_STAGE(PG8_SB(0, 0), b2, voffB); PG8_STAGE(PG8_SB(0, 1), b2 + hstepB, voffB); PG8_STAGE(PG8_SA(0, 0), a2, voffA);
;             PG8_WAIT_V(8); PG8_WAIT_L(0); PG8_BAR; PG8_MMA(1, 0, At, B0); PG8_MMA(1, 1, At, B1); PG8_BAR; PG8_SCHED;
.LBB0_1652:
	s_mov_b32 s48, 0
	s_mov_b64 s[4:5], -1
	s_mov_b64 s[46:47], 0
	s_waitcnt lgkmcnt(0)
	s_waitcnt vmcnt(0)
	s_add_u32 s33, s8, s48
	s_addc_u32 s49, s9, 0
	s_add_u32 s54, s33, 0x100
	s_addc_u32 s55, s49, 0
	s_and_b64 s[52:53], s[46:47], exec
	s_cselect_b32 s53, s41, s55
	s_cselect_b32 s52, s40, s54
	s_add_u32 s48, s6, s48
	s_addc_u32 s54, s7, 0
	s_add_u32 s48, s48, 0x100
	s_addc_u32 s54, s54, 0
	s_and_b64 s[46:47], s[46:47], exec
	s_cselect_b32 s55, s43, s54
	s_cselect_b32 s54, s42, s48
	s_add_u32 s58, s33, 0xb0080
	ds_read_b128 v[142:145], v166
	ds_read_b128 v[146:149], v166 offset:1024
	ds_read_b128 v[150:153], v166 offset:2048
	ds_read_b128 v[154:157], v166 offset:3072
	ds_read_b128 v[158:161], v167
	ds_read_b128 v[170:173], v167 offset:1024
	ds_read_b128 v[174:177], v167 offset:2048
	ds_read_b128 v[178:181], v167 offset:3072
	s_addc_u32 s59, s49, 0
	s_add_i32 s63, s80, s23
	s_add_i32 m0, s68, 0xc000
	s_add_i32 s64, s68, 0xe000
	s_add_i32 s74, s63, 0x2000
	s_add_u32 s56, s54, 0xb0000
	s_addc_u32 s57, s55, 0
	s_add_i32 s62, s81, s23
	s_add_i32 s75, s62, 0x2000
	s_add_i32 s93, 0, 0x18000
	s_add_i32 s33, 0, 0x1c000
	s_add_u32 s48, s52, 0xb0000
	s_addc_u32 s49, s53, 0
	s_add_i32 s92, s93, s23
	s_add_i32 s90, s92, 0x2000
	s_add_u32 s46, s54, 0xb0080
	s_addc_u32 s47, s55, 0
	s_add_i32 s91, s33, s23
	s_add_i32 s89, s91, 0x2000
	v_lshl_add_u64 v[162:163], s[58:59], 0, v[136:137]
	ds_read_b128 v[182:185], v168
	ds_read_b128 v[186:189], v168 offset:1024
	ds_read_b128 v[190:193], v168 offset:2048
	ds_read_b128 v[194:197], v168 offset:3072
	ds_read_b128 v[198:201], v168 offset:4096
	ds_read_b128 v[202:205], v168 offset:5120
	ds_read_b128 v[206:209], v168 offset:6144
	ds_read_b128 v[210:213], v168 offset:7168
	global_load_lds_dwordx4 v[162:163], off
	v_lshl_add_u64 v[162:163], s[58:59], 0, v[132:133]
	s_mov_b32 m0, s64
	s_nop 0
	global_load_lds_dwordx4 v[162:163], off
	s_waitcnt vmcnt(8)
	s_waitcnt lgkmcnt(0)
	s_barrier
	s_setprio 0
	s_waitcnt lgkmcnt(0)
	v_mfma_f32_16x16x32_bf16 v[126:129], v[142:145], v[182:185], 0
	v_mfma_f32_16x16x32_bf16 v[122:125], v[150:153], v[182:185], 0
	v_mfma_f32_16x16x32_bf16 v[110:113], v[142:145], v[190:193], 0
	v_mfma_f32_16x16x32_bf16 v[106:109], v[150:153], v[190:193], 0
	v_mfma_f32_16x16x32_bf16 v[94:97], v[142:145], v[198:201], 0
	v_mfma_f32_16x16x32_bf16 v[90:93], v[150:153], v[198:201], 0
	v_mfma_f32_16x16x32_bf16 v[78:81], v[142:145], v[206:209], 0
	v_mfma_f32_16x16x32_bf16 v[74:77], v[150:153], v[206:209], 0
	v_mfma_f32_16x16x32_bf16 v[126:129], v[146:149], v[186:189], v[126:129]
	v_mfma_f32_16x16x32_bf16 v[122:125], v[154:157], v[186:189], v[122:125]
	v_mfma_f32_16x16x32_bf16 v[110:113], v[146:149], v[194:197], v[110:113]
	v_mfma_f32_16x16x32_bf16 v[106:109], v[154:157], v[194:197], v[106:109]
	v_mfma_f32_16x16x32_bf16 v[94:97], v[146:149], v[202:205], v[94:97]
	v_mfma_f32_16x16x32_bf16 v[90:93], v[154:157], v[202:205], v[90:93]
	v_mfma_f32_16x16x32_bf16 v[78:81], v[146:149], v[210:213], v[78:81]
	v_mfma_f32_16x16x32_bf16 v[74:77], v[154:157], v[210:213], v[74:77]
	s_setprio 2
	s_setprio 0
	v_mfma_f32_16x16x32_bf16 v[118:121], v[158:161], v[182:185], 0
	v_mfma_f32_16x16x32_bf16 v[114:117], v[174:177], v[182:185], 0
	v_mfma_f32_16x16x32_bf16 v[102:105], v[158:161], v[190:193], 0
	v_mfma_f32_16x16x32_bf16 v[98:101], v[174:177], v[190:193], 0
	v_mfma_f32_16x16x32_bf16 v[86:89], v[158:161], v[198:201], 0
	v_mfma_f32_16x16x32_bf16 v[82:85], v[174:177], v[198:201], 0
	v_mfma_f32_16x16x32_bf16 v[70:73], v[158:161], v[206:209], 0
	v_mfma_f32_16x16x32_bf16 v[66:69], v[174:177], v[206:209], 0
	v_mfma_f32_16x16x32_bf16 v[118:121], v[170:173], v[186:189], v[118:121]
	v_mfma_f32_16x16x32_bf16 v[114:117], v[178:181], v[186:189], v[114:117]
	v_mfma_f32_16x16x32_bf16 v[102:105], v[170:173], v[194:197], v[102:105]
	v_mfma_f32_16x16x32_bf16 v[98:101], v[178:181], v[194:197], v[98:101]
	v_mfma_f32_16x16x32_bf16 v[86:89], v[170:173], v[202:205], v[86:89]
	v_mfma_f32_16x16x32_bf16 v[82:85], v[178:181], v[202:205], v[82:85]
	v_mfma_f32_16x16x32_bf16 v[70:73], v[170:173], v[210:213], v[70:73]
	v_mfma_f32_16x16x32_bf16 v[66:69], v[178:181], v[210:213], v[66:69]
	s_setprio 2
	s_barrier
	s_mov_b32 m0, s63
	v_lshl_add_u64 v[162:163], s[54:55], 0, v[134:135]
	ds_read_b128 v[182:185], v168 offset:16384
	ds_read_b128 v[186:189], v168 offset:17408
	ds_read_b128 v[190:193], v168 offset:18432
	ds_read_b128 v[194:197], v168 offset:19456
	ds_read_b128 v[198:201], v168 offset:20480
	ds_read_b128 v[202:205], v168 offset:21504
	ds_read_b128 v[206:209], v168 offset:22528
	ds_read_b128 v[210:213], v168 offset:23552
	global_load_lds_dwordx4 v[162:163], off
	v_lshl_add_u64 v[214:215], s[54:55], 0, v[130:131]
	s_mov_b32 m0, s74
	v_lshl_add_u64 v[216:217], s[56:57], 0, v[134:135]
	global_load_lds_dwordx4 v[214:215], off
	s_mov_b32 m0, s62
	v_lshl_add_u64 v[218:219], s[52:53], 0, v[132:133]
	global_load_lds_dwordx4 v[216:217], off
	v_lshl_add_u64 v[216:217], s[56:57], 0, v[130:131]
	s_mov_b32 m0, s75
	s_nop 0
	global_load_lds_dwordx4 v[216:217], off
	v_lshl_add_u64 v[216:217], s[52:53], 0, v[136:137]
	s_mov_b32 m0, s68
	s_nop 0
	global_load_lds_dwordx4 v[216:217], off
	s_mov_b32 m0, s69
	s_nop 0
	global_load_lds_dwordx4 v[218:219], off
	s_waitcnt vmcnt(8)
	s_waitcnt lgkmcnt(0)
	s_barrier
; #define PG8_STAGE(bufoff, gbase, voff) do { _Pragma("unroll") for (int _i = 0; _i < 2; ++_i) \
;         __builtin_amdgcn_global_load_lds((const unsigned*)((const char*)(gbase) + (voff)[_i]), (LAS unsigned*)(lds + (bufoff) + ldsw + _i * 8192), 16, 0, 0); } while (0)
; #define PG8_LDA(dst, b, h) do { _Pragma("unroll") for (int m = 0; m < 4; ++m) _Pragma("unroll") for (int k = 0; k < 2; ++k) dst[m][k] = *(const LAS bf16x8*)(lds + PG8_SA(b, h) + aoff + m * 2048 + k * 1024); } while (0)
; #define PG8_LDB(dst, b, h) do { _Pragma("unroll") for (int n = 0; n < 2; ++n) _Pragma("unroll") for (int k = 0; k < 2; ++k) dst[n][k] = *(const LAS bf16x8*)(lds + PG8_SB(b, h) + boff + n * 2048 + k * 1024); } while (0)
; #define PG8_MMA(ai, bj, At, Bt) do { __builtin_amdgcn_s_setprio(1); _Pragma("unroll") for (int m = 0; m < 4; ++m) _Pragma("unroll") for (int n = 0; n < 2; ++n) _Pragma("unroll") for (int k = 0; k < 2; ++k) \
;         acc[ai][bj][m][n] = __builtin_amdgcn_mfma_f32_16x16x32_bf16(Bt[n][k], At[m][k], acc[ai][bj][m][n], 0, 0, 0); __builtin_amdgcn_s_setprio(0); } while (0)
; #define PG8_WAIT_V(n) asm volatile("s_waitcnt vmcnt(" #n ")" ::: "memory")
; #define PG8_WAIT_L(n) asm volatile("s_waitcnt lgkmcnt(" #n ")" ::: "memory")
; #define PG8_BAR __builtin_amdgcn_s_barrier()
; #define PG8_SCHED __builtin_amdgcn_sched_barrier(0)
; template <class Epi>
; __device__ __forceinline__ void gemm_phase(LAS unsigned char* lds, const Gemm g, int G, int c, const Epi& E) {
;     ...
;             PG8_WAIT_V(8); PG8_WAIT_L(0); PG8_BAR; PG8_MMA(1, 0, At, B0); PG8_MMA(1, 1, At, B1); PG8_BAR; PG8_SCHED;
;             PG8_LDB(B0, 1, 0); PG8_LDB(B1, 1, 1); PG8_SCHED; PG8_LDA(At, 1, 0); PG8_STAGE(PG8_SA(0, 1), a2 + hstepA, voffA);
;             PG8_WAIT_V(8); PG8_WAIT_L(0); PG8_BAR; PG8_MMA(0, 0, At, B0); PG8_MMA(0, 1, At, B1); PG8_BAR; PG8_SCHED;
	s_setprio 0
	s_waitcnt lgkmcnt(0)
	v_mfma_f32_16x16x32_bf16 v[62:65], v[142:145], v[182:185], 0
	v_mfma_f32_16x16x32_bf16 v[58:61], v[150:153], v[182:185], 0
	v_mfma_f32_16x16x32_bf16 v[46:49], v[142:145], v[190:193], 0
	v_mfma_f32_16x16x32_bf16 v[42:45], v[150:153], v[190:193], 0
	v_mfma_f32_16x16x32_bf16 v[30:33], v[142:145], v[198:201], 0
	v_mfma_f32_16x16x32_bf16 v[26:29], v[150:153], v[198:201], 0
	v_mfma_f32_16x16x32_bf16 v[14:17], v[142:145], v[206:209], 0
	v_mfma_f32_16x16x32_bf16 v[10:13], v[150:153], v[206:209], 0
	v_mfma_f32_16x16x32_bf16 v[62:65], v[146:149], v[186:189], v[62:65]
	v_mfma_f32_16x16x32_bf16 v[58:61], v[154:157], v[186:189], v[58:61]
	v_mfma_f32_16x16x32_bf16 v[46:49], v[146:149], v[194:197], v[46:49]
	v_mfma_f32_16x16x32_bf16 v[42:45], v[154:157], v[194:197], v[42:45]
	v_mfma_f32_16x16x32_bf16 v[30:33], v[146:149], v[202:205], v[30:33]
	v_mfma_f32_16x16x32_bf16 v[26:29], v[154:157], v[202:205], v[26:29]
	v_mfma_f32_16x16x32_bf16 v[14:17], v[146:149], v[210:213], v[14:17]
	v_mfma_f32_16x16x32_bf16 v[10:13], v[154:157], v[210:213], v[10:13]
	s_setprio 2
	s_setprio 0
	v_mfma_f32_16x16x32_bf16 v[54:57], v[158:161], v[182:185], 0
	v_mfma_f32_16x16x32_bf16 v[50:53], v[174:177], v[182:185], 0
	v_mfma_f32_16x16x32_bf16 v[38:41], v[158:161], v[190:193], 0
	v_mfma_f32_16x16x32_bf16 v[34:37], v[174:177], v[190:193], 0
	v_mfma_f32_16x16x32_bf16 v[22:25], v[158:161], v[198:201], 0
	v_mfma_f32_16x16x32_bf16 v[18:21], v[174:177], v[198:201], 0
	v_mfma_f32_16x16x32_bf16 v[6:9], v[158:161], v[206:209], 0
	v_mfma_f32_16x16x32_bf16 v[2:5], v[174:177], v[206:209], 0
	v_mfma_f32_16x16x32_bf16 v[54:57], v[170:173], v[186:189], v[54:57]
	v_mfma_f32_16x16x32_bf16 v[50:53], v[178:181], v[186:189], v[50:53]
	v_mfma_f32_16x16x32_bf16 v[38:41], v[170:173], v[194:197], v[38:41]
	v_mfma_f32_16x16x32_bf16 v[34:37], v[178:181], v[194:197], v[34:37]
	v_mfma_f32_16x16x32_bf16 v[22:25], v[170:173], v[202:205], v[22:25]
	v_mfma_f32_16x16x32_bf16 v[18:21], v[178:181], v[202:205], v[18:21]
	v_mfma_f32_16x16x32_bf16 v[6:9], v[170:173], v[210:213], v[6:9]
	v_mfma_f32_16x16x32_bf16 v[2:5], v[178:181], v[210:213], v[2:5]
	s_setprio 2
	s_barrier
	v_add_u32_e32 v154, s93, v165
	v_add_u32_e32 v178, s33, v165
	ds_read_b128 v[142:145], v154
	ds_read_b128 v[146:149], v154 offset:1024
	ds_read_b128 v[150:153], v154 offset:2048
	ds_read_b128 v[154:157], v154 offset:3072
	ds_read_b128 v[158:161], v178
	ds_read_b128 v[170:173], v178 offset:1024
	ds_read_b128 v[174:177], v178 offset:2048
	ds_read_b128 v[178:181], v178 offset:3072
	s_mov_b32 m0, s70
	v_lshl_add_u64 v[220:221], s[48:49], 0, v[136:137]
	ds_read_b128 v[182:185], v168 offset:32768
	ds_read_b128 v[186:189], v168 offset:33792
	ds_read_b128 v[190:193], v168 offset:34816
	ds_read_b128 v[194:197], v168 offset:35840
	ds_read_b128 v[198:201], v168 offset:36864
	ds_read_b128 v[202:205], v168 offset:37888
	ds_read_b128 v[206:209], v168 offset:38912
	ds_read_b128 v[210:213], v168 offset:39936
	global_load_lds_dwordx4 v[220:221], off
	v_lshl_add_u64 v[220:221], s[48:49], 0, v[132:133]
	s_mov_b32 m0, s71
	s_nop 0
	global_load_lds_dwordx4 v[220:221], off
	s_waitcnt vmcnt(8)
	s_waitcnt lgkmcnt(0)
	s_barrier
	s_setprio 0
	s_waitcnt lgkmcnt(0)
	v_mfma_f32_16x16x32_bf16 v[126:129], v[142:145], v[182:185], v[126:129]
	v_mfma_f32_16x16x32_bf16 v[122:125], v[150:153], v[182:185], v[122:125]
	v_mfma_f32_16x16x32_bf16 v[110:113], v[142:145], v[190:193], v[110:113]
	v_mfma_f32_16x16x32_bf16 v[106:109], v[150:153], v[190:193], v[106:109]
	v_mfma_f32_16x16x32_bf16 v[94:97], v[142:145], v[198:201], v[94:97]
	v_mfma_f32_16x16x32_bf16 v[90:93], v[150:153], v[198:201], v[90:93]
	v_mfma_f32_16x16x32_bf16 v[78:81], v[142:145], v[206:209], v[78:81]
	v_mfma_f32_16x16x32_bf16 v[74:77], v[150:153], v[206:209], v[74:77]
	v_mfma_f32_16x16x32_bf16 v[126:129], v[146:149], v[186:189], v[126:129]
	v_mfma_f32_16x16x32_bf16 v[122:125], v[154:157], v[186:189], v[122:125]
	v_mfma_f32_16x16x32_bf16 v[110:113], v[146:149], v[194:197], v[110:113]
	v_mfma_f32_16x16x32_bf16 v[106:109], v[154:157], v[194:197], v[106:109]
	v_mfma_f32_16x16x32_bf16 v[94:97], v[146:149], v[202:205], v[94:97]
	v_mfma_f32_16x16x32_bf16 v[90:93], v[154:157], v[202:205], v[90:93]
	v_mfma_f32_16x16x32_bf16 v[78:81], v[146:149], v[210:213], v[78:81]
	v_mfma_f32_16x16x32_bf16 v[74:77], v[154:157], v[210:213], v[74:77]
	s_setprio 2
	s_setprio 0
	v_mfma_f32_16x16x32_bf16 v[118:121], v[158:161], v[182:185], v[118:121]
	v_mfma_f32_16x16x32_bf16 v[114:117], v[174:177], v[182:185], v[114:117]
	v_mfma_f32_16x16x32_bf16 v[102:105], v[158:161], v[190:193], v[102:105]
	v_mfma_f32_16x16x32_bf16 v[98:101], v[174:177], v[190:193], v[98:101]
	v_mfma_f32_16x16x32_bf16 v[86:89], v[158:161], v[198:201], v[86:89]
	v_mfma_f32_16x16x32_bf16 v[82:85], v[174:177], v[198:201], v[82:85]
	v_mfma_f32_16x16x32_bf16 v[70:73], v[158:161], v[206:209], v[70:73]
	v_mfma_f32_16x16x32_bf16 v[66:69], v[174:177], v[206:209], v[66:69]
	v_mfma_f32_16x16x32_bf16 v[118:121], v[170:173], v[186:189], v[118:121]
	v_mfma_f32_16x16x32_bf16 v[114:117], v[178:181], v[186:189], v[114:117]
	v_mfma_f32_16x16x32_bf16 v[102:105], v[170:173], v[194:197], v[102:105]
	v_mfma_f32_16x16x32_bf16 v[98:101], v[178:181], v[194:197], v[98:101]
	v_mfma_f32_16x16x32_bf16 v[86:89], v[170:173], v[202:205], v[86:89]
	v_mfma_f32_16x16x32_bf16 v[82:85], v[178:181], v[202:205], v[82:85]
	v_mfma_f32_16x16x32_bf16 v[70:73], v[170:173], v[210:213], v[70:73]
	v_mfma_f32_16x16x32_bf16 v[66:69], v[178:181], v[210:213], v[66:69]
	s_setprio 2
	s_barrier
; #define PG8_STAGE(bufoff, gbase, voff) do { _Pragma("unroll") for (int _i = 0; _i < 2; ++_i) \
;         __builtin_amdgcn_global_load_lds((const unsigned*)((const char*)(gbase) + (voff)[_i]), (LAS unsigned*)(lds + (bufoff) + ldsw + _i * 8192), 16, 0, 0); } while (0)
; #define PG8_LDA(dst, b, h) do { _Pragma("unroll") for (int m = 0; m < 4; ++m) _Pragma("unroll") for (int k = 0; k < 2; ++k) dst[m][k] = *(const LAS bf16x8*)(lds + PG8_SA(b, h) + aoff + m * 2048 + k * 1024); } while (0)
; #define PG8_MMA(ai, bj, At, Bt) do { __builtin_amdgcn_s_setprio(1); _Pragma("unroll") for (int m = 0; m < 4; ++m) _Pragma("unroll") for (int n = 0; n < 2; ++n) _Pragma("unroll") for (int k = 0; k < 2; ++k) \
;         acc[ai][bj][m][n] = __builtin_amdgcn_mfma_f32_16x16x32_bf16(Bt[n][k], At[m][k], acc[ai][bj][m][n], 0, 0, 0); __builtin_amdgcn_s_setprio(0); } while (0)
; #define PG8_WAIT_V(n) asm volatile("s_waitcnt vmcnt(" #n ")" ::: "memory")
; #define PG8_WAIT_L(n) asm volatile("s_waitcnt lgkmcnt(" #n ")" ::: "memory")
; #define PG8_BAR __builtin_amdgcn_s_barrier()
; #define PG8_SCHED __builtin_amdgcn_sched_barrier(0)
; template <class Epi>
; __device__ __forceinline__ void gemm_phase(LAS unsigned char* lds, const Gemm g, int G, int c, const Epi& E) {
;     ...
;             PG8_LDA(At, 1, 1); PG8_STAGE(PG8_SB(1, 0), b3, voffB); PG8_STAGE(PG8_SB(1, 1), b3 + hstepB, voffB); PG8_STAGE(PG8_SA(1, 0), a3, voffA);
;             PG8_WAIT_V(8); PG8_WAIT_L(0); PG8_BAR; PG8_MMA(1, 0, At, B0); PG8_MMA(1, 1, At, B1); PG8_BAR; PG8_SCHED;
;         }
	s_mov_b32 m0, s92
	v_lshl_add_u64 v[162:163], v[162:163], 0, s[18:19]
	ds_read_b128 v[182:185], v168 offset:49152
	ds_read_b128 v[186:189], v168 offset:50176
	ds_read_b128 v[190:193], v168 offset:51200
	ds_read_b128 v[194:197], v168 offset:52224
	ds_read_b128 v[198:201], v168 offset:53248
	ds_read_b128 v[202:205], v168 offset:54272
	ds_read_b128 v[206:209], v168 offset:55296
	ds_read_b128 v[210:213], v168 offset:56320
	global_load_lds_dwordx4 v[162:163], off
	v_lshl_add_u64 v[162:163], v[214:215], 0, s[18:19]
	s_mov_b32 m0, s90
	s_nop 0
	global_load_lds_dwordx4 v[162:163], off
	v_lshl_add_u64 v[162:163], s[46:47], 0, v[134:135]
	s_mov_b32 m0, s91
	s_nop 0
	global_load_lds_dwordx4 v[162:163], off
	v_lshl_add_u64 v[162:163], s[46:47], 0, v[130:131]
	s_mov_b32 m0, s89
	s_nop 0
	global_load_lds_dwordx4 v[162:163], off
	v_lshl_add_u64 v[162:163], v[216:217], 0, s[18:19]
	s_mov_b32 m0, s78
	s_nop 0
	global_load_lds_dwordx4 v[162:163], off
	v_lshl_add_u64 v[162:163], v[218:219], 0, s[18:19]
	s_mov_b32 m0, s79
	s_nop 0
	global_load_lds_dwordx4 v[162:163], off
	s_waitcnt vmcnt(8)
	s_waitcnt lgkmcnt(0)
	s_barrier
	s_setprio 0
	s_waitcnt lgkmcnt(0)
	v_mfma_f32_16x16x32_bf16 v[62:65], v[142:145], v[182:185], v[62:65]
	v_mfma_f32_16x16x32_bf16 v[58:61], v[150:153], v[182:185], v[58:61]
	v_mfma_f32_16x16x32_bf16 v[46:49], v[142:145], v[190:193], v[46:49]
	v_mfma_f32_16x16x32_bf16 v[42:45], v[150:153], v[190:193], v[42:45]
	v_mfma_f32_16x16x32_bf16 v[30:33], v[142:145], v[198:201], v[30:33]
	v_mfma_f32_16x16x32_bf16 v[26:29], v[150:153], v[198:201], v[26:29]
	v_mfma_f32_16x16x32_bf16 v[14:17], v[142:145], v[206:209], v[14:17]
	v_mfma_f32_16x16x32_bf16 v[10:13], v[150:153], v[206:209], v[10:13]
	v_mfma_f32_16x16x32_bf16 v[62:65], v[146:149], v[186:189], v[62:65]
	v_mfma_f32_16x16x32_bf16 v[58:61], v[154:157], v[186:189], v[58:61]
	v_mfma_f32_16x16x32_bf16 v[46:49], v[146:149], v[194:197], v[46:49]
	v_mfma_f32_16x16x32_bf16 v[42:45], v[154:157], v[194:197], v[42:45]
	v_mfma_f32_16x16x32_bf16 v[30:33], v[146:149], v[202:205], v[30:33]
	v_mfma_f32_16x16x32_bf16 v[26:29], v[154:157], v[202:205], v[26:29]
	v_mfma_f32_16x16x32_bf16 v[14:17], v[146:149], v[210:213], v[14:17]
	v_mfma_f32_16x16x32_bf16 v[10:13], v[154:157], v[210:213], v[10:13]
	s_setprio 2
	s_setprio 0
	v_mfma_f32_16x16x32_bf16 v[54:57], v[158:161], v[182:185], v[54:57]
	v_mfma_f32_16x16x32_bf16 v[50:53], v[174:177], v[182:185], v[50:53]
	v_mfma_f32_16x16x32_bf16 v[38:41], v[158:161], v[190:193], v[38:41]
	v_mfma_f32_16x16x32_bf16 v[34:37], v[174:177], v[190:193], v[34:37]
	v_mfma_f32_16x16x32_bf16 v[22:25], v[158:161], v[198:201], v[22:25]
	v_mfma_f32_16x16x32_bf16 v[18:21], v[174:177], v[198:201], v[18:21]
	v_mfma_f32_16x16x32_bf16 v[6:9], v[158:161], v[206:209], v[6:9]
	v_mfma_f32_16x16x32_bf16 v[2:5], v[174:177], v[206:209], v[2:5]
	v_mfma_f32_16x16x32_bf16 v[54:57], v[170:173], v[186:189], v[54:57]
	v_mfma_f32_16x16x32_bf16 v[50:53], v[178:181], v[186:189], v[50:53]
	v_mfma_f32_16x16x32_bf16 v[38:41], v[170:173], v[194:197], v[38:41]
	v_mfma_f32_16x16x32_bf16 v[34:37], v[178:181], v[194:197], v[34:37]
	v_mfma_f32_16x16x32_bf16 v[22:25], v[170:173], v[202:205], v[22:25]
	v_mfma_f32_16x16x32_bf16 v[18:21], v[178:181], v[202:205], v[18:21]
	v_mfma_f32_16x16x32_bf16 v[6:9], v[170:173], v[210:213], v[6:9]
	v_mfma_f32_16x16x32_bf16 v[2:5], v[178:181], v[210:213], v[2:5]
	s_setprio 2
	s_barrier
	s_movk_i32 s48, 0x100
	s_andn2_b64 vcc, exec, s[4:5]
	s_mov_b64 s[46:47], -1
	s_mov_b64 s[4:5], 0
	s_cbranch_vccz .LBB0_1653

; #define PG8_STAGE(bufoff, gbase, voff) do { _Pragma("unroll") for (int _i = 0; _i < 2; ++_i) \
;         __builtin_amdgcn_global_load_lds((const unsigned*)((const char*)(gbase) + (voff)[_i]), (LAS unsigned*)(lds + (bufoff) + ldsw + _i * 8192), 16, 0, 0); } while (0)
; #define PG8_LDA(dst, b, h) do { _Pragma("unroll") for (int m = 0; m < 4; ++m) _Pragma("unroll") for (int k = 0; k < 2; ++k) dst[m][k] = *(const LAS bf16x8*)(lds + PG8_SA(b, h) + aoff + m * 2048 + k * 1024); } while (0)
; #define PG8_LDB(dst, b, h) do { _Pragma("unroll") for (int n = 0; n < 2; ++n) _Pragma("unroll") for (int k = 0; k < 2; ++k) dst[n][k] = *(const LAS bf16x8*)(lds + PG8_SB(b, h) + boff + n * 2048 + k * 1024); } while (0)
; #define PG8_MMA(ai, bj, At, Bt) do { __builtin_amdgcn_s_setprio(1); _Pragma("unroll") for (int m = 0; m < 4; ++m) _Pragma("unroll") for (int n = 0; n < 2; ++n) _Pragma("unroll") for (int k = 0; k < 2; ++k) \
;         acc[ai][bj][m][n] = __builtin_amdgcn_mfma_f32_16x16x32_bf16(Bt[n][k], At[m][k], acc[ai][bj][m][n], 0, 0, 0); __builtin_amdgcn_s_setprio(0); } while (0)
; template <class Epi>
; __device__ __forceinline__ void gemm_phase(LAS unsigned char* lds, const Gemm g, int G, int c, const Epi& E) {
;     ...
;         const bool has_next = S.next(ui + 1, nxt);
;         const char* nA = has_next ? (const char*)(g.A + (size_t)nxt.pb * g.sA) + (size_t)nxt.pm * 2 * hstepA : cA;
;         const char* nB = has_next ? (const char*)(g.Bt + (size_t)nxt.pb * g.sB) + (size_t)nxt.pn * 2 * hstepB : cB;
; #pragma nounroll
;         for (int t = 0; t < nt; t += 2) {
;             const bool last = (t == nt - 2);
;             const char* a1 = cA + (size_t)(t + 1) * kstep;
;             const char* a2 = last ? nA : cA + (size_t)(t + 2) * kstep; const char* b2 = last ? nB : cB + (size_t)(t + 2) * kstep;
;             const char* a3 = a2 + kstep; const char* b3 = b2 + kstep;
;             PG8_LDB(B0, 0, 0); PG8_LDB(B1, 0, 1); PG8_SCHED; PG8_LDA(At, 0, 0); PG8_STAGE(PG8_SA(1, 1), a1 + hstepA, voffA);
;             PG8_WAIT_V(8); PG8_WAIT_L(0); PG8_BAR; PG8_MMA(0, 0, At, B0); PG8_MMA(0, 1, At, B1); PG8_BAR; PG8_SCHED;
;             PG8_LDA(At, 0, 1); PG8_STAGE(PG8_SB(0, 0), b2, voffB); PG8_STAGE(PG8_SB(0, 1), b2 + hstepB, voffB); PG8_STAGE(PG8_SA(0, 0), a2, voffA);
;             PG8_WAIT_V(8); PG8_WAIT_L(0); PG8_BAR; PG8_MMA(1, 0, At, B0); PG8_MMA(1, 1, At, B1); PG8_BAR; PG8_SCHED;
.LBB0_1824:
	s_ashr_i32 s15, s14, 31
	s_lshl_b64 s[18:19], s[14:15], 21
	s_add_u32 s18, s34, s18
	s_addc_u32 s19, s35, s19
	s_and_b64 s[24:25], s[2:3], exec
	s_cselect_b32 s15, s19, s41
	s_cselect_b32 s63, s18, s40
	s_ashr_i32 s11, s10, 31
	s_lshl_b64 s[24:25], s[10:11], 21
	s_add_u32 s11, s46, s24
	s_addc_u32 s33, s47, s25
	s_ashr_i32 s13, s12, 31
	s_lshl_b64 s[24:25], s[12:13], 21
	s_add_u32 s24, s11, s24
	s_addc_u32 s25, s33, s25
	s_and_b64 s[44:45], s[2:3], exec
	s_cselect_b32 s11, s25, s43
	s_cselect_b32 s13, s24, s42
	s_add_u32 s40, s40, 0x100080
	s_addc_u32 s41, s41, 0
	s_add_u32 s66, s42, 0x100
	s_addc_u32 s67, s43, 0
	s_mov_b32 s68, -2
	ds_read_b128 v[146:149], v152
	ds_read_b128 v[156:159], v152 offset:1024
	ds_read_b128 v[160:163], v152 offset:2048
	ds_read_b128 v[164:167], v152 offset:3072
	ds_read_b128 v[168:171], v153
	ds_read_b128 v[172:175], v153 offset:1024
	ds_read_b128 v[176:179], v153 offset:2048
	ds_read_b128 v[180:183], v153 offset:3072
	s_add_u32 s33, s40, 0xfff00080
	s_addc_u32 s42, s41, -1
	s_cmp_eq_u32 s68, 60
	s_cselect_b32 s45, s15, s42
	s_cselect_b32 s44, s63, s33
	s_cselect_b32 s43, s11, s67
	s_cselect_b32 s42, s13, s66
	v_lshl_add_u64 v[216:217], s[40:41], 0, v[138:139]
	s_add_i32 m0, s17, 0xc000
	ds_read_b128 v[184:187], v154
	ds_read_b128 v[188:191], v154 offset:1024
	ds_read_b128 v[192:195], v154 offset:2048
	ds_read_b128 v[196:199], v154 offset:3072
	ds_read_b128 v[200:203], v154 offset:4096
	ds_read_b128 v[204:207], v154 offset:5120
	ds_read_b128 v[208:211], v154 offset:6144
	ds_read_b128 v[212:215], v154 offset:7168
	global_load_lds_dwordx4 v[216:217], off
	v_lshl_add_u64 v[216:217], s[40:41], 0, v[140:141]
	s_add_i32 m0, s17, 0xe000
	s_nop 0
	global_load_lds_dwordx4 v[216:217], off
	s_waitcnt vmcnt(8)
	s_waitcnt lgkmcnt(0)
	s_barrier
	s_setprio 0
	s_waitcnt lgkmcnt(0)
	v_mfma_f32_16x16x32_bf16 v[126:129], v[146:149], v[184:187], 0
	v_mfma_f32_16x16x32_bf16 v[122:125], v[160:163], v[184:187], 0
	v_mfma_f32_16x16x32_bf16 v[118:121], v[146:149], v[192:195], 0
	v_mfma_f32_16x16x32_bf16 v[110:113], v[160:163], v[192:195], 0
	v_mfma_f32_16x16x32_bf16 v[102:105], v[146:149], v[200:203], 0
	v_mfma_f32_16x16x32_bf16 v[94:97], v[160:163], v[200:203], 0
	v_mfma_f32_16x16x32_bf16 v[86:89], v[146:149], v[208:211], 0
	v_mfma_f32_16x16x32_bf16 v[78:81], v[160:163], v[208:211], 0
	v_mfma_f32_16x16x32_bf16 v[126:129], v[156:159], v[188:191], v[126:129]
	v_mfma_f32_16x16x32_bf16 v[122:125], v[164:167], v[188:191], v[122:125]
	v_mfma_f32_16x16x32_bf16 v[118:121], v[156:159], v[196:199], v[118:121]
	v_mfma_f32_16x16x32_bf16 v[110:113], v[164:167], v[196:199], v[110:113]
	v_mfma_f32_16x16x32_bf16 v[102:105], v[156:159], v[204:207], v[102:105]
	v_mfma_f32_16x16x32_bf16 v[94:97], v[164:167], v[204:207], v[94:97]
	v_mfma_f32_16x16x32_bf16 v[86:89], v[156:159], v[212:215], v[86:89]
	v_mfma_f32_16x16x32_bf16 v[78:81], v[164:167], v[212:215], v[78:81]
	s_setprio 2
	s_setprio 0
	v_mfma_f32_16x16x32_bf16 v[114:117], v[168:171], v[184:187], 0
	v_mfma_f32_16x16x32_bf16 v[106:109], v[176:179], v[184:187], 0
	v_mfma_f32_16x16x32_bf16 v[98:101], v[168:171], v[192:195], 0
	v_mfma_f32_16x16x32_bf16 v[90:93], v[176:179], v[192:195], 0
	v_mfma_f32_16x16x32_bf16 v[82:85], v[168:171], v[200:203], 0
	v_mfma_f32_16x16x32_bf16 v[74:77], v[176:179], v[200:203], 0
	v_mfma_f32_16x16x32_bf16 v[70:73], v[168:171], v[208:211], 0
	v_mfma_f32_16x16x32_bf16 v[66:69], v[176:179], v[208:211], 0
	v_mfma_f32_16x16x32_bf16 v[114:117], v[172:175], v[188:191], v[114:117]
	v_mfma_f32_16x16x32_bf16 v[106:109], v[180:183], v[188:191], v[106:109]
	v_mfma_f32_16x16x32_bf16 v[98:101], v[172:175], v[196:199], v[98:101]
	v_mfma_f32_16x16x32_bf16 v[90:93], v[180:183], v[196:199], v[90:93]
	v_mfma_f32_16x16x32_bf16 v[82:85], v[172:175], v[204:207], v[82:85]
	v_mfma_f32_16x16x32_bf16 v[74:77], v[180:183], v[204:207], v[74:77]
	v_mfma_f32_16x16x32_bf16 v[70:73], v[172:175], v[212:215], v[70:73]
	v_mfma_f32_16x16x32_bf16 v[66:69], v[180:183], v[212:215], v[66:69]
	s_setprio 2
	s_barrier
	s_add_i32 s33, s61, s52
	v_lshl_add_u64 v[216:217], s[42:43], 0, v[134:135]
	s_mov_b32 m0, s33
	ds_read_b128 v[184:187], v154 offset:16384
	ds_read_b128 v[188:191], v154 offset:17408
	ds_read_b128 v[192:195], v154 offset:18432
	ds_read_b128 v[196:199], v154 offset:19456
	ds_read_b128 v[200:203], v154 offset:20480
	ds_read_b128 v[204:207], v154 offset:21504
	ds_read_b128 v[208:211], v154 offset:22528
	ds_read_b128 v[212:215], v154 offset:23552
	global_load_lds_dwordx4 v[216:217], off
	s_add_i32 m0, s33, 0x2000
	s_add_u32 s64, s42, 0x100000
	v_lshl_add_u64 v[218:219], s[42:43], 0, v[130:131]
	s_addc_u32 s65, s43, 0
	s_add_i32 s33, s62, s52
	global_load_lds_dwordx4 v[218:219], off
	v_lshl_add_u64 v[220:221], s[64:65], 0, v[134:135]
	s_mov_b32 m0, s33
	v_lshl_add_u64 v[222:223], s[44:45], 0, v[132:133]
	global_load_lds_dwordx4 v[220:221], off
	v_lshl_add_u64 v[220:221], s[64:65], 0, v[130:131]
	s_add_i32 m0, s33, 0x2000
	s_nop 0
	global_load_lds_dwordx4 v[220:221], off
	v_lshl_add_u64 v[220:221], s[44:45], 0, v[136:137]
	s_mov_b32 m0, s17
	s_nop 0
	global_load_lds_dwordx4 v[220:221], off
	s_mov_b32 m0, s37
	s_nop 0
	global_load_lds_dwordx4 v[222:223], off
	s_waitcnt vmcnt(8)
	s_waitcnt lgkmcnt(0)
	s_barrier
; #define PG8_STAGE(bufoff, gbase, voff) do { _Pragma("unroll") for (int _i = 0; _i < 2; ++_i) \
;         __builtin_amdgcn_global_load_lds((const unsigned*)((const char*)(gbase) + (voff)[_i]), (LAS unsigned*)(lds + (bufoff) + ldsw + _i * 8192), 16, 0, 0); } while (0)
; #define PG8_LDA(dst, b, h) do { _Pragma("unroll") for (int m = 0; m < 4; ++m) _Pragma("unroll") for (int k = 0; k < 2; ++k) dst[m][k] = *(const LAS bf16x8*)(lds + PG8_SA(b, h) + aoff + m * 2048 + k * 1024); } while (0)
; #define PG8_LDB(dst, b, h) do { _Pragma("unroll") for (int n = 0; n < 2; ++n) _Pragma("unroll") for (int k = 0; k < 2; ++k) dst[n][k] = *(const LAS bf16x8*)(lds + PG8_SB(b, h) + boff + n * 2048 + k * 1024); } while (0)
; #define PG8_MMA(ai, bj, At, Bt) do { __builtin_amdgcn_s_setprio(1); _Pragma("unroll") for (int m = 0; m < 4; ++m) _Pragma("unroll") for (int n = 0; n < 2; ++n) _Pragma("unroll") for (int k = 0; k < 2; ++k) \
;         acc[ai][bj][m][n] = __builtin_amdgcn_mfma_f32_16x16x32_bf16(Bt[n][k], At[m][k], acc[ai][bj][m][n], 0, 0, 0); __builtin_amdgcn_s_setprio(0); } while (0)
; #define PG8_WAIT_V(n) asm volatile("s_waitcnt vmcnt(" #n ")" ::: "memory")
; #define PG8_WAIT_L(n) asm volatile("s_waitcnt lgkmcnt(" #n ")" ::: "memory")
; #define PG8_BAR __builtin_amdgcn_s_barrier()
; #define PG8_SCHED __builtin_amdgcn_sched_barrier(0)
; template <class Epi>
; __device__ __forceinline__ void gemm_phase(LAS unsigned char* lds, const Gemm g, int G, int c, const Epi& E) {
;     ...
;             PG8_WAIT_V(8); PG8_WAIT_L(0); PG8_BAR; PG8_MMA(1, 0, At, B0); PG8_MMA(1, 1, At, B1); PG8_BAR; PG8_SCHED;
;             PG8_LDB(B0, 1, 0); PG8_LDB(B1, 1, 1); PG8_SCHED; PG8_LDA(At, 1, 0); PG8_STAGE(PG8_SA(0, 1), a2 + hstepA, voffA);
;             PG8_WAIT_V(8); PG8_WAIT_L(0); PG8_BAR; PG8_MMA(0, 0, At, B0); PG8_MMA(0, 1, At, B1); PG8_BAR; PG8_SCHED;
	s_setprio 0
	s_waitcnt lgkmcnt(0)
	v_mfma_f32_16x16x32_bf16 v[62:65], v[146:149], v[184:187], 0
	v_mfma_f32_16x16x32_bf16 v[58:61], v[160:163], v[184:187], 0
	v_mfma_f32_16x16x32_bf16 v[54:57], v[146:149], v[192:195], 0
	v_mfma_f32_16x16x32_bf16 v[46:49], v[160:163], v[192:195], 0
	v_mfma_f32_16x16x32_bf16 v[38:41], v[146:149], v[200:203], 0
	v_mfma_f32_16x16x32_bf16 v[30:33], v[160:163], v[200:203], 0
	v_mfma_f32_16x16x32_bf16 v[22:25], v[146:149], v[208:211], 0
	v_mfma_f32_16x16x32_bf16 v[14:17], v[160:163], v[208:211], 0
	v_mfma_f32_16x16x32_bf16 v[62:65], v[156:159], v[188:191], v[62:65]
	v_mfma_f32_16x16x32_bf16 v[58:61], v[164:167], v[188:191], v[58:61]
	v_mfma_f32_16x16x32_bf16 v[54:57], v[156:159], v[196:199], v[54:57]
	v_mfma_f32_16x16x32_bf16 v[46:49], v[164:167], v[196:199], v[46:49]
	v_mfma_f32_16x16x32_bf16 v[38:41], v[156:159], v[204:207], v[38:41]
	v_mfma_f32_16x16x32_bf16 v[30:33], v[164:167], v[204:207], v[30:33]
	v_mfma_f32_16x16x32_bf16 v[22:25], v[156:159], v[212:215], v[22:25]
	v_mfma_f32_16x16x32_bf16 v[14:17], v[164:167], v[212:215], v[14:17]
	s_setprio 2
	s_setprio 0
	v_mfma_f32_16x16x32_bf16 v[50:53], v[168:171], v[184:187], 0
	v_mfma_f32_16x16x32_bf16 v[42:45], v[176:179], v[184:187], 0
	v_mfma_f32_16x16x32_bf16 v[34:37], v[168:171], v[192:195], 0
	v_mfma_f32_16x16x32_bf16 v[26:29], v[176:179], v[192:195], 0
	v_mfma_f32_16x16x32_bf16 v[18:21], v[168:171], v[200:203], 0
	v_mfma_f32_16x16x32_bf16 v[10:13], v[176:179], v[200:203], 0
	v_mfma_f32_16x16x32_bf16 v[6:9], v[168:171], v[208:211], 0
	v_mfma_f32_16x16x32_bf16 v[2:5], v[176:179], v[208:211], 0
	v_mfma_f32_16x16x32_bf16 v[50:53], v[172:175], v[188:191], v[50:53]
	v_mfma_f32_16x16x32_bf16 v[42:45], v[180:183], v[188:191], v[42:45]
	v_mfma_f32_16x16x32_bf16 v[34:37], v[172:175], v[196:199], v[34:37]
	v_mfma_f32_16x16x32_bf16 v[26:29], v[180:183], v[196:199], v[26:29]
	v_mfma_f32_16x16x32_bf16 v[18:21], v[172:175], v[204:207], v[18:21]
	v_mfma_f32_16x16x32_bf16 v[10:13], v[180:183], v[204:207], v[10:13]
	v_mfma_f32_16x16x32_bf16 v[6:9], v[172:175], v[212:215], v[6:9]
	v_mfma_f32_16x16x32_bf16 v[2:5], v[180:183], v[212:215], v[2:5]
	s_setprio 2
	s_barrier
	s_add_i32 s33, 0, 0x18000
	v_add_u32_e32 v155, s33, v151
	s_add_i32 s64, 0, 0x1c000
	ds_read_b128 v[146:149], v155
	ds_read_b128 v[156:159], v155 offset:1024
	ds_read_b128 v[160:163], v155 offset:2048
	ds_read_b128 v[164:167], v155 offset:3072
	v_add_u32_e32 v155, s64, v151
	ds_read_b128 v[168:171], v155
	ds_read_b128 v[172:175], v155 offset:1024
	ds_read_b128 v[176:179], v155 offset:2048
	ds_read_b128 v[180:183], v155 offset:3072
	s_add_u32 s44, s44, 0x100000
	s_addc_u32 s45, s45, 0
	s_mov_b32 m0, s39
	v_lshl_add_u64 v[226:227], s[44:45], 0, v[136:137]
	ds_read_b128 v[184:187], v154 offset:32768
	ds_read_b128 v[188:191], v154 offset:33792
	ds_read_b128 v[192:195], v154 offset:34816
	ds_read_b128 v[196:199], v154 offset:35840
	ds_read_b128 v[200:203], v154 offset:36864
	ds_read_b128 v[204:207], v154 offset:37888
	ds_read_b128 v[208:211], v154 offset:38912
	ds_read_b128 v[212:215], v154 offset:39936
	global_load_lds_dwordx4 v[226:227], off
	v_lshl_add_u64 v[226:227], s[44:45], 0, v[132:133]
	s_mov_b32 m0, s53
	s_nop 0
	global_load_lds_dwordx4 v[226:227], off
	s_waitcnt vmcnt(8)
	s_waitcnt lgkmcnt(0)
	s_barrier
	s_setprio 0
	s_waitcnt lgkmcnt(0)
	v_mfma_f32_16x16x32_bf16 v[126:129], v[146:149], v[184:187], v[126:129]
	v_mfma_f32_16x16x32_bf16 v[122:125], v[160:163], v[184:187], v[122:125]
	v_mfma_f32_16x16x32_bf16 v[118:121], v[146:149], v[192:195], v[118:121]
	v_mfma_f32_16x16x32_bf16 v[110:113], v[160:163], v[192:195], v[110:113]
	v_mfma_f32_16x16x32_bf16 v[102:105], v[146:149], v[200:203], v[102:105]
	v_mfma_f32_16x16x32_bf16 v[94:97], v[160:163], v[200:203], v[94:97]
	v_mfma_f32_16x16x32_bf16 v[86:89], v[146:149], v[208:211], v[86:89]
	v_mfma_f32_16x16x32_bf16 v[78:81], v[160:163], v[208:211], v[78:81]
	v_mfma_f32_16x16x32_bf16 v[126:129], v[156:159], v[188:191], v[126:129]
	v_mfma_f32_16x16x32_bf16 v[122:125], v[164:167], v[188:191], v[122:125]
	v_mfma_f32_16x16x32_bf16 v[118:121], v[156:159], v[196:199], v[118:121]
	v_mfma_f32_16x16x32_bf16 v[110:113], v[164:167], v[196:199], v[110:113]
	v_mfma_f32_16x16x32_bf16 v[102:105], v[156:159], v[204:207], v[102:105]
	v_mfma_f32_16x16x32_bf16 v[94:97], v[164:167], v[204:207], v[94:97]
	v_mfma_f32_16x16x32_bf16 v[86:89], v[156:159], v[212:215], v[86:89]
	v_mfma_f32_16x16x32_bf16 v[78:81], v[164:167], v[212:215], v[78:81]
	s_setprio 2
	s_setprio 0
	v_mfma_f32_16x16x32_bf16 v[114:117], v[168:171], v[184:187], v[114:117]
	v_mfma_f32_16x16x32_bf16 v[106:109], v[176:179], v[184:187], v[106:109]
	v_mfma_f32_16x16x32_bf16 v[98:101], v[168:171], v[192:195], v[98:101]
	v_mfma_f32_16x16x32_bf16 v[90:93], v[176:179], v[192:195], v[90:93]
	v_mfma_f32_16x16x32_bf16 v[82:85], v[168:171], v[200:203], v[82:85]
	v_mfma_f32_16x16x32_bf16 v[74:77], v[176:179], v[200:203], v[74:77]
	v_mfma_f32_16x16x32_bf16 v[70:73], v[168:171], v[208:211], v[70:73]
	v_mfma_f32_16x16x32_bf16 v[66:69], v[176:179], v[208:211], v[66:69]
	v_mfma_f32_16x16x32_bf16 v[114:117], v[172:175], v[188:191], v[114:117]
	v_mfma_f32_16x16x32_bf16 v[106:109], v[180:183], v[188:191], v[106:109]
	v_mfma_f32_16x16x32_bf16 v[98:101], v[172:175], v[196:199], v[98:101]
	v_mfma_f32_16x16x32_bf16 v[90:93], v[180:183], v[196:199], v[90:93]
	v_mfma_f32_16x16x32_bf16 v[82:85], v[172:175], v[204:207], v[82:85]
	v_mfma_f32_16x16x32_bf16 v[74:77], v[180:183], v[204:207], v[74:77]
	v_mfma_f32_16x16x32_bf16 v[70:73], v[172:175], v[212:215], v[70:73]
	v_mfma_f32_16x16x32_bf16 v[66:69], v[180:183], v[212:215], v[66:69]
	s_setprio 2
	s_barrier
; #define PG8_STAGE(bufoff, gbase, voff) do { _Pragma("unroll") for (int _i = 0; _i < 2; ++_i) \
;         __builtin_amdgcn_global_load_lds((const unsigned*)((const char*)(gbase) + (voff)[_i]), (LAS unsigned*)(lds + (bufoff) + ldsw + _i * 8192), 16, 0, 0); } while (0)
; #define PG8_LDA(dst, b, h) do { _Pragma("unroll") for (int m = 0; m < 4; ++m) _Pragma("unroll") for (int k = 0; k < 2; ++k) dst[m][k] = *(const LAS bf16x8*)(lds + PG8_SA(b, h) + aoff + m * 2048 + k * 1024); } while (0)
; #define PG8_MMA(ai, bj, At, Bt) do { __builtin_amdgcn_s_setprio(1); _Pragma("unroll") for (int m = 0; m < 4; ++m) _Pragma("unroll") for (int n = 0; n < 2; ++n) _Pragma("unroll") for (int k = 0; k < 2; ++k) \
;         acc[ai][bj][m][n] = __builtin_amdgcn_mfma_f32_16x16x32_bf16(Bt[n][k], At[m][k], acc[ai][bj][m][n], 0, 0, 0); __builtin_amdgcn_s_setprio(0); } while (0)
; #define PG8_WAIT_V(n) asm volatile("s_waitcnt vmcnt(" #n ")" ::: "memory")
; #define PG8_WAIT_L(n) asm volatile("s_waitcnt lgkmcnt(" #n ")" ::: "memory")
; #define PG8_BAR __builtin_amdgcn_s_barrier()
; #define PG8_SCHED __builtin_amdgcn_sched_barrier(0)
; template <class Epi>
; __device__ __forceinline__ void gemm_phase(LAS unsigned char* lds, const Gemm g, int G, int c, const Epi& E) {
;     ...
;             PG8_LDA(At, 1, 1); PG8_STAGE(PG8_SB(1, 0), b3, voffB); PG8_STAGE(PG8_SB(1, 1), b3 + hstepB, voffB); PG8_STAGE(PG8_SA(1, 0), a3, voffA);
;             PG8_WAIT_V(8); PG8_WAIT_L(0); PG8_BAR; PG8_MMA(1, 0, At, B0); PG8_MMA(1, 1, At, B1); PG8_BAR; PG8_SCHED;
;         }
	s_add_i32 s33, s33, s52
	v_lshl_add_u64 v[216:217], v[216:217], 0, s[6:7]
	s_mov_b32 m0, s33
	ds_read_b128 v[184:187], v154 offset:49152
	ds_read_b128 v[188:191], v154 offset:50176
	ds_read_b128 v[192:195], v154 offset:51200
	ds_read_b128 v[196:199], v154 offset:52224
	ds_read_b128 v[200:203], v154 offset:53248
	ds_read_b128 v[204:207], v154 offset:54272
	ds_read_b128 v[208:211], v154 offset:55296
	ds_read_b128 v[212:215], v154 offset:56320
	global_load_lds_dwordx4 v[216:217], off
	s_add_i32 m0, s33, 0x2000
	s_add_u32 s42, s42, 0x100080
	v_lshl_add_u64 v[216:217], v[218:219], 0, s[6:7]
	s_addc_u32 s43, s43, 0
	s_add_i32 s33, s64, s52
	global_load_lds_dwordx4 v[216:217], off
	v_lshl_add_u64 v[216:217], s[42:43], 0, v[134:135]
	s_mov_b32 m0, s33
	s_nop 0
	global_load_lds_dwordx4 v[216:217], off
	v_lshl_add_u64 v[216:217], s[42:43], 0, v[130:131]
	s_add_i32 m0, s33, 0x2000
	s_nop 0
	global_load_lds_dwordx4 v[216:217], off
	v_lshl_add_u64 v[216:217], v[220:221], 0, s[6:7]
	s_mov_b32 m0, s59
	s_nop 0
	global_load_lds_dwordx4 v[216:217], off
	v_lshl_add_u64 v[216:217], v[222:223], 0, s[6:7]
	s_mov_b32 m0, s60
	s_nop 0
	global_load_lds_dwordx4 v[216:217], off
	s_waitcnt vmcnt(8)
	s_waitcnt lgkmcnt(0)
	s_barrier
	s_setprio 0
	s_waitcnt lgkmcnt(0)
	v_mfma_f32_16x16x32_bf16 v[62:65], v[146:149], v[184:187], v[62:65]
	v_mfma_f32_16x16x32_bf16 v[58:61], v[160:163], v[184:187], v[58:61]
	v_mfma_f32_16x16x32_bf16 v[54:57], v[146:149], v[192:195], v[54:57]
	v_mfma_f32_16x16x32_bf16 v[46:49], v[160:163], v[192:195], v[46:49]
	v_mfma_f32_16x16x32_bf16 v[38:41], v[146:149], v[200:203], v[38:41]
	v_mfma_f32_16x16x32_bf16 v[30:33], v[160:163], v[200:203], v[30:33]
	v_mfma_f32_16x16x32_bf16 v[22:25], v[146:149], v[208:211], v[22:25]
	v_mfma_f32_16x16x32_bf16 v[14:17], v[160:163], v[208:211], v[14:17]
	v_mfma_f32_16x16x32_bf16 v[62:65], v[156:159], v[188:191], v[62:65]
	v_mfma_f32_16x16x32_bf16 v[58:61], v[164:167], v[188:191], v[58:61]
	v_mfma_f32_16x16x32_bf16 v[54:57], v[156:159], v[196:199], v[54:57]
	v_mfma_f32_16x16x32_bf16 v[46:49], v[164:167], v[196:199], v[46:49]
	v_mfma_f32_16x16x32_bf16 v[38:41], v[156:159], v[204:207], v[38:41]
	v_mfma_f32_16x16x32_bf16 v[30:33], v[164:167], v[204:207], v[30:33]
	v_mfma_f32_16x16x32_bf16 v[22:25], v[156:159], v[212:215], v[22:25]
	v_mfma_f32_16x16x32_bf16 v[14:17], v[164:167], v[212:215], v[14:17]
	s_setprio 2
	s_setprio 0
	v_mfma_f32_16x16x32_bf16 v[50:53], v[168:171], v[184:187], v[50:53]
	v_mfma_f32_16x16x32_bf16 v[42:45], v[176:179], v[184:187], v[42:45]
	v_mfma_f32_16x16x32_bf16 v[34:37], v[168:171], v[192:195], v[34:37]
	v_mfma_f32_16x16x32_bf16 v[26:29], v[176:179], v[192:195], v[26:29]
	v_mfma_f32_16x16x32_bf16 v[18:21], v[168:171], v[200:203], v[18:21]
	v_mfma_f32_16x16x32_bf16 v[10:13], v[176:179], v[200:203], v[10:13]
	v_mfma_f32_16x16x32_bf16 v[6:9], v[168:171], v[208:211], v[6:9]
	v_mfma_f32_16x16x32_bf16 v[2:5], v[176:179], v[208:211], v[2:5]
	v_mfma_f32_16x16x32_bf16 v[50:53], v[172:175], v[188:191], v[50:53]
	v_mfma_f32_16x16x32_bf16 v[42:45], v[180:183], v[188:191], v[42:45]
	v_mfma_f32_16x16x32_bf16 v[34:37], v[172:175], v[196:199], v[34:37]
	v_mfma_f32_16x16x32_bf16 v[26:29], v[180:183], v[196:199], v[26:29]
	v_mfma_f32_16x16x32_bf16 v[18:21], v[172:175], v[204:207], v[18:21]
	v_mfma_f32_16x16x32_bf16 v[10:13], v[180:183], v[204:207], v[10:13]
	v_mfma_f32_16x16x32_bf16 v[6:9], v[172:175], v[212:215], v[6:9]
	v_mfma_f32_16x16x32_bf16 v[2:5], v[180:183], v[212:215], v[2:5]
	s_setprio 2
	s_barrier
	s_add_i32 s68, s68, 2
	s_add_u32 s40, s40, 0x100
	s_addc_u32 s41, s41, 0
	s_add_u32 s66, s66, 0x100
	s_addc_u32 s67, s67, 0
	s_cmp_gt_u32 s68, 61
	s_cbranch_scc0 .LBB0_1825

; #define PG8_STAGE(bufoff, gbase, voff) do { _Pragma("unroll") for (int _i = 0; _i < 2; ++_i) \
;         __builtin_amdgcn_global_load_lds((const unsigned*)((const char*)(gbase) + (voff)[_i]), (LAS unsigned*)(lds + (bufoff) + ldsw + _i * 8192), 16, 0, 0); } while (0)
; #define PG8_LDA(dst, b, h) do { _Pragma("unroll") for (int m = 0; m < 4; ++m) _Pragma("unroll") for (int k = 0; k < 2; ++k) dst[m][k] = *(const LAS bf16x8*)(lds + PG8_SA(b, h) + aoff + m * 2048 + k * 1024); } while (0)
; #define PG8_LDB(dst, b, h) do { _Pragma("unroll") for (int n = 0; n < 2; ++n) _Pragma("unroll") for (int k = 0; k < 2; ++k) dst[n][k] = *(const LAS bf16x8*)(lds + PG8_SB(b, h) + boff + n * 2048 + k * 1024); } while (0)
; #define PG8_MMA(ai, bj, At, Bt) do { __builtin_amdgcn_s_setprio(1); _Pragma("unroll") for (int m = 0; m < 4; ++m) _Pragma("unroll") for (int n = 0; n < 2; ++n) _Pragma("unroll") for (int k = 0; k < 2; ++k) \
;         acc[ai][bj][m][n] = __builtin_amdgcn_mfma_f32_16x16x32_bf16(Bt[n][k], At[m][k], acc[ai][bj][m][n], 0, 0, 0); __builtin_amdgcn_s_setprio(0); } while (0)
; template <class Epi>
; __device__ __forceinline__ void gemm_phase(LAS unsigned char* lds, const Gemm g, int G, int c, const Epi& E) {
;     ...
;         const bool has_next = S.next(ui + 1, nxt);
;         const char* nA = has_next ? (const char*)(g.A + (size_t)nxt.pb * g.sA) + (size_t)nxt.pm * 2 * hstepA : cA;
;         const char* nB = has_next ? (const char*)(g.Bt + (size_t)nxt.pb * g.sB) + (size_t)nxt.pn * 2 * hstepB : cB;
; #pragma nounroll
;         for (int t = 0; t < nt; t += 2) {
;             const bool last = (t == nt - 2);
;             const char* a1 = cA + (size_t)(t + 1) * kstep;
;             const char* a2 = last ? nA : cA + (size_t)(t + 2) * kstep; const char* b2 = last ? nB : cB + (size_t)(t + 2) * kstep;
;             const char* a3 = a2 + kstep; const char* b3 = b2 + kstep;
;             PG8_LDB(B0, 0, 0); PG8_LDB(B1, 0, 1); PG8_SCHED; PG8_LDA(At, 0, 0); PG8_STAGE(PG8_SA(1, 1), a1 + hstepA, voffA);
;             PG8_WAIT_V(8); PG8_WAIT_L(0); PG8_BAR; PG8_MMA(0, 0, At, B0); PG8_MMA(0, 1, At, B1); PG8_BAR; PG8_SCHED;
;             PG8_LDA(At, 0, 1); PG8_STAGE(PG8_SB(0, 0), b2, voffB); PG8_STAGE(PG8_SB(0, 1), b2 + hstepB, voffB); PG8_STAGE(PG8_SA(0, 0), a2, voffA);
;             PG8_WAIT_V(8); PG8_WAIT_L(0); PG8_BAR; PG8_MMA(1, 0, At, B0); PG8_MMA(1, 1, At, B1); PG8_BAR; PG8_SCHED;
.LBB0_1930:
	s_ashr_i32 s15, s14, 31
	s_lshl_b64 s[20:21], s[14:15], 19
	s_add_u32 s20, s40, s20
	s_addc_u32 s21, s41, s21
	s_and_b64 s[4:5], s[4:5], exec
	s_cselect_b32 s15, s21, s37
	s_cselect_b32 s17, s20, s36
	s_add_u32 s4, s38, 0x40080
	s_addc_u32 s5, s39, 0
	s_add_u32 s60, s36, 0x100
	s_addc_u32 s61, s37, 0
	s_mov_b32 s62, -2
	s_waitcnt vmcnt(0)
	ds_read_b128 v[122:125], v168
	ds_read_b128 v[126:129], v168 offset:1024
	ds_read_b128 v[130:133], v168 offset:2048
	ds_read_b128 v[134:137], v168 offset:3072
	ds_read_b128 v[162:165], v169
	ds_read_b128 v[172:175], v169 offset:1024
	ds_read_b128 v[176:179], v169 offset:2048
	ds_read_b128 v[180:183], v169 offset:3072
	s_add_u32 s33, s4, 0xfffc0080
	s_addc_u32 s36, s5, -1
	s_cmp_eq_u32 s62, 12
	s_cselect_b32 s39, s19, s36
	s_cselect_b32 s38, s18, s33
	s_cselect_b32 s37, s15, s61
	s_cselect_b32 s36, s17, s60
	v_lshl_add_u64 v[216:217], s[4:5], 0, v[154:155]
	s_add_i32 m0, s23, 0xc000
	ds_read_b128 v[184:187], v170
	ds_read_b128 v[188:191], v170 offset:1024
	ds_read_b128 v[192:195], v170 offset:2048
	ds_read_b128 v[196:199], v170 offset:3072
	ds_read_b128 v[200:203], v170 offset:4096
	ds_read_b128 v[204:207], v170 offset:5120
	ds_read_b128 v[208:211], v170 offset:6144
	ds_read_b128 v[212:215], v170 offset:7168
	global_load_lds_dwordx4 v[216:217], off
	v_lshl_add_u64 v[216:217], s[4:5], 0, v[156:157]
	s_add_i32 m0, s23, 0xe000
	s_nop 0
	global_load_lds_dwordx4 v[216:217], off
	s_waitcnt vmcnt(8)
	s_waitcnt lgkmcnt(0)
	s_barrier
	s_setprio 0
	s_waitcnt lgkmcnt(0)
	v_mfma_f32_16x16x32_bf16 v[142:145], v[122:125], v[184:187], 0
	v_mfma_f32_16x16x32_bf16 v[138:141], v[130:133], v[184:187], 0
	v_mfma_f32_16x16x32_bf16 v[118:121], v[122:125], v[192:195], 0
	v_mfma_f32_16x16x32_bf16 v[106:109], v[130:133], v[192:195], 0
	v_mfma_f32_16x16x32_bf16 v[102:105], v[122:125], v[200:203], 0
	v_mfma_f32_16x16x32_bf16 v[90:93], v[130:133], v[200:203], 0
	v_mfma_f32_16x16x32_bf16 v[86:89], v[122:125], v[208:211], 0
	v_mfma_f32_16x16x32_bf16 v[74:77], v[130:133], v[208:211], 0
	v_mfma_f32_16x16x32_bf16 v[142:145], v[126:129], v[188:191], v[142:145]
	v_mfma_f32_16x16x32_bf16 v[138:141], v[134:137], v[188:191], v[138:141]
	v_mfma_f32_16x16x32_bf16 v[118:121], v[126:129], v[196:199], v[118:121]
	v_mfma_f32_16x16x32_bf16 v[106:109], v[134:137], v[196:199], v[106:109]
	v_mfma_f32_16x16x32_bf16 v[102:105], v[126:129], v[204:207], v[102:105]
	v_mfma_f32_16x16x32_bf16 v[90:93], v[134:137], v[204:207], v[90:93]
	v_mfma_f32_16x16x32_bf16 v[86:89], v[126:129], v[212:215], v[86:89]
	v_mfma_f32_16x16x32_bf16 v[74:77], v[134:137], v[212:215], v[74:77]
	s_setprio 2
	s_setprio 0
	v_mfma_f32_16x16x32_bf16 v[114:117], v[162:165], v[184:187], 0
	v_mfma_f32_16x16x32_bf16 v[110:113], v[176:179], v[184:187], 0
	v_mfma_f32_16x16x32_bf16 v[98:101], v[162:165], v[192:195], 0
	v_mfma_f32_16x16x32_bf16 v[94:97], v[176:179], v[192:195], 0
	v_mfma_f32_16x16x32_bf16 v[82:85], v[162:165], v[200:203], 0
	v_mfma_f32_16x16x32_bf16 v[78:81], v[176:179], v[200:203], 0
	v_mfma_f32_16x16x32_bf16 v[70:73], v[162:165], v[208:211], 0
	v_mfma_f32_16x16x32_bf16 v[66:69], v[176:179], v[208:211], 0
	v_mfma_f32_16x16x32_bf16 v[114:117], v[172:175], v[188:191], v[114:117]
	v_mfma_f32_16x16x32_bf16 v[110:113], v[180:183], v[188:191], v[110:113]
	v_mfma_f32_16x16x32_bf16 v[98:101], v[172:175], v[196:199], v[98:101]
	v_mfma_f32_16x16x32_bf16 v[94:97], v[180:183], v[196:199], v[94:97]
	v_mfma_f32_16x16x32_bf16 v[82:85], v[172:175], v[204:207], v[82:85]
	v_mfma_f32_16x16x32_bf16 v[78:81], v[180:183], v[204:207], v[78:81]
	v_mfma_f32_16x16x32_bf16 v[70:73], v[172:175], v[212:215], v[70:73]
	v_mfma_f32_16x16x32_bf16 v[66:69], v[180:183], v[212:215], v[66:69]
	s_setprio 2
	s_barrier
	s_add_i32 s33, s56, s42
	v_lshl_add_u64 v[216:217], s[36:37], 0, v[150:151]
	s_mov_b32 m0, s33
	ds_read_b128 v[184:187], v170 offset:16384
	ds_read_b128 v[188:191], v170 offset:17408
	ds_read_b128 v[192:195], v170 offset:18432
	ds_read_b128 v[196:199], v170 offset:19456
	ds_read_b128 v[200:203], v170 offset:20480
	ds_read_b128 v[204:207], v170 offset:21504
	ds_read_b128 v[208:211], v170 offset:22528
	ds_read_b128 v[212:215], v170 offset:23552
	global_load_lds_dwordx4 v[216:217], off
	s_add_i32 m0, s33, 0x2000
	s_add_u32 s64, s36, 0x40000
	v_lshl_add_u64 v[218:219], s[36:37], 0, v[146:147]
	s_addc_u32 s65, s37, 0
	s_add_i32 s33, s57, s42
	global_load_lds_dwordx4 v[218:219], off
	v_lshl_add_u64 v[220:221], s[64:65], 0, v[150:151]
	s_mov_b32 m0, s33
	v_lshl_add_u64 v[222:223], s[38:39], 0, v[148:149]
	global_load_lds_dwordx4 v[220:221], off
	v_lshl_add_u64 v[220:221], s[64:65], 0, v[146:147]
	s_add_i32 m0, s33, 0x2000
	s_nop 0
	global_load_lds_dwordx4 v[220:221], off
	v_lshl_add_u64 v[220:221], s[38:39], 0, v[152:153]
	s_mov_b32 m0, s23
	s_nop 0
	global_load_lds_dwordx4 v[220:221], off
	s_mov_b32 m0, s25
	s_nop 0
	global_load_lds_dwordx4 v[222:223], off
	s_waitcnt vmcnt(8)
	s_waitcnt lgkmcnt(0)
	s_barrier
; #define PG8_STAGE(bufoff, gbase, voff) do { _Pragma("unroll") for (int _i = 0; _i < 2; ++_i) \
;         __builtin_amdgcn_global_load_lds((const unsigned*)((const char*)(gbase) + (voff)[_i]), (LAS unsigned*)(lds + (bufoff) + ldsw + _i * 8192), 16, 0, 0); } while (0)
; #define PG8_LDA(dst, b, h) do { _Pragma("unroll") for (int m = 0; m < 4; ++m) _Pragma("unroll") for (int k = 0; k < 2; ++k) dst[m][k] = *(const LAS bf16x8*)(lds + PG8_SA(b, h) + aoff + m * 2048 + k * 1024); } while (0)
; #define PG8_LDB(dst, b, h) do { _Pragma("unroll") for (int n = 0; n < 2; ++n) _Pragma("unroll") for (int k = 0; k < 2; ++k) dst[n][k] = *(const LAS bf16x8*)(lds + PG8_SB(b, h) + boff + n * 2048 + k * 1024); } while (0)
; #define PG8_MMA(ai, bj, At, Bt) do { __builtin_amdgcn_s_setprio(1); _Pragma("unroll") for (int m = 0; m < 4; ++m) _Pragma("unroll") for (int n = 0; n < 2; ++n) _Pragma("unroll") for (int k = 0; k < 2; ++k) \
;         acc[ai][bj][m][n] = __builtin_amdgcn_mfma_f32_16x16x32_bf16(Bt[n][k], At[m][k], acc[ai][bj][m][n], 0, 0, 0); __builtin_amdgcn_s_setprio(0); } while (0)
; #define PG8_WAIT_V(n) asm volatile("s_waitcnt vmcnt(" #n ")" ::: "memory")
; #define PG8_WAIT_L(n) asm volatile("s_waitcnt lgkmcnt(" #n ")" ::: "memory")
; #define PG8_BAR __builtin_amdgcn_s_barrier()
; #define PG8_SCHED __builtin_amdgcn_sched_barrier(0)
; template <class Epi>
; __device__ __forceinline__ void gemm_phase(LAS unsigned char* lds, const Gemm g, int G, int c, const Epi& E) {
;     ...
;             PG8_WAIT_V(8); PG8_WAIT_L(0); PG8_BAR; PG8_MMA(1, 0, At, B0); PG8_MMA(1, 1, At, B1); PG8_BAR; PG8_SCHED;
;             PG8_LDB(B0, 1, 0); PG8_LDB(B1, 1, 1); PG8_SCHED; PG8_LDA(At, 1, 0); PG8_STAGE(PG8_SA(0, 1), a2 + hstepA, voffA);
;             PG8_WAIT_V(8); PG8_WAIT_L(0); PG8_BAR; PG8_MMA(0, 0, At, B0); PG8_MMA(0, 1, At, B1); PG8_BAR; PG8_SCHED;
	s_setprio 0
	s_waitcnt lgkmcnt(0)
	v_mfma_f32_16x16x32_bf16 v[62:65], v[122:125], v[184:187], 0
	v_mfma_f32_16x16x32_bf16 v[58:61], v[130:133], v[184:187], 0
	v_mfma_f32_16x16x32_bf16 v[54:57], v[122:125], v[192:195], 0
	v_mfma_f32_16x16x32_bf16 v[42:45], v[130:133], v[192:195], 0
	v_mfma_f32_16x16x32_bf16 v[38:41], v[122:125], v[200:203], 0
	v_mfma_f32_16x16x32_bf16 v[26:29], v[130:133], v[200:203], 0
	v_mfma_f32_16x16x32_bf16 v[22:25], v[122:125], v[208:211], 0
	v_mfma_f32_16x16x32_bf16 v[10:13], v[130:133], v[208:211], 0
	v_mfma_f32_16x16x32_bf16 v[62:65], v[126:129], v[188:191], v[62:65]
	v_mfma_f32_16x16x32_bf16 v[58:61], v[134:137], v[188:191], v[58:61]
	v_mfma_f32_16x16x32_bf16 v[54:57], v[126:129], v[196:199], v[54:57]
	v_mfma_f32_16x16x32_bf16 v[42:45], v[134:137], v[196:199], v[42:45]
	v_mfma_f32_16x16x32_bf16 v[38:41], v[126:129], v[204:207], v[38:41]
	v_mfma_f32_16x16x32_bf16 v[26:29], v[134:137], v[204:207], v[26:29]
	v_mfma_f32_16x16x32_bf16 v[22:25], v[126:129], v[212:215], v[22:25]
	v_mfma_f32_16x16x32_bf16 v[10:13], v[134:137], v[212:215], v[10:13]
	s_setprio 2
	s_setprio 0
	v_mfma_f32_16x16x32_bf16 v[50:53], v[162:165], v[184:187], 0
	v_mfma_f32_16x16x32_bf16 v[46:49], v[176:179], v[184:187], 0
	v_mfma_f32_16x16x32_bf16 v[34:37], v[162:165], v[192:195], 0
	v_mfma_f32_16x16x32_bf16 v[30:33], v[176:179], v[192:195], 0
	v_mfma_f32_16x16x32_bf16 v[18:21], v[162:165], v[200:203], 0
	v_mfma_f32_16x16x32_bf16 v[14:17], v[176:179], v[200:203], 0
	v_mfma_f32_16x16x32_bf16 v[6:9], v[162:165], v[208:211], 0
	v_mfma_f32_16x16x32_bf16 v[2:5], v[176:179], v[208:211], 0
	v_mfma_f32_16x16x32_bf16 v[50:53], v[172:175], v[188:191], v[50:53]
	v_mfma_f32_16x16x32_bf16 v[46:49], v[180:183], v[188:191], v[46:49]
	v_mfma_f32_16x16x32_bf16 v[34:37], v[172:175], v[196:199], v[34:37]
	v_mfma_f32_16x16x32_bf16 v[30:33], v[180:183], v[196:199], v[30:33]
	v_mfma_f32_16x16x32_bf16 v[18:21], v[172:175], v[204:207], v[18:21]
	v_mfma_f32_16x16x32_bf16 v[14:17], v[180:183], v[204:207], v[14:17]
	v_mfma_f32_16x16x32_bf16 v[6:9], v[172:175], v[212:215], v[6:9]
	v_mfma_f32_16x16x32_bf16 v[2:5], v[180:183], v[212:215], v[2:5]
	s_setprio 2
	s_barrier
	s_add_i32 s33, 0, 0x18000
	s_add_i32 s63, 0, 0x1c000
	v_add_u32_e32 v134, s33, v167
	v_add_u32_e32 v171, s63, v167
	ds_read_b128 v[122:125], v134
	ds_read_b128 v[126:129], v134 offset:1024
	ds_read_b128 v[130:133], v134 offset:2048
	ds_read_b128 v[134:137], v134 offset:3072
	ds_read_b128 v[162:165], v171
	ds_read_b128 v[172:175], v171 offset:1024
	ds_read_b128 v[176:179], v171 offset:2048
	ds_read_b128 v[180:183], v171 offset:3072
	s_add_u32 s38, s38, 0x40000
	s_addc_u32 s39, s39, 0
	s_mov_b32 m0, s44
	v_lshl_add_u64 v[224:225], s[38:39], 0, v[152:153]
	ds_read_b128 v[184:187], v170 offset:32768
	ds_read_b128 v[188:191], v170 offset:33792
	ds_read_b128 v[192:195], v170 offset:34816
	ds_read_b128 v[196:199], v170 offset:35840
	ds_read_b128 v[200:203], v170 offset:36864
	ds_read_b128 v[204:207], v170 offset:37888
	ds_read_b128 v[208:211], v170 offset:38912
	ds_read_b128 v[212:215], v170 offset:39936
	global_load_lds_dwordx4 v[224:225], off
	v_lshl_add_u64 v[224:225], s[38:39], 0, v[148:149]
	s_mov_b32 m0, s45
	s_nop 0
	global_load_lds_dwordx4 v[224:225], off
	s_waitcnt vmcnt(8)
	s_waitcnt lgkmcnt(0)
	s_barrier
	s_setprio 0
	s_waitcnt lgkmcnt(0)
	v_mfma_f32_16x16x32_bf16 v[142:145], v[122:125], v[184:187], v[142:145]
	v_mfma_f32_16x16x32_bf16 v[138:141], v[130:133], v[184:187], v[138:141]
	v_mfma_f32_16x16x32_bf16 v[118:121], v[122:125], v[192:195], v[118:121]
	v_mfma_f32_16x16x32_bf16 v[106:109], v[130:133], v[192:195], v[106:109]
	v_mfma_f32_16x16x32_bf16 v[102:105], v[122:125], v[200:203], v[102:105]
	v_mfma_f32_16x16x32_bf16 v[90:93], v[130:133], v[200:203], v[90:93]
	v_mfma_f32_16x16x32_bf16 v[86:89], v[122:125], v[208:211], v[86:89]
	v_mfma_f32_16x16x32_bf16 v[74:77], v[130:133], v[208:211], v[74:77]
	v_mfma_f32_16x16x32_bf16 v[142:145], v[126:129], v[188:191], v[142:145]
	v_mfma_f32_16x16x32_bf16 v[138:141], v[134:137], v[188:191], v[138:141]
	v_mfma_f32_16x16x32_bf16 v[118:121], v[126:129], v[196:199], v[118:121]
	v_mfma_f32_16x16x32_bf16 v[106:109], v[134:137], v[196:199], v[106:109]
	v_mfma_f32_16x16x32_bf16 v[102:105], v[126:129], v[204:207], v[102:105]
	v_mfma_f32_16x16x32_bf16 v[90:93], v[134:137], v[204:207], v[90:93]
	v_mfma_f32_16x16x32_bf16 v[86:89], v[126:129], v[212:215], v[86:89]
	v_mfma_f32_16x16x32_bf16 v[74:77], v[134:137], v[212:215], v[74:77]
	s_setprio 2
	s_setprio 0
	v_mfma_f32_16x16x32_bf16 v[114:117], v[162:165], v[184:187], v[114:117]
	v_mfma_f32_16x16x32_bf16 v[110:113], v[176:179], v[184:187], v[110:113]
	v_mfma_f32_16x16x32_bf16 v[98:101], v[162:165], v[192:195], v[98:101]
	v_mfma_f32_16x16x32_bf16 v[94:97], v[176:179], v[192:195], v[94:97]
	v_mfma_f32_16x16x32_bf16 v[82:85], v[162:165], v[200:203], v[82:85]
	v_mfma_f32_16x16x32_bf16 v[78:81], v[176:179], v[200:203], v[78:81]
	v_mfma_f32_16x16x32_bf16 v[70:73], v[162:165], v[208:211], v[70:73]
	v_mfma_f32_16x16x32_bf16 v[66:69], v[176:179], v[208:211], v[66:69]
	v_mfma_f32_16x16x32_bf16 v[114:117], v[172:175], v[188:191], v[114:117]
	v_mfma_f32_16x16x32_bf16 v[110:113], v[180:183], v[188:191], v[110:113]
	v_mfma_f32_16x16x32_bf16 v[98:101], v[172:175], v[196:199], v[98:101]
	v_mfma_f32_16x16x32_bf16 v[94:97], v[180:183], v[196:199], v[94:97]
	v_mfma_f32_16x16x32_bf16 v[82:85], v[172:175], v[204:207], v[82:85]
	v_mfma_f32_16x16x32_bf16 v[78:81], v[180:183], v[204:207], v[78:81]
	v_mfma_f32_16x16x32_bf16 v[70:73], v[172:175], v[212:215], v[70:73]
	v_mfma_f32_16x16x32_bf16 v[66:69], v[180:183], v[212:215], v[66:69]
	s_setprio 2
	s_barrier
; #define PG8_STAGE(bufoff, gbase, voff) do { _Pragma("unroll") for (int _i = 0; _i < 2; ++_i) \
;         __builtin_amdgcn_global_load_lds((const unsigned*)((const char*)(gbase) + (voff)[_i]), (LAS unsigned*)(lds + (bufoff) + ldsw + _i * 8192), 16, 0, 0); } while (0)
; #define PG8_LDA(dst, b, h) do { _Pragma("unroll") for (int m = 0; m < 4; ++m) _Pragma("unroll") for (int k = 0; k < 2; ++k) dst[m][k] = *(const LAS bf16x8*)(lds + PG8_SA(b, h) + aoff + m * 2048 + k * 1024); } while (0)
; #define PG8_MMA(ai, bj, At, Bt) do { __builtin_amdgcn_s_setprio(1); _Pragma("unroll") for (int m = 0; m < 4; ++m) _Pragma("unroll") for (int n = 0; n < 2; ++n) _Pragma("unroll") for (int k = 0; k < 2; ++k) \
;         acc[ai][bj][m][n] = __builtin_amdgcn_mfma_f32_16x16x32_bf16(Bt[n][k], At[m][k], acc[ai][bj][m][n], 0, 0, 0); __builtin_amdgcn_s_setprio(0); } while (0)
; #define PG8_WAIT_V(n) asm volatile("s_waitcnt vmcnt(" #n ")" ::: "memory")
; #define PG8_WAIT_L(n) asm volatile("s_waitcnt lgkmcnt(" #n ")" ::: "memory")
; #define PG8_BAR __builtin_amdgcn_s_barrier()
; #define PG8_SCHED __builtin_amdgcn_sched_barrier(0)
; template <class Epi>
; __device__ __forceinline__ void gemm_phase(LAS unsigned char* lds, const Gemm g, int G, int c, const Epi& E) {
;     ...
;         for (int t = 0; t < nt; t += 2) {
;     ...
;             PG8_LDA(At, 1, 1); PG8_STAGE(PG8_SB(1, 0), b3, voffB); PG8_STAGE(PG8_SB(1, 1), b3 + hstepB, voffB); PG8_STAGE(PG8_SA(1, 0), a3, voffA);
;             PG8_WAIT_V(8); PG8_WAIT_L(0); PG8_BAR; PG8_MMA(1, 0, At, B0); PG8_MMA(1, 1, At, B1); PG8_BAR; PG8_SCHED;
	s_add_i32 s33, s33, s42
	v_lshl_add_u64 v[216:217], v[216:217], 0, s[10:11]
	s_mov_b32 m0, s33
	ds_read_b128 v[184:187], v170 offset:49152
	ds_read_b128 v[188:191], v170 offset:50176
	ds_read_b128 v[192:195], v170 offset:51200
	ds_read_b128 v[196:199], v170 offset:52224
	ds_read_b128 v[200:203], v170 offset:53248
	ds_read_b128 v[204:207], v170 offset:54272
	ds_read_b128 v[208:211], v170 offset:55296
	ds_read_b128 v[212:215], v170 offset:56320
	global_load_lds_dwordx4 v[216:217], off
	s_add_i32 m0, s33, 0x2000
	s_add_u32 s36, s36, 0x40080
	v_lshl_add_u64 v[216:217], v[218:219], 0, s[10:11]
	s_addc_u32 s37, s37, 0
	s_add_i32 s33, s63, s42
	global_load_lds_dwordx4 v[216:217], off
	v_lshl_add_u64 v[216:217], s[36:37], 0, v[150:151]
	s_mov_b32 m0, s33
	s_nop 0
	global_load_lds_dwordx4 v[216:217], off
	v_lshl_add_u64 v[216:217], s[36:37], 0, v[146:147]
	s_add_i32 m0, s33, 0x2000
	s_nop 0
	global_load_lds_dwordx4 v[216:217], off
	v_lshl_add_u64 v[216:217], v[220:221], 0, s[10:11]
	s_mov_b32 m0, s53
	s_nop 0
	global_load_lds_dwordx4 v[216:217], off
	v_lshl_add_u64 v[216:217], v[222:223], 0, s[10:11]
	s_mov_b32 m0, s54
	s_nop 0
	global_load_lds_dwordx4 v[216:217], off
	s_waitcnt vmcnt(8)
	s_waitcnt lgkmcnt(0)
	s_barrier
	s_setprio 0
	s_waitcnt lgkmcnt(0)
	v_mfma_f32_16x16x32_bf16 v[62:65], v[122:125], v[184:187], v[62:65]
	v_mfma_f32_16x16x32_bf16 v[58:61], v[130:133], v[184:187], v[58:61]
	v_mfma_f32_16x16x32_bf16 v[54:57], v[122:125], v[192:195], v[54:57]
	v_mfma_f32_16x16x32_bf16 v[42:45], v[130:133], v[192:195], v[42:45]
	v_mfma_f32_16x16x32_bf16 v[38:41], v[122:125], v[200:203], v[38:41]
	v_mfma_f32_16x16x32_bf16 v[26:29], v[130:133], v[200:203], v[26:29]
	v_mfma_f32_16x16x32_bf16 v[22:25], v[122:125], v[208:211], v[22:25]
	v_mfma_f32_16x16x32_bf16 v[10:13], v[130:133], v[208:211], v[10:13]
	v_mfma_f32_16x16x32_bf16 v[62:65], v[126:129], v[188:191], v[62:65]
	v_mfma_f32_16x16x32_bf16 v[58:61], v[134:137], v[188:191], v[58:61]
	v_mfma_f32_16x16x32_bf16 v[54:57], v[126:129], v[196:199], v[54:57]
	v_mfma_f32_16x16x32_bf16 v[42:45], v[134:137], v[196:199], v[42:45]
	v_mfma_f32_16x16x32_bf16 v[38:41], v[126:129], v[204:207], v[38:41]
	v_mfma_f32_16x16x32_bf16 v[26:29], v[134:137], v[204:207], v[26:29]
	v_mfma_f32_16x16x32_bf16 v[22:25], v[126:129], v[212:215], v[22:25]
	v_mfma_f32_16x16x32_bf16 v[10:13], v[134:137], v[212:215], v[10:13]
	s_setprio 2
	s_setprio 0
	v_mfma_f32_16x16x32_bf16 v[50:53], v[162:165], v[184:187], v[50:53]
	v_mfma_f32_16x16x32_bf16 v[46:49], v[176:179], v[184:187], v[46:49]
	v_mfma_f32_16x16x32_bf16 v[34:37], v[162:165], v[192:195], v[34:37]
	v_mfma_f32_16x16x32_bf16 v[30:33], v[176:179], v[192:195], v[30:33]
	v_mfma_f32_16x16x32_bf16 v[18:21], v[162:165], v[200:203], v[18:21]
	v_mfma_f32_16x16x32_bf16 v[14:17], v[176:179], v[200:203], v[14:17]
	v_mfma_f32_16x16x32_bf16 v[6:9], v[162:165], v[208:211], v[6:9]
	v_mfma_f32_16x16x32_bf16 v[2:5], v[176:179], v[208:211], v[2:5]
	v_mfma_f32_16x16x32_bf16 v[50:53], v[172:175], v[188:191], v[50:53]
	v_mfma_f32_16x16x32_bf16 v[46:49], v[180:183], v[188:191], v[46:49]
	v_mfma_f32_16x16x32_bf16 v[34:37], v[172:175], v[196:199], v[34:37]
	v_mfma_f32_16x16x32_bf16 v[30:33], v[180:183], v[196:199], v[30:33]
	v_mfma_f32_16x16x32_bf16 v[18:21], v[172:175], v[204:207], v[18:21]
	v_mfma_f32_16x16x32_bf16 v[14:17], v[180:183], v[204:207], v[14:17]
	v_mfma_f32_16x16x32_bf16 v[6:9], v[172:175], v[212:215], v[6:9]
	v_mfma_f32_16x16x32_bf16 v[2:5], v[180:183], v[212:215], v[2:5]
	s_setprio 2
	s_barrier
	s_add_i32 s62, s62, 2
	s_add_u32 s4, s4, 0x100
	s_addc_u32 s5, s5, 0
	s_add_u32 s60, s60, 0x100
	s_addc_u32 s61, s61, 0
	s_cmp_gt_u32 s62, 13
	s_cbranch_scc0 .LBB0_1931

; #define PG8_STAGE(bufoff, gbase, voff) do { _Pragma("unroll") for (int _i = 0; _i < 2; ++_i) \
;         __builtin_amdgcn_global_load_lds((const unsigned*)((const char*)(gbase) + (voff)[_i]), (LAS unsigned*)(lds + (bufoff) + ldsw + _i * 8192), 16, 0, 0); } while (0)
; #define PG8_LDA(dst, b, h) do { _Pragma("unroll") for (int m = 0; m < 4; ++m) _Pragma("unroll") for (int k = 0; k < 2; ++k) dst[m][k] = *(const LAS bf16x8*)(lds + PG8_SA(b, h) + aoff + m * 2048 + k * 1024); } while (0)
; #define PG8_LDB(dst, b, h) do { _Pragma("unroll") for (int n = 0; n < 2; ++n) _Pragma("unroll") for (int k = 0; k < 2; ++k) dst[n][k] = *(const LAS bf16x8*)(lds + PG8_SB(b, h) + boff + n * 2048 + k * 1024); } while (0)
; #define PG8_WAIT_V(n) asm volatile("s_waitcnt vmcnt(" #n ")" ::: "memory")
; #define PG8_WAIT_L(n) asm volatile("s_waitcnt lgkmcnt(" #n ")" ::: "memory")
; #define PG8_BAR __builtin_amdgcn_s_barrier()
; #define PG8_SCHED __builtin_amdgcn_sched_barrier(0)
; template <class Epi>
; __device__ __forceinline__ void gemm_phase(LAS unsigned char* lds, const Gemm g, int G, int c, const Epi& E) {
;     ...
;         const char* nA = has_next ? (const char*)(g.A + (size_t)nxt.pb * g.sA) + (size_t)nxt.pm * 2 * hstepA : cA;
;         const char* nB = has_next ? (const char*)(g.Bt + (size_t)nxt.pb * g.sB) + (size_t)nxt.pn * 2 * hstepB : cB;
; #pragma nounroll
;         for (int t = 0; t < nt; t += 2) {
;             const bool last = (t == nt - 2);
;             const char* a1 = cA + (size_t)(t + 1) * kstep;
;             const char* a2 = last ? nA : cA + (size_t)(t + 2) * kstep; const char* b2 = last ? nB : cB + (size_t)(t + 2) * kstep;
;             const char* a3 = a2 + kstep; const char* b3 = b2 + kstep;
;             PG8_LDB(B0, 0, 0); PG8_LDB(B1, 0, 1); PG8_SCHED; PG8_LDA(At, 0, 0); PG8_STAGE(PG8_SA(1, 1), a1 + hstepA, voffA);
;             PG8_WAIT_V(8); PG8_WAIT_L(0); PG8_BAR; PG8_MMA(0, 0, At, B0); PG8_MMA(0, 1, At, B1); PG8_BAR; PG8_SCHED;
;             PG8_LDA(At, 0, 1); PG8_STAGE(PG8_SB(0, 0), b2, voffB); PG8_STAGE(PG8_SB(0, 1), b2 + hstepB, voffB); PG8_STAGE(PG8_SA(0, 0), a2, voffA);
;             PG8_WAIT_V(8); PG8_WAIT_L(0); PG8_BAR; PG8_MMA(1, 0, At, B0); PG8_MMA(1, 1, At, B1); PG8_BAR; PG8_SCHED;
;     ...
;                     for (int n = 0; n < 2; ++n) acc[a][b][m][n] = (f32x4){0.f, 0.f, 0.f, 0.f};
.LBB0_2083:
	s_ashr_i32 s17, s16, 31
	s_lshl_b64 s[22:23], s[16:17], 19
	s_add_u32 s22, s43, s22
	s_addc_u32 s23, s44, s23
	s_and_b64 s[4:5], s[4:5], exec
	s_cselect_b32 s17, s23, s39
	s_cselect_b32 s19, s22, s38
	s_add_u32 s4, s40, 0x40080
	s_addc_u32 s5, s41, 0
	s_add_u32 s66, s38, 0x100
	s_addc_u32 s67, s39, 0
	s_mov_b32 s68, -2
	ds_read_b128 v[152:155], v148
	ds_read_b128 v[156:159], v148 offset:1024
	ds_read_b128 v[160:163], v148 offset:2048
	ds_read_b128 v[164:167], v148 offset:3072
	ds_read_b128 v[168:171], v149
	ds_read_b128 v[172:175], v149 offset:1024
	ds_read_b128 v[176:179], v149 offset:2048
	ds_read_b128 v[180:183], v149 offset:3072
	s_add_u32 s33, s4, 0xfffc0080
	s_addc_u32 s38, s5, -1
	s_cmp_eq_u32 s68, 12
	s_cselect_b32 s41, s21, s38
	s_cselect_b32 s40, s20, s33
	s_cselect_b32 s39, s17, s67
	s_cselect_b32 s38, s19, s66
	v_lshl_add_u64 v[216:217], s[4:5], 0, v[138:139]
	s_add_i32 m0, s25, 0xc000
	ds_read_b128 v[184:187], v150
	ds_read_b128 v[188:191], v150 offset:1024
	ds_read_b128 v[192:195], v150 offset:2048
	ds_read_b128 v[196:199], v150 offset:3072
	ds_read_b128 v[200:203], v150 offset:4096
	ds_read_b128 v[204:207], v150 offset:5120
	ds_read_b128 v[208:211], v150 offset:6144
	ds_read_b128 v[212:215], v150 offset:7168
	global_load_lds_dwordx4 v[216:217], off
	v_lshl_add_u64 v[216:217], s[4:5], 0, v[140:141]
	s_add_i32 m0, s25, 0xe000
	s_nop 0
	global_load_lds_dwordx4 v[216:217], off
	s_waitcnt vmcnt(8)
	s_waitcnt lgkmcnt(0)
	s_barrier
	s_setprio 0
	s_waitcnt lgkmcnt(0)
	v_mfma_f32_16x16x32_bf16 v[126:129], v[152:155], v[184:187], 0
	v_mfma_f32_16x16x32_bf16 v[122:125], v[160:163], v[184:187], 0
	v_mfma_f32_16x16x32_bf16 v[110:113], v[152:155], v[192:195], 0
	v_mfma_f32_16x16x32_bf16 v[106:109], v[160:163], v[192:195], 0
	v_mfma_f32_16x16x32_bf16 v[94:97], v[152:155], v[200:203], 0
	v_mfma_f32_16x16x32_bf16 v[90:93], v[160:163], v[200:203], 0
	v_mfma_f32_16x16x32_bf16 v[78:81], v[152:155], v[208:211], 0
	v_mfma_f32_16x16x32_bf16 v[74:77], v[160:163], v[208:211], 0
	v_mfma_f32_16x16x32_bf16 v[126:129], v[156:159], v[188:191], v[126:129]
	v_mfma_f32_16x16x32_bf16 v[122:125], v[164:167], v[188:191], v[122:125]
	v_mfma_f32_16x16x32_bf16 v[110:113], v[156:159], v[196:199], v[110:113]
	v_mfma_f32_16x16x32_bf16 v[106:109], v[164:167], v[196:199], v[106:109]
	v_mfma_f32_16x16x32_bf16 v[94:97], v[156:159], v[204:207], v[94:97]
	v_mfma_f32_16x16x32_bf16 v[90:93], v[164:167], v[204:207], v[90:93]
	v_mfma_f32_16x16x32_bf16 v[78:81], v[156:159], v[212:215], v[78:81]
	v_mfma_f32_16x16x32_bf16 v[74:77], v[164:167], v[212:215], v[74:77]
	s_setprio 2
	s_setprio 0
	v_mfma_f32_16x16x32_bf16 v[118:121], v[168:171], v[184:187], 0
	v_mfma_f32_16x16x32_bf16 v[114:117], v[176:179], v[184:187], 0
	v_mfma_f32_16x16x32_bf16 v[102:105], v[168:171], v[192:195], 0
	v_mfma_f32_16x16x32_bf16 v[98:101], v[176:179], v[192:195], 0
	v_mfma_f32_16x16x32_bf16 v[86:89], v[168:171], v[200:203], 0
	v_mfma_f32_16x16x32_bf16 v[82:85], v[176:179], v[200:203], 0
	v_mfma_f32_16x16x32_bf16 v[70:73], v[168:171], v[208:211], 0
	v_mfma_f32_16x16x32_bf16 v[66:69], v[176:179], v[208:211], 0
	v_mfma_f32_16x16x32_bf16 v[118:121], v[172:175], v[188:191], v[118:121]
	v_mfma_f32_16x16x32_bf16 v[114:117], v[180:183], v[188:191], v[114:117]
	v_mfma_f32_16x16x32_bf16 v[102:105], v[172:175], v[196:199], v[102:105]
	v_mfma_f32_16x16x32_bf16 v[98:101], v[180:183], v[196:199], v[98:101]
	v_mfma_f32_16x16x32_bf16 v[86:89], v[172:175], v[204:207], v[86:89]
	v_mfma_f32_16x16x32_bf16 v[82:85], v[180:183], v[204:207], v[82:85]
	v_mfma_f32_16x16x32_bf16 v[70:73], v[172:175], v[212:215], v[70:73]
	v_mfma_f32_16x16x32_bf16 v[66:69], v[180:183], v[212:215], v[66:69]
	s_setprio 2
	s_barrier
	s_add_i32 s33, s56, s46
	v_lshl_add_u64 v[216:217], s[38:39], 0, v[134:135]
	s_mov_b32 m0, s33
	ds_read_b128 v[184:187], v150 offset:16384
	ds_read_b128 v[188:191], v150 offset:17408
	ds_read_b128 v[192:195], v150 offset:18432
	ds_read_b128 v[196:199], v150 offset:19456
	ds_read_b128 v[200:203], v150 offset:20480
	ds_read_b128 v[204:207], v150 offset:21504
	ds_read_b128 v[208:211], v150 offset:22528
	ds_read_b128 v[212:215], v150 offset:23552
	global_load_lds_dwordx4 v[216:217], off
	s_add_i32 m0, s33, 0x2000
	s_add_u32 s70, s38, 0x40000
	v_lshl_add_u64 v[218:219], s[38:39], 0, v[130:131]
	s_addc_u32 s71, s39, 0
	s_add_i32 s33, s57, s46
	global_load_lds_dwordx4 v[218:219], off
	v_lshl_add_u64 v[220:221], s[70:71], 0, v[134:135]
	s_mov_b32 m0, s33
	v_lshl_add_u64 v[222:223], s[40:41], 0, v[132:133]
	global_load_lds_dwordx4 v[220:221], off
	v_lshl_add_u64 v[220:221], s[70:71], 0, v[130:131]
	s_add_i32 m0, s33, 0x2000
	s_nop 0
	global_load_lds_dwordx4 v[220:221], off
	v_lshl_add_u64 v[220:221], s[40:41], 0, v[136:137]
	s_mov_b32 m0, s25
	s_nop 0
	global_load_lds_dwordx4 v[220:221], off
	s_mov_b32 m0, s37
	s_nop 0
	global_load_lds_dwordx4 v[222:223], off
	s_waitcnt vmcnt(8)
	s_waitcnt lgkmcnt(0)
	s_barrier
; #define PG8_STAGE(bufoff, gbase, voff) do { _Pragma("unroll") for (int _i = 0; _i < 2; ++_i) \
;         __builtin_amdgcn_global_load_lds((const unsigned*)((const char*)(gbase) + (voff)[_i]), (LAS unsigned*)(lds + (bufoff) + ldsw + _i * 8192), 16, 0, 0); } while (0)
; #define PG8_LDA(dst, b, h) do { _Pragma("unroll") for (int m = 0; m < 4; ++m) _Pragma("unroll") for (int k = 0; k < 2; ++k) dst[m][k] = *(const LAS bf16x8*)(lds + PG8_SA(b, h) + aoff + m * 2048 + k * 1024); } while (0)
; #define PG8_LDB(dst, b, h) do { _Pragma("unroll") for (int n = 0; n < 2; ++n) _Pragma("unroll") for (int k = 0; k < 2; ++k) dst[n][k] = *(const LAS bf16x8*)(lds + PG8_SB(b, h) + boff + n * 2048 + k * 1024); } while (0)
; #define PG8_MMA(ai, bj, At, Bt) do { __builtin_amdgcn_s_setprio(1); _Pragma("unroll") for (int m = 0; m < 4; ++m) _Pragma("unroll") for (int n = 0; n < 2; ++n) _Pragma("unroll") for (int k = 0; k < 2; ++k) \
;         acc[ai][bj][m][n] = __builtin_amdgcn_mfma_f32_16x16x32_bf16(Bt[n][k], At[m][k], acc[ai][bj][m][n], 0, 0, 0); __builtin_amdgcn_s_setprio(0); } while (0)
; #define PG8_WAIT_V(n) asm volatile("s_waitcnt vmcnt(" #n ")" ::: "memory")
; #define PG8_WAIT_L(n) asm volatile("s_waitcnt lgkmcnt(" #n ")" ::: "memory")
; #define PG8_BAR __builtin_amdgcn_s_barrier()
; #define PG8_SCHED __builtin_amdgcn_sched_barrier(0)
; template <class Epi>
; __device__ __forceinline__ void gemm_phase(LAS unsigned char* lds, const Gemm g, int G, int c, const Epi& E) {
;     ...
;             PG8_WAIT_V(8); PG8_WAIT_L(0); PG8_BAR; PG8_MMA(1, 0, At, B0); PG8_MMA(1, 1, At, B1); PG8_BAR; PG8_SCHED;
;             PG8_LDB(B0, 1, 0); PG8_LDB(B1, 1, 1); PG8_SCHED; PG8_LDA(At, 1, 0); PG8_STAGE(PG8_SA(0, 1), a2 + hstepA, voffA);
;             PG8_WAIT_V(8); PG8_WAIT_L(0); PG8_BAR; PG8_MMA(0, 0, At, B0); PG8_MMA(0, 1, At, B1); PG8_BAR; PG8_SCHED;
	s_setprio 0
	s_waitcnt lgkmcnt(0)
	v_mfma_f32_16x16x32_bf16 v[62:65], v[152:155], v[184:187], 0
	v_mfma_f32_16x16x32_bf16 v[58:61], v[160:163], v[184:187], 0
	v_mfma_f32_16x16x32_bf16 v[46:49], v[152:155], v[192:195], 0
	v_mfma_f32_16x16x32_bf16 v[42:45], v[160:163], v[192:195], 0
	v_mfma_f32_16x16x32_bf16 v[30:33], v[152:155], v[200:203], 0
	v_mfma_f32_16x16x32_bf16 v[26:29], v[160:163], v[200:203], 0
	v_mfma_f32_16x16x32_bf16 v[14:17], v[152:155], v[208:211], 0
	v_mfma_f32_16x16x32_bf16 v[10:13], v[160:163], v[208:211], 0
	v_mfma_f32_16x16x32_bf16 v[62:65], v[156:159], v[188:191], v[62:65]
	v_mfma_f32_16x16x32_bf16 v[58:61], v[164:167], v[188:191], v[58:61]
	v_mfma_f32_16x16x32_bf16 v[46:49], v[156:159], v[196:199], v[46:49]
	v_mfma_f32_16x16x32_bf16 v[42:45], v[164:167], v[196:199], v[42:45]
	v_mfma_f32_16x16x32_bf16 v[30:33], v[156:159], v[204:207], v[30:33]
	v_mfma_f32_16x16x32_bf16 v[26:29], v[164:167], v[204:207], v[26:29]
	v_mfma_f32_16x16x32_bf16 v[14:17], v[156:159], v[212:215], v[14:17]
	v_mfma_f32_16x16x32_bf16 v[10:13], v[164:167], v[212:215], v[10:13]
	s_setprio 2
	s_setprio 0
	v_mfma_f32_16x16x32_bf16 v[54:57], v[168:171], v[184:187], 0
	v_mfma_f32_16x16x32_bf16 v[50:53], v[176:179], v[184:187], 0
	v_mfma_f32_16x16x32_bf16 v[38:41], v[168:171], v[192:195], 0
	v_mfma_f32_16x16x32_bf16 v[34:37], v[176:179], v[192:195], 0
	v_mfma_f32_16x16x32_bf16 v[22:25], v[168:171], v[200:203], 0
	v_mfma_f32_16x16x32_bf16 v[18:21], v[176:179], v[200:203], 0
	v_mfma_f32_16x16x32_bf16 v[6:9], v[168:171], v[208:211], 0
	v_mfma_f32_16x16x32_bf16 v[2:5], v[176:179], v[208:211], 0
	v_mfma_f32_16x16x32_bf16 v[54:57], v[172:175], v[188:191], v[54:57]
	v_mfma_f32_16x16x32_bf16 v[50:53], v[180:183], v[188:191], v[50:53]
	v_mfma_f32_16x16x32_bf16 v[38:41], v[172:175], v[196:199], v[38:41]
	v_mfma_f32_16x16x32_bf16 v[34:37], v[180:183], v[196:199], v[34:37]
	v_mfma_f32_16x16x32_bf16 v[22:25], v[172:175], v[204:207], v[22:25]
	v_mfma_f32_16x16x32_bf16 v[18:21], v[180:183], v[204:207], v[18:21]
	v_mfma_f32_16x16x32_bf16 v[6:9], v[172:175], v[212:215], v[6:9]
	v_mfma_f32_16x16x32_bf16 v[2:5], v[180:183], v[212:215], v[2:5]
	s_setprio 2
	s_barrier
	s_add_i32 s33, 0, 0x18000
	s_add_i32 s69, 0, 0x1c000
	v_add_u32_e32 v164, s33, v147
	v_add_u32_e32 v180, s69, v147
	ds_read_b128 v[152:155], v164
	ds_read_b128 v[156:159], v164 offset:1024
	ds_read_b128 v[160:163], v164 offset:2048
	ds_read_b128 v[164:167], v164 offset:3072
	ds_read_b128 v[168:171], v180
	ds_read_b128 v[172:175], v180 offset:1024
	ds_read_b128 v[176:179], v180 offset:2048
	ds_read_b128 v[180:183], v180 offset:3072
	s_add_u32 s40, s40, 0x40000
	s_addc_u32 s41, s41, 0
	s_mov_b32 m0, s47
	v_lshl_add_u64 v[224:225], s[40:41], 0, v[136:137]
	ds_read_b128 v[184:187], v150 offset:32768
	ds_read_b128 v[188:191], v150 offset:33792
	ds_read_b128 v[192:195], v150 offset:34816
	ds_read_b128 v[196:199], v150 offset:35840
	ds_read_b128 v[200:203], v150 offset:36864
	ds_read_b128 v[204:207], v150 offset:37888
	ds_read_b128 v[208:211], v150 offset:38912
	ds_read_b128 v[212:215], v150 offset:39936
	global_load_lds_dwordx4 v[224:225], off
	v_lshl_add_u64 v[224:225], s[40:41], 0, v[132:133]
	s_mov_b32 m0, s48
	s_nop 0
	global_load_lds_dwordx4 v[224:225], off
	s_waitcnt vmcnt(8)
	s_waitcnt lgkmcnt(0)
	s_barrier
	s_setprio 0
	s_waitcnt lgkmcnt(0)
	v_mfma_f32_16x16x32_bf16 v[126:129], v[152:155], v[184:187], v[126:129]
	v_mfma_f32_16x16x32_bf16 v[122:125], v[160:163], v[184:187], v[122:125]
	v_mfma_f32_16x16x32_bf16 v[110:113], v[152:155], v[192:195], v[110:113]
	v_mfma_f32_16x16x32_bf16 v[106:109], v[160:163], v[192:195], v[106:109]
	v_mfma_f32_16x16x32_bf16 v[94:97], v[152:155], v[200:203], v[94:97]
	v_mfma_f32_16x16x32_bf16 v[90:93], v[160:163], v[200:203], v[90:93]
	v_mfma_f32_16x16x32_bf16 v[78:81], v[152:155], v[208:211], v[78:81]
	v_mfma_f32_16x16x32_bf16 v[74:77], v[160:163], v[208:211], v[74:77]
	v_mfma_f32_16x16x32_bf16 v[126:129], v[156:159], v[188:191], v[126:129]
	v_mfma_f32_16x16x32_bf16 v[122:125], v[164:167], v[188:191], v[122:125]
	v_mfma_f32_16x16x32_bf16 v[110:113], v[156:159], v[196:199], v[110:113]
	v_mfma_f32_16x16x32_bf16 v[106:109], v[164:167], v[196:199], v[106:109]
	v_mfma_f32_16x16x32_bf16 v[94:97], v[156:159], v[204:207], v[94:97]
	v_mfma_f32_16x16x32_bf16 v[90:93], v[164:167], v[204:207], v[90:93]
	v_mfma_f32_16x16x32_bf16 v[78:81], v[156:159], v[212:215], v[78:81]
	v_mfma_f32_16x16x32_bf16 v[74:77], v[164:167], v[212:215], v[74:77]
	s_setprio 2
	s_setprio 0
	v_mfma_f32_16x16x32_bf16 v[118:121], v[168:171], v[184:187], v[118:121]
	v_mfma_f32_16x16x32_bf16 v[114:117], v[176:179], v[184:187], v[114:117]
	v_mfma_f32_16x16x32_bf16 v[102:105], v[168:171], v[192:195], v[102:105]
	v_mfma_f32_16x16x32_bf16 v[98:101], v[176:179], v[192:195], v[98:101]
	v_mfma_f32_16x16x32_bf16 v[86:89], v[168:171], v[200:203], v[86:89]
	v_mfma_f32_16x16x32_bf16 v[82:85], v[176:179], v[200:203], v[82:85]
	v_mfma_f32_16x16x32_bf16 v[70:73], v[168:171], v[208:211], v[70:73]
	v_mfma_f32_16x16x32_bf16 v[66:69], v[176:179], v[208:211], v[66:69]
	v_mfma_f32_16x16x32_bf16 v[118:121], v[172:175], v[188:191], v[118:121]
	v_mfma_f32_16x16x32_bf16 v[114:117], v[180:183], v[188:191], v[114:117]
	v_mfma_f32_16x16x32_bf16 v[102:105], v[172:175], v[196:199], v[102:105]
	v_mfma_f32_16x16x32_bf16 v[98:101], v[180:183], v[196:199], v[98:101]
	v_mfma_f32_16x16x32_bf16 v[86:89], v[172:175], v[204:207], v[86:89]
	v_mfma_f32_16x16x32_bf16 v[82:85], v[180:183], v[204:207], v[82:85]
	v_mfma_f32_16x16x32_bf16 v[70:73], v[172:175], v[212:215], v[70:73]
	v_mfma_f32_16x16x32_bf16 v[66:69], v[180:183], v[212:215], v[66:69]
	s_setprio 2
	s_barrier
; #define PG8_STAGE(bufoff, gbase, voff) do { _Pragma("unroll") for (int _i = 0; _i < 2; ++_i) \
;         __builtin_amdgcn_global_load_lds((const unsigned*)((const char*)(gbase) + (voff)[_i]), (LAS unsigned*)(lds + (bufoff) + ldsw + _i * 8192), 16, 0, 0); } while (0)
; #define PG8_LDA(dst, b, h) do { _Pragma("unroll") for (int m = 0; m < 4; ++m) _Pragma("unroll") for (int k = 0; k < 2; ++k) dst[m][k] = *(const LAS bf16x8*)(lds + PG8_SA(b, h) + aoff + m * 2048 + k * 1024); } while (0)
; #define PG8_LDB(dst, b, h) do { _Pragma("unroll") for (int n = 0; n < 2; ++n) _Pragma("unroll") for (int k = 0; k < 2; ++k) dst[n][k] = *(const LAS bf16x8*)(lds + PG8_SB(b, h) + boff + n * 2048 + k * 1024); } while (0)
; #define PG8_WAIT_V(n) asm volatile("s_waitcnt vmcnt(" #n ")" ::: "memory")
; #define PG8_WAIT_L(n) asm volatile("s_waitcnt lgkmcnt(" #n ")" ::: "memory")
; template <class Epi>
; __device__ __forceinline__ void gemm_phase(LAS unsigned char* lds, const Gemm g, int G, int c, const Epi& E) {
;     ...
;         for (int t = 0; t < nt; t += 2) {
;             const bool last = (t == nt - 2);
;             const char* a1 = cA + (size_t)(t + 1) * kstep;
;             const char* a2 = last ? nA : cA + (size_t)(t + 2) * kstep; const char* b2 = last ? nB : cB + (size_t)(t + 2) * kstep;
;             const char* a3 = a2 + kstep; const char* b3 = b2 + kstep;
;             PG8_LDB(B0, 0, 0); PG8_LDB(B1, 0, 1); PG8_SCHED; PG8_LDA(At, 0, 0); PG8_STAGE(PG8_SA(1, 1), a1 + hstepA, voffA);
;             PG8_WAIT_V(8); PG8_WAIT_L(0); PG8_BAR; PG8_MMA(0, 0, At, B0); PG8_MMA(0, 1, At, B1); PG8_BAR; PG8_SCHED;
;             PG8_LDA(At, 0, 1); PG8_STAGE(PG8_SB(0, 0), b2, voffB); PG8_STAGE(PG8_SB(0, 1), b2 + hstepB, voffB); PG8_STAGE(PG8_SA(0, 0), a2, voffA);
;             PG8_WAIT_V(8); PG8_WAIT_L(0); PG8_BAR; PG8_MMA(1, 0, At, B0); PG8_MMA(1, 1, At, B1); PG8_BAR; PG8_SCHED;
;             PG8_LDB(B0, 1, 0); PG8_LDB(B1, 1, 1); PG8_SCHED; PG8_LDA(At, 1, 0); PG8_STAGE(PG8_SA(0, 1), a2 + hstepA, voffA);
;             PG8_WAIT_V(8); PG8_WAIT_L(0); PG8_BAR; PG8_MMA(0, 0, At, B0); PG8_MMA(0, 1, At, B1); PG8_BAR; PG8_SCHED;
;             PG8_LDA(At, 1, 1); PG8_STAGE(PG8_SB(1, 0), b3, voffB); PG8_STAGE(PG8_SB(1, 1), b3 + hstepB, voffB); PG8_STAGE(PG8_SA(1, 0), a3, voffA);
;             PG8_WAIT_V(8); PG8_WAIT_L(0); PG8_BAR; PG8_MMA(1, 0, At, B0); PG8_MMA(1, 1, At, B1); PG8_BAR; PG8_SCHED;
	s_add_i32 s33, s33, s46
	v_lshl_add_u64 v[216:217], v[216:217], 0, s[12:13]
	s_mov_b32 m0, s33
	ds_read_b128 v[184:187], v150 offset:49152
	ds_read_b128 v[188:191], v150 offset:50176
	ds_read_b128 v[192:195], v150 offset:51200
	ds_read_b128 v[196:199], v150 offset:52224
	ds_read_b128 v[200:203], v150 offset:53248
	ds_read_b128 v[204:207], v150 offset:54272
	ds_read_b128 v[208:211], v150 offset:55296
	ds_read_b128 v[212:215], v150 offset:56320
	global_load_lds_dwordx4 v[216:217], off
	s_add_i32 m0, s33, 0x2000
	s_add_u32 s38, s38, 0x40080
	v_lshl_add_u64 v[216:217], v[218:219], 0, s[12:13]
	s_addc_u32 s39, s39, 0
	s_add_i32 s33, s69, s46
	global_load_lds_dwordx4 v[216:217], off
	v_lshl_add_u64 v[216:217], s[38:39], 0, v[134:135]
	s_mov_b32 m0, s33
	s_nop 0
	global_load_lds_dwordx4 v[216:217], off
	v_lshl_add_u64 v[216:217], s[38:39], 0, v[130:131]
	s_add_i32 m0, s33, 0x2000
	s_nop 0
	global_load_lds_dwordx4 v[216:217], off
	v_lshl_add_u64 v[216:217], v[220:221], 0, s[12:13]
	s_mov_b32 m0, s53
	s_nop 0
	global_load_lds_dwordx4 v[216:217], off
	v_lshl_add_u64 v[216:217], v[222:223], 0, s[12:13]
	s_mov_b32 m0, s54
	s_nop 0
	global_load_lds_dwordx4 v[216:217], off
	s_waitcnt vmcnt(8)
	s_waitcnt lgkmcnt(0)
	s_barrier
	s_setprio 0
	s_waitcnt lgkmcnt(0)
	v_mfma_f32_16x16x32_bf16 v[62:65], v[152:155], v[184:187], v[62:65]
	v_mfma_f32_16x16x32_bf16 v[58:61], v[160:163], v[184:187], v[58:61]
	v_mfma_f32_16x16x32_bf16 v[46:49], v[152:155], v[192:195], v[46:49]
	v_mfma_f32_16x16x32_bf16 v[42:45], v[160:163], v[192:195], v[42:45]
	v_mfma_f32_16x16x32_bf16 v[30:33], v[152:155], v[200:203], v[30:33]
	v_mfma_f32_16x16x32_bf16 v[26:29], v[160:163], v[200:203], v[26:29]
	v_mfma_f32_16x16x32_bf16 v[14:17], v[152:155], v[208:211], v[14:17]
	v_mfma_f32_16x16x32_bf16 v[10:13], v[160:163], v[208:211], v[10:13]
	v_mfma_f32_16x16x32_bf16 v[62:65], v[156:159], v[188:191], v[62:65]
	v_mfma_f32_16x16x32_bf16 v[58:61], v[164:167], v[188:191], v[58:61]
	v_mfma_f32_16x16x32_bf16 v[46:49], v[156:159], v[196:199], v[46:49]
	v_mfma_f32_16x16x32_bf16 v[42:45], v[164:167], v[196:199], v[42:45]
	v_mfma_f32_16x16x32_bf16 v[30:33], v[156:159], v[204:207], v[30:33]
	v_mfma_f32_16x16x32_bf16 v[26:29], v[164:167], v[204:207], v[26:29]
	v_mfma_f32_16x16x32_bf16 v[14:17], v[156:159], v[212:215], v[14:17]
	v_mfma_f32_16x16x32_bf16 v[10:13], v[164:167], v[212:215], v[10:13]
	s_setprio 2
	s_setprio 0
	v_mfma_f32_16x16x32_bf16 v[54:57], v[168:171], v[184:187], v[54:57]
	v_mfma_f32_16x16x32_bf16 v[50:53], v[176:179], v[184:187], v[50:53]
	v_mfma_f32_16x16x32_bf16 v[38:41], v[168:171], v[192:195], v[38:41]
	v_mfma_f32_16x16x32_bf16 v[34:37], v[176:179], v[192:195], v[34:37]
	v_mfma_f32_16x16x32_bf16 v[22:25], v[168:171], v[200:203], v[22:25]
	v_mfma_f32_16x16x32_bf16 v[18:21], v[176:179], v[200:203], v[18:21]
	v_mfma_f32_16x16x32_bf16 v[6:9], v[168:171], v[208:211], v[6:9]
	v_mfma_f32_16x16x32_bf16 v[2:5], v[176:179], v[208:211], v[2:5]
	v_mfma_f32_16x16x32_bf16 v[54:57], v[172:175], v[188:191], v[54:57]
	v_mfma_f32_16x16x32_bf16 v[50:53], v[180:183], v[188:191], v[50:53]
	v_mfma_f32_16x16x32_bf16 v[38:41], v[172:175], v[196:199], v[38:41]
	v_mfma_f32_16x16x32_bf16 v[34:37], v[180:183], v[196:199], v[34:37]
	v_mfma_f32_16x16x32_bf16 v[22:25], v[172:175], v[204:207], v[22:25]
	v_mfma_f32_16x16x32_bf16 v[18:21], v[180:183], v[204:207], v[18:21]
	v_mfma_f32_16x16x32_bf16 v[6:9], v[172:175], v[212:215], v[6:9]
	v_mfma_f32_16x16x32_bf16 v[2:5], v[180:183], v[212:215], v[2:5]
	s_setprio 2
	s_barrier
	s_add_i32 s68, s68, 2
	s_add_u32 s4, s4, 0x100
	s_addc_u32 s5, s5, 0
	s_add_u32 s66, s66, 0x100
	s_addc_u32 s67, s67, 0
	s_cmp_gt_u32 s68, 13
	s_cbranch_scc0 .LBB0_2084

; #define PG8_STAGE(bufoff, gbase, voff) do { _Pragma("unroll") for (int _i = 0; _i < 2; ++_i) \
;         __builtin_amdgcn_global_load_lds((const unsigned*)((const char*)(gbase) + (voff)[_i]), (LAS unsigned*)(lds + (bufoff) + ldsw + _i * 8192), 16, 0, 0); } while (0)
; #define PG8_LDA(dst, b, h) do { _Pragma("unroll") for (int m = 0; m < 4; ++m) _Pragma("unroll") for (int k = 0; k < 2; ++k) dst[m][k] = *(const LAS bf16x8*)(lds + PG8_SA(b, h) + aoff + m * 2048 + k * 1024); } while (0)
; #define PG8_LDB(dst, b, h) do { _Pragma("unroll") for (int n = 0; n < 2; ++n) _Pragma("unroll") for (int k = 0; k < 2; ++k) dst[n][k] = *(const LAS bf16x8*)(lds + PG8_SB(b, h) + boff + n * 2048 + k * 1024); } while (0)
; #define PG8_MMA(ai, bj, At, Bt) do { __builtin_amdgcn_s_setprio(1); _Pragma("unroll") for (int m = 0; m < 4; ++m) _Pragma("unroll") for (int n = 0; n < 2; ++n) _Pragma("unroll") for (int k = 0; k < 2; ++k) \
;         acc[ai][bj][m][n] = __builtin_amdgcn_mfma_f32_16x16x32_bf16(Bt[n][k], At[m][k], acc[ai][bj][m][n], 0, 0, 0); __builtin_amdgcn_s_setprio(0); } while (0)
; #define PG8_WAIT_V(n) asm volatile("s_waitcnt vmcnt(" #n ")" ::: "memory")
; #define PG8_WAIT_L(n) asm volatile("s_waitcnt lgkmcnt(" #n ")" ::: "memory")
; #define PG8_BAR __builtin_amdgcn_s_barrier()
; #define PG8_SCHED __builtin_amdgcn_sched_barrier(0)
; template <class Epi>
; __device__ __forceinline__ void gemm_phase(LAS unsigned char* lds, const Gemm g, int G, int c, const Epi& E) {
;     ...
;             PG8_LDB(B0, 0, 0); PG8_LDB(B1, 0, 1); PG8_SCHED; PG8_LDA(At, 0, 0); PG8_STAGE(PG8_SA(1, 1), a1 + hstepA, voffA);
;             PG8_WAIT_V(8); PG8_WAIT_L(0); PG8_BAR; PG8_MMA(0, 0, At, B0); PG8_MMA(0, 1, At, B1); PG8_BAR; PG8_SCHED;
;             PG8_LDA(At, 0, 1); PG8_STAGE(PG8_SB(0, 0), b2, voffB); PG8_STAGE(PG8_SB(0, 1), b2 + hstepB, voffB); PG8_STAGE(PG8_SA(0, 0), a2, voffA);
;             PG8_WAIT_V(8); PG8_WAIT_L(0); PG8_BAR; PG8_MMA(1, 0, At, B0); PG8_MMA(1, 1, At, B1); PG8_BAR; PG8_SCHED;
;     ...
;                     for (int n = 0; n < 2; ++n) acc[a][b][m][n] = (f32x4){0.f, 0.f, 0.f, 0.f};
.LBB0_2168:
	s_add_u32 s60, s20, 0x100
	s_addc_u32 s61, s21, 0
	s_mov_b32 s62, -2
	s_waitcnt vmcnt(0)
	ds_read_b128 v[106:109], v168
	ds_read_b128 v[110:113], v168 offset:1024
	ds_read_b128 v[114:117], v168 offset:2048
	ds_read_b128 v[118:121], v168 offset:3072
	ds_read_b128 v[162:165], v169
	ds_read_b128 v[172:175], v169 offset:1024
	ds_read_b128 v[176:179], v169 offset:2048
	ds_read_b128 v[180:183], v169 offset:3072
	s_add_u32 s20, s18, 0x100
	s_addc_u32 s21, s19, 0
	s_cmp_eq_u32 s62, 40
	s_cselect_b32 s25, s5, s21
	s_cselect_b32 s24, s4, s20
	s_cselect_b32 s23, s17, s61
	s_cselect_b32 s22, s16, s60
	v_lshl_add_u64 v[216:217], s[18:19], 0, v[154:155]
	s_add_i32 m0, s40, 0xc000
	ds_read_b128 v[184:187], v170
	ds_read_b128 v[188:191], v170 offset:1024
	ds_read_b128 v[192:195], v170 offset:2048
	ds_read_b128 v[196:199], v170 offset:3072
	ds_read_b128 v[200:203], v170 offset:4096
	ds_read_b128 v[204:207], v170 offset:5120
	ds_read_b128 v[208:211], v170 offset:6144
	ds_read_b128 v[212:215], v170 offset:7168
	global_load_lds_dwordx4 v[216:217], off
	v_lshl_add_u64 v[216:217], s[18:19], 0, v[156:157]
	s_add_i32 m0, s40, 0xe000
	s_nop 0
	global_load_lds_dwordx4 v[216:217], off
	s_waitcnt vmcnt(8)
	s_waitcnt lgkmcnt(0)
	s_barrier
	s_setprio 0
	s_waitcnt lgkmcnt(0)
	v_mfma_f32_16x16x32_bf16 v[142:145], v[106:109], v[184:187], 0
	v_mfma_f32_16x16x32_bf16 v[138:141], v[114:117], v[184:187], 0
	v_mfma_f32_16x16x32_bf16 v[126:129], v[106:109], v[192:195], 0
	v_mfma_f32_16x16x32_bf16 v[122:125], v[114:117], v[192:195], 0
	v_mfma_f32_16x16x32_bf16 v[94:97], v[106:109], v[200:203], 0
	v_mfma_f32_16x16x32_bf16 v[90:93], v[114:117], v[200:203], 0
	v_mfma_f32_16x16x32_bf16 v[78:81], v[106:109], v[208:211], 0
	v_mfma_f32_16x16x32_bf16 v[74:77], v[114:117], v[208:211], 0
	v_mfma_f32_16x16x32_bf16 v[142:145], v[110:113], v[188:191], v[142:145]
	v_mfma_f32_16x16x32_bf16 v[138:141], v[118:121], v[188:191], v[138:141]
	v_mfma_f32_16x16x32_bf16 v[126:129], v[110:113], v[196:199], v[126:129]
	v_mfma_f32_16x16x32_bf16 v[122:125], v[118:121], v[196:199], v[122:125]
	v_mfma_f32_16x16x32_bf16 v[94:97], v[110:113], v[204:207], v[94:97]
	v_mfma_f32_16x16x32_bf16 v[90:93], v[118:121], v[204:207], v[90:93]
	v_mfma_f32_16x16x32_bf16 v[78:81], v[110:113], v[212:215], v[78:81]
	v_mfma_f32_16x16x32_bf16 v[74:77], v[118:121], v[212:215], v[74:77]
	s_setprio 2
	s_setprio 0
	v_mfma_f32_16x16x32_bf16 v[134:137], v[162:165], v[184:187], 0
	v_mfma_f32_16x16x32_bf16 v[130:133], v[176:179], v[184:187], 0
	v_mfma_f32_16x16x32_bf16 v[102:105], v[162:165], v[192:195], 0
	v_mfma_f32_16x16x32_bf16 v[98:101], v[176:179], v[192:195], 0
	v_mfma_f32_16x16x32_bf16 v[86:89], v[162:165], v[200:203], 0
	v_mfma_f32_16x16x32_bf16 v[82:85], v[176:179], v[200:203], 0
	v_mfma_f32_16x16x32_bf16 v[70:73], v[162:165], v[208:211], 0
	v_mfma_f32_16x16x32_bf16 v[66:69], v[176:179], v[208:211], 0
	v_mfma_f32_16x16x32_bf16 v[134:137], v[172:175], v[188:191], v[134:137]
	v_mfma_f32_16x16x32_bf16 v[130:133], v[180:183], v[188:191], v[130:133]
	v_mfma_f32_16x16x32_bf16 v[102:105], v[172:175], v[196:199], v[102:105]
	v_mfma_f32_16x16x32_bf16 v[98:101], v[180:183], v[196:199], v[98:101]
	v_mfma_f32_16x16x32_bf16 v[86:89], v[172:175], v[204:207], v[86:89]
	v_mfma_f32_16x16x32_bf16 v[82:85], v[180:183], v[204:207], v[82:85]
	v_mfma_f32_16x16x32_bf16 v[70:73], v[172:175], v[212:215], v[70:73]
	v_mfma_f32_16x16x32_bf16 v[66:69], v[180:183], v[212:215], v[66:69]
	s_setprio 2
	s_barrier
	s_add_i32 s18, s52, s38
	v_lshl_add_u64 v[216:217], s[22:23], 0, v[150:151]
	s_mov_b32 m0, s18
	ds_read_b128 v[184:187], v170 offset:16384
	ds_read_b128 v[188:191], v170 offset:17408
	ds_read_b128 v[192:195], v170 offset:18432
	ds_read_b128 v[196:199], v170 offset:19456
	ds_read_b128 v[200:203], v170 offset:20480
	ds_read_b128 v[204:207], v170 offset:21504
	ds_read_b128 v[208:211], v170 offset:22528
	ds_read_b128 v[212:215], v170 offset:23552
	global_load_lds_dwordx4 v[216:217], off
	s_add_i32 m0, s18, 0x2000
	s_add_u32 s18, s22, 0xb0000
	v_lshl_add_u64 v[218:219], s[22:23], 0, v[146:147]
	s_addc_u32 s19, s23, 0
	s_add_i32 s33, s53, s38
	global_load_lds_dwordx4 v[218:219], off
	v_lshl_add_u64 v[220:221], s[18:19], 0, v[150:151]
	s_mov_b32 m0, s33
	v_lshl_add_u64 v[222:223], s[24:25], 0, v[148:149]
	global_load_lds_dwordx4 v[220:221], off
	v_lshl_add_u64 v[220:221], s[18:19], 0, v[146:147]
	s_add_i32 m0, s33, 0x2000
	s_nop 0
	global_load_lds_dwordx4 v[220:221], off
	v_lshl_add_u64 v[220:221], s[24:25], 0, v[152:153]
	s_mov_b32 m0, s40
	s_nop 0
	global_load_lds_dwordx4 v[220:221], off
	s_mov_b32 m0, s41
	s_nop 0
	global_load_lds_dwordx4 v[222:223], off
	s_waitcnt vmcnt(8)
	s_waitcnt lgkmcnt(0)
	s_barrier
; #define PG8_STAGE(bufoff, gbase, voff) do { _Pragma("unroll") for (int _i = 0; _i < 2; ++_i) \
;         __builtin_amdgcn_global_load_lds((const unsigned*)((const char*)(gbase) + (voff)[_i]), (LAS unsigned*)(lds + (bufoff) + ldsw + _i * 8192), 16, 0, 0); } while (0)
; #define PG8_LDA(dst, b, h) do { _Pragma("unroll") for (int m = 0; m < 4; ++m) _Pragma("unroll") for (int k = 0; k < 2; ++k) dst[m][k] = *(const LAS bf16x8*)(lds + PG8_SA(b, h) + aoff + m * 2048 + k * 1024); } while (0)
; #define PG8_LDB(dst, b, h) do { _Pragma("unroll") for (int n = 0; n < 2; ++n) _Pragma("unroll") for (int k = 0; k < 2; ++k) dst[n][k] = *(const LAS bf16x8*)(lds + PG8_SB(b, h) + boff + n * 2048 + k * 1024); } while (0)
; #define PG8_MMA(ai, bj, At, Bt) do { __builtin_amdgcn_s_setprio(1); _Pragma("unroll") for (int m = 0; m < 4; ++m) _Pragma("unroll") for (int n = 0; n < 2; ++n) _Pragma("unroll") for (int k = 0; k < 2; ++k) \
;         acc[ai][bj][m][n] = __builtin_amdgcn_mfma_f32_16x16x32_bf16(Bt[n][k], At[m][k], acc[ai][bj][m][n], 0, 0, 0); __builtin_amdgcn_s_setprio(0); } while (0)
; #define PG8_WAIT_V(n) asm volatile("s_waitcnt vmcnt(" #n ")" ::: "memory")
; #define PG8_WAIT_L(n) asm volatile("s_waitcnt lgkmcnt(" #n ")" ::: "memory")
; #define PG8_BAR __builtin_amdgcn_s_barrier()
; #define PG8_SCHED __builtin_amdgcn_sched_barrier(0)
; template <class Epi>
; __device__ __forceinline__ void gemm_phase(LAS unsigned char* lds, const Gemm g, int G, int c, const Epi& E) {
;     ...
;             PG8_WAIT_V(8); PG8_WAIT_L(0); PG8_BAR; PG8_MMA(1, 0, At, B0); PG8_MMA(1, 1, At, B1); PG8_BAR; PG8_SCHED;
;             PG8_LDB(B0, 1, 0); PG8_LDB(B1, 1, 1); PG8_SCHED; PG8_LDA(At, 1, 0); PG8_STAGE(PG8_SA(0, 1), a2 + hstepA, voffA);
;             PG8_WAIT_V(8); PG8_WAIT_L(0); PG8_BAR; PG8_MMA(0, 0, At, B0); PG8_MMA(0, 1, At, B1); PG8_BAR; PG8_SCHED;
	s_setprio 0
	s_waitcnt lgkmcnt(0)
	v_mfma_f32_16x16x32_bf16 v[62:65], v[106:109], v[184:187], 0
	v_mfma_f32_16x16x32_bf16 v[58:61], v[114:117], v[184:187], 0
	v_mfma_f32_16x16x32_bf16 v[46:49], v[106:109], v[192:195], 0
	v_mfma_f32_16x16x32_bf16 v[42:45], v[114:117], v[192:195], 0
	v_mfma_f32_16x16x32_bf16 v[30:33], v[106:109], v[200:203], 0
	v_mfma_f32_16x16x32_bf16 v[26:29], v[114:117], v[200:203], 0
	v_mfma_f32_16x16x32_bf16 v[14:17], v[106:109], v[208:211], 0
	v_mfma_f32_16x16x32_bf16 v[10:13], v[114:117], v[208:211], 0
	v_mfma_f32_16x16x32_bf16 v[62:65], v[110:113], v[188:191], v[62:65]
	v_mfma_f32_16x16x32_bf16 v[58:61], v[118:121], v[188:191], v[58:61]
	v_mfma_f32_16x16x32_bf16 v[46:49], v[110:113], v[196:199], v[46:49]
	v_mfma_f32_16x16x32_bf16 v[42:45], v[118:121], v[196:199], v[42:45]
	v_mfma_f32_16x16x32_bf16 v[30:33], v[110:113], v[204:207], v[30:33]
	v_mfma_f32_16x16x32_bf16 v[26:29], v[118:121], v[204:207], v[26:29]
	v_mfma_f32_16x16x32_bf16 v[14:17], v[110:113], v[212:215], v[14:17]
	v_mfma_f32_16x16x32_bf16 v[10:13], v[118:121], v[212:215], v[10:13]
	s_setprio 2
	s_setprio 0
	v_mfma_f32_16x16x32_bf16 v[54:57], v[162:165], v[184:187], 0
	v_mfma_f32_16x16x32_bf16 v[50:53], v[176:179], v[184:187], 0
	v_mfma_f32_16x16x32_bf16 v[38:41], v[162:165], v[192:195], 0
	v_mfma_f32_16x16x32_bf16 v[34:37], v[176:179], v[192:195], 0
	v_mfma_f32_16x16x32_bf16 v[22:25], v[162:165], v[200:203], 0
	v_mfma_f32_16x16x32_bf16 v[18:21], v[176:179], v[200:203], 0
	v_mfma_f32_16x16x32_bf16 v[6:9], v[162:165], v[208:211], 0
	v_mfma_f32_16x16x32_bf16 v[2:5], v[176:179], v[208:211], 0
	v_mfma_f32_16x16x32_bf16 v[54:57], v[172:175], v[188:191], v[54:57]
	v_mfma_f32_16x16x32_bf16 v[50:53], v[180:183], v[188:191], v[50:53]
	v_mfma_f32_16x16x32_bf16 v[38:41], v[172:175], v[196:199], v[38:41]
	v_mfma_f32_16x16x32_bf16 v[34:37], v[180:183], v[196:199], v[34:37]
	v_mfma_f32_16x16x32_bf16 v[22:25], v[172:175], v[204:207], v[22:25]
	v_mfma_f32_16x16x32_bf16 v[18:21], v[180:183], v[204:207], v[18:21]
	v_mfma_f32_16x16x32_bf16 v[6:9], v[172:175], v[212:215], v[6:9]
	v_mfma_f32_16x16x32_bf16 v[2:5], v[180:183], v[212:215], v[2:5]
	s_setprio 2
	s_barrier
	s_add_i32 s33, 0, 0x18000
	s_add_i32 s63, 0, 0x1c000
	v_add_u32_e32 v118, s33, v167
	v_add_u32_e32 v171, s63, v167
	ds_read_b128 v[106:109], v118
	ds_read_b128 v[110:113], v118 offset:1024
	ds_read_b128 v[114:117], v118 offset:2048
	ds_read_b128 v[118:121], v118 offset:3072
	ds_read_b128 v[162:165], v171
	ds_read_b128 v[172:175], v171 offset:1024
	ds_read_b128 v[176:179], v171 offset:2048
	ds_read_b128 v[180:183], v171 offset:3072
	s_add_u32 s18, s24, 0xb0000
	s_addc_u32 s19, s25, 0
	s_mov_b32 m0, s42
	v_lshl_add_u64 v[224:225], s[18:19], 0, v[152:153]
	ds_read_b128 v[184:187], v170 offset:32768
	ds_read_b128 v[188:191], v170 offset:33792
	ds_read_b128 v[192:195], v170 offset:34816
	ds_read_b128 v[196:199], v170 offset:35840
	ds_read_b128 v[200:203], v170 offset:36864
	ds_read_b128 v[204:207], v170 offset:37888
	ds_read_b128 v[208:211], v170 offset:38912
	ds_read_b128 v[212:215], v170 offset:39936
	global_load_lds_dwordx4 v[224:225], off
	v_lshl_add_u64 v[224:225], s[18:19], 0, v[148:149]
	s_mov_b32 m0, s43
	s_nop 0
	global_load_lds_dwordx4 v[224:225], off
	s_waitcnt vmcnt(8)
	s_waitcnt lgkmcnt(0)
	s_barrier
	s_setprio 0
	s_waitcnt lgkmcnt(0)
	v_mfma_f32_16x16x32_bf16 v[142:145], v[106:109], v[184:187], v[142:145]
	v_mfma_f32_16x16x32_bf16 v[138:141], v[114:117], v[184:187], v[138:141]
	v_mfma_f32_16x16x32_bf16 v[126:129], v[106:109], v[192:195], v[126:129]
	v_mfma_f32_16x16x32_bf16 v[122:125], v[114:117], v[192:195], v[122:125]
	v_mfma_f32_16x16x32_bf16 v[94:97], v[106:109], v[200:203], v[94:97]
	v_mfma_f32_16x16x32_bf16 v[90:93], v[114:117], v[200:203], v[90:93]
	v_mfma_f32_16x16x32_bf16 v[78:81], v[106:109], v[208:211], v[78:81]
	v_mfma_f32_16x16x32_bf16 v[74:77], v[114:117], v[208:211], v[74:77]
	v_mfma_f32_16x16x32_bf16 v[142:145], v[110:113], v[188:191], v[142:145]
	v_mfma_f32_16x16x32_bf16 v[138:141], v[118:121], v[188:191], v[138:141]
	v_mfma_f32_16x16x32_bf16 v[126:129], v[110:113], v[196:199], v[126:129]
	v_mfma_f32_16x16x32_bf16 v[122:125], v[118:121], v[196:199], v[122:125]
	v_mfma_f32_16x16x32_bf16 v[94:97], v[110:113], v[204:207], v[94:97]
	v_mfma_f32_16x16x32_bf16 v[90:93], v[118:121], v[204:207], v[90:93]
	v_mfma_f32_16x16x32_bf16 v[78:81], v[110:113], v[212:215], v[78:81]
	v_mfma_f32_16x16x32_bf16 v[74:77], v[118:121], v[212:215], v[74:77]
	s_setprio 2
	s_setprio 0
	v_mfma_f32_16x16x32_bf16 v[134:137], v[162:165], v[184:187], v[134:137]
	v_mfma_f32_16x16x32_bf16 v[130:133], v[176:179], v[184:187], v[130:133]
	v_mfma_f32_16x16x32_bf16 v[102:105], v[162:165], v[192:195], v[102:105]
	v_mfma_f32_16x16x32_bf16 v[98:101], v[176:179], v[192:195], v[98:101]
	v_mfma_f32_16x16x32_bf16 v[86:89], v[162:165], v[200:203], v[86:89]
	v_mfma_f32_16x16x32_bf16 v[82:85], v[176:179], v[200:203], v[82:85]
	v_mfma_f32_16x16x32_bf16 v[70:73], v[162:165], v[208:211], v[70:73]
	v_mfma_f32_16x16x32_bf16 v[66:69], v[176:179], v[208:211], v[66:69]
	v_mfma_f32_16x16x32_bf16 v[134:137], v[172:175], v[188:191], v[134:137]
	v_mfma_f32_16x16x32_bf16 v[130:133], v[180:183], v[188:191], v[130:133]
	v_mfma_f32_16x16x32_bf16 v[102:105], v[172:175], v[196:199], v[102:105]
	v_mfma_f32_16x16x32_bf16 v[98:101], v[180:183], v[196:199], v[98:101]
	v_mfma_f32_16x16x32_bf16 v[86:89], v[172:175], v[204:207], v[86:89]
	v_mfma_f32_16x16x32_bf16 v[82:85], v[180:183], v[204:207], v[82:85]
	v_mfma_f32_16x16x32_bf16 v[70:73], v[172:175], v[212:215], v[70:73]
	v_mfma_f32_16x16x32_bf16 v[66:69], v[180:183], v[212:215], v[66:69]
	s_setprio 2
	s_barrier
; #define PG8_STAGE(bufoff, gbase, voff) do { _Pragma("unroll") for (int _i = 0; _i < 2; ++_i) \
;         __builtin_amdgcn_global_load_lds((const unsigned*)((const char*)(gbase) + (voff)[_i]), (LAS unsigned*)(lds + (bufoff) + ldsw + _i * 8192), 16, 0, 0); } while (0)
; #define PG8_LDA(dst, b, h) do { _Pragma("unroll") for (int m = 0; m < 4; ++m) _Pragma("unroll") for (int k = 0; k < 2; ++k) dst[m][k] = *(const LAS bf16x8*)(lds + PG8_SA(b, h) + aoff + m * 2048 + k * 1024); } while (0)
; #define PG8_LDB(dst, b, h) do { _Pragma("unroll") for (int n = 0; n < 2; ++n) _Pragma("unroll") for (int k = 0; k < 2; ++k) dst[n][k] = *(const LAS bf16x8*)(lds + PG8_SB(b, h) + boff + n * 2048 + k * 1024); } while (0)
; #define PG8_WAIT_V(n) asm volatile("s_waitcnt vmcnt(" #n ")" ::: "memory")
; #define PG8_WAIT_L(n) asm volatile("s_waitcnt lgkmcnt(" #n ")" ::: "memory")
; template <class Epi>
; __device__ __forceinline__ void gemm_phase(LAS unsigned char* lds, const Gemm g, int G, int c, const Epi& E) {
;     ...
;         for (int t = 0; t < nt; t += 2) {
;             const bool last = (t == nt - 2);
;             const char* a1 = cA + (size_t)(t + 1) * kstep;
;             const char* a2 = last ? nA : cA + (size_t)(t + 2) * kstep; const char* b2 = last ? nB : cB + (size_t)(t + 2) * kstep;
;             const char* a3 = a2 + kstep; const char* b3 = b2 + kstep;
;             PG8_LDB(B0, 0, 0); PG8_LDB(B1, 0, 1); PG8_SCHED; PG8_LDA(At, 0, 0); PG8_STAGE(PG8_SA(1, 1), a1 + hstepA, voffA);
;             PG8_WAIT_V(8); PG8_WAIT_L(0); PG8_BAR; PG8_MMA(0, 0, At, B0); PG8_MMA(0, 1, At, B1); PG8_BAR; PG8_SCHED;
;             PG8_LDA(At, 0, 1); PG8_STAGE(PG8_SB(0, 0), b2, voffB); PG8_STAGE(PG8_SB(0, 1), b2 + hstepB, voffB); PG8_STAGE(PG8_SA(0, 0), a2, voffA);
;             PG8_WAIT_V(8); PG8_WAIT_L(0); PG8_BAR; PG8_MMA(1, 0, At, B0); PG8_MMA(1, 1, At, B1); PG8_BAR; PG8_SCHED;
;             PG8_LDB(B0, 1, 0); PG8_LDB(B1, 1, 1); PG8_SCHED; PG8_LDA(At, 1, 0); PG8_STAGE(PG8_SA(0, 1), a2 + hstepA, voffA);
;             PG8_WAIT_V(8); PG8_WAIT_L(0); PG8_BAR; PG8_MMA(0, 0, At, B0); PG8_MMA(0, 1, At, B1); PG8_BAR; PG8_SCHED;
;             PG8_LDA(At, 1, 1); PG8_STAGE(PG8_SB(1, 0), b3, voffB); PG8_STAGE(PG8_SB(1, 1), b3 + hstepB, voffB); PG8_STAGE(PG8_SA(1, 0), a3, voffA);
;             PG8_WAIT_V(8); PG8_WAIT_L(0); PG8_BAR; PG8_MMA(1, 0, At, B0); PG8_MMA(1, 1, At, B1); PG8_BAR; PG8_SCHED;
	s_add_i32 s18, s33, s38
	v_lshl_add_u64 v[216:217], v[216:217], 0, s[12:13]
	s_mov_b32 m0, s18
	ds_read_b128 v[184:187], v170 offset:49152
	ds_read_b128 v[188:191], v170 offset:50176
	ds_read_b128 v[192:195], v170 offset:51200
	ds_read_b128 v[196:199], v170 offset:52224
	ds_read_b128 v[200:203], v170 offset:53248
	ds_read_b128 v[204:207], v170 offset:54272
	ds_read_b128 v[208:211], v170 offset:55296
	ds_read_b128 v[212:215], v170 offset:56320
	global_load_lds_dwordx4 v[216:217], off
	s_add_i32 m0, s18, 0x2000
	s_add_u32 s18, s22, 0xb0080
	v_lshl_add_u64 v[216:217], v[218:219], 0, s[12:13]
	s_addc_u32 s19, s23, 0
	s_add_i32 s22, s63, s38
	global_load_lds_dwordx4 v[216:217], off
	v_lshl_add_u64 v[216:217], s[18:19], 0, v[150:151]
	s_mov_b32 m0, s22
	s_nop 0
	global_load_lds_dwordx4 v[216:217], off
	v_lshl_add_u64 v[216:217], s[18:19], 0, v[146:147]
	s_add_i32 m0, s22, 0x2000
	s_nop 0
	global_load_lds_dwordx4 v[216:217], off
	v_lshl_add_u64 v[216:217], v[220:221], 0, s[12:13]
	s_mov_b32 m0, s49
	s_nop 0
	global_load_lds_dwordx4 v[216:217], off
	v_lshl_add_u64 v[216:217], v[222:223], 0, s[12:13]
	s_mov_b32 m0, s50
	s_nop 0
	global_load_lds_dwordx4 v[216:217], off
	s_waitcnt vmcnt(8)
	s_waitcnt lgkmcnt(0)
	s_barrier
	s_setprio 0
	s_waitcnt lgkmcnt(0)
	v_mfma_f32_16x16x32_bf16 v[62:65], v[106:109], v[184:187], v[62:65]
	v_mfma_f32_16x16x32_bf16 v[58:61], v[114:117], v[184:187], v[58:61]
	v_mfma_f32_16x16x32_bf16 v[46:49], v[106:109], v[192:195], v[46:49]
	v_mfma_f32_16x16x32_bf16 v[42:45], v[114:117], v[192:195], v[42:45]
	v_mfma_f32_16x16x32_bf16 v[30:33], v[106:109], v[200:203], v[30:33]
	v_mfma_f32_16x16x32_bf16 v[26:29], v[114:117], v[200:203], v[26:29]
	v_mfma_f32_16x16x32_bf16 v[14:17], v[106:109], v[208:211], v[14:17]
	v_mfma_f32_16x16x32_bf16 v[10:13], v[114:117], v[208:211], v[10:13]
	v_mfma_f32_16x16x32_bf16 v[62:65], v[110:113], v[188:191], v[62:65]
	v_mfma_f32_16x16x32_bf16 v[58:61], v[118:121], v[188:191], v[58:61]
	v_mfma_f32_16x16x32_bf16 v[46:49], v[110:113], v[196:199], v[46:49]
	v_mfma_f32_16x16x32_bf16 v[42:45], v[118:121], v[196:199], v[42:45]
	v_mfma_f32_16x16x32_bf16 v[30:33], v[110:113], v[204:207], v[30:33]
	v_mfma_f32_16x16x32_bf16 v[26:29], v[118:121], v[204:207], v[26:29]
	v_mfma_f32_16x16x32_bf16 v[14:17], v[110:113], v[212:215], v[14:17]
	v_mfma_f32_16x16x32_bf16 v[10:13], v[118:121], v[212:215], v[10:13]
	s_setprio 2
	s_setprio 0
	v_mfma_f32_16x16x32_bf16 v[54:57], v[162:165], v[184:187], v[54:57]
	v_mfma_f32_16x16x32_bf16 v[50:53], v[176:179], v[184:187], v[50:53]
	v_mfma_f32_16x16x32_bf16 v[38:41], v[162:165], v[192:195], v[38:41]
	v_mfma_f32_16x16x32_bf16 v[34:37], v[176:179], v[192:195], v[34:37]
	v_mfma_f32_16x16x32_bf16 v[22:25], v[162:165], v[200:203], v[22:25]
	v_mfma_f32_16x16x32_bf16 v[18:21], v[176:179], v[200:203], v[18:21]
	v_mfma_f32_16x16x32_bf16 v[6:9], v[162:165], v[208:211], v[6:9]
	v_mfma_f32_16x16x32_bf16 v[2:5], v[176:179], v[208:211], v[2:5]
	v_mfma_f32_16x16x32_bf16 v[54:57], v[172:175], v[188:191], v[54:57]
	v_mfma_f32_16x16x32_bf16 v[50:53], v[180:183], v[188:191], v[50:53]
	v_mfma_f32_16x16x32_bf16 v[38:41], v[172:175], v[196:199], v[38:41]
	v_mfma_f32_16x16x32_bf16 v[34:37], v[180:183], v[196:199], v[34:37]
	v_mfma_f32_16x16x32_bf16 v[22:25], v[172:175], v[204:207], v[22:25]
	v_mfma_f32_16x16x32_bf16 v[18:21], v[180:183], v[204:207], v[18:21]
	v_mfma_f32_16x16x32_bf16 v[6:9], v[172:175], v[212:215], v[6:9]
	v_mfma_f32_16x16x32_bf16 v[2:5], v[180:183], v[212:215], v[2:5]
	s_setprio 2
	s_barrier
	s_add_i32 s62, s62, 2
	s_add_u32 s60, s60, 0x100
	s_addc_u32 s61, s61, 0
	s_cmp_gt_u32 s62, 41
	s_mov_b64 s[18:19], s[20:21]
	s_cbranch_scc0 .LBB0_2169
